# v55 + gate phases: the 16 streaming pp-tile loads of pass B issued before pass A (sigmoid pass) into registers dead across it; LDS commit unchanged
# baseline (speedup 1.0000x reference)
; DI unsigned pack2(float a, float b) { f32x2_t v = {a, b}; bf16x2_t r = __builtin_convertvector(v, bf16x2_t); return __builtin_bit_cast(unsigned, r); }
; DI float sigmoidf_(float x) { return __builtin_amdgcn_rcpf(1.f + __expf(-x)); }
; template <bool NT>
; DI void stage_load_tile(bf16_t* stg, const bf16_t* tilebase) {
;     ...
; #pragma unroll
;   for (int hf = 0; hf < 2; ++hf) {
; #pragma unroll
;     for (int it = 8 * hf; it < 8 * hf + 8; ++it) {
;       const u32x4* gp = (const u32x4*)(tilebase + (o0 + (unsigned)(it * 16 * 1024)));
;       stage_write16(stg, r0 + 16 * it, c, NT ? __builtin_nontemporal_load(gp) : *gp);
; template <bool LAST>
; DI void phase_gate(const Params& P, int layer, unsigned char* smem, int L, int G) {
;     ...
;     unsigned gq[4][2][8];
; #pragma unroll
;     for (int i = 0; i < 4; ++i)
; #pragma unroll
;       for (int q4 = 0; q4 < 4; ++q4) {
;         const int fl = wm * 128 + i * 32 + 8 * q4 + 4 * h;
;         const f32x4 c1v = *(const f32x4*)(vecL + fl), c2v = *(const f32x4*)(vecL + 256 + fl);
;         const float c1a[4] = {c1v.x, c1v.y, c1v.z, c1v.w}, c2a[4] = {c2v.x, c2v.y, c2v.z, c2v.w};
; #pragma unroll
;         for (int j = 0; j < 2; ++j) {
;           const int lrow = wn * 64 + j * 32 + r;
;           const float mu = rowA[lrow], rstd = rowB[lrow];
;           float sg4[4];
; #pragma unroll
;           for (int e = 0; e < 4; ++e) sg4[e] = sigmoidf_(rstd * (accu[i][j][4 * q4 + e] - mu * c1a[e]) + c2a[e]);
;           gq[i][j][2 * q4] = pack2(sg4[0], sg4[1]); gq[i][j][2 * q4 + 1] = pack2(sg4[2], sg4[3]);
;         }
;         __builtin_amdgcn_sched_barrier(0);
;       }
.LBB0_479:
	s_ashr_i32 s25, s24, 31
	s_lshl_b64 s[24:25], s[24:25], 19
	s_add_u32 s30, s66, s24
	s_addc_u32 s31, s67, s25
	v_and_b32_e32 v188, 31, v192
	v_ashrrev_i32_e32 v189, 5, v192
	v_lshlrev_b32_e32 v188, 3, v188
	v_lshl_or_b32 v188, v189, 10, v188
	v_add_u32_e32 v188, v188, v162
	v_lshlrev_b32_e32 v188, 1, v188
	global_load_dwordx4 v[180:183], v188, s[30:31] nt
	s_add_u32 s100, s30, 0x8000
	s_addc_u32 s101, s31, 0
	global_load_dwordx4 v[184:187], v188, s[100:101] nt
	s_add_u32 s100, s30, 0x10000
	s_addc_u32 s101, s31, 0
	global_load_dwordx4 v[194:197], v188, s[100:101] nt
	s_add_u32 s100, s30, 0x18000
	s_addc_u32 s101, s31, 0
	global_load_dwordx4 v[198:201], v188, s[100:101] nt
	s_add_u32 s100, s30, 0x20000
	s_addc_u32 s101, s31, 0
	global_load_dwordx4 v[202:205], v188, s[100:101] nt
	s_add_u32 s100, s30, 0x28000
	s_addc_u32 s101, s31, 0
	global_load_dwordx4 v[206:209], v188, s[100:101] nt
	s_add_u32 s100, s30, 0x30000
	s_addc_u32 s101, s31, 0
	global_load_dwordx4 v[210:213], v188, s[100:101] nt
	s_add_u32 s100, s30, 0x38000
	s_addc_u32 s101, s31, 0
	global_load_dwordx4 v[214:217], v188, s[100:101] nt
	s_add_u32 s100, s30, 0x40000
	s_addc_u32 s101, s31, 0
	global_load_dwordx4 v[218:221], v188, s[100:101] nt
	s_add_u32 s100, s30, 0x48000
	s_addc_u32 s101, s31, 0
	global_load_dwordx4 v[222:225], v188, s[100:101] nt
	s_add_u32 s100, s30, 0x50000
	s_addc_u32 s101, s31, 0
	global_load_dwordx4 v[226:229], v188, s[100:101] nt
	s_add_u32 s100, s30, 0x58000
	s_addc_u32 s101, s31, 0
	global_load_dwordx4 v[230:233], v188, s[100:101] nt
	s_add_u32 s100, s30, 0x60000
	s_addc_u32 s101, s31, 0
	global_load_dwordx4 v[234:237], v188, s[100:101] nt
	s_add_u32 s100, s30, 0x68000
	s_addc_u32 s101, s31, 0
	global_load_dwordx4 v[238:241], v188, s[100:101] nt
	s_add_u32 s100, s30, 0x70000
	s_addc_u32 s101, s31, 0
	global_load_dwordx4 v[242:245], v188, s[100:101] nt
	s_add_u32 s100, s30, 0x78000
	s_addc_u32 s101, s31, 0
	global_load_dwordx4 v[248:251], v188, s[100:101] nt
	v_lshrrev_b32_e32 v160, 1, v163
	v_lshrrev_b32_e32 v163, 3, v163
	v_and_b32_e32 v163, 4, v163
	v_and_or_b32 v160, v160, s43, v163
	v_lshlrev_b32_e32 v160, 2, v160
	v_add_u32_e32 v163, 0x24800, v160
	v_add_u32_e32 v164, 0x24c00, v160
	v_and_b32_e32 v167, 0x37c, v168
	ds_read_b128 v[170:173], v163
	ds_read_b128 v[174:177], v164
	v_or_b32_e32 v164, 0x24000, v167
	v_or_b32_e32 v166, 0x24080, v167
	v_or_b32_e32 v165, 0x24400, v167
	ds_read_b32 v168, v164
	ds_read_b32 v169, v165
	v_or_b32_e32 v167, 0x24480, v167
	ds_read_b32 v178, v166
	ds_read_b32 v179, v167
	s_waitcnt lgkmcnt(3)
	v_fma_f32 v112, -v170, v168, v112
	v_fma_f32 v113, -v171, v168, v113
	s_waitcnt lgkmcnt(1)
	v_fma_f32 v98, -v172, v178, v98
	v_fma_f32 v114, -v172, v168, v114
	v_fma_f32 v115, -v173, v168, v115
	v_fma_f32 v96, -v170, v178, v96
	v_fma_f32 v97, -v171, v178, v97
	s_waitcnt lgkmcnt(0)
	v_fma_f32 v98, v179, v98, v176
	v_fma_f32 v99, -v173, v178, v99
	v_fma_f32 v112, v169, v112, v174
	v_fma_f32 v113, v169, v113, v175
	v_fma_f32 v114, v169, v114, v176
	v_fma_f32 v115, v169, v115, v177
	v_fma_f32 v96, v179, v96, v174
	v_fma_f32 v97, v179, v97, v175
	v_mul_f32_e32 v98, 0xbfb8aa3b, v98
	v_fmac_f32_e32 v177, v179, v99
	v_mul_f32_e32 v112, 0xbfb8aa3b, v112
	v_mul_f32_e32 v113, 0xbfb8aa3b, v113
	v_mul_f32_e32 v114, 0xbfb8aa3b, v114
	v_mul_f32_e32 v115, 0xbfb8aa3b, v115
	v_mul_f32_e32 v96, 0xbfb8aa3b, v96
	v_mul_f32_e32 v97, 0xbfb8aa3b, v97
	v_exp_f32_e32 v98, v98
	v_mul_f32_e32 v99, 0xbfb8aa3b, v177
	v_exp_f32_e32 v112, v112
	v_exp_f32_e32 v113, v113
	v_exp_f32_e32 v114, v114
	v_exp_f32_e32 v115, v115
	v_exp_f32_e32 v96, v96
	v_exp_f32_e32 v97, v97
	v_exp_f32_e32 v99, v99
	v_add_f32_e32 v98, 1.0, v98
	v_add_f32_e32 v112, 1.0, v112
	v_add_f32_e32 v113, 1.0, v113
	v_add_f32_e32 v114, 1.0, v114
	v_add_f32_e32 v115, 1.0, v115
	v_add_f32_e32 v96, 1.0, v96
	v_add_f32_e32 v97, 1.0, v97
	v_rcp_f32_e32 v168, v98
	v_add_f32_e32 v98, 1.0, v99
	v_rcp_f32_e32 v112, v112
	v_rcp_f32_e32 v113, v113
	v_rcp_f32_e32 v114, v114
	v_rcp_f32_e32 v115, v115
	v_rcp_f32_e32 v96, v96
	v_rcp_f32_e32 v97, v97
	v_rcp_f32_e32 v169, v98
	v_cvt_pk_bf16_f32 v99, v112, v113
	v_cvt_pk_bf16_f32 v98, v114, v115
	v_cvt_pk_bf16_f32 v97, v96, v97
	v_cvt_pk_bf16_f32 v96, v168, v169
	v_add_u32_e32 v112, 0x24820, v160
	v_add_u32_e32 v168, 0x24c20, v160
	ds_read_b128 v[112:115], v112
	ds_read_b128 v[168:171], v168
	ds_read_b32 v172, v164
	ds_read_b32 v173, v165
	ds_read_b32 v174, v166
	ds_read_b32 v175, v167
	s_waitcnt lgkmcnt(3)
	v_fma_f32 v116, -v112, v172, v116
	v_fma_f32 v117, -v113, v172, v117
	s_waitcnt lgkmcnt(1)
	v_fma_f32 v102, -v114, v174, v102
	v_fma_f32 v118, -v114, v172, v118
	v_fma_f32 v119, -v115, v172, v119
	v_fma_f32 v100, -v112, v174, v100
	v_fma_f32 v101, -v113, v174, v101
	s_waitcnt lgkmcnt(0)
	v_fma_f32 v102, v175, v102, v170
	v_fma_f32 v103, -v115, v174, v103
	v_fma_f32 v116, v173, v116, v168
	v_fma_f32 v117, v173, v117, v169
	v_fma_f32 v118, v173, v118, v170
	v_fma_f32 v119, v173, v119, v171
	v_fma_f32 v100, v175, v100, v168
	v_fma_f32 v101, v175, v101, v169
	v_mul_f32_e32 v102, 0xbfb8aa3b, v102
	v_fmac_f32_e32 v171, v175, v103
	v_mul_f32_e32 v116, 0xbfb8aa3b, v116
	v_mul_f32_e32 v117, 0xbfb8aa3b, v117
	v_mul_f32_e32 v118, 0xbfb8aa3b, v118
	v_mul_f32_e32 v119, 0xbfb8aa3b, v119
	v_mul_f32_e32 v100, 0xbfb8aa3b, v100
	v_mul_f32_e32 v101, 0xbfb8aa3b, v101
	v_exp_f32_e32 v102, v102
	v_mul_f32_e32 v103, 0xbfb8aa3b, v171
	v_exp_f32_e32 v116, v116
	v_exp_f32_e32 v117, v117
	v_exp_f32_e32 v118, v118
	v_exp_f32_e32 v119, v119
	v_exp_f32_e32 v100, v100
	v_exp_f32_e32 v101, v101
	v_exp_f32_e32 v103, v103
	v_add_f32_e32 v102, 1.0, v102
	v_add_f32_e32 v116, 1.0, v116
	v_add_f32_e32 v117, 1.0, v117
	v_add_f32_e32 v118, 1.0, v118
	v_add_f32_e32 v119, 1.0, v119
	v_add_f32_e32 v100, 1.0, v100
	v_add_f32_e32 v101, 1.0, v101
	v_rcp_f32_e32 v113, v102
	v_add_f32_e32 v102, 1.0, v103
	v_rcp_f32_e32 v116, v116
	v_rcp_f32_e32 v117, v117
	v_rcp_f32_e32 v118, v118
	v_rcp_f32_e32 v112, v119
	v_rcp_f32_e32 v100, v100
	v_rcp_f32_e32 v101, v101
	v_rcp_f32_e32 v114, v102
	v_cvt_pk_bf16_f32 v103, v116, v117
	v_cvt_pk_bf16_f32 v102, v118, v112
	v_cvt_pk_bf16_f32 v101, v100, v101
	v_cvt_pk_bf16_f32 v100, v113, v114
	v_add_u32_e32 v112, 0x24840, v160
	v_add_u32_e32 v116, 0x24c40, v160
	ds_read_b128 v[112:115], v112
	ds_read_b128 v[116:119], v116
	ds_read_b32 v168, v164
	ds_read_b32 v169, v165
	ds_read_b32 v170, v166
	ds_read_b32 v171, v167
	s_waitcnt lgkmcnt(3)
; DI unsigned pack2(float a, float b) { f32x2_t v = {a, b}; bf16x2_t r = __builtin_convertvector(v, bf16x2_t); return __builtin_bit_cast(unsigned, r); }
; DI float sigmoidf_(float x) { return __builtin_amdgcn_rcpf(1.f + __expf(-x)); }
; template <bool LAST>
; DI void phase_gate(const Params& P, int layer, unsigned char* smem, int L, int G) {
;     ...
; #pragma unroll
;     for (int i = 0; i < 4; ++i)
; #pragma unroll
;       for (int q4 = 0; q4 < 4; ++q4) {
;         const int fl = wm * 128 + i * 32 + 8 * q4 + 4 * h;
;         const f32x4 c1v = *(const f32x4*)(vecL + fl), c2v = *(const f32x4*)(vecL + 256 + fl);
;         const float c1a[4] = {c1v.x, c1v.y, c1v.z, c1v.w}, c2a[4] = {c2v.x, c2v.y, c2v.z, c2v.w};
; #pragma unroll
;         for (int j = 0; j < 2; ++j) {
;           const int lrow = wn * 64 + j * 32 + r;
;           const float mu = rowA[lrow], rstd = rowB[lrow];
;           float sg4[4];
; #pragma unroll
;           for (int e = 0; e < 4; ++e) sg4[e] = sigmoidf_(rstd * (accu[i][j][4 * q4 + e] - mu * c1a[e]) + c2a[e]);
;           gq[i][j][2 * q4] = pack2(sg4[0], sg4[1]); gq[i][j][2 * q4 + 1] = pack2(sg4[2], sg4[3]);
;         }
;         __builtin_amdgcn_sched_barrier(0);
;       }
	v_fma_f32 v120, -v112, v168, v120
	v_fma_f32 v121, -v113, v168, v121
	s_waitcnt lgkmcnt(1)
	v_fma_f32 v106, -v114, v170, v106
	v_fma_f32 v122, -v114, v168, v122
	v_fma_f32 v123, -v115, v168, v123
	v_fma_f32 v104, -v112, v170, v104
	v_fma_f32 v105, -v113, v170, v105
	s_waitcnt lgkmcnt(0)
	v_fma_f32 v106, v171, v106, v118
	v_fma_f32 v107, -v115, v170, v107
	v_fma_f32 v120, v169, v120, v116
	v_fma_f32 v121, v169, v121, v117
	v_fma_f32 v122, v169, v122, v118
	v_fma_f32 v123, v169, v123, v119
	v_fma_f32 v104, v171, v104, v116
	v_fma_f32 v105, v171, v105, v117
	v_mul_f32_e32 v106, 0xbfb8aa3b, v106
	v_fmac_f32_e32 v119, v171, v107
	v_mul_f32_e32 v120, 0xbfb8aa3b, v120
	v_mul_f32_e32 v121, 0xbfb8aa3b, v121
	v_mul_f32_e32 v122, 0xbfb8aa3b, v122
	v_mul_f32_e32 v123, 0xbfb8aa3b, v123
	v_mul_f32_e32 v104, 0xbfb8aa3b, v104
	v_mul_f32_e32 v105, 0xbfb8aa3b, v105
	v_exp_f32_e32 v106, v106
	v_mul_f32_e32 v107, 0xbfb8aa3b, v119
	v_exp_f32_e32 v120, v120
	v_exp_f32_e32 v121, v121
	v_exp_f32_e32 v122, v122
	v_exp_f32_e32 v123, v123
	v_exp_f32_e32 v104, v104
	v_exp_f32_e32 v105, v105
	v_exp_f32_e32 v107, v107
	v_add_f32_e32 v106, 1.0, v106
	v_add_f32_e32 v120, 1.0, v120
	v_add_f32_e32 v121, 1.0, v121
	v_add_f32_e32 v122, 1.0, v122
	v_add_f32_e32 v123, 1.0, v123
	v_add_f32_e32 v104, 1.0, v104
	v_add_f32_e32 v105, 1.0, v105
	v_rcp_f32_e32 v113, v106
	v_add_f32_e32 v106, 1.0, v107
	v_rcp_f32_e32 v120, v120
	v_rcp_f32_e32 v121, v121
	v_rcp_f32_e32 v122, v122
	v_rcp_f32_e32 v112, v123
	v_rcp_f32_e32 v104, v104
	v_rcp_f32_e32 v105, v105
	v_rcp_f32_e32 v114, v106
	v_cvt_pk_bf16_f32 v107, v120, v121
	v_cvt_pk_bf16_f32 v106, v122, v112
	v_cvt_pk_bf16_f32 v105, v104, v105
	v_cvt_pk_bf16_f32 v104, v113, v114
	v_add_u32_e32 v112, 0x24860, v160
	v_add_u32_e32 v116, 0x24c60, v160
	ds_read_b128 v[112:115], v112
	ds_read_b128 v[116:119], v116
	ds_read_b32 v120, v164
	ds_read_b32 v121, v165
	ds_read_b32 v122, v166
	ds_read_b32 v123, v167
	s_waitcnt lgkmcnt(3)
	v_fma_f32 v125, -v113, v120, v125
	v_fma_f32 v124, -v112, v120, v124
	s_waitcnt lgkmcnt(1)
	v_fma_f32 v110, -v114, v122, v110
	v_fma_f32 v125, v121, v125, v117
	v_fma_f32 v126, -v114, v120, v126
	v_fma_f32 v120, -v115, v120, v127
	v_fma_f32 v108, -v112, v122, v108
	v_fma_f32 v109, -v113, v122, v109
	s_waitcnt lgkmcnt(0)
	v_fma_f32 v110, v123, v110, v118
	v_fma_f32 v111, -v115, v122, v111
	v_fma_f32 v124, v121, v124, v116
	v_mul_f32_e32 v125, 0xbfb8aa3b, v125
	v_fma_f32 v126, v121, v126, v118
	v_fma_f32 v120, v121, v120, v119
	v_fma_f32 v108, v123, v108, v116
	v_fma_f32 v109, v123, v109, v117
	v_mul_f32_e32 v110, 0xbfb8aa3b, v110
	v_fmac_f32_e32 v119, v123, v111
	v_mul_f32_e32 v124, 0xbfb8aa3b, v124
	v_exp_f32_e32 v125, v125
	v_mul_f32_e32 v126, 0xbfb8aa3b, v126
	v_mul_f32_e32 v120, 0xbfb8aa3b, v120
	v_mul_f32_e32 v108, 0xbfb8aa3b, v108
	v_mul_f32_e32 v109, 0xbfb8aa3b, v109
	v_exp_f32_e32 v110, v110
	v_mul_f32_e32 v111, 0xbfb8aa3b, v119
	v_exp_f32_e32 v124, v124
	v_exp_f32_e32 v126, v126
	v_exp_f32_e32 v120, v120
	v_exp_f32_e32 v108, v108
	v_exp_f32_e32 v109, v109
	v_exp_f32_e32 v111, v111
	v_add_f32_e32 v125, 1.0, v125
	v_add_f32_e32 v110, 1.0, v110
	v_add_f32_e32 v124, 1.0, v124
	v_rcp_f32_e32 v121, v125
	v_add_f32_e32 v125, 1.0, v126
	v_add_f32_e32 v120, 1.0, v120
	v_add_f32_e32 v108, 1.0, v108
	v_add_f32_e32 v109, 1.0, v109
	v_rcp_f32_e32 v113, v110
	v_add_f32_e32 v110, 1.0, v111
	v_rcp_f32_e32 v124, v124
	v_rcp_f32_e32 v125, v125
	v_rcp_f32_e32 v112, v120
	v_rcp_f32_e32 v108, v108
	v_rcp_f32_e32 v109, v109
	v_rcp_f32_e32 v114, v110
	v_cvt_pk_bf16_f32 v111, v124, v121
	v_cvt_pk_bf16_f32 v110, v125, v112
	v_cvt_pk_bf16_f32 v109, v108, v109
	v_cvt_pk_bf16_f32 v108, v113, v114
	v_add_u32_e32 v112, 0x24880, v160
	v_add_u32_e32 v116, 0x24c80, v160
	ds_read_b128 v[112:115], v112
	ds_read_b128 v[116:119], v116
	ds_read_b32 v120, v164
	ds_read_b32 v121, v165
	ds_read_b32 v122, v166
	ds_read_b32 v123, v167
	s_waitcnt lgkmcnt(3)
	v_fma_f32 v80, -v112, v120, v80
	v_fma_f32 v81, -v113, v120, v81
	s_waitcnt lgkmcnt(1)
	v_fma_f32 v66, -v114, v122, v66
	v_fma_f32 v82, -v114, v120, v82
	v_fma_f32 v83, -v115, v120, v83
	v_fma_f32 v64, -v112, v122, v64
	v_fma_f32 v65, -v113, v122, v65
	s_waitcnt lgkmcnt(0)
	v_fma_f32 v66, v123, v66, v118
	v_fma_f32 v67, -v115, v122, v67
	v_fma_f32 v80, v121, v80, v116
	v_fma_f32 v81, v121, v81, v117
	v_fma_f32 v82, v121, v82, v118
	v_fma_f32 v83, v121, v83, v119
	v_fma_f32 v64, v123, v64, v116
	v_fma_f32 v65, v123, v65, v117
	v_mul_f32_e32 v66, 0xbfb8aa3b, v66
	v_fmac_f32_e32 v119, v123, v67
	v_mul_f32_e32 v80, 0xbfb8aa3b, v80
	v_mul_f32_e32 v81, 0xbfb8aa3b, v81
	v_mul_f32_e32 v82, 0xbfb8aa3b, v82
	v_mul_f32_e32 v83, 0xbfb8aa3b, v83
	v_mul_f32_e32 v64, 0xbfb8aa3b, v64
	v_mul_f32_e32 v65, 0xbfb8aa3b, v65
	v_exp_f32_e32 v66, v66
	v_mul_f32_e32 v67, 0xbfb8aa3b, v119
	v_exp_f32_e32 v80, v80
	v_exp_f32_e32 v81, v81
	v_exp_f32_e32 v82, v82
	v_exp_f32_e32 v83, v83
	v_exp_f32_e32 v64, v64
	v_exp_f32_e32 v65, v65
	v_exp_f32_e32 v67, v67
	v_add_f32_e32 v66, 1.0, v66
	v_add_f32_e32 v80, 1.0, v80
	v_add_f32_e32 v81, 1.0, v81
	v_add_f32_e32 v82, 1.0, v82
	v_add_f32_e32 v83, 1.0, v83
	v_add_f32_e32 v64, 1.0, v64
	v_add_f32_e32 v65, 1.0, v65
	v_rcp_f32_e32 v112, v66
	v_add_f32_e32 v66, 1.0, v67
	v_rcp_f32_e32 v80, v80
	v_rcp_f32_e32 v81, v81
	v_rcp_f32_e32 v82, v82
	v_rcp_f32_e32 v83, v83
	v_rcp_f32_e32 v64, v64
	v_rcp_f32_e32 v65, v65
	v_rcp_f32_e32 v113, v66
	v_cvt_pk_bf16_f32 v67, v80, v81
	v_cvt_pk_bf16_f32 v66, v82, v83
	v_cvt_pk_bf16_f32 v65, v64, v65
	v_cvt_pk_bf16_f32 v64, v112, v113
	v_add_u32_e32 v80, 0x248a0, v160
	v_add_u32_e32 v112, 0x24ca0, v160
	ds_read_b128 v[80:83], v80
	ds_read_b128 v[112:115], v112
	ds_read_b32 v116, v164
	ds_read_b32 v117, v165
	ds_read_b32 v118, v166
	ds_read_b32 v119, v167
	s_waitcnt lgkmcnt(3)
; DI unsigned pack2(float a, float b) { f32x2_t v = {a, b}; bf16x2_t r = __builtin_convertvector(v, bf16x2_t); return __builtin_bit_cast(unsigned, r); }
; DI float sigmoidf_(float x) { return __builtin_amdgcn_rcpf(1.f + __expf(-x)); }
; template <bool LAST>
; DI void phase_gate(const Params& P, int layer, unsigned char* smem, int L, int G) {
;     ...
; #pragma unroll
;     for (int i = 0; i < 4; ++i)
; #pragma unroll
;       for (int q4 = 0; q4 < 4; ++q4) {
;         const int fl = wm * 128 + i * 32 + 8 * q4 + 4 * h;
;         const f32x4 c1v = *(const f32x4*)(vecL + fl), c2v = *(const f32x4*)(vecL + 256 + fl);
;         const float c1a[4] = {c1v.x, c1v.y, c1v.z, c1v.w}, c2a[4] = {c2v.x, c2v.y, c2v.z, c2v.w};
; #pragma unroll
;         for (int j = 0; j < 2; ++j) {
;           const int lrow = wn * 64 + j * 32 + r;
;           const float mu = rowA[lrow], rstd = rowB[lrow];
;           float sg4[4];
; #pragma unroll
;           for (int e = 0; e < 4; ++e) sg4[e] = sigmoidf_(rstd * (accu[i][j][4 * q4 + e] - mu * c1a[e]) + c2a[e]);
;           gq[i][j][2 * q4] = pack2(sg4[0], sg4[1]); gq[i][j][2 * q4 + 1] = pack2(sg4[2], sg4[3]);
;         }
;         __builtin_amdgcn_sched_barrier(0);
;       }
	v_fma_f32 v84, -v80, v116, v84
	v_fma_f32 v85, -v81, v116, v85
	s_waitcnt lgkmcnt(1)
	v_fma_f32 v70, -v82, v118, v70
	v_fma_f32 v86, -v82, v116, v86
	v_fma_f32 v87, -v83, v116, v87
	v_fma_f32 v68, -v80, v118, v68
	v_fma_f32 v69, -v81, v118, v69
	s_waitcnt lgkmcnt(0)
	v_fma_f32 v70, v119, v70, v114
	v_fma_f32 v71, -v83, v118, v71
	v_fma_f32 v84, v117, v84, v112
	v_fma_f32 v85, v117, v85, v113
	v_fma_f32 v86, v117, v86, v114
	v_fma_f32 v87, v117, v87, v115
	v_fma_f32 v68, v119, v68, v112
	v_fma_f32 v69, v119, v69, v113
	v_mul_f32_e32 v70, 0xbfb8aa3b, v70
	v_fmac_f32_e32 v115, v119, v71
	v_mul_f32_e32 v84, 0xbfb8aa3b, v84
	v_mul_f32_e32 v85, 0xbfb8aa3b, v85
	v_mul_f32_e32 v86, 0xbfb8aa3b, v86
	v_mul_f32_e32 v87, 0xbfb8aa3b, v87
	v_mul_f32_e32 v68, 0xbfb8aa3b, v68
	v_mul_f32_e32 v69, 0xbfb8aa3b, v69
	v_exp_f32_e32 v70, v70
	v_mul_f32_e32 v71, 0xbfb8aa3b, v115
	v_exp_f32_e32 v84, v84
	v_exp_f32_e32 v85, v85
	v_exp_f32_e32 v86, v86
	v_exp_f32_e32 v87, v87
	v_exp_f32_e32 v68, v68
	v_exp_f32_e32 v69, v69
	v_exp_f32_e32 v71, v71
	v_add_f32_e32 v70, 1.0, v70
	v_add_f32_e32 v84, 1.0, v84
	v_add_f32_e32 v85, 1.0, v85
	v_add_f32_e32 v86, 1.0, v86
	v_add_f32_e32 v87, 1.0, v87
	v_add_f32_e32 v68, 1.0, v68
	v_add_f32_e32 v69, 1.0, v69
	v_rcp_f32_e32 v81, v70
	v_add_f32_e32 v70, 1.0, v71
	v_rcp_f32_e32 v84, v84
	v_rcp_f32_e32 v85, v85
	v_rcp_f32_e32 v86, v86
	v_rcp_f32_e32 v80, v87
	v_rcp_f32_e32 v68, v68
	v_rcp_f32_e32 v69, v69
	v_rcp_f32_e32 v82, v70
	v_cvt_pk_bf16_f32 v71, v84, v85
	v_cvt_pk_bf16_f32 v70, v86, v80
	v_cvt_pk_bf16_f32 v69, v68, v69
	v_cvt_pk_bf16_f32 v68, v81, v82
	v_add_u32_e32 v80, 0x248c0, v160
	v_add_u32_e32 v84, 0x24cc0, v160
	ds_read_b128 v[80:83], v80
	ds_read_b128 v[84:87], v84
	ds_read_b32 v112, v164
	ds_read_b32 v113, v165
	ds_read_b32 v114, v166
	ds_read_b32 v115, v167
	s_waitcnt lgkmcnt(3)
	v_fma_f32 v88, -v80, v112, v88
	v_fma_f32 v89, -v81, v112, v89
	s_waitcnt lgkmcnt(1)
	v_fma_f32 v74, -v82, v114, v74
	v_fma_f32 v90, -v82, v112, v90
	v_fma_f32 v91, -v83, v112, v91
	v_fma_f32 v72, -v80, v114, v72
	v_fma_f32 v73, -v81, v114, v73
	s_waitcnt lgkmcnt(0)
	v_fma_f32 v74, v115, v74, v86
	v_fma_f32 v75, -v83, v114, v75
	v_fma_f32 v88, v113, v88, v84
	v_fma_f32 v89, v113, v89, v85
	v_fma_f32 v90, v113, v90, v86
	v_fma_f32 v91, v113, v91, v87
	v_fma_f32 v72, v115, v72, v84
	v_fma_f32 v73, v115, v73, v85
	v_mul_f32_e32 v74, 0xbfb8aa3b, v74
	v_fmac_f32_e32 v87, v115, v75
	v_mul_f32_e32 v88, 0xbfb8aa3b, v88
	v_mul_f32_e32 v89, 0xbfb8aa3b, v89
	v_mul_f32_e32 v90, 0xbfb8aa3b, v90
	v_mul_f32_e32 v91, 0xbfb8aa3b, v91
	v_mul_f32_e32 v72, 0xbfb8aa3b, v72
	v_mul_f32_e32 v73, 0xbfb8aa3b, v73
	v_exp_f32_e32 v74, v74
	v_mul_f32_e32 v75, 0xbfb8aa3b, v87
	v_exp_f32_e32 v88, v88
	v_exp_f32_e32 v89, v89
	v_exp_f32_e32 v90, v90
	v_exp_f32_e32 v91, v91
	v_exp_f32_e32 v72, v72
	v_exp_f32_e32 v73, v73
	v_exp_f32_e32 v75, v75
	v_add_f32_e32 v74, 1.0, v74
	v_add_f32_e32 v88, 1.0, v88
	v_add_f32_e32 v89, 1.0, v89
	v_add_f32_e32 v90, 1.0, v90
	v_add_f32_e32 v91, 1.0, v91
	v_add_f32_e32 v72, 1.0, v72
	v_add_f32_e32 v73, 1.0, v73
	v_rcp_f32_e32 v81, v74
	v_add_f32_e32 v74, 1.0, v75
	v_rcp_f32_e32 v88, v88
	v_rcp_f32_e32 v89, v89
	v_rcp_f32_e32 v90, v90
	v_rcp_f32_e32 v80, v91
	v_rcp_f32_e32 v72, v72
	v_rcp_f32_e32 v73, v73
	v_rcp_f32_e32 v82, v74
	v_cvt_pk_bf16_f32 v75, v88, v89
	v_cvt_pk_bf16_f32 v74, v90, v80
	v_cvt_pk_bf16_f32 v73, v72, v73
	v_cvt_pk_bf16_f32 v72, v81, v82
	v_add_u32_e32 v80, 0x248e0, v160
	v_add_u32_e32 v84, 0x24ce0, v160
	ds_read_b128 v[80:83], v80
	ds_read_b128 v[84:87], v84
	ds_read_b32 v88, v164
	ds_read_b32 v89, v165
	ds_read_b32 v90, v166
	ds_read_b32 v91, v167
	s_waitcnt lgkmcnt(3)
	v_fma_f32 v93, -v81, v88, v93
	v_fma_f32 v92, -v80, v88, v92
	s_waitcnt lgkmcnt(1)
	v_fma_f32 v78, -v82, v90, v78
	v_fma_f32 v93, v89, v93, v85
	v_fma_f32 v94, -v82, v88, v94
	v_fma_f32 v88, -v83, v88, v95
	v_fma_f32 v76, -v80, v90, v76
	v_fma_f32 v77, -v81, v90, v77
	s_waitcnt lgkmcnt(0)
	v_fma_f32 v78, v91, v78, v86
	v_fma_f32 v79, -v83, v90, v79
	v_fma_f32 v92, v89, v92, v84
	v_mul_f32_e32 v93, 0xbfb8aa3b, v93
	v_fma_f32 v94, v89, v94, v86
	v_fma_f32 v88, v89, v88, v87
	v_fma_f32 v76, v91, v76, v84
	v_fma_f32 v77, v91, v77, v85
	v_mul_f32_e32 v78, 0xbfb8aa3b, v78
	v_fmac_f32_e32 v87, v91, v79
	v_mul_f32_e32 v92, 0xbfb8aa3b, v92
	v_exp_f32_e32 v93, v93
	v_mul_f32_e32 v94, 0xbfb8aa3b, v94
	v_mul_f32_e32 v88, 0xbfb8aa3b, v88
	v_mul_f32_e32 v76, 0xbfb8aa3b, v76
	v_mul_f32_e32 v77, 0xbfb8aa3b, v77
	v_exp_f32_e32 v78, v78
	v_mul_f32_e32 v79, 0xbfb8aa3b, v87
	v_exp_f32_e32 v92, v92
	v_exp_f32_e32 v94, v94
	v_exp_f32_e32 v88, v88
	v_exp_f32_e32 v76, v76
	v_exp_f32_e32 v77, v77
	v_exp_f32_e32 v79, v79
	v_add_f32_e32 v93, 1.0, v93
	v_add_f32_e32 v78, 1.0, v78
	v_add_f32_e32 v92, 1.0, v92
	v_rcp_f32_e32 v89, v93
	v_add_f32_e32 v93, 1.0, v94
	v_add_f32_e32 v88, 1.0, v88
	v_add_f32_e32 v76, 1.0, v76
	v_add_f32_e32 v77, 1.0, v77
	v_rcp_f32_e32 v81, v78
	v_add_f32_e32 v78, 1.0, v79
	v_rcp_f32_e32 v92, v92
	v_rcp_f32_e32 v93, v93
	v_rcp_f32_e32 v80, v88
	v_rcp_f32_e32 v76, v76
	v_rcp_f32_e32 v77, v77
	v_rcp_f32_e32 v82, v78
	v_cvt_pk_bf16_f32 v79, v92, v89
	v_cvt_pk_bf16_f32 v78, v93, v80
	v_cvt_pk_bf16_f32 v77, v76, v77
	v_cvt_pk_bf16_f32 v76, v81, v82
	v_add_u32_e32 v80, 0x24900, v160
	v_add_u32_e32 v84, 0x24d00, v160
	ds_read_b128 v[80:83], v80
	ds_read_b128 v[84:87], v84
	ds_read_b32 v88, v164
	ds_read_b32 v89, v165
	ds_read_b32 v90, v166
	ds_read_b32 v91, v167
	s_waitcnt lgkmcnt(3)
	v_fma_f32 v48, -v80, v88, v48
	v_fma_f32 v49, -v81, v88, v49
	s_waitcnt lgkmcnt(1)
	v_fma_f32 v34, -v82, v90, v34
	v_fma_f32 v50, -v82, v88, v50
	v_fma_f32 v51, -v83, v88, v51
	v_fma_f32 v32, -v80, v90, v32
	v_fma_f32 v33, -v81, v90, v33
	s_waitcnt lgkmcnt(0)
; DI unsigned pack2(float a, float b) { f32x2_t v = {a, b}; bf16x2_t r = __builtin_convertvector(v, bf16x2_t); return __builtin_bit_cast(unsigned, r); }
; DI float sigmoidf_(float x) { return __builtin_amdgcn_rcpf(1.f + __expf(-x)); }
; template <bool LAST>
; DI void phase_gate(const Params& P, int layer, unsigned char* smem, int L, int G) {
;     ...
; #pragma unroll
;     for (int i = 0; i < 4; ++i)
; #pragma unroll
;       for (int q4 = 0; q4 < 4; ++q4) {
;         const int fl = wm * 128 + i * 32 + 8 * q4 + 4 * h;
;         const f32x4 c1v = *(const f32x4*)(vecL + fl), c2v = *(const f32x4*)(vecL + 256 + fl);
;         const float c1a[4] = {c1v.x, c1v.y, c1v.z, c1v.w}, c2a[4] = {c2v.x, c2v.y, c2v.z, c2v.w};
; #pragma unroll
;         for (int j = 0; j < 2; ++j) {
;           const int lrow = wn * 64 + j * 32 + r;
;           const float mu = rowA[lrow], rstd = rowB[lrow];
;           float sg4[4];
; #pragma unroll
;           for (int e = 0; e < 4; ++e) sg4[e] = sigmoidf_(rstd * (accu[i][j][4 * q4 + e] - mu * c1a[e]) + c2a[e]);
;           gq[i][j][2 * q4] = pack2(sg4[0], sg4[1]); gq[i][j][2 * q4 + 1] = pack2(sg4[2], sg4[3]);
;         }
;         __builtin_amdgcn_sched_barrier(0);
;       }
	v_fma_f32 v34, v91, v34, v86
	v_fma_f32 v35, -v83, v90, v35
	v_fma_f32 v48, v89, v48, v84
	v_fma_f32 v49, v89, v49, v85
	v_fma_f32 v50, v89, v50, v86
	v_fma_f32 v51, v89, v51, v87
	v_fma_f32 v32, v91, v32, v84
	v_fma_f32 v33, v91, v33, v85
	v_mul_f32_e32 v34, 0xbfb8aa3b, v34
	v_fmac_f32_e32 v87, v91, v35
	v_mul_f32_e32 v48, 0xbfb8aa3b, v48
	v_mul_f32_e32 v49, 0xbfb8aa3b, v49
	v_mul_f32_e32 v50, 0xbfb8aa3b, v50
	v_mul_f32_e32 v51, 0xbfb8aa3b, v51
	v_mul_f32_e32 v32, 0xbfb8aa3b, v32
	v_mul_f32_e32 v33, 0xbfb8aa3b, v33
	v_exp_f32_e32 v34, v34
	v_mul_f32_e32 v35, 0xbfb8aa3b, v87
	v_exp_f32_e32 v48, v48
	v_exp_f32_e32 v49, v49
	v_exp_f32_e32 v50, v50
	v_exp_f32_e32 v51, v51
	v_exp_f32_e32 v32, v32
	v_exp_f32_e32 v33, v33
	v_exp_f32_e32 v35, v35
	v_add_f32_e32 v34, 1.0, v34
	v_add_f32_e32 v48, 1.0, v48
	v_add_f32_e32 v49, 1.0, v49
	v_add_f32_e32 v50, 1.0, v50
	v_add_f32_e32 v51, 1.0, v51
	v_add_f32_e32 v32, 1.0, v32
	v_add_f32_e32 v33, 1.0, v33
	v_rcp_f32_e32 v80, v34
	v_add_f32_e32 v34, 1.0, v35
	v_rcp_f32_e32 v48, v48
	v_rcp_f32_e32 v49, v49
	v_rcp_f32_e32 v50, v50
	v_rcp_f32_e32 v51, v51
	v_rcp_f32_e32 v32, v32
	v_rcp_f32_e32 v33, v33
	v_rcp_f32_e32 v81, v34
	v_cvt_pk_bf16_f32 v35, v48, v49
	v_cvt_pk_bf16_f32 v34, v50, v51
	v_cvt_pk_bf16_f32 v33, v32, v33
	v_cvt_pk_bf16_f32 v32, v80, v81
	v_add_u32_e32 v48, 0x24920, v160
	v_add_u32_e32 v80, 0x24d20, v160
	ds_read_b128 v[48:51], v48
	ds_read_b128 v[80:83], v80
	ds_read_b32 v84, v164
	ds_read_b32 v85, v165
	ds_read_b32 v86, v166
	ds_read_b32 v87, v167
	s_waitcnt lgkmcnt(3)
	v_fma_f32 v53, -v49, v84, v53
	v_fma_f32 v52, -v48, v84, v52
	s_waitcnt lgkmcnt(1)
	v_fma_f32 v36, -v48, v86, v36
	s_waitcnt lgkmcnt(0)
	v_fma_f32 v36, v87, v36, v80
	v_fma_f32 v37, -v49, v86, v37
	v_mul_f32_e32 v36, 0xbfb8aa3b, v36
	v_fma_f32 v37, v87, v37, v81
	v_exp_f32_e32 v36, v36
	v_mul_f32_e32 v37, 0xbfb8aa3b, v37
	v_exp_f32_e32 v37, v37
	v_fma_f32 v54, -v50, v84, v54
	v_add_f32_e32 v36, 1.0, v36
	v_rcp_f32_e32 v49, v36
	v_add_f32_e32 v36, 1.0, v37
	v_fma_f32 v37, -v50, v86, v38
	v_fma_f32 v55, -v51, v84, v55
	v_fma_f32 v37, v87, v37, v82
	v_fma_f32 v38, -v51, v86, v39
	v_fma_f32 v52, v85, v52, v80
	v_fma_f32 v53, v85, v53, v81
	v_fma_f32 v54, v85, v54, v82
	v_fma_f32 v55, v85, v55, v83
	v_mul_f32_e32 v37, 0xbfb8aa3b, v37
	v_fmac_f32_e32 v83, v87, v38
	v_mul_f32_e32 v52, 0xbfb8aa3b, v52
	v_mul_f32_e32 v53, 0xbfb8aa3b, v53
	v_mul_f32_e32 v54, 0xbfb8aa3b, v54
	v_mul_f32_e32 v55, 0xbfb8aa3b, v55
	v_exp_f32_e32 v37, v37
	v_mul_f32_e32 v38, 0xbfb8aa3b, v83
	v_exp_f32_e32 v52, v52
	v_exp_f32_e32 v53, v53
	v_exp_f32_e32 v54, v54
	v_exp_f32_e32 v55, v55
	v_exp_f32_e32 v38, v38
	v_rcp_f32_e32 v39, v36
	v_add_f32_e32 v36, 1.0, v37
	v_add_f32_e32 v52, 1.0, v52
	v_add_f32_e32 v53, 1.0, v53
	v_add_f32_e32 v54, 1.0, v54
	v_add_f32_e32 v55, 1.0, v55
	v_rcp_f32_e32 v37, v36
	v_add_f32_e32 v36, 1.0, v38
	v_rcp_f32_e32 v52, v52
	v_rcp_f32_e32 v53, v53
	v_rcp_f32_e32 v54, v54
	v_rcp_f32_e32 v48, v55
	v_rcp_f32_e32 v38, v36
	v_cvt_pk_bf16_f32 v80, v52, v53
	v_cvt_pk_bf16_f32 v55, v49, v39
	v_cvt_pk_bf16_f32 v36, v54, v48
	v_cvt_pk_bf16_f32 v53, v37, v38
	v_add_u32_e32 v37, 0x24940, v160
	v_add_u32_e32 v38, 0x24d40, v160
	ds_read_b128 v[48:51], v37
	ds_read_b128 v[82:85], v38
	ds_read_b32 v37, v164
	ds_read_b32 v38, v165
	ds_read_b32 v39, v166
	ds_read_b32 v52, v167
	s_waitcnt lgkmcnt(3)
	v_fma_f32 v54, -v48, v37, v56
	v_fma_f32 v56, -v49, v37, v57
	s_waitcnt lgkmcnt(2)
	v_fma_f32 v56, v38, v56, v83
	v_fma_f32 v57, -v50, v37, v58
	v_fma_f32 v37, -v51, v37, v59
	s_waitcnt lgkmcnt(1)
	v_fma_f32 v40, -v48, v39, v40
	v_fma_f32 v41, -v49, v39, v41
	v_fma_f32 v42, -v50, v39, v42
	v_fma_f32 v39, -v51, v39, v43
	v_fma_f32 v54, v38, v54, v82
	v_mul_f32_e32 v56, 0xbfb8aa3b, v56
	v_fma_f32 v57, v38, v57, v84
	v_fma_f32 v37, v38, v37, v85
	s_waitcnt lgkmcnt(0)
	v_fma_f32 v40, v52, v40, v82
	v_fma_f32 v41, v52, v41, v83
	v_fma_f32 v42, v52, v42, v84
	v_fmac_f32_e32 v85, v52, v39
	v_mul_f32_e32 v54, 0xbfb8aa3b, v54
	v_exp_f32_e32 v56, v56
	v_mul_f32_e32 v57, 0xbfb8aa3b, v57
	v_mul_f32_e32 v37, 0xbfb8aa3b, v37
	v_mul_f32_e32 v40, 0xbfb8aa3b, v40
	v_mul_f32_e32 v41, 0xbfb8aa3b, v41
	v_mul_f32_e32 v42, 0xbfb8aa3b, v42
	v_mul_f32_e32 v39, 0xbfb8aa3b, v85
	v_exp_f32_e32 v54, v54
	v_exp_f32_e32 v57, v57
	v_exp_f32_e32 v37, v37
	v_exp_f32_e32 v40, v40
	v_exp_f32_e32 v41, v41
	v_exp_f32_e32 v42, v42
	v_exp_f32_e32 v39, v39
	v_add_f32_e32 v56, 1.0, v56
	v_add_f32_e32 v54, 1.0, v54
	v_rcp_f32_e32 v38, v56
	v_add_f32_e32 v56, 1.0, v57
	v_add_f32_e32 v37, 1.0, v37
	v_add_f32_e32 v40, 1.0, v40
	v_add_f32_e32 v41, 1.0, v41
	v_add_f32_e32 v42, 1.0, v42
	v_add_f32_e32 v39, 1.0, v39
	v_rcp_f32_e32 v54, v54
	v_rcp_f32_e32 v56, v56
	v_rcp_f32_e32 v37, v37
	v_rcp_f32_e32 v40, v40
	v_rcp_f32_e32 v41, v41
	v_rcp_f32_e32 v42, v42
	v_rcp_f32_e32 v39, v39
	v_cvt_pk_bf16_f32 v83, v54, v38
	v_cvt_pk_bf16_f32 v82, v56, v37
	v_cvt_pk_bf16_f32 v81, v40, v41
	v_cvt_pk_bf16_f32 v59, v42, v39
	v_add_u32_e32 v37, 0x24960, v160
	v_add_u32_e32 v42, 0x24d60, v160
	ds_read_b128 v[38:41], v37
	ds_read_b128 v[48:51], v42
	ds_read_b32 v37, v164
	ds_read_b32 v42, v165
	ds_read_b32 v43, v166
	ds_read_b32 v52, v167
	s_waitcnt lgkmcnt(3)
	v_fma_f32 v56, -v39, v37, v61
	v_fma_f32 v54, -v38, v37, v60
	s_waitcnt lgkmcnt(2)
	v_fma_f32 v56, v42, v56, v49
	v_fma_f32 v57, -v40, v37, v62
	v_fma_f32 v37, -v41, v37, v63
	s_waitcnt lgkmcnt(1)
	v_fma_f32 v38, -v38, v43, v44
	v_fma_f32 v39, -v39, v43, v45
	v_fma_f32 v40, -v40, v43, v46
	v_fma_f32 v41, -v41, v43, v47
	v_fma_f32 v54, v42, v54, v48
	v_mul_f32_e32 v56, 0xbfb8aa3b, v56
	v_fma_f32 v57, v42, v57, v50
	v_fma_f32 v37, v42, v37, v51
	s_waitcnt lgkmcnt(0)
; DI unsigned pack2(float a, float b) { f32x2_t v = {a, b}; bf16x2_t r = __builtin_convertvector(v, bf16x2_t); return __builtin_bit_cast(unsigned, r); }
; DI float sigmoidf_(float x) { return __builtin_amdgcn_rcpf(1.f + __expf(-x)); }
; template <bool LAST>
; DI void phase_gate(const Params& P, int layer, unsigned char* smem, int L, int G) {
;     ...
; #pragma unroll
;     for (int i = 0; i < 4; ++i)
; #pragma unroll
;       for (int q4 = 0; q4 < 4; ++q4) {
;         const int fl = wm * 128 + i * 32 + 8 * q4 + 4 * h;
;         const f32x4 c1v = *(const f32x4*)(vecL + fl), c2v = *(const f32x4*)(vecL + 256 + fl);
;         const float c1a[4] = {c1v.x, c1v.y, c1v.z, c1v.w}, c2a[4] = {c2v.x, c2v.y, c2v.z, c2v.w};
; #pragma unroll
;         for (int j = 0; j < 2; ++j) {
;           const int lrow = wn * 64 + j * 32 + r;
;           const float mu = rowA[lrow], rstd = rowB[lrow];
;           float sg4[4];
; #pragma unroll
;           for (int e = 0; e < 4; ++e) sg4[e] = sigmoidf_(rstd * (accu[i][j][4 * q4 + e] - mu * c1a[e]) + c2a[e]);
;           gq[i][j][2 * q4] = pack2(sg4[0], sg4[1]); gq[i][j][2 * q4 + 1] = pack2(sg4[2], sg4[3]);
;         }
;         __builtin_amdgcn_sched_barrier(0);
;       }
	v_fma_f32 v38, v52, v38, v48
	v_fma_f32 v39, v52, v39, v49
	v_fma_f32 v40, v52, v40, v50
	v_fmac_f32_e32 v51, v52, v41
	v_mul_f32_e32 v54, 0xbfb8aa3b, v54
	v_exp_f32_e32 v56, v56
	v_mul_f32_e32 v57, 0xbfb8aa3b, v57
	v_mul_f32_e32 v37, 0xbfb8aa3b, v37
	v_mul_f32_e32 v38, 0xbfb8aa3b, v38
	v_mul_f32_e32 v39, 0xbfb8aa3b, v39
	v_mul_f32_e32 v40, 0xbfb8aa3b, v40
	v_mul_f32_e32 v41, 0xbfb8aa3b, v51
	v_exp_f32_e32 v54, v54
	v_exp_f32_e32 v57, v57
	v_exp_f32_e32 v37, v37
	v_exp_f32_e32 v38, v38
	v_exp_f32_e32 v39, v39
	v_exp_f32_e32 v40, v40
	v_exp_f32_e32 v41, v41
	v_add_f32_e32 v56, 1.0, v56
	v_add_f32_e32 v54, 1.0, v54
	v_rcp_f32_e32 v42, v56
	v_add_f32_e32 v56, 1.0, v57
	v_add_f32_e32 v37, 1.0, v37
	v_add_f32_e32 v38, 1.0, v38
	v_add_f32_e32 v39, 1.0, v39
	v_add_f32_e32 v40, 1.0, v40
	v_add_f32_e32 v41, 1.0, v41
	v_rcp_f32_e32 v54, v54
	v_rcp_f32_e32 v56, v56
	v_rcp_f32_e32 v37, v37
	v_rcp_f32_e32 v38, v38
	v_rcp_f32_e32 v39, v39
	v_rcp_f32_e32 v40, v40
	v_rcp_f32_e32 v41, v41
	v_cvt_pk_bf16_f32 v91, v54, v42
	v_cvt_pk_bf16_f32 v86, v56, v37
	v_cvt_pk_bf16_f32 v85, v38, v39
	v_cvt_pk_bf16_f32 v84, v40, v41
	v_add_u32_e32 v37, 0x24980, v160
	v_add_u32_e32 v42, 0x24d80, v160
	ds_read_b128 v[38:41], v37
	ds_read_b128 v[42:45], v42
	ds_read_b32 v37, v164
	ds_read_b32 v46, v165
	ds_read_b32 v47, v166
	ds_read_b32 v48, v167
	s_waitcnt lgkmcnt(3)
	v_fma_f32 v16, -v38, v37, v16
	v_fma_f32 v17, -v39, v37, v17
	v_fma_f32 v18, -v40, v37, v18
	v_fma_f32 v19, -v41, v37, v19
	s_waitcnt lgkmcnt(1)
	v_fma_f32 v0, -v38, v47, v0
	v_fma_f32 v1, -v39, v47, v1
	v_fma_f32 v2, -v40, v47, v2
	v_fma_f32 v3, -v41, v47, v3
	v_fma_f32 v16, v46, v16, v42
	v_fma_f32 v17, v46, v17, v43
	v_fma_f32 v18, v46, v18, v44
	v_fma_f32 v19, v46, v19, v45
	s_waitcnt lgkmcnt(0)
	v_fma_f32 v0, v48, v0, v42
	v_fma_f32 v1, v48, v1, v43
	v_fma_f32 v2, v48, v2, v44
	v_fmac_f32_e32 v45, v48, v3
	v_mul_f32_e32 v16, 0xbfb8aa3b, v16
	v_mul_f32_e32 v17, 0xbfb8aa3b, v17
	v_mul_f32_e32 v18, 0xbfb8aa3b, v18
	v_mul_f32_e32 v19, 0xbfb8aa3b, v19
	v_mul_f32_e32 v0, 0xbfb8aa3b, v0
	v_mul_f32_e32 v1, 0xbfb8aa3b, v1
	v_mul_f32_e32 v2, 0xbfb8aa3b, v2
	v_mul_f32_e32 v3, 0xbfb8aa3b, v45
	v_exp_f32_e32 v16, v16
	v_exp_f32_e32 v17, v17
	v_exp_f32_e32 v18, v18
	v_exp_f32_e32 v19, v19
	v_exp_f32_e32 v0, v0
	v_exp_f32_e32 v1, v1
	v_exp_f32_e32 v2, v2
	v_exp_f32_e32 v3, v3
	v_add_f32_e32 v16, 1.0, v16
	v_add_f32_e32 v17, 1.0, v17
	v_add_f32_e32 v18, 1.0, v18
	v_add_f32_e32 v19, 1.0, v19
	v_add_f32_e32 v0, 1.0, v0
	v_add_f32_e32 v1, 1.0, v1
	v_add_f32_e32 v2, 1.0, v2
	v_add_f32_e32 v3, 1.0, v3
	v_rcp_f32_e32 v16, v16
	v_rcp_f32_e32 v17, v17
	v_rcp_f32_e32 v18, v18
	v_rcp_f32_e32 v19, v19
	v_rcp_f32_e32 v0, v0
	v_rcp_f32_e32 v1, v1
	v_rcp_f32_e32 v2, v2
	v_rcp_f32_e32 v37, v3
	v_cvt_pk_bf16_f32 v17, v16, v17
	v_cvt_pk_bf16_f32 v16, v18, v19
	v_cvt_pk_bf16_f32 v3, v0, v1
	v_cvt_pk_bf16_f32 v2, v2, v37
	v_add_u32_e32 v0, 0x249a0, v160
	v_add_u32_e32 v1, 0x24da0, v160
	ds_read_b128 v[38:41], v0
	ds_read_b128 v[42:45], v1
	ds_read_b32 v0, v164
	ds_read_b32 v1, v165
	ds_read_b32 v18, v166
	ds_read_b32 v19, v167
	s_waitcnt lgkmcnt(3)
	v_fma_f32 v21, -v39, v0, v21
	v_fma_f32 v20, -v38, v0, v20
	s_waitcnt lgkmcnt(1)
	v_fma_f32 v6, -v40, v18, v6
	v_fma_f32 v21, v1, v21, v43
	v_fma_f32 v22, -v40, v0, v22
	v_fma_f32 v0, -v41, v0, v23
	v_fma_f32 v4, -v38, v18, v4
	v_fma_f32 v5, -v39, v18, v5
	s_waitcnt lgkmcnt(0)
	v_fma_f32 v6, v19, v6, v44
	v_fma_f32 v7, -v41, v18, v7
	v_fma_f32 v20, v1, v20, v42
	v_mul_f32_e32 v21, 0xbfb8aa3b, v21
	v_fma_f32 v22, v1, v22, v44
	v_fma_f32 v0, v1, v0, v45
	v_fma_f32 v4, v19, v4, v42
	v_fma_f32 v5, v19, v5, v43
	v_mul_f32_e32 v6, 0xbfb8aa3b, v6
	v_fmac_f32_e32 v45, v19, v7
	v_mul_f32_e32 v20, 0xbfb8aa3b, v20
	v_exp_f32_e32 v21, v21
	v_mul_f32_e32 v22, 0xbfb8aa3b, v22
	v_mul_f32_e32 v0, 0xbfb8aa3b, v0
	v_mul_f32_e32 v4, 0xbfb8aa3b, v4
	v_mul_f32_e32 v5, 0xbfb8aa3b, v5
	v_exp_f32_e32 v6, v6
	v_mul_f32_e32 v7, 0xbfb8aa3b, v45
	v_exp_f32_e32 v20, v20
	v_exp_f32_e32 v22, v22
	v_exp_f32_e32 v0, v0
	v_exp_f32_e32 v4, v4
	v_exp_f32_e32 v5, v5
	v_exp_f32_e32 v7, v7
	v_add_f32_e32 v21, 1.0, v21
	v_add_f32_e32 v6, 1.0, v6
	v_add_f32_e32 v20, 1.0, v20
	v_rcp_f32_e32 v1, v21
	v_add_f32_e32 v21, 1.0, v22
	v_add_f32_e32 v0, 1.0, v0
	v_add_f32_e32 v4, 1.0, v4
	v_add_f32_e32 v5, 1.0, v5
	v_rcp_f32_e32 v18, v6
	v_add_f32_e32 v6, 1.0, v7
	v_rcp_f32_e32 v20, v20
	v_rcp_f32_e32 v21, v21
	v_rcp_f32_e32 v0, v0
	v_rcp_f32_e32 v4, v4
	v_rcp_f32_e32 v5, v5
	v_rcp_f32_e32 v19, v6
	v_cvt_pk_bf16_f32 v7, v20, v1
	v_cvt_pk_bf16_f32 v6, v21, v0
	v_cvt_pk_bf16_f32 v5, v4, v5
	v_cvt_pk_bf16_f32 v4, v18, v19
	v_add_u32_e32 v0, 0x249c0, v160
	v_add_u32_e32 v1, 0x24dc0, v160
	ds_read_b128 v[18:21], v0
	ds_read_b128 v[38:41], v1
	ds_read_b32 v0, v164
	ds_read_b32 v1, v165
	ds_read_b32 v22, v166
	ds_read_b32 v23, v167
	s_waitcnt lgkmcnt(3)
	v_fma_f32 v25, -v19, v0, v25
	v_fma_f32 v24, -v18, v0, v24
	s_waitcnt lgkmcnt(1)
	v_fma_f32 v9, -v19, v22, v9
	s_waitcnt lgkmcnt(0)
; DI unsigned pack2(float a, float b) { f32x2_t v = {a, b}; bf16x2_t r = __builtin_convertvector(v, bf16x2_t); return __builtin_bit_cast(unsigned, r); }
; DI float sigmoidf_(float x) { return __builtin_amdgcn_rcpf(1.f + __expf(-x)); }
; DI int otid() { int t = threadIdx.x; asm volatile("" : "+v"(t)); return t; }
; template <bool NT>
; DI void stage_load_tile(bf16_t* stg, const bf16_t* tilebase) {
;   const int tid = otid();
;   const int r0 = tid >> 5, c = tid & 31;
;   const unsigned o0 = (unsigned)(r0 * 1024 + c * 8);
;   __builtin_amdgcn_sched_barrier(0);
; #pragma unroll
;   for (int hf = 0; hf < 2; ++hf) {
; #pragma unroll
;     for (int it = 8 * hf; it < 8 * hf + 8; ++it) {
;       const u32x4* gp = (const u32x4*)(tilebase + (o0 + (unsigned)(it * 16 * 1024)));
;       stage_write16(stg, r0 + 16 * it, c, NT ? __builtin_nontemporal_load(gp) : *gp);
;     }
;     __builtin_amdgcn_sched_barrier(0);
;   }
; template <bool LAST>
; DI void phase_gate(const Params& P, int layer, unsigned char* smem, int L, int G) {
;     ...
; #pragma unroll
;           for (int e = 0; e < 4; ++e) sg4[e] = sigmoidf_(rstd * (accu[i][j][4 * q4 + e] - mu * c1a[e]) + c2a[e]);
;           gq[i][j][2 * q4] = pack2(sg4[0], sg4[1]); gq[i][j][2 * q4 + 1] = pack2(sg4[2], sg4[3]);
;         }
;         __builtin_amdgcn_sched_barrier(0);
;       }
;     stage_load_tile<true>(stg, PPb + (size_t)mt * 256 * 1024 + nt * 256);
;     __syncthreads();
	v_fma_f32 v9, v23, v9, v39
	v_fma_f32 v10, -v20, v22, v10
	v_fma_f32 v25, v1, v25, v39
	v_fma_f32 v26, -v20, v0, v26
	v_fma_f32 v0, -v21, v0, v27
	v_fma_f32 v8, -v18, v22, v8
	v_mul_f32_e32 v9, 0xbfb8aa3b, v9
	v_fma_f32 v10, v23, v10, v40
	v_fma_f32 v11, -v21, v22, v11
	v_fma_f32 v24, v1, v24, v38
	v_mul_f32_e32 v25, 0xbfb8aa3b, v25
	v_fma_f32 v26, v1, v26, v40
	v_fma_f32 v0, v1, v0, v41
	v_fma_f32 v8, v23, v8, v38
	v_exp_f32_e32 v9, v9
	v_mul_f32_e32 v10, 0xbfb8aa3b, v10
	v_fmac_f32_e32 v41, v23, v11
	v_mul_f32_e32 v24, 0xbfb8aa3b, v24
	v_exp_f32_e32 v25, v25
	v_mul_f32_e32 v26, 0xbfb8aa3b, v26
	v_mul_f32_e32 v0, 0xbfb8aa3b, v0
	v_mul_f32_e32 v8, 0xbfb8aa3b, v8
	v_exp_f32_e32 v10, v10
	v_mul_f32_e32 v11, 0xbfb8aa3b, v41
	v_exp_f32_e32 v24, v24
	v_exp_f32_e32 v26, v26
	v_exp_f32_e32 v0, v0
	v_exp_f32_e32 v8, v8
	v_exp_f32_e32 v11, v11
	v_add_f32_e32 v9, 1.0, v9
	v_add_f32_e32 v25, 1.0, v25
	v_rcp_f32_e32 v18, v9
	v_add_f32_e32 v9, 1.0, v10
	v_add_f32_e32 v24, 1.0, v24
	v_rcp_f32_e32 v1, v25
	v_add_f32_e32 v25, 1.0, v26
	v_add_f32_e32 v0, 1.0, v0
	v_add_f32_e32 v8, 1.0, v8
	v_rcp_f32_e32 v10, v9
	v_add_f32_e32 v9, 1.0, v11
	v_rcp_f32_e32 v24, v24
	v_rcp_f32_e32 v25, v25
	v_rcp_f32_e32 v0, v0
	v_rcp_f32_e32 v8, v8
	v_rcp_f32_e32 v11, v9
	v_cvt_pk_bf16_f32 v27, v24, v1
	v_cvt_pk_bf16_f32 v9, v25, v0
	v_cvt_pk_bf16_f32 v19, v8, v18
	v_cvt_pk_bf16_f32 v8, v10, v11
	v_add_u32_e32 v0, 0x24de0, v160
	ds_read_b128 v[20:23], v163 offset:480
	ds_read_b32 v1, v164
	ds_read_b128 v[38:41], v0
	ds_read_b32 v0, v165
	ds_read_b32 v10, v166
	ds_read_b32 v18, v167
	s_waitcnt lgkmcnt(4)
	v_fma_f32 v24, -v21, v1, v29
	v_fma_f32 v11, -v20, v1, v28
	s_waitcnt lgkmcnt(2)
	v_fma_f32 v24, v0, v24, v39
	v_fma_f32 v25, -v22, v1, v30
	v_fma_f32 v1, -v23, v1, v31
	s_waitcnt lgkmcnt(1)
	v_fma_f32 v12, -v20, v10, v12
	v_fma_f32 v13, -v21, v10, v13
	v_fma_f32 v14, -v22, v10, v14
	v_fma_f32 v10, -v23, v10, v15
	v_fma_f32 v11, v0, v11, v38
	v_mul_f32_e32 v24, 0xbfb8aa3b, v24
	v_fma_f32 v25, v0, v25, v40
	v_fma_f32 v0, v0, v1, v41
	s_waitcnt lgkmcnt(0)
	v_fma_f32 v12, v18, v12, v38
	v_fma_f32 v13, v18, v13, v39
	v_fma_f32 v14, v18, v14, v40
	v_fmac_f32_e32 v41, v18, v10
	v_mul_f32_e32 v11, 0xbfb8aa3b, v11
	v_exp_f32_e32 v24, v24
	v_mul_f32_e32 v25, 0xbfb8aa3b, v25
	v_mul_f32_e32 v0, 0xbfb8aa3b, v0
	v_mul_f32_e32 v12, 0xbfb8aa3b, v12
	v_mul_f32_e32 v13, 0xbfb8aa3b, v13
	v_mul_f32_e32 v14, 0xbfb8aa3b, v14
	v_mul_f32_e32 v10, 0xbfb8aa3b, v41
	v_exp_f32_e32 v11, v11
	v_exp_f32_e32 v25, v25
	v_exp_f32_e32 v0, v0
	v_exp_f32_e32 v12, v12
	v_exp_f32_e32 v13, v13
	v_exp_f32_e32 v14, v14
	v_exp_f32_e32 v10, v10
	v_add_f32_e32 v24, 1.0, v24
	v_add_f32_e32 v11, 1.0, v11
	v_rcp_f32_e32 v1, v24
	v_add_f32_e32 v24, 1.0, v25
	v_add_f32_e32 v0, 1.0, v0
	v_add_f32_e32 v12, 1.0, v12
	v_add_f32_e32 v13, 1.0, v13
	v_add_f32_e32 v14, 1.0, v14
	v_add_f32_e32 v10, 1.0, v10
	v_rcp_f32_e32 v11, v11
	v_rcp_f32_e32 v24, v24
	v_rcp_f32_e32 v0, v0
	v_rcp_f32_e32 v12, v12
	v_rcp_f32_e32 v13, v13
	v_rcp_f32_e32 v14, v14
	v_rcp_f32_e32 v10, v10
	v_cvt_pk_bf16_f32 v112, v11, v1
	v_cvt_pk_bf16_f32 v30, v24, v0
	v_cvt_pk_bf16_f32 v29, v12, v13
	v_cvt_pk_bf16_f32 v28, v14, v10
	v_mov_b32_e32 v163, v161
	v_lshlrev_b64 v[0:1], 1, v[162:163]
	v_and_b32_e32 v26, 31, v192
	v_ashrrev_i32_e32 v18, 5, v192
	v_mul_lo_u32 v18, v18, s44
	v_lshl_add_u32 v18, v26, 4, v18
	v_add_u32_e32 v24, 0x2080, v18
	v_add_u32_e32 v25, 0x4100, v18
	v_add_u32_e32 v26, 0x6180, v18
	v_add_u32_e32 v31, 0x8200, v18
	v_add_u32_e32 v37, 0xa280, v18
	v_add_u32_e32 v50, 0xc300, v18
	v_add_u32_e32 v51, 0xe380, v18
	s_waitcnt vmcnt(15)
	ds_write2_b64 v18, v[180:181], v[182:183] offset1:1
	s_waitcnt vmcnt(14)
	ds_write2_b64 v24, v[184:185], v[186:187] offset1:1
	s_waitcnt vmcnt(13)
	ds_write2_b64 v25, v[194:195], v[196:197] offset1:1
	s_waitcnt vmcnt(12)
	ds_write2_b64 v26, v[198:199], v[200:201] offset1:1
	s_waitcnt vmcnt(11)
	ds_write2_b64 v31, v[202:203], v[204:205] offset1:1
	s_waitcnt vmcnt(10)
	ds_write2_b64 v37, v[206:207], v[208:209] offset1:1
	s_waitcnt vmcnt(9)
	ds_write2_b64 v50, v[210:211], v[212:213] offset1:1
	s_waitcnt vmcnt(8)
	ds_write2_b64 v51, v[214:215], v[216:217] offset1:1
	v_add_u32_e32 v14, 0x10400, v18
	v_add_u32_e32 v15, 0x12480, v18
	v_add_u32_e32 v24, 0x14500, v18
	v_add_u32_e32 v25, 0x16580, v18
	v_add_u32_e32 v26, 0x18600, v18
	v_add_u32_e32 v31, 0x1a680, v18
	v_add_u32_e32 v37, 0x1c700, v18
	v_add_u32_e32 v18, 0x1e780, v18
	s_waitcnt vmcnt(7)
	ds_write2_b64 v14, v[218:219], v[220:221] offset1:1
	s_waitcnt vmcnt(6)
	ds_write2_b64 v15, v[222:223], v[224:225] offset1:1
	s_waitcnt vmcnt(5)
	ds_write2_b64 v24, v[226:227], v[228:229] offset1:1
	s_waitcnt vmcnt(4)
	ds_write2_b64 v25, v[230:231], v[232:233] offset1:1
	s_waitcnt vmcnt(3)
	ds_write2_b64 v26, v[234:235], v[236:237] offset1:1
	s_waitcnt vmcnt(2)
	ds_write2_b64 v31, v[238:239], v[240:241] offset1:1
	s_waitcnt vmcnt(1)
	ds_write2_b64 v37, v[242:243], v[244:245] offset1:1
	s_waitcnt vmcnt(0)
	ds_write2_b64 v18, v[248:249], v[250:251] offset1:1
	v_mov_b32_e32 v10, v192
	s_waitcnt lgkmcnt(0)
	s_barrier
; DI unsigned pack2(float a, float b) { f32x2_t v = {a, b}; bf16x2_t r = __builtin_convertvector(v, bf16x2_t); return __builtin_bit_cast(unsigned, r); }
; DI float bflo(unsigned u) { return __uint_as_float(u << 16); }
; DI float bfhi(unsigned u) { return __uint_as_float(u & 0xffff0000u); }
; DI int otid() { int t = threadIdx.x; asm volatile("" : "+v"(t)); return t; }
; template <bool LAST>
; DI void phase_gate(const Params& P, int layer, unsigned char* smem, int L, int G) {
;     ...
;     {
;       const int tid1 = otid();
;       const int lane1 = tid1 & 63, w1 = tid1 >> 6, r1 = lane1 & 31, h1 = lane1 >> 5, wm1 = w1 >> 2, wn1 = w1 & 3;
; #pragma unroll
;       for (int i = 0; i < 4; ++i)
; #pragma unroll
;         for (int q4 = 0; q4 < 4; ++q4) {
; #pragma unroll
;           for (int j = 0; j < 2; ++j) {
;             const uint2 pv = *(const uint2*)(stg + (wn1 * 64 + j * 32 + r1) * STG + wm1 * 128 + i * 32 + 8 * q4 + 4 * h1);
;             const unsigned g0 = gq[i][j][2 * q4], g1 = gq[i][j][2 * q4 + 1];
;             gq[i][j][2 * q4] = pack2(bflo(g0) * bflo(pv.x), bfhi(g0) * bfhi(pv.x));
;             gq[i][j][2 * q4 + 1] = pack2(bflo(g1) * bflo(pv.y), bfhi(g1) * bfhi(pv.y));
;           }
;           __builtin_amdgcn_sched_barrier(0);
;         }
;     }
	v_and_b32_e32 v13, 0xffff0000, v99
	v_lshrrev_b32_e32 v12, 2, v10
	v_and_b32_e32 v12, 8, v12
	v_and_b32_e32 v11, 0xdf, v10
	v_and_or_b32 v10, v10, s42, v12
	v_mad_u32_u24 v113, v11, s44, v10
	ds_read_b64 v[10:11], v113
	ds_read_b64 v[14:15], v113 offset:16640
	v_lshlrev_b32_e32 v12, 16, v99
	s_waitcnt lgkmcnt(1)
	v_lshlrev_b32_e32 v20, 16, v10
	v_and_b32_e32 v21, 0xffff0000, v10
	v_pk_mul_f32 v[12:13], v[12:13], v[20:21]
	v_lshlrev_b32_e32 v10, 16, v11
	v_cvt_pk_bf16_f32 v31, v12, v13
	v_lshlrev_b32_e32 v12, 16, v98
	v_and_b32_e32 v13, 0xffff0000, v98
	v_and_b32_e32 v11, 0xffff0000, v11
	v_pk_mul_f32 v[10:11], v[12:13], v[10:11]
	s_waitcnt lgkmcnt(0)
	v_lshlrev_b32_e32 v12, 16, v14
	v_cvt_pk_bf16_f32 v98, v10, v11
	v_lshlrev_b32_e32 v10, 16, v97
	v_and_b32_e32 v11, 0xffff0000, v97
	v_and_b32_e32 v13, 0xffff0000, v14
	v_pk_mul_f32 v[10:11], v[10:11], v[12:13]
	v_lshlrev_b32_e32 v12, 16, v15
	v_cvt_pk_bf16_f32 v97, v10, v11
	v_lshlrev_b32_e32 v10, 16, v96
	v_and_b32_e32 v11, 0xffff0000, v96
	v_and_b32_e32 v13, 0xffff0000, v15
	v_pk_mul_f32 v[10:11], v[10:11], v[12:13]
	s_nop 0
	v_cvt_pk_bf16_f32 v96, v10, v11
	ds_read_b64 v[10:11], v113 offset:16
	ds_read_b64 v[14:15], v113 offset:16656
	v_lshlrev_b32_e32 v12, 16, v103
	v_and_b32_e32 v13, 0xffff0000, v103
	s_waitcnt lgkmcnt(1)
	v_lshlrev_b32_e32 v20, 16, v10
	v_and_b32_e32 v21, 0xffff0000, v10
	v_pk_mul_f32 v[12:13], v[12:13], v[20:21]
	v_lshlrev_b32_e32 v10, 16, v11
	v_cvt_pk_bf16_f32 v93, v12, v13
	v_lshlrev_b32_e32 v12, 16, v102
	v_and_b32_e32 v13, 0xffff0000, v102
	v_and_b32_e32 v11, 0xffff0000, v11
	v_pk_mul_f32 v[10:11], v[12:13], v[10:11]
	s_waitcnt lgkmcnt(0)
	v_lshlrev_b32_e32 v12, 16, v14
	v_cvt_pk_bf16_f32 v95, v10, v11
	v_lshlrev_b32_e32 v10, 16, v101
	v_and_b32_e32 v11, 0xffff0000, v101
	v_and_b32_e32 v13, 0xffff0000, v14
	v_pk_mul_f32 v[10:11], v[10:11], v[12:13]
	v_lshlrev_b32_e32 v12, 16, v15
	v_cvt_pk_bf16_f32 v92, v10, v11
	v_lshlrev_b32_e32 v10, 16, v100
	v_and_b32_e32 v11, 0xffff0000, v100
	v_and_b32_e32 v13, 0xffff0000, v15
	v_pk_mul_f32 v[10:11], v[10:11], v[12:13]
	s_nop 0
	v_cvt_pk_bf16_f32 v94, v10, v11
	ds_read_b64 v[10:11], v113 offset:32
	ds_read_b64 v[14:15], v113 offset:16672
	v_lshlrev_b32_e32 v12, 16, v107
	v_and_b32_e32 v13, 0xffff0000, v107
	s_waitcnt lgkmcnt(1)
	v_lshlrev_b32_e32 v20, 16, v10
	v_and_b32_e32 v21, 0xffff0000, v10
	v_pk_mul_f32 v[12:13], v[12:13], v[20:21]
	v_lshlrev_b32_e32 v10, 16, v11
	v_cvt_pk_bf16_f32 v88, v12, v13
	v_lshlrev_b32_e32 v12, 16, v106
	v_and_b32_e32 v13, 0xffff0000, v106
	v_and_b32_e32 v11, 0xffff0000, v11
	v_pk_mul_f32 v[10:11], v[12:13], v[10:11]
	s_waitcnt lgkmcnt(0)
	v_lshlrev_b32_e32 v12, 16, v14
	v_cvt_pk_bf16_f32 v90, v10, v11
	v_lshlrev_b32_e32 v10, 16, v105
	v_and_b32_e32 v11, 0xffff0000, v105
	v_and_b32_e32 v13, 0xffff0000, v14
	v_pk_mul_f32 v[10:11], v[10:11], v[12:13]
	v_lshlrev_b32_e32 v12, 16, v15
	v_cvt_pk_bf16_f32 v87, v10, v11
	v_lshlrev_b32_e32 v10, 16, v104
	v_and_b32_e32 v11, 0xffff0000, v104
	v_and_b32_e32 v13, 0xffff0000, v15
	v_pk_mul_f32 v[10:11], v[10:11], v[12:13]
	s_nop 0
	v_cvt_pk_bf16_f32 v89, v10, v11
	ds_read_b64 v[10:11], v113 offset:48
	ds_read_b64 v[14:15], v113 offset:16688
	v_lshlrev_b32_e32 v12, 16, v111
	v_and_b32_e32 v13, 0xffff0000, v111
	s_waitcnt lgkmcnt(1)
	v_lshlrev_b32_e32 v20, 16, v10
	v_and_b32_e32 v21, 0xffff0000, v10
	v_pk_mul_f32 v[12:13], v[12:13], v[20:21]
	v_lshlrev_b32_e32 v10, 16, v11
	v_cvt_pk_bf16_f32 v61, v12, v13
	v_lshlrev_b32_e32 v12, 16, v110
	v_and_b32_e32 v13, 0xffff0000, v110
	v_and_b32_e32 v11, 0xffff0000, v11
	v_pk_mul_f32 v[10:11], v[12:13], v[10:11]
	s_waitcnt lgkmcnt(0)
	v_lshlrev_b32_e32 v12, 16, v14
	v_cvt_pk_bf16_f32 v63, v10, v11
	v_lshlrev_b32_e32 v10, 16, v109
	v_and_b32_e32 v11, 0xffff0000, v109
	v_and_b32_e32 v13, 0xffff0000, v14
	v_pk_mul_f32 v[10:11], v[10:11], v[12:13]
	v_lshlrev_b32_e32 v12, 16, v15
	v_cvt_pk_bf16_f32 v60, v10, v11
	v_lshlrev_b32_e32 v10, 16, v108
	v_and_b32_e32 v11, 0xffff0000, v108
	v_and_b32_e32 v13, 0xffff0000, v15
	v_pk_mul_f32 v[10:11], v[10:11], v[12:13]
	s_nop 0
	v_cvt_pk_bf16_f32 v62, v10, v11
	ds_read_b64 v[10:11], v113 offset:64
	ds_read_b64 v[14:15], v113 offset:16704
	v_lshlrev_b32_e32 v12, 16, v67
	v_and_b32_e32 v13, 0xffff0000, v67
	s_waitcnt lgkmcnt(1)
	v_lshlrev_b32_e32 v20, 16, v10
	v_and_b32_e32 v21, 0xffff0000, v10
	v_pk_mul_f32 v[12:13], v[12:13], v[20:21]
	v_lshlrev_b32_e32 v10, 16, v11
	v_cvt_pk_bf16_f32 v56, v12, v13
	v_lshlrev_b32_e32 v12, 16, v66
	v_and_b32_e32 v13, 0xffff0000, v66
	v_and_b32_e32 v11, 0xffff0000, v11
	v_pk_mul_f32 v[10:11], v[12:13], v[10:11]
	s_waitcnt lgkmcnt(0)
	v_lshlrev_b32_e32 v12, 16, v14
	v_cvt_pk_bf16_f32 v58, v10, v11
	v_lshlrev_b32_e32 v10, 16, v65
	v_and_b32_e32 v11, 0xffff0000, v65
	v_and_b32_e32 v13, 0xffff0000, v14
	v_pk_mul_f32 v[10:11], v[10:11], v[12:13]
	v_lshlrev_b32_e32 v12, 16, v15
	v_cvt_pk_bf16_f32 v54, v10, v11
	v_lshlrev_b32_e32 v10, 16, v64
	v_and_b32_e32 v11, 0xffff0000, v64
	v_and_b32_e32 v13, 0xffff0000, v15
	v_pk_mul_f32 v[10:11], v[10:11], v[12:13]
	s_nop 0
	v_cvt_pk_bf16_f32 v57, v10, v11
	ds_read_b64 v[10:11], v113 offset:80
	ds_read_b64 v[14:15], v113 offset:16720
	v_lshlrev_b32_e32 v12, 16, v71
	v_and_b32_e32 v13, 0xffff0000, v71
	s_waitcnt lgkmcnt(1)
	v_lshlrev_b32_e32 v20, 16, v10
	v_and_b32_e32 v21, 0xffff0000, v10
	v_pk_mul_f32 v[12:13], v[12:13], v[20:21]
	v_lshlrev_b32_e32 v10, 16, v11
	v_cvt_pk_bf16_f32 v50, v12, v13
	v_lshlrev_b32_e32 v12, 16, v70
	v_and_b32_e32 v13, 0xffff0000, v70
	v_and_b32_e32 v11, 0xffff0000, v11
	v_pk_mul_f32 v[10:11], v[12:13], v[10:11]
	s_waitcnt lgkmcnt(0)
; DI unsigned pack2(float a, float b) { f32x2_t v = {a, b}; bf16x2_t r = __builtin_convertvector(v, bf16x2_t); return __builtin_bit_cast(unsigned, r); }
; DI float bflo(unsigned u) { return __uint_as_float(u << 16); }
; DI float bfhi(unsigned u) { return __uint_as_float(u & 0xffff0000u); }
; DI int otid() { int t = threadIdx.x; asm volatile("" : "+v"(t)); return t; }
; template <bool LAST>
; DI void phase_gate(const Params& P, int layer, unsigned char* smem, int L, int G) {
;     ...
;     {
;       const int tid1 = otid();
;       const int lane1 = tid1 & 63, w1 = tid1 >> 6, r1 = lane1 & 31, h1 = lane1 >> 5, wm1 = w1 >> 2, wn1 = w1 & 3;
; #pragma unroll
;       for (int i = 0; i < 4; ++i)
; #pragma unroll
;         for (int q4 = 0; q4 < 4; ++q4) {
; #pragma unroll
;           for (int j = 0; j < 2; ++j) {
;             const uint2 pv = *(const uint2*)(stg + (wn1 * 64 + j * 32 + r1) * STG + wm1 * 128 + i * 32 + 8 * q4 + 4 * h1);
;             const unsigned g0 = gq[i][j][2 * q4], g1 = gq[i][j][2 * q4 + 1];
;             gq[i][j][2 * q4] = pack2(bflo(g0) * bflo(pv.x), bfhi(g0) * bfhi(pv.x));
;             gq[i][j][2 * q4 + 1] = pack2(bflo(g1) * bflo(pv.y), bfhi(g1) * bfhi(pv.y));
;           }
;           __builtin_amdgcn_sched_barrier(0);
;         }
;     }
	v_lshlrev_b32_e32 v12, 16, v14
	v_cvt_pk_bf16_f32 v52, v10, v11
	v_lshlrev_b32_e32 v10, 16, v69
	v_and_b32_e32 v11, 0xffff0000, v69
	v_and_b32_e32 v13, 0xffff0000, v14
	v_pk_mul_f32 v[10:11], v[10:11], v[12:13]
	v_lshlrev_b32_e32 v12, 16, v15
	v_cvt_pk_bf16_f32 v49, v10, v11
	v_lshlrev_b32_e32 v10, 16, v68
	v_and_b32_e32 v11, 0xffff0000, v68
	v_and_b32_e32 v13, 0xffff0000, v15
	v_pk_mul_f32 v[10:11], v[10:11], v[12:13]
	s_nop 0
	v_cvt_pk_bf16_f32 v51, v10, v11
	ds_read_b64 v[10:11], v113 offset:96
	ds_read_b64 v[14:15], v113 offset:16736
	v_lshlrev_b32_e32 v12, 16, v75
	v_and_b32_e32 v13, 0xffff0000, v75
	s_waitcnt lgkmcnt(1)
	v_lshlrev_b32_e32 v20, 16, v10
	v_and_b32_e32 v21, 0xffff0000, v10
	v_pk_mul_f32 v[12:13], v[12:13], v[20:21]
	v_lshlrev_b32_e32 v10, 16, v11
	v_cvt_pk_bf16_f32 v46, v12, v13
	v_lshlrev_b32_e32 v12, 16, v74
	v_and_b32_e32 v13, 0xffff0000, v74
	v_and_b32_e32 v11, 0xffff0000, v11
	v_pk_mul_f32 v[10:11], v[12:13], v[10:11]
	s_waitcnt lgkmcnt(0)
	v_lshlrev_b32_e32 v12, 16, v14
	v_cvt_pk_bf16_f32 v48, v10, v11
	v_lshlrev_b32_e32 v10, 16, v73
	v_and_b32_e32 v11, 0xffff0000, v73
	v_and_b32_e32 v13, 0xffff0000, v14
	v_pk_mul_f32 v[10:11], v[10:11], v[12:13]
	v_lshlrev_b32_e32 v12, 16, v15
	v_cvt_pk_bf16_f32 v45, v10, v11
	v_lshlrev_b32_e32 v10, 16, v72
	v_and_b32_e32 v11, 0xffff0000, v72
	v_and_b32_e32 v13, 0xffff0000, v15
	v_pk_mul_f32 v[10:11], v[10:11], v[12:13]
	s_nop 0
	v_cvt_pk_bf16_f32 v47, v10, v11
	ds_read_b64 v[10:11], v113 offset:112
	ds_read_b64 v[14:15], v113 offset:16752
	v_lshlrev_b32_e32 v12, 16, v79
	v_and_b32_e32 v13, 0xffff0000, v79
	s_waitcnt lgkmcnt(1)
	v_lshlrev_b32_e32 v20, 16, v10
	v_and_b32_e32 v21, 0xffff0000, v10
	v_pk_mul_f32 v[12:13], v[12:13], v[20:21]
	v_lshlrev_b32_e32 v10, 16, v11
	v_cvt_pk_bf16_f32 v42, v12, v13
	v_lshlrev_b32_e32 v12, 16, v78
	v_and_b32_e32 v13, 0xffff0000, v78
	v_and_b32_e32 v11, 0xffff0000, v11
	v_pk_mul_f32 v[10:11], v[12:13], v[10:11]
	s_waitcnt lgkmcnt(0)
	v_lshlrev_b32_e32 v12, 16, v14
	v_cvt_pk_bf16_f32 v44, v10, v11
	v_lshlrev_b32_e32 v10, 16, v77
	v_and_b32_e32 v11, 0xffff0000, v77
	v_and_b32_e32 v13, 0xffff0000, v14
	v_pk_mul_f32 v[10:11], v[10:11], v[12:13]
	v_lshlrev_b32_e32 v12, 16, v15
	v_cvt_pk_bf16_f32 v41, v10, v11
	v_lshlrev_b32_e32 v10, 16, v76
	v_and_b32_e32 v11, 0xffff0000, v76
	v_and_b32_e32 v13, 0xffff0000, v15
	v_pk_mul_f32 v[10:11], v[10:11], v[12:13]
	s_nop 0
	v_cvt_pk_bf16_f32 v43, v10, v11
	ds_read_b64 v[10:11], v113 offset:128
	ds_read_b64 v[14:15], v113 offset:16768
	v_lshlrev_b32_e32 v12, 16, v35
	v_and_b32_e32 v13, 0xffff0000, v35
	s_waitcnt lgkmcnt(1)
	v_lshlrev_b32_e32 v20, 16, v10
	v_and_b32_e32 v21, 0xffff0000, v10
	v_pk_mul_f32 v[12:13], v[12:13], v[20:21]
	v_lshlrev_b32_e32 v10, 16, v11
	v_cvt_pk_bf16_f32 v38, v12, v13
	v_lshlrev_b32_e32 v12, 16, v34
	v_and_b32_e32 v13, 0xffff0000, v34
	v_and_b32_e32 v11, 0xffff0000, v11
	v_pk_mul_f32 v[10:11], v[12:13], v[10:11]
	s_waitcnt lgkmcnt(0)
	v_lshlrev_b32_e32 v12, 16, v14
	v_cvt_pk_bf16_f32 v40, v10, v11
	v_lshlrev_b32_e32 v10, 16, v33
	v_and_b32_e32 v11, 0xffff0000, v33
	v_and_b32_e32 v13, 0xffff0000, v14
	v_pk_mul_f32 v[10:11], v[10:11], v[12:13]
	v_lshlrev_b32_e32 v12, 16, v15
	v_cvt_pk_bf16_f32 v37, v10, v11
	v_lshlrev_b32_e32 v10, 16, v32
	v_and_b32_e32 v11, 0xffff0000, v32
	v_and_b32_e32 v13, 0xffff0000, v15
	v_pk_mul_f32 v[10:11], v[10:11], v[12:13]
	s_nop 0
	v_cvt_pk_bf16_f32 v39, v10, v11
	ds_read_b64 v[10:11], v113 offset:144
	ds_read_b64 v[14:15], v113 offset:16784
	v_lshlrev_b32_e32 v12, 16, v80
	v_and_b32_e32 v13, 0xffff0000, v80
	s_waitcnt lgkmcnt(1)
	v_lshlrev_b32_e32 v20, 16, v10
	v_and_b32_e32 v21, 0xffff0000, v10
	v_pk_mul_f32 v[12:13], v[12:13], v[20:21]
	v_lshlrev_b32_e32 v10, 16, v11
	v_cvt_pk_bf16_f32 v34, v12, v13
	v_lshlrev_b32_e32 v12, 16, v36
	v_and_b32_e32 v13, 0xffff0000, v36
	v_and_b32_e32 v11, 0xffff0000, v11
	v_pk_mul_f32 v[10:11], v[12:13], v[10:11]
	s_waitcnt lgkmcnt(0)
	v_lshlrev_b32_e32 v12, 16, v14
	v_cvt_pk_bf16_f32 v36, v10, v11
	v_lshlrev_b32_e32 v10, 16, v55
	v_and_b32_e32 v11, 0xffff0000, v55
	v_and_b32_e32 v13, 0xffff0000, v14
	v_pk_mul_f32 v[10:11], v[10:11], v[12:13]
	v_lshlrev_b32_e32 v12, 16, v15
	v_cvt_pk_bf16_f32 v32, v10, v11
	v_lshlrev_b32_e32 v10, 16, v53
	v_and_b32_e32 v11, 0xffff0000, v53
	v_and_b32_e32 v13, 0xffff0000, v15
	v_pk_mul_f32 v[10:11], v[10:11], v[12:13]
	s_nop 0
	v_cvt_pk_bf16_f32 v35, v10, v11
	ds_read_b64 v[10:11], v113 offset:160
	ds_read_b64 v[14:15], v113 offset:16800
	v_lshlrev_b32_e32 v12, 16, v83
	v_and_b32_e32 v13, 0xffff0000, v83
	s_waitcnt lgkmcnt(1)
	v_lshlrev_b32_e32 v20, 16, v10
	v_and_b32_e32 v21, 0xffff0000, v10
	v_pk_mul_f32 v[12:13], v[12:13], v[20:21]
	v_lshlrev_b32_e32 v10, 16, v11
	v_cvt_pk_bf16_f32 v24, v12, v13
	v_lshlrev_b32_e32 v12, 16, v82
	v_and_b32_e32 v13, 0xffff0000, v82
	v_and_b32_e32 v11, 0xffff0000, v11
	v_pk_mul_f32 v[10:11], v[12:13], v[10:11]
	s_waitcnt lgkmcnt(0)
	v_lshlrev_b32_e32 v12, 16, v14
	v_cvt_pk_bf16_f32 v26, v10, v11
	v_lshlrev_b32_e32 v10, 16, v81
	v_and_b32_e32 v11, 0xffff0000, v81
	v_and_b32_e32 v13, 0xffff0000, v14
	v_pk_mul_f32 v[10:11], v[10:11], v[12:13]
	v_lshlrev_b32_e32 v12, 16, v15
	v_cvt_pk_bf16_f32 v23, v10, v11
	v_lshlrev_b32_e32 v10, 16, v59
	v_and_b32_e32 v11, 0xffff0000, v59
	v_and_b32_e32 v13, 0xffff0000, v15
	v_pk_mul_f32 v[10:11], v[10:11], v[12:13]
	s_nop 0
	v_cvt_pk_bf16_f32 v25, v10, v11
	ds_read_b64 v[10:11], v113 offset:176
	ds_read_b64 v[14:15], v113 offset:16816
	v_lshlrev_b32_e32 v12, 16, v91
	v_and_b32_e32 v13, 0xffff0000, v91
	s_waitcnt lgkmcnt(1)
; DI unsigned pack2(float a, float b) { f32x2_t v = {a, b}; bf16x2_t r = __builtin_convertvector(v, bf16x2_t); return __builtin_bit_cast(unsigned, r); }
; DI float bflo(unsigned u) { return __uint_as_float(u << 16); }
; DI float bfhi(unsigned u) { return __uint_as_float(u & 0xffff0000u); }
; DI int otid() { int t = threadIdx.x; asm volatile("" : "+v"(t)); return t; }
; template <bool LAST>
; DI void phase_gate(const Params& P, int layer, unsigned char* smem, int L, int G) {
;     ...
;     {
;       const int tid1 = otid();
;       const int lane1 = tid1 & 63, w1 = tid1 >> 6, r1 = lane1 & 31, h1 = lane1 >> 5, wm1 = w1 >> 2, wn1 = w1 & 3;
; #pragma unroll
;       for (int i = 0; i < 4; ++i)
; #pragma unroll
;         for (int q4 = 0; q4 < 4; ++q4) {
; #pragma unroll
;           for (int j = 0; j < 2; ++j) {
;             const uint2 pv = *(const uint2*)(stg + (wn1 * 64 + j * 32 + r1) * STG + wm1 * 128 + i * 32 + 8 * q4 + 4 * h1);
;             const unsigned g0 = gq[i][j][2 * q4], g1 = gq[i][j][2 * q4 + 1];
;             gq[i][j][2 * q4] = pack2(bflo(g0) * bflo(pv.x), bfhi(g0) * bfhi(pv.x));
;             gq[i][j][2 * q4 + 1] = pack2(bflo(g1) * bflo(pv.y), bfhi(g1) * bfhi(pv.y));
;           }
;           __builtin_amdgcn_sched_barrier(0);
;         }
;     }
;     __syncthreads();
	v_lshlrev_b32_e32 v20, 16, v10
	v_and_b32_e32 v21, 0xffff0000, v10
	v_pk_mul_f32 v[12:13], v[12:13], v[20:21]
	v_lshlrev_b32_e32 v10, 16, v11
	v_cvt_pk_bf16_f32 v20, v12, v13
	v_lshlrev_b32_e32 v12, 16, v86
	v_and_b32_e32 v13, 0xffff0000, v86
	v_and_b32_e32 v11, 0xffff0000, v11
	v_pk_mul_f32 v[10:11], v[12:13], v[10:11]
	s_waitcnt lgkmcnt(0)
	v_lshlrev_b32_e32 v12, 16, v14
	v_cvt_pk_bf16_f32 v22, v10, v11
	v_lshlrev_b32_e32 v10, 16, v85
	v_and_b32_e32 v11, 0xffff0000, v85
	v_and_b32_e32 v13, 0xffff0000, v14
	v_pk_mul_f32 v[10:11], v[10:11], v[12:13]
	v_lshlrev_b32_e32 v12, 16, v15
	v_cvt_pk_bf16_f32 v18, v10, v11
	v_lshlrev_b32_e32 v10, 16, v84
	v_and_b32_e32 v11, 0xffff0000, v84
	v_and_b32_e32 v13, 0xffff0000, v15
	v_pk_mul_f32 v[10:11], v[10:11], v[12:13]
	s_nop 0
	v_cvt_pk_bf16_f32 v21, v10, v11
	ds_read_b64 v[10:11], v113 offset:192
	ds_read_b64 v[64:65], v113 offset:16832
	v_lshlrev_b32_e32 v12, 16, v17
	v_and_b32_e32 v13, 0xffff0000, v17
	s_waitcnt lgkmcnt(1)
	v_lshlrev_b32_e32 v14, 16, v10
	v_and_b32_e32 v15, 0xffff0000, v10
	v_pk_mul_f32 v[12:13], v[12:13], v[14:15]
	v_lshlrev_b32_e32 v10, 16, v11
	v_cvt_pk_bf16_f32 v15, v12, v13
	v_lshlrev_b32_e32 v12, 16, v16
	v_and_b32_e32 v13, 0xffff0000, v16
	v_and_b32_e32 v11, 0xffff0000, v11
	v_pk_mul_f32 v[10:11], v[12:13], v[10:11]
	s_waitcnt lgkmcnt(0)
	v_lshlrev_b32_e32 v12, 16, v64
	v_cvt_pk_bf16_f32 v17, v10, v11
	v_lshlrev_b32_e32 v10, 16, v3
	v_and_b32_e32 v11, 0xffff0000, v3
	v_and_b32_e32 v13, 0xffff0000, v64
	v_pk_mul_f32 v[10:11], v[10:11], v[12:13]
	v_lshlrev_b32_e32 v12, 16, v65
	v_cvt_pk_bf16_f32 v14, v10, v11
	v_lshlrev_b32_e32 v10, 16, v2
	v_and_b32_e32 v11, 0xffff0000, v2
	v_and_b32_e32 v13, 0xffff0000, v65
	v_pk_mul_f32 v[2:3], v[10:11], v[12:13]
	s_nop 0
	v_cvt_pk_bf16_f32 v16, v2, v3
	ds_read_b64 v[2:3], v113 offset:208
	ds_read_b64 v[64:65], v113 offset:16848
	v_lshlrev_b32_e32 v10, 16, v7
	v_and_b32_e32 v11, 0xffff0000, v7
	s_waitcnt lgkmcnt(1)
	v_lshlrev_b32_e32 v12, 16, v2
	v_and_b32_e32 v13, 0xffff0000, v2
	v_pk_mul_f32 v[10:11], v[10:11], v[12:13]
	v_lshlrev_b32_e32 v12, 16, v6
	v_lshlrev_b32_e32 v2, 16, v3
	v_and_b32_e32 v13, 0xffff0000, v6
	v_and_b32_e32 v3, 0xffff0000, v3
	v_pk_mul_f32 v[2:3], v[12:13], v[2:3]
	s_waitcnt lgkmcnt(0)
	v_lshlrev_b32_e32 v6, 16, v64
	v_cvt_pk_bf16_f32 v13, v2, v3
	v_lshlrev_b32_e32 v2, 16, v5
	v_and_b32_e32 v3, 0xffff0000, v5
	v_and_b32_e32 v7, 0xffff0000, v64
	v_pk_mul_f32 v[2:3], v[2:3], v[6:7]
	v_cvt_pk_bf16_f32 v11, v10, v11
	v_cvt_pk_bf16_f32 v10, v2, v3
	v_lshlrev_b32_e32 v2, 16, v4
	v_lshlrev_b32_e32 v6, 16, v65
	v_and_b32_e32 v3, 0xffff0000, v4
	v_and_b32_e32 v7, 0xffff0000, v65
	v_pk_mul_f32 v[2:3], v[2:3], v[6:7]
	s_nop 0
	v_cvt_pk_bf16_f32 v12, v2, v3
	ds_read_b64 v[2:3], v113 offset:224
	ds_read_b64 v[64:65], v113 offset:16864
	v_lshlrev_b32_e32 v4, 16, v27
	v_and_b32_e32 v5, 0xffff0000, v27
	s_waitcnt lgkmcnt(1)
	v_lshlrev_b32_e32 v6, 16, v2
	v_and_b32_e32 v7, 0xffff0000, v2
	v_pk_mul_f32 v[4:5], v[4:5], v[6:7]
	v_lshlrev_b32_e32 v2, 16, v3
	v_cvt_pk_bf16_f32 v7, v4, v5
	v_lshlrev_b32_e32 v4, 16, v9
	v_and_b32_e32 v5, 0xffff0000, v9
	v_and_b32_e32 v3, 0xffff0000, v3
	v_pk_mul_f32 v[2:3], v[4:5], v[2:3]
	s_waitcnt lgkmcnt(0)
	v_lshlrev_b32_e32 v4, 16, v64
	v_cvt_pk_bf16_f32 v9, v2, v3
	v_lshlrev_b32_e32 v2, 16, v19
	v_and_b32_e32 v3, 0xffff0000, v19
	v_and_b32_e32 v5, 0xffff0000, v64
	v_pk_mul_f32 v[2:3], v[2:3], v[4:5]
	v_lshlrev_b32_e32 v4, 16, v65
	v_cvt_pk_bf16_f32 v6, v2, v3
	v_lshlrev_b32_e32 v2, 16, v8
	v_and_b32_e32 v3, 0xffff0000, v8
	v_and_b32_e32 v5, 0xffff0000, v65
	v_pk_mul_f32 v[2:3], v[2:3], v[4:5]
	s_nop 0
	v_cvt_pk_bf16_f32 v8, v2, v3
	ds_read_b64 v[2:3], v113 offset:240
	ds_read_b64 v[64:65], v113 offset:16880
	v_lshlrev_b32_e32 v4, 16, v112
	v_and_b32_e32 v5, 0xffff0000, v112
	s_waitcnt lgkmcnt(1)
	v_lshlrev_b32_e32 v66, 16, v2
	v_and_b32_e32 v67, 0xffff0000, v2
	v_pk_mul_f32 v[4:5], v[4:5], v[66:67]
	v_lshlrev_b32_e32 v66, 16, v30
	v_lshlrev_b32_e32 v2, 16, v3
	v_and_b32_e32 v67, 0xffff0000, v30
	v_and_b32_e32 v3, 0xffff0000, v3
	v_pk_mul_f32 v[2:3], v[66:67], v[2:3]
	v_cvt_pk_bf16_f32 v4, v4, v5
	v_cvt_pk_bf16_f32 v5, v2, v3
	v_lshlrev_b32_e32 v2, 16, v29
	s_waitcnt lgkmcnt(0)
	v_lshlrev_b32_e32 v66, 16, v64
	v_and_b32_e32 v3, 0xffff0000, v29
	v_and_b32_e32 v67, 0xffff0000, v64
	v_pk_mul_f32 v[2:3], v[2:3], v[66:67]
	v_lshlrev_b32_e32 v66, 16, v28
	v_lshlrev_b32_e32 v64, 16, v65
	v_and_b32_e32 v67, 0xffff0000, v28
	v_and_b32_e32 v65, 0xffff0000, v65
	v_pk_mul_f32 v[28:29], v[66:67], v[64:65]
	v_cvt_pk_bf16_f32 v2, v2, v3
	v_cvt_pk_bf16_f32 v3, v28, v29
	v_mov_b32_e32 v19, v192
	s_barrier
; DI int otid() { int t = threadIdx.x; asm volatile("" : "+v"(t)); return t; }
; template <bool NT>
; DI void stage_load_tile(bf16_t* stg, const bf16_t* tilebase) {
;   const int tid = otid();
;   const int r0 = tid >> 5, c = tid & 31;
;   const unsigned o0 = (unsigned)(r0 * 1024 + c * 8);
;   __builtin_amdgcn_sched_barrier(0);
; #pragma unroll
;   for (int hf = 0; hf < 2; ++hf) {
; #pragma unroll
;     for (int it = 8 * hf; it < 8 * hf + 8; ++it) {
;       const u32x4* gp = (const u32x4*)(tilebase + (o0 + (unsigned)(it * 16 * 1024)));
;       stage_write16(stg, r0 + 16 * it, c, NT ? __builtin_nontemporal_load(gp) : *gp);
;     }
;     __builtin_amdgcn_sched_barrier(0);
;   }
; template <bool LAST>
; DI void phase_gate(const Params& P, int layer, unsigned char* smem, int L, int G) {
;     ...
;     stage_load_tile<false>(stg, Sb + (size_t)mt * 256 * 1024 + nt * 256);
;     __syncthreads();
	s_add_u32 s30, s76, s24
	v_ashrrev_i32_e32 v27, 5, v19
	v_and_b32_e32 v19, 31, v19
	s_addc_u32 s31, s77, s25
	v_lshlrev_b32_e32 v30, 3, v19
	v_lshl_add_u64 v[28:29], s[30:31], 0, v[0:1]
	v_lshl_or_b32 v160, v27, 10, v30
	v_add_u32_e32 v66, 0x4000, v160
	v_mov_b32_e32 v67, v161
	v_add_u32_e32 v72, 0x8000, v160
	v_mov_b32_e32 v73, v161
	v_add_u32_e32 v74, 0xc000, v160
	v_mov_b32_e32 v75, v161
	v_add_u32_e32 v80, 0x10000, v160
	v_mov_b32_e32 v81, v161
	v_add_u32_e32 v82, 0x14000, v160
	v_mov_b32_e32 v83, v161
	v_lshl_add_u64 v[64:65], v[160:161], 1, v[28:29]
	v_lshl_add_u64 v[68:69], v[66:67], 1, v[28:29]
	v_lshl_add_u64 v[72:73], v[72:73], 1, v[28:29]
	v_lshl_add_u64 v[76:77], v[74:75], 1, v[28:29]
	v_lshl_add_u64 v[80:81], v[80:81], 1, v[28:29]
	v_lshl_add_u64 v[84:85], v[82:83], 1, v[28:29]
	global_load_dwordx4 v[64:67], v[64:65], off
	s_nop 0
	global_load_dwordx4 v[68:71], v[68:69], off
	s_nop 0
	global_load_dwordx4 v[72:75], v[72:73], off
	s_nop 0
	global_load_dwordx4 v[76:79], v[76:77], off
	s_nop 0
	global_load_dwordx4 v[80:83], v[80:81], off
	s_nop 0
	global_load_dwordx4 v[100:103], v[84:85], off
	v_add_u32_e32 v84, 0x18000, v160
	v_mov_b32_e32 v85, v161
	v_add_u32_e32 v104, 0x1c000, v160
	v_mov_b32_e32 v105, v161
	v_lshl_add_u64 v[84:85], v[84:85], 1, v[28:29]
	v_lshl_add_u64 v[108:109], v[104:105], 1, v[28:29]
	global_load_dwordx4 v[104:107], v[84:85], off
	s_nop 0
	global_load_dwordx4 v[108:111], v[108:109], off
	v_add_u32_e32 v218, 0x20000, v160
	v_mov_b32_e32 v219, v161
	v_add_u32_e32 v220, 0x24000, v160
	v_mov_b32_e32 v221, v161
	v_add_u32_e32 v226, 0x28000, v160
	v_mov_b32_e32 v227, v161
	v_add_u32_e32 v228, 0x2c000, v160
	v_mov_b32_e32 v229, v161
	v_add_u32_e32 v234, 0x30000, v160
	v_mov_b32_e32 v235, v161
	v_add_u32_e32 v236, 0x34000, v160
	v_mov_b32_e32 v237, v161
	v_lshl_add_u64 v[218:219], v[218:219], 1, v[28:29]
	v_lshl_add_u64 v[222:223], v[220:221], 1, v[28:29]
	v_lshl_add_u64 v[226:227], v[226:227], 1, v[28:29]
	v_lshl_add_u64 v[230:231], v[228:229], 1, v[28:29]
	v_lshl_add_u64 v[234:235], v[234:235], 1, v[28:29]
	v_lshl_add_u64 v[252:253], v[236:237], 1, v[28:29]
	global_load_dwordx4 v[218:221], v[218:219], off
	s_nop 0
	global_load_dwordx4 v[222:225], v[222:223], off
	s_nop 0
	global_load_dwordx4 v[226:229], v[226:227], off
	s_nop 0
	global_load_dwordx4 v[230:233], v[230:231], off
	s_nop 0
	global_load_dwordx4 v[234:237], v[234:235], off
	s_nop 0
	global_load_dwordx4 v[238:241], v[252:253], off
	v_add_u32_e32 v252, 0x38000, v160
	v_mov_b32_e32 v253, v161
	v_lshl_add_u64 v[252:253], v[252:253], 1, v[28:29]
	v_add_u32_e32 v160, 0x3c000, v160
	v_lshl_add_u64 v[190:191], v[160:161], 1, v[28:29]
	global_load_dwordx4 v[242:245], v[252:253], off
	global_load_dwordx4 v[248:251], v[190:191], off
	v_mul_lo_u32 v27, v27, s44
	v_lshl_add_u32 v19, v19, 4, v27
	v_add_u32_e32 v27, 0x2080, v19
	v_add_u32_e32 v30, 0x4100, v19
	v_add_u32_e32 v33, 0x6180, v19
	v_add_u32_e32 v53, 0x8200, v19
	v_add_u32_e32 v55, 0xa280, v19
	v_add_u32_e32 v59, 0xc300, v19
	v_add_u32_e32 v84, 0xe380, v19
	s_waitcnt vmcnt(15)
	ds_write2_b64 v19, v[64:65], v[66:67] offset1:1
	s_waitcnt vmcnt(14)
	ds_write2_b64 v27, v[68:69], v[70:71] offset1:1
	s_waitcnt vmcnt(13)
	ds_write2_b64 v30, v[72:73], v[74:75] offset1:1
	s_waitcnt vmcnt(12)
	ds_write2_b64 v33, v[76:77], v[78:79] offset1:1
	s_waitcnt vmcnt(11)
	ds_write2_b64 v53, v[80:81], v[82:83] offset1:1
	s_waitcnt vmcnt(10)
	ds_write2_b64 v55, v[100:101], v[102:103] offset1:1
	s_waitcnt vmcnt(9)
	ds_write2_b64 v59, v[104:105], v[106:107] offset1:1
	s_waitcnt vmcnt(8)
	ds_write2_b64 v84, v[108:109], v[110:111] offset1:1
	v_add_u32_e32 v27, 0x10400, v19
	v_add_u32_e32 v28, 0x12480, v19
	v_add_u32_e32 v29, 0x14500, v19
	v_add_u32_e32 v30, 0x16580, v19
	v_add_u32_e32 v33, 0x18600, v19
	v_add_u32_e32 v53, 0x1a680, v19
	v_add_u32_e32 v55, 0x1c700, v19
	v_add_u32_e32 v19, 0x1e780, v19
	s_waitcnt vmcnt(7)
	ds_write2_b64 v27, v[218:219], v[220:221] offset1:1
	s_waitcnt vmcnt(6)
	ds_write2_b64 v28, v[222:223], v[224:225] offset1:1
	s_waitcnt vmcnt(5)
	ds_write2_b64 v29, v[226:227], v[228:229] offset1:1
	s_waitcnt vmcnt(4)
	ds_write2_b64 v30, v[230:231], v[232:233] offset1:1
	s_waitcnt vmcnt(3)
	ds_write2_b64 v33, v[234:235], v[236:237] offset1:1
	s_waitcnt vmcnt(2)
	ds_write2_b64 v53, v[238:239], v[240:241] offset1:1
	s_waitcnt vmcnt(1)
	ds_write2_b64 v55, v[242:243], v[244:245] offset1:1
	s_waitcnt vmcnt(0)
	ds_write2_b64 v19, v[248:249], v[250:251] offset1:1
	v_mov_b32_e32 v19, v192
	s_waitcnt lgkmcnt(0)
	s_barrier
; DI unsigned pack2(float a, float b) { f32x2_t v = {a, b}; bf16x2_t r = __builtin_convertvector(v, bf16x2_t); return __builtin_bit_cast(unsigned, r); }
; DI float bflo(unsigned u) { return __uint_as_float(u << 16); }
; DI float bfhi(unsigned u) { return __uint_as_float(u & 0xffff0000u); }
; DI int otid() { int t = threadIdx.x; asm volatile("" : "+v"(t)); return t; }
; template <bool LAST>
; DI void phase_gate(const Params& P, int layer, unsigned char* smem, int L, int G) {
;     ...
;     const int tid2 = otid();
;     const int lane2 = tid2 & 63, w2 = tid2 >> 6, r2 = lane2 & 31, h2 = lane2 >> 5, wm2 = w2 >> 2, wn2 = w2 & 3;
; #pragma unroll
;     for (int i = 0; i < 4; ++i)
; #pragma unroll
;       for (int q4 = 0; q4 < 4; ++q4) {
;         const int fl = wm2 * 128 + i * 32 + 8 * q4 + 4 * h2;
;         const int f0 = nt * 256 + fl;
;         const f32x4 gv = *(const f32x4*)(vecL + 512 + fl), bv = *(const f32x4*)(vecL + 768 + fl);
;         const float ga[4] = {gv.x, gv.y, gv.z, gv.w}, ba[4] = {bv.x, bv.y, bv.z, bv.w};
; #pragma unroll
;         for (int j = 0; j < 2; ++j) {
;           const int lrow = wn2 * 64 + j * 32 + r2;
;           const float mu = rowA[lrow], rstd = rowB[lrow];
;           uint2* sp = (uint2*)(stg + lrow * STG + fl);
;           const uint2 sv = *sp;
;           const float sa[4] = {bflo(sv.x), bfhi(sv.x), bflo(sv.y), bfhi(sv.y)};
;           float y[4];
;           const float gg[4] = {bflo(gq[i][j][2 * q4]), bfhi(gq[i][j][2 * q4]), bflo(gq[i][j][2 * q4 + 1]), bfhi(gq[i][j][2 * q4 + 1])};
; #pragma unroll
;           for (int e = 0; e < 4; ++e) y[e] = (sa[e] - mu) * rstd * ga[e] + ba[e] + gg[e];
;           if (LAST) { f32x4 o = {y[0], y[1], y[2], y[3]}; *(f32x4*)(P.out + (size_t)(mt * 256 + lrow) * 1024 + f0) = o; }
;           else { uint2 pk; pk.x = pack2(y[0], y[1]); pk.y = pack2(y[2], y[3]); *sp = pk; }
;         }
;         __builtin_amdgcn_sched_barrier(0);
;       }
	v_lshlrev_b32_e32 v82, 16, v31
	v_lshrrev_b32_e32 v28, 3, v19
	v_ashrrev_i32_e32 v27, 1, v19
	v_and_b32_e32 v28, 4, v28
	v_and_or_b32 v30, v27, s45, v28
	v_and_b32_e32 v19, 0xdf, v19
	v_lshlrev_b32_e32 v27, 2, v30
	v_lshlrev_b32_e32 v33, 2, v19
	v_mul_u32_u24_e32 v19, 0x208, v19
	v_add_u32_e32 v28, 0x25000, v27
	v_lshl_add_u32 v19, v30, 1, v19
	v_add_u32_e32 v29, 0x25400, v27
	ds_read_b128 v[64:67], v28
	ds_read_b128 v[68:71], v29
	ds_read_b64 v[72:73], v19
	v_or_b32_e32 v29, 0x24000, v33
	v_or_b32_e32 v30, 0x24400, v33
	ds_read_b32 v74, v29
	ds_read_b32 v76, v30
	ds_read_b64 v[78:79], v19 offset:16640
	v_and_b32_e32 v83, 0xffff0000, v31
	s_waitcnt lgkmcnt(3)
	v_lshlrev_b32_e32 v80, 16, v72
	v_and_b32_e32 v81, 0xffff0000, v72
	v_lshlrev_b32_e32 v72, 16, v73
	v_and_b32_e32 v73, 0xffff0000, v73
	s_waitcnt lgkmcnt(2)
	v_pk_add_f32 v[80:81], v[80:81], v[74:75] op_sel_hi:[1,0] neg_lo:[0,1] neg_hi:[0,1]
	v_pk_add_f32 v[72:73], v[72:73], v[74:75] op_sel_hi:[1,0] neg_lo:[0,1] neg_hi:[0,1]
	s_waitcnt lgkmcnt(1)
	v_pk_mul_f32 v[80:81], v[76:77], v[80:81] op_sel_hi:[0,1]
	v_pk_mul_f32 v[72:73], v[76:77], v[72:73] op_sel_hi:[0,1]
	v_lshlrev_b32_e32 v84, 16, v98
	v_and_b32_e32 v85, 0xffff0000, v98
	v_pk_fma_f32 v[80:81], v[64:65], v[80:81], v[68:69]
	v_pk_fma_f32 v[72:73], v[66:67], v[72:73], v[70:71]
	v_pk_add_f32 v[80:81], v[80:81], v[82:83]
	v_pk_add_f32 v[72:73], v[72:73], v[84:85]
	v_cvt_pk_bf16_f32 v74, v80, v81
	v_cvt_pk_bf16_f32 v75, v72, v73
	ds_write_b64 v19, v[74:75]
	v_or_b32_e32 v31, 0x24080, v33
	v_or_b32_e32 v33, 0x24480, v33
	ds_read_b32 v72, v31
	ds_read_b32 v74, v33
	s_waitcnt lgkmcnt(3)
	v_lshlrev_b32_e32 v76, 16, v78
	v_and_b32_e32 v77, 0xffff0000, v78
	v_lshlrev_b32_e32 v78, 16, v79
	s_waitcnt lgkmcnt(1)
	v_pk_add_f32 v[76:77], v[76:77], v[72:73] op_sel_hi:[1,0] neg_lo:[0,1] neg_hi:[0,1]
	v_and_b32_e32 v79, 0xffff0000, v79
	s_waitcnt lgkmcnt(0)
	v_pk_mul_f32 v[76:77], v[74:75], v[76:77] op_sel_hi:[0,1]
	v_pk_fma_f32 v[64:65], v[64:65], v[76:77], v[68:69]
	v_pk_add_f32 v[68:69], v[78:79], v[72:73] op_sel_hi:[1,0] neg_lo:[0,1] neg_hi:[0,1]
	v_lshlrev_b32_e32 v80, 16, v97
	v_pk_mul_f32 v[68:69], v[74:75], v[68:69] op_sel_hi:[0,1]
	v_and_b32_e32 v81, 0xffff0000, v97
	v_lshlrev_b32_e32 v82, 16, v96
	v_and_b32_e32 v83, 0xffff0000, v96
	v_pk_fma_f32 v[66:67], v[66:67], v[68:69], v[70:71]
	v_pk_add_f32 v[64:65], v[64:65], v[80:81]
	v_pk_add_f32 v[66:67], v[66:67], v[82:83]
	v_cvt_pk_bf16_f32 v64, v64, v65
	v_cvt_pk_bf16_f32 v65, v66, v67
	ds_write_b64 v19, v[64:65] offset:16640
	v_add_u32_e32 v53, 0x25020, v27
	v_add_u32_e32 v55, 0x25420, v27
	ds_read_b64 v[72:73], v19 offset:16
	ds_read_b128 v[64:67], v53
	ds_read_b128 v[68:71], v55
	ds_read_b32 v74, v29
	ds_read_b32 v76, v30
	ds_read_b64 v[78:79], v19 offset:16656
	s_waitcnt lgkmcnt(5)
	v_lshlrev_b32_e32 v80, 16, v72
	v_and_b32_e32 v81, 0xffff0000, v72
	v_lshlrev_b32_e32 v72, 16, v73
	v_and_b32_e32 v73, 0xffff0000, v73
	s_waitcnt lgkmcnt(2)
	v_pk_add_f32 v[80:81], v[80:81], v[74:75] op_sel_hi:[1,0] neg_lo:[0,1] neg_hi:[0,1]
	v_pk_add_f32 v[72:73], v[72:73], v[74:75] op_sel_hi:[1,0] neg_lo:[0,1] neg_hi:[0,1]
	s_waitcnt lgkmcnt(1)
	v_pk_mul_f32 v[80:81], v[76:77], v[80:81] op_sel_hi:[0,1]
	v_pk_mul_f32 v[72:73], v[76:77], v[72:73] op_sel_hi:[0,1]
	v_lshlrev_b32_e32 v82, 16, v93
	v_and_b32_e32 v83, 0xffff0000, v93
	v_lshlrev_b32_e32 v84, 16, v95
	v_and_b32_e32 v85, 0xffff0000, v95
	v_pk_fma_f32 v[80:81], v[64:65], v[80:81], v[68:69]
	v_pk_fma_f32 v[72:73], v[66:67], v[72:73], v[70:71]
	v_pk_add_f32 v[80:81], v[80:81], v[82:83]
	v_pk_add_f32 v[72:73], v[72:73], v[84:85]
	v_cvt_pk_bf16_f32 v74, v80, v81
	v_cvt_pk_bf16_f32 v75, v72, v73
	ds_write_b64 v19, v[74:75] offset:16
	ds_read_b32 v72, v31
	ds_read_b32 v74, v33
	s_waitcnt lgkmcnt(3)
	v_lshlrev_b32_e32 v76, 16, v78
	v_and_b32_e32 v77, 0xffff0000, v78
	v_lshlrev_b32_e32 v78, 16, v79
	s_waitcnt lgkmcnt(1)
	v_pk_add_f32 v[76:77], v[76:77], v[72:73] op_sel_hi:[1,0] neg_lo:[0,1] neg_hi:[0,1]
	v_and_b32_e32 v79, 0xffff0000, v79
	s_waitcnt lgkmcnt(0)
	v_pk_mul_f32 v[76:77], v[74:75], v[76:77] op_sel_hi:[0,1]
	v_pk_fma_f32 v[64:65], v[64:65], v[76:77], v[68:69]
	v_pk_add_f32 v[68:69], v[78:79], v[72:73] op_sel_hi:[1,0] neg_lo:[0,1] neg_hi:[0,1]
	v_lshlrev_b32_e32 v80, 16, v92
	v_pk_mul_f32 v[68:69], v[74:75], v[68:69] op_sel_hi:[0,1]
	v_and_b32_e32 v81, 0xffff0000, v92
	v_lshlrev_b32_e32 v82, 16, v94
	v_and_b32_e32 v83, 0xffff0000, v94
	v_pk_fma_f32 v[66:67], v[66:67], v[68:69], v[70:71]
	v_pk_add_f32 v[64:65], v[64:65], v[80:81]
	v_pk_add_f32 v[66:67], v[66:67], v[82:83]
	v_cvt_pk_bf16_f32 v64, v64, v65
	v_cvt_pk_bf16_f32 v65, v66, v67
	ds_write_b64 v19, v[64:65] offset:16656
	v_add_u32_e32 v53, 0x25040, v27
	v_add_u32_e32 v55, 0x25440, v27
	ds_read_b64 v[72:73], v19 offset:32
	ds_read_b128 v[64:67], v53
	ds_read_b128 v[68:71], v55
	ds_read_b32 v74, v29
	ds_read_b32 v76, v30
	ds_read_b64 v[78:79], v19 offset:16672
	s_waitcnt lgkmcnt(5)
	v_lshlrev_b32_e32 v80, 16, v72
	v_and_b32_e32 v81, 0xffff0000, v72
	v_lshlrev_b32_e32 v72, 16, v73
	v_and_b32_e32 v73, 0xffff0000, v73
	s_waitcnt lgkmcnt(2)
	v_pk_add_f32 v[80:81], v[80:81], v[74:75] op_sel_hi:[1,0] neg_lo:[0,1] neg_hi:[0,1]
	v_pk_add_f32 v[72:73], v[72:73], v[74:75] op_sel_hi:[1,0] neg_lo:[0,1] neg_hi:[0,1]
	s_waitcnt lgkmcnt(1)
	v_pk_mul_f32 v[80:81], v[76:77], v[80:81] op_sel_hi:[0,1]
	v_pk_mul_f32 v[72:73], v[76:77], v[72:73] op_sel_hi:[0,1]
	v_lshlrev_b32_e32 v82, 16, v88
	v_and_b32_e32 v83, 0xffff0000, v88
	v_lshlrev_b32_e32 v84, 16, v90
	v_and_b32_e32 v85, 0xffff0000, v90
	v_pk_fma_f32 v[80:81], v[64:65], v[80:81], v[68:69]
	v_pk_fma_f32 v[72:73], v[66:67], v[72:73], v[70:71]
	v_pk_add_f32 v[80:81], v[80:81], v[82:83]
	v_pk_add_f32 v[72:73], v[72:73], v[84:85]
	v_cvt_pk_bf16_f32 v74, v80, v81
	v_cvt_pk_bf16_f32 v75, v72, v73
	ds_write_b64 v19, v[74:75] offset:32
	ds_read_b32 v72, v31
	ds_read_b32 v74, v33
	s_waitcnt lgkmcnt(3)
; DI unsigned pack2(float a, float b) { f32x2_t v = {a, b}; bf16x2_t r = __builtin_convertvector(v, bf16x2_t); return __builtin_bit_cast(unsigned, r); }
; DI float bflo(unsigned u) { return __uint_as_float(u << 16); }
; DI float bfhi(unsigned u) { return __uint_as_float(u & 0xffff0000u); }
; DI int otid() { int t = threadIdx.x; asm volatile("" : "+v"(t)); return t; }
; template <bool LAST>
; DI void phase_gate(const Params& P, int layer, unsigned char* smem, int L, int G) {
;     ...
;     const int tid2 = otid();
;     const int lane2 = tid2 & 63, w2 = tid2 >> 6, r2 = lane2 & 31, h2 = lane2 >> 5, wm2 = w2 >> 2, wn2 = w2 & 3;
; #pragma unroll
;     for (int i = 0; i < 4; ++i)
; #pragma unroll
;       for (int q4 = 0; q4 < 4; ++q4) {
;         const int fl = wm2 * 128 + i * 32 + 8 * q4 + 4 * h2;
;         const int f0 = nt * 256 + fl;
;         const f32x4 gv = *(const f32x4*)(vecL + 512 + fl), bv = *(const f32x4*)(vecL + 768 + fl);
;         const float ga[4] = {gv.x, gv.y, gv.z, gv.w}, ba[4] = {bv.x, bv.y, bv.z, bv.w};
; #pragma unroll
;         for (int j = 0; j < 2; ++j) {
;           const int lrow = wn2 * 64 + j * 32 + r2;
;           const float mu = rowA[lrow], rstd = rowB[lrow];
;           uint2* sp = (uint2*)(stg + lrow * STG + fl);
;           const uint2 sv = *sp;
;           const float sa[4] = {bflo(sv.x), bfhi(sv.x), bflo(sv.y), bfhi(sv.y)};
;           float y[4];
;           const float gg[4] = {bflo(gq[i][j][2 * q4]), bfhi(gq[i][j][2 * q4]), bflo(gq[i][j][2 * q4 + 1]), bfhi(gq[i][j][2 * q4 + 1])};
; #pragma unroll
;           for (int e = 0; e < 4; ++e) y[e] = (sa[e] - mu) * rstd * ga[e] + ba[e] + gg[e];
;           if (LAST) { f32x4 o = {y[0], y[1], y[2], y[3]}; *(f32x4*)(P.out + (size_t)(mt * 256 + lrow) * 1024 + f0) = o; }
;           else { uint2 pk; pk.x = pack2(y[0], y[1]); pk.y = pack2(y[2], y[3]); *sp = pk; }
;         }
;         __builtin_amdgcn_sched_barrier(0);
;       }
	v_lshlrev_b32_e32 v76, 16, v78
	v_and_b32_e32 v77, 0xffff0000, v78
	v_lshlrev_b32_e32 v78, 16, v79
	s_waitcnt lgkmcnt(1)
	v_pk_add_f32 v[76:77], v[76:77], v[72:73] op_sel_hi:[1,0] neg_lo:[0,1] neg_hi:[0,1]
	v_and_b32_e32 v79, 0xffff0000, v79
	s_waitcnt lgkmcnt(0)
	v_pk_mul_f32 v[76:77], v[74:75], v[76:77] op_sel_hi:[0,1]
	v_pk_fma_f32 v[64:65], v[64:65], v[76:77], v[68:69]
	v_pk_add_f32 v[68:69], v[78:79], v[72:73] op_sel_hi:[1,0] neg_lo:[0,1] neg_hi:[0,1]
	v_lshlrev_b32_e32 v80, 16, v87
	v_pk_mul_f32 v[68:69], v[74:75], v[68:69] op_sel_hi:[0,1]
	v_and_b32_e32 v81, 0xffff0000, v87
	v_lshlrev_b32_e32 v82, 16, v89
	v_and_b32_e32 v83, 0xffff0000, v89
	v_pk_fma_f32 v[66:67], v[66:67], v[68:69], v[70:71]
	v_pk_add_f32 v[64:65], v[64:65], v[80:81]
	v_pk_add_f32 v[66:67], v[66:67], v[82:83]
	v_cvt_pk_bf16_f32 v64, v64, v65
	v_cvt_pk_bf16_f32 v65, v66, v67
	ds_write_b64 v19, v[64:65] offset:16672
	v_add_u32_e32 v53, 0x25060, v27
	v_add_u32_e32 v55, 0x25460, v27
	ds_read_b64 v[72:73], v19 offset:48
	ds_read_b128 v[64:67], v53
	ds_read_b128 v[68:71], v55
	ds_read_b32 v74, v29
	ds_read_b32 v76, v30
	ds_read_b64 v[78:79], v19 offset:16688
	s_waitcnt lgkmcnt(5)
	v_lshlrev_b32_e32 v80, 16, v72
	v_and_b32_e32 v81, 0xffff0000, v72
	v_lshlrev_b32_e32 v72, 16, v73
	v_and_b32_e32 v73, 0xffff0000, v73
	s_waitcnt lgkmcnt(2)
	v_pk_add_f32 v[80:81], v[80:81], v[74:75] op_sel_hi:[1,0] neg_lo:[0,1] neg_hi:[0,1]
	v_pk_add_f32 v[72:73], v[72:73], v[74:75] op_sel_hi:[1,0] neg_lo:[0,1] neg_hi:[0,1]
	s_waitcnt lgkmcnt(1)
	v_pk_mul_f32 v[80:81], v[76:77], v[80:81] op_sel_hi:[0,1]
	v_pk_mul_f32 v[72:73], v[76:77], v[72:73] op_sel_hi:[0,1]
	v_lshlrev_b32_e32 v82, 16, v61
	v_and_b32_e32 v83, 0xffff0000, v61
	v_lshlrev_b32_e32 v84, 16, v63
	v_and_b32_e32 v85, 0xffff0000, v63
	v_pk_fma_f32 v[80:81], v[64:65], v[80:81], v[68:69]
	v_pk_fma_f32 v[72:73], v[66:67], v[72:73], v[70:71]
	v_pk_add_f32 v[80:81], v[80:81], v[82:83]
	v_pk_add_f32 v[72:73], v[72:73], v[84:85]
	v_cvt_pk_bf16_f32 v74, v80, v81
	v_cvt_pk_bf16_f32 v75, v72, v73
	ds_write_b64 v19, v[74:75] offset:48
	ds_read_b32 v72, v31
	ds_read_b32 v74, v33
	s_waitcnt lgkmcnt(3)
	v_lshlrev_b32_e32 v76, 16, v78
	v_and_b32_e32 v77, 0xffff0000, v78
	v_lshlrev_b32_e32 v80, 16, v60
	v_and_b32_e32 v81, 0xffff0000, v60
	v_lshlrev_b32_e32 v60, 16, v62
	v_and_b32_e32 v61, 0xffff0000, v62
	s_waitcnt lgkmcnt(1)
	v_pk_add_f32 v[62:63], v[76:77], v[72:73] op_sel_hi:[1,0] neg_lo:[0,1] neg_hi:[0,1]
	v_lshlrev_b32_e32 v78, 16, v79
	v_and_b32_e32 v79, 0xffff0000, v79
	s_waitcnt lgkmcnt(0)
	v_pk_mul_f32 v[62:63], v[74:75], v[62:63] op_sel_hi:[0,1]
	v_pk_fma_f32 v[62:63], v[64:65], v[62:63], v[68:69]
	v_pk_add_f32 v[64:65], v[78:79], v[72:73] op_sel_hi:[1,0] neg_lo:[0,1] neg_hi:[0,1]
	v_pk_add_f32 v[62:63], v[62:63], v[80:81]
	v_pk_mul_f32 v[64:65], v[74:75], v[64:65] op_sel_hi:[0,1]
	v_pk_fma_f32 v[64:65], v[66:67], v[64:65], v[70:71]
	v_cvt_pk_bf16_f32 v62, v62, v63
	v_pk_add_f32 v[60:61], v[64:65], v[60:61]
	s_nop 0
	v_cvt_pk_bf16_f32 v63, v60, v61
	ds_write_b64 v19, v[62:63] offset:16688
	v_add_u32_e32 v53, 0x25080, v27
	v_add_u32_e32 v55, 0x25480, v27
	ds_read_b64 v[68:69], v19 offset:64
	ds_read_b128 v[60:63], v53
	ds_read_b128 v[64:67], v55
	ds_read_b32 v70, v29
	ds_read_b32 v72, v30
	ds_read_b64 v[74:75], v19 offset:16704
	s_waitcnt lgkmcnt(5)
	v_lshlrev_b32_e32 v76, 16, v68
	v_and_b32_e32 v77, 0xffff0000, v68
	v_lshlrev_b32_e32 v68, 16, v69
	v_and_b32_e32 v69, 0xffff0000, v69
	v_lshlrev_b32_e32 v80, 16, v58
	v_and_b32_e32 v81, 0xffff0000, v58
	s_waitcnt lgkmcnt(2)
	v_pk_add_f32 v[58:59], v[76:77], v[70:71] op_sel_hi:[1,0] neg_lo:[0,1] neg_hi:[0,1]
	v_pk_add_f32 v[68:69], v[68:69], v[70:71] op_sel_hi:[1,0] neg_lo:[0,1] neg_hi:[0,1]
	s_waitcnt lgkmcnt(1)
	v_pk_mul_f32 v[58:59], v[72:73], v[58:59] op_sel_hi:[0,1]
	v_pk_mul_f32 v[68:69], v[72:73], v[68:69] op_sel_hi:[0,1]
	v_lshlrev_b32_e32 v78, 16, v56
	v_and_b32_e32 v79, 0xffff0000, v56
	v_pk_fma_f32 v[58:59], v[60:61], v[58:59], v[64:65]
	v_pk_fma_f32 v[68:69], v[62:63], v[68:69], v[66:67]
	v_pk_add_f32 v[58:59], v[58:59], v[78:79]
	v_pk_add_f32 v[68:69], v[68:69], v[80:81]
	v_cvt_pk_bf16_f32 v58, v58, v59
	v_cvt_pk_bf16_f32 v59, v68, v69
	ds_write_b64 v19, v[58:59] offset:64
	ds_read_b32 v56, v31
	ds_read_b32 v58, v33
	s_waitcnt lgkmcnt(3)
	v_lshlrev_b32_e32 v68, 16, v74
	v_and_b32_e32 v69, 0xffff0000, v74
	v_lshlrev_b32_e32 v70, 16, v75
	v_and_b32_e32 v71, 0xffff0000, v75
	v_lshlrev_b32_e32 v72, 16, v54
	v_and_b32_e32 v73, 0xffff0000, v54
	v_lshlrev_b32_e32 v54, 16, v57
	v_and_b32_e32 v55, 0xffff0000, v57
	s_waitcnt lgkmcnt(1)
	v_pk_add_f32 v[68:69], v[68:69], v[56:57] op_sel_hi:[1,0] neg_lo:[0,1] neg_hi:[0,1]
	v_pk_add_f32 v[56:57], v[70:71], v[56:57] op_sel_hi:[1,0] neg_lo:[0,1] neg_hi:[0,1]
	s_waitcnt lgkmcnt(0)
	v_pk_mul_f32 v[68:69], v[58:59], v[68:69] op_sel_hi:[0,1]
	v_pk_mul_f32 v[56:57], v[58:59], v[56:57] op_sel_hi:[0,1]
	v_pk_fma_f32 v[60:61], v[60:61], v[68:69], v[64:65]
	v_pk_fma_f32 v[56:57], v[62:63], v[56:57], v[66:67]
	v_pk_add_f32 v[60:61], v[60:61], v[72:73]
	v_pk_add_f32 v[54:55], v[56:57], v[54:55]
	v_cvt_pk_bf16_f32 v56, v60, v61
	v_cvt_pk_bf16_f32 v57, v54, v55
	ds_write_b64 v19, v[56:57] offset:16704
	v_add_u32_e32 v58, 0x254a0, v27
	v_add_u32_e32 v53, 0x250a0, v27
	ds_read_b64 v[62:63], v19 offset:80
	ds_read_b128 v[54:57], v53
	ds_read_b128 v[58:61], v58
	ds_read_b32 v64, v29
	ds_read_b32 v66, v30
	ds_read_b64 v[68:69], v19 offset:16720
	s_waitcnt lgkmcnt(5)
	v_lshlrev_b32_e32 v70, 16, v62
	v_and_b32_e32 v71, 0xffff0000, v62
	v_lshlrev_b32_e32 v62, 16, v63
	v_and_b32_e32 v63, 0xffff0000, v63
	v_lshlrev_b32_e32 v74, 16, v52
	v_and_b32_e32 v75, 0xffff0000, v52
	s_waitcnt lgkmcnt(2)
; DI unsigned pack2(float a, float b) { f32x2_t v = {a, b}; bf16x2_t r = __builtin_convertvector(v, bf16x2_t); return __builtin_bit_cast(unsigned, r); }
; DI float bflo(unsigned u) { return __uint_as_float(u << 16); }
; DI float bfhi(unsigned u) { return __uint_as_float(u & 0xffff0000u); }
; DI int otid() { int t = threadIdx.x; asm volatile("" : "+v"(t)); return t; }
; template <bool LAST>
; DI void phase_gate(const Params& P, int layer, unsigned char* smem, int L, int G) {
;     ...
;     const int tid2 = otid();
;     const int lane2 = tid2 & 63, w2 = tid2 >> 6, r2 = lane2 & 31, h2 = lane2 >> 5, wm2 = w2 >> 2, wn2 = w2 & 3;
; #pragma unroll
;     for (int i = 0; i < 4; ++i)
; #pragma unroll
;       for (int q4 = 0; q4 < 4; ++q4) {
;         const int fl = wm2 * 128 + i * 32 + 8 * q4 + 4 * h2;
;         const int f0 = nt * 256 + fl;
;         const f32x4 gv = *(const f32x4*)(vecL + 512 + fl), bv = *(const f32x4*)(vecL + 768 + fl);
;         const float ga[4] = {gv.x, gv.y, gv.z, gv.w}, ba[4] = {bv.x, bv.y, bv.z, bv.w};
; #pragma unroll
;         for (int j = 0; j < 2; ++j) {
;           const int lrow = wn2 * 64 + j * 32 + r2;
;           const float mu = rowA[lrow], rstd = rowB[lrow];
;           uint2* sp = (uint2*)(stg + lrow * STG + fl);
;           const uint2 sv = *sp;
;           const float sa[4] = {bflo(sv.x), bfhi(sv.x), bflo(sv.y), bfhi(sv.y)};
;           float y[4];
;           const float gg[4] = {bflo(gq[i][j][2 * q4]), bfhi(gq[i][j][2 * q4]), bflo(gq[i][j][2 * q4 + 1]), bfhi(gq[i][j][2 * q4 + 1])};
; #pragma unroll
;           for (int e = 0; e < 4; ++e) y[e] = (sa[e] - mu) * rstd * ga[e] + ba[e] + gg[e];
;           if (LAST) { f32x4 o = {y[0], y[1], y[2], y[3]}; *(f32x4*)(P.out + (size_t)(mt * 256 + lrow) * 1024 + f0) = o; }
;           else { uint2 pk; pk.x = pack2(y[0], y[1]); pk.y = pack2(y[2], y[3]); *sp = pk; }
;         }
;         __builtin_amdgcn_sched_barrier(0);
;       }
	v_pk_add_f32 v[52:53], v[70:71], v[64:65] op_sel_hi:[1,0] neg_lo:[0,1] neg_hi:[0,1]
	v_pk_add_f32 v[62:63], v[62:63], v[64:65] op_sel_hi:[1,0] neg_lo:[0,1] neg_hi:[0,1]
	s_waitcnt lgkmcnt(1)
	v_pk_mul_f32 v[52:53], v[66:67], v[52:53] op_sel_hi:[0,1]
	v_pk_mul_f32 v[62:63], v[66:67], v[62:63] op_sel_hi:[0,1]
	v_lshlrev_b32_e32 v72, 16, v50
	v_and_b32_e32 v73, 0xffff0000, v50
	v_pk_fma_f32 v[52:53], v[54:55], v[52:53], v[58:59]
	v_pk_fma_f32 v[62:63], v[56:57], v[62:63], v[60:61]
	v_pk_add_f32 v[52:53], v[52:53], v[72:73]
	v_pk_add_f32 v[62:63], v[62:63], v[74:75]
	v_cvt_pk_bf16_f32 v52, v52, v53
	v_cvt_pk_bf16_f32 v53, v62, v63
	ds_write_b64 v19, v[52:53] offset:80
	ds_read_b32 v50, v31
	ds_read_b32 v52, v33
	s_waitcnt lgkmcnt(3)
	v_lshlrev_b32_e32 v62, 16, v68
	v_and_b32_e32 v63, 0xffff0000, v68
	v_lshlrev_b32_e32 v64, 16, v69
	v_and_b32_e32 v65, 0xffff0000, v69
	v_lshlrev_b32_e32 v68, 16, v51
	v_and_b32_e32 v69, 0xffff0000, v51
	s_waitcnt lgkmcnt(1)
	v_pk_add_f32 v[62:63], v[62:63], v[50:51] op_sel_hi:[1,0] neg_lo:[0,1] neg_hi:[0,1]
	v_pk_add_f32 v[50:51], v[64:65], v[50:51] op_sel_hi:[1,0] neg_lo:[0,1] neg_hi:[0,1]
	s_waitcnt lgkmcnt(0)
	v_pk_mul_f32 v[62:63], v[52:53], v[62:63] op_sel_hi:[0,1]
	v_pk_mul_f32 v[50:51], v[52:53], v[50:51] op_sel_hi:[0,1]
	v_lshlrev_b32_e32 v66, 16, v49
	v_and_b32_e32 v67, 0xffff0000, v49
	v_pk_fma_f32 v[54:55], v[54:55], v[62:63], v[58:59]
	v_pk_fma_f32 v[50:51], v[56:57], v[50:51], v[60:61]
	v_pk_add_f32 v[54:55], v[54:55], v[66:67]
	v_pk_add_f32 v[50:51], v[50:51], v[68:69]
	v_cvt_pk_bf16_f32 v52, v54, v55
	v_cvt_pk_bf16_f32 v53, v50, v51
	ds_write_b64 v19, v[52:53] offset:16720
	v_add_u32_e32 v54, 0x254c0, v27
	v_add_u32_e32 v49, 0x250c0, v27
	ds_read_b64 v[58:59], v19 offset:96
	ds_read_b128 v[50:53], v49
	ds_read_b128 v[54:57], v54
	ds_read_b32 v60, v29
	ds_read_b32 v62, v30
	ds_read_b64 v[64:65], v19 offset:16736
	s_waitcnt lgkmcnt(5)
	v_lshlrev_b32_e32 v66, 16, v58
	v_and_b32_e32 v67, 0xffff0000, v58
	v_lshlrev_b32_e32 v58, 16, v59
	v_and_b32_e32 v59, 0xffff0000, v59
	v_lshlrev_b32_e32 v70, 16, v48
	v_and_b32_e32 v71, 0xffff0000, v48
	s_waitcnt lgkmcnt(2)
	v_pk_add_f32 v[48:49], v[66:67], v[60:61] op_sel_hi:[1,0] neg_lo:[0,1] neg_hi:[0,1]
	v_pk_add_f32 v[58:59], v[58:59], v[60:61] op_sel_hi:[1,0] neg_lo:[0,1] neg_hi:[0,1]
	s_waitcnt lgkmcnt(1)
	v_pk_mul_f32 v[48:49], v[62:63], v[48:49] op_sel_hi:[0,1]
	v_pk_mul_f32 v[58:59], v[62:63], v[58:59] op_sel_hi:[0,1]
	v_lshlrev_b32_e32 v68, 16, v46
	v_and_b32_e32 v69, 0xffff0000, v46
	v_pk_fma_f32 v[48:49], v[50:51], v[48:49], v[54:55]
	v_pk_fma_f32 v[58:59], v[52:53], v[58:59], v[56:57]
	v_pk_add_f32 v[48:49], v[48:49], v[68:69]
	v_pk_add_f32 v[58:59], v[58:59], v[70:71]
	v_cvt_pk_bf16_f32 v48, v48, v49
	v_cvt_pk_bf16_f32 v49, v58, v59
	ds_write_b64 v19, v[48:49] offset:96
	ds_read_b32 v46, v31
	ds_read_b32 v48, v33
	s_waitcnt lgkmcnt(3)
	v_lshlrev_b32_e32 v58, 16, v64
	v_and_b32_e32 v59, 0xffff0000, v64
	v_lshlrev_b32_e32 v60, 16, v65
	v_and_b32_e32 v61, 0xffff0000, v65
	v_lshlrev_b32_e32 v64, 16, v47
	v_and_b32_e32 v65, 0xffff0000, v47
	s_waitcnt lgkmcnt(1)
	v_pk_add_f32 v[58:59], v[58:59], v[46:47] op_sel_hi:[1,0] neg_lo:[0,1] neg_hi:[0,1]
	v_pk_add_f32 v[46:47], v[60:61], v[46:47] op_sel_hi:[1,0] neg_lo:[0,1] neg_hi:[0,1]
	s_waitcnt lgkmcnt(0)
	v_pk_mul_f32 v[58:59], v[48:49], v[58:59] op_sel_hi:[0,1]
	v_pk_mul_f32 v[46:47], v[48:49], v[46:47] op_sel_hi:[0,1]
	v_lshlrev_b32_e32 v62, 16, v45
	v_and_b32_e32 v63, 0xffff0000, v45
	v_pk_fma_f32 v[50:51], v[50:51], v[58:59], v[54:55]
	v_pk_fma_f32 v[46:47], v[52:53], v[46:47], v[56:57]
	v_pk_add_f32 v[50:51], v[50:51], v[62:63]
	v_pk_add_f32 v[46:47], v[46:47], v[64:65]
	v_cvt_pk_bf16_f32 v48, v50, v51
	v_cvt_pk_bf16_f32 v49, v46, v47
	ds_write_b64 v19, v[48:49] offset:16736
	v_add_u32_e32 v50, 0x254e0, v27
	v_add_u32_e32 v45, 0x250e0, v27
	ds_read_b64 v[54:55], v19 offset:112
	ds_read_b128 v[46:49], v45
	ds_read_b128 v[50:53], v50
	ds_read_b32 v56, v29
	ds_read_b32 v58, v30
	ds_read_b64 v[60:61], v19 offset:16752
	s_waitcnt lgkmcnt(5)
	v_lshlrev_b32_e32 v62, 16, v54
	v_and_b32_e32 v63, 0xffff0000, v54
	v_lshlrev_b32_e32 v54, 16, v55
	v_and_b32_e32 v55, 0xffff0000, v55
	v_lshlrev_b32_e32 v66, 16, v44
	v_and_b32_e32 v67, 0xffff0000, v44
	s_waitcnt lgkmcnt(2)
	v_pk_add_f32 v[44:45], v[62:63], v[56:57] op_sel_hi:[1,0] neg_lo:[0,1] neg_hi:[0,1]
	v_pk_add_f32 v[54:55], v[54:55], v[56:57] op_sel_hi:[1,0] neg_lo:[0,1] neg_hi:[0,1]
	s_waitcnt lgkmcnt(1)
	v_pk_mul_f32 v[44:45], v[58:59], v[44:45] op_sel_hi:[0,1]
	v_pk_mul_f32 v[54:55], v[58:59], v[54:55] op_sel_hi:[0,1]
	v_lshlrev_b32_e32 v64, 16, v42
	v_and_b32_e32 v65, 0xffff0000, v42
	v_pk_fma_f32 v[44:45], v[46:47], v[44:45], v[50:51]
	v_pk_fma_f32 v[54:55], v[48:49], v[54:55], v[52:53]
	v_pk_add_f32 v[44:45], v[44:45], v[64:65]
	v_pk_add_f32 v[54:55], v[54:55], v[66:67]
	v_cvt_pk_bf16_f32 v44, v44, v45
	v_cvt_pk_bf16_f32 v45, v54, v55
	ds_write_b64 v19, v[44:45] offset:112
	ds_read_b32 v42, v31
	ds_read_b32 v44, v33
	s_waitcnt lgkmcnt(3)
	v_lshlrev_b32_e32 v54, 16, v60
	v_and_b32_e32 v55, 0xffff0000, v60
	v_lshlrev_b32_e32 v56, 16, v61
	v_and_b32_e32 v57, 0xffff0000, v61
	v_lshlrev_b32_e32 v60, 16, v43
	v_and_b32_e32 v61, 0xffff0000, v43
	s_waitcnt lgkmcnt(1)
	v_pk_add_f32 v[54:55], v[54:55], v[42:43] op_sel_hi:[1,0] neg_lo:[0,1] neg_hi:[0,1]
	v_pk_add_f32 v[42:43], v[56:57], v[42:43] op_sel_hi:[1,0] neg_lo:[0,1] neg_hi:[0,1]
	s_waitcnt lgkmcnt(0)
; DI unsigned pack2(float a, float b) { f32x2_t v = {a, b}; bf16x2_t r = __builtin_convertvector(v, bf16x2_t); return __builtin_bit_cast(unsigned, r); }
; DI float bflo(unsigned u) { return __uint_as_float(u << 16); }
; DI float bfhi(unsigned u) { return __uint_as_float(u & 0xffff0000u); }
; DI int otid() { int t = threadIdx.x; asm volatile("" : "+v"(t)); return t; }
; template <bool LAST>
; DI void phase_gate(const Params& P, int layer, unsigned char* smem, int L, int G) {
;     ...
;     const int tid2 = otid();
;     const int lane2 = tid2 & 63, w2 = tid2 >> 6, r2 = lane2 & 31, h2 = lane2 >> 5, wm2 = w2 >> 2, wn2 = w2 & 3;
; #pragma unroll
;     for (int i = 0; i < 4; ++i)
; #pragma unroll
;       for (int q4 = 0; q4 < 4; ++q4) {
;         const int fl = wm2 * 128 + i * 32 + 8 * q4 + 4 * h2;
;         const int f0 = nt * 256 + fl;
;         const f32x4 gv = *(const f32x4*)(vecL + 512 + fl), bv = *(const f32x4*)(vecL + 768 + fl);
;         const float ga[4] = {gv.x, gv.y, gv.z, gv.w}, ba[4] = {bv.x, bv.y, bv.z, bv.w};
; #pragma unroll
;         for (int j = 0; j < 2; ++j) {
;           const int lrow = wn2 * 64 + j * 32 + r2;
;           const float mu = rowA[lrow], rstd = rowB[lrow];
;           uint2* sp = (uint2*)(stg + lrow * STG + fl);
;           const uint2 sv = *sp;
;           const float sa[4] = {bflo(sv.x), bfhi(sv.x), bflo(sv.y), bfhi(sv.y)};
;           float y[4];
;           const float gg[4] = {bflo(gq[i][j][2 * q4]), bfhi(gq[i][j][2 * q4]), bflo(gq[i][j][2 * q4 + 1]), bfhi(gq[i][j][2 * q4 + 1])};
; #pragma unroll
;           for (int e = 0; e < 4; ++e) y[e] = (sa[e] - mu) * rstd * ga[e] + ba[e] + gg[e];
;           if (LAST) { f32x4 o = {y[0], y[1], y[2], y[3]}; *(f32x4*)(P.out + (size_t)(mt * 256 + lrow) * 1024 + f0) = o; }
;           else { uint2 pk; pk.x = pack2(y[0], y[1]); pk.y = pack2(y[2], y[3]); *sp = pk; }
;         }
;         __builtin_amdgcn_sched_barrier(0);
;       }
	v_pk_mul_f32 v[54:55], v[44:45], v[54:55] op_sel_hi:[0,1]
	v_pk_mul_f32 v[42:43], v[44:45], v[42:43] op_sel_hi:[0,1]
	v_lshlrev_b32_e32 v58, 16, v41
	v_and_b32_e32 v59, 0xffff0000, v41
	v_pk_fma_f32 v[46:47], v[46:47], v[54:55], v[50:51]
	v_pk_fma_f32 v[42:43], v[48:49], v[42:43], v[52:53]
	v_pk_add_f32 v[46:47], v[46:47], v[58:59]
	v_pk_add_f32 v[42:43], v[42:43], v[60:61]
	v_cvt_pk_bf16_f32 v44, v46, v47
	v_cvt_pk_bf16_f32 v45, v42, v43
	ds_write_b64 v19, v[44:45] offset:16752
	v_add_u32_e32 v46, 0x25500, v27
	v_add_u32_e32 v41, 0x25100, v27
	ds_read_b64 v[50:51], v19 offset:128
	ds_read_b128 v[42:45], v41
	ds_read_b128 v[46:49], v46
	ds_read_b32 v52, v29
	ds_read_b32 v54, v30
	ds_read_b64 v[56:57], v19 offset:16768
	s_waitcnt lgkmcnt(5)
	v_lshlrev_b32_e32 v58, 16, v50
	v_and_b32_e32 v59, 0xffff0000, v50
	v_lshlrev_b32_e32 v50, 16, v51
	v_and_b32_e32 v51, 0xffff0000, v51
	v_lshlrev_b32_e32 v62, 16, v40
	v_and_b32_e32 v63, 0xffff0000, v40
	s_waitcnt lgkmcnt(2)
	v_pk_add_f32 v[40:41], v[58:59], v[52:53] op_sel_hi:[1,0] neg_lo:[0,1] neg_hi:[0,1]
	v_pk_add_f32 v[50:51], v[50:51], v[52:53] op_sel_hi:[1,0] neg_lo:[0,1] neg_hi:[0,1]
	s_waitcnt lgkmcnt(1)
	v_pk_mul_f32 v[40:41], v[54:55], v[40:41] op_sel_hi:[0,1]
	v_pk_mul_f32 v[50:51], v[54:55], v[50:51] op_sel_hi:[0,1]
	v_lshlrev_b32_e32 v60, 16, v38
	v_and_b32_e32 v61, 0xffff0000, v38
	v_pk_fma_f32 v[40:41], v[42:43], v[40:41], v[46:47]
	v_pk_fma_f32 v[50:51], v[44:45], v[50:51], v[48:49]
	v_pk_add_f32 v[40:41], v[40:41], v[60:61]
	v_pk_add_f32 v[50:51], v[50:51], v[62:63]
	v_cvt_pk_bf16_f32 v40, v40, v41
	v_cvt_pk_bf16_f32 v41, v50, v51
	ds_write_b64 v19, v[40:41] offset:128
	ds_read_b32 v38, v31
	ds_read_b32 v40, v33
	s_waitcnt lgkmcnt(3)
	v_lshlrev_b32_e32 v50, 16, v56
	v_and_b32_e32 v51, 0xffff0000, v56
	v_lshlrev_b32_e32 v52, 16, v57
	v_and_b32_e32 v53, 0xffff0000, v57
	v_lshlrev_b32_e32 v56, 16, v39
	v_and_b32_e32 v57, 0xffff0000, v39
	s_waitcnt lgkmcnt(1)
	v_pk_add_f32 v[50:51], v[50:51], v[38:39] op_sel_hi:[1,0] neg_lo:[0,1] neg_hi:[0,1]
	v_pk_add_f32 v[38:39], v[52:53], v[38:39] op_sel_hi:[1,0] neg_lo:[0,1] neg_hi:[0,1]
	s_waitcnt lgkmcnt(0)
	v_pk_mul_f32 v[50:51], v[40:41], v[50:51] op_sel_hi:[0,1]
	v_pk_mul_f32 v[38:39], v[40:41], v[38:39] op_sel_hi:[0,1]
	v_lshlrev_b32_e32 v54, 16, v37
	v_and_b32_e32 v55, 0xffff0000, v37
	v_pk_fma_f32 v[42:43], v[42:43], v[50:51], v[46:47]
	v_pk_fma_f32 v[38:39], v[44:45], v[38:39], v[48:49]
	v_pk_add_f32 v[42:43], v[42:43], v[54:55]
	v_pk_add_f32 v[38:39], v[38:39], v[56:57]
	v_cvt_pk_bf16_f32 v40, v42, v43
	v_cvt_pk_bf16_f32 v41, v38, v39
	ds_write_b64 v19, v[40:41] offset:16768
	v_add_u32_e32 v42, 0x25520, v27
	v_add_u32_e32 v37, 0x25120, v27
	ds_read_b64 v[46:47], v19 offset:144
	ds_read_b128 v[38:41], v37
	ds_read_b128 v[42:45], v42
	ds_read_b32 v48, v29
	ds_read_b32 v50, v30
	ds_read_b64 v[52:53], v19 offset:16784
	s_waitcnt lgkmcnt(5)
	v_lshlrev_b32_e32 v54, 16, v46
	v_and_b32_e32 v55, 0xffff0000, v46
	v_lshlrev_b32_e32 v46, 16, v47
	v_and_b32_e32 v47, 0xffff0000, v47
	v_lshlrev_b32_e32 v58, 16, v36
	v_and_b32_e32 v59, 0xffff0000, v36
	s_waitcnt lgkmcnt(2)
	v_pk_add_f32 v[36:37], v[54:55], v[48:49] op_sel_hi:[1,0] neg_lo:[0,1] neg_hi:[0,1]
	v_pk_add_f32 v[46:47], v[46:47], v[48:49] op_sel_hi:[1,0] neg_lo:[0,1] neg_hi:[0,1]
	s_waitcnt lgkmcnt(1)
	v_pk_mul_f32 v[36:37], v[50:51], v[36:37] op_sel_hi:[0,1]
	v_pk_mul_f32 v[46:47], v[50:51], v[46:47] op_sel_hi:[0,1]
	v_lshlrev_b32_e32 v56, 16, v34
	v_and_b32_e32 v57, 0xffff0000, v34
	v_pk_fma_f32 v[36:37], v[38:39], v[36:37], v[42:43]
	v_pk_fma_f32 v[46:47], v[40:41], v[46:47], v[44:45]
	v_pk_add_f32 v[36:37], v[36:37], v[56:57]
	v_pk_add_f32 v[46:47], v[46:47], v[58:59]
	v_cvt_pk_bf16_f32 v36, v36, v37
	v_cvt_pk_bf16_f32 v37, v46, v47
	ds_write_b64 v19, v[36:37] offset:144
	ds_read_b32 v34, v31
	ds_read_b32 v36, v33
	s_waitcnt lgkmcnt(3)
	v_lshlrev_b32_e32 v46, 16, v52
	v_and_b32_e32 v47, 0xffff0000, v52
	v_lshlrev_b32_e32 v48, 16, v53
	v_and_b32_e32 v49, 0xffff0000, v53
	v_lshlrev_b32_e32 v52, 16, v35
	v_and_b32_e32 v53, 0xffff0000, v35
	s_waitcnt lgkmcnt(1)
	v_pk_add_f32 v[46:47], v[46:47], v[34:35] op_sel_hi:[1,0] neg_lo:[0,1] neg_hi:[0,1]
	v_pk_add_f32 v[34:35], v[48:49], v[34:35] op_sel_hi:[1,0] neg_lo:[0,1] neg_hi:[0,1]
	s_waitcnt lgkmcnt(0)
	v_pk_mul_f32 v[46:47], v[36:37], v[46:47] op_sel_hi:[0,1]
	v_pk_mul_f32 v[34:35], v[36:37], v[34:35] op_sel_hi:[0,1]
	v_lshlrev_b32_e32 v50, 16, v32
	v_and_b32_e32 v51, 0xffff0000, v32
	v_pk_fma_f32 v[38:39], v[38:39], v[46:47], v[42:43]
	v_pk_fma_f32 v[34:35], v[40:41], v[34:35], v[44:45]
	v_pk_add_f32 v[38:39], v[38:39], v[50:51]
	v_pk_add_f32 v[34:35], v[34:35], v[52:53]
	v_cvt_pk_bf16_f32 v36, v38, v39
	v_cvt_pk_bf16_f32 v37, v34, v35
	ds_write_b64 v19, v[36:37] offset:16784
	v_add_u32_e32 v32, 0x25140, v27
	v_add_u32_e32 v38, 0x25540, v27
	ds_read_b64 v[42:43], v19 offset:160
	ds_read_b128 v[34:37], v32
	ds_read_b128 v[38:41], v38
	ds_read_b32 v32, v29
	ds_read_b32 v44, v30
	ds_read_b64 v[46:47], v19 offset:16800
	s_waitcnt lgkmcnt(5)
	v_lshlrev_b32_e32 v48, 16, v42
	v_and_b32_e32 v49, 0xffff0000, v42
	v_lshlrev_b32_e32 v42, 16, v43
	v_and_b32_e32 v43, 0xffff0000, v43
	s_waitcnt lgkmcnt(2)
	v_pk_add_f32 v[48:49], v[48:49], v[32:33] op_sel_hi:[1,0] neg_lo:[0,1] neg_hi:[0,1]
	v_pk_add_f32 v[42:43], v[42:43], v[32:33] op_sel_hi:[1,0] neg_lo:[0,1] neg_hi:[0,1]
	s_waitcnt lgkmcnt(1)
; DI unsigned pack2(float a, float b) { f32x2_t v = {a, b}; bf16x2_t r = __builtin_convertvector(v, bf16x2_t); return __builtin_bit_cast(unsigned, r); }
; DI float bflo(unsigned u) { return __uint_as_float(u << 16); }
; DI float bfhi(unsigned u) { return __uint_as_float(u & 0xffff0000u); }
; DI int otid() { int t = threadIdx.x; asm volatile("" : "+v"(t)); return t; }
; template <bool LAST>
; DI void phase_gate(const Params& P, int layer, unsigned char* smem, int L, int G) {
;     ...
;     const int tid2 = otid();
;     const int lane2 = tid2 & 63, w2 = tid2 >> 6, r2 = lane2 & 31, h2 = lane2 >> 5, wm2 = w2 >> 2, wn2 = w2 & 3;
; #pragma unroll
;     for (int i = 0; i < 4; ++i)
; #pragma unroll
;       for (int q4 = 0; q4 < 4; ++q4) {
;         const int fl = wm2 * 128 + i * 32 + 8 * q4 + 4 * h2;
;         const int f0 = nt * 256 + fl;
;         const f32x4 gv = *(const f32x4*)(vecL + 512 + fl), bv = *(const f32x4*)(vecL + 768 + fl);
;         const float ga[4] = {gv.x, gv.y, gv.z, gv.w}, ba[4] = {bv.x, bv.y, bv.z, bv.w};
; #pragma unroll
;         for (int j = 0; j < 2; ++j) {
;           const int lrow = wn2 * 64 + j * 32 + r2;
;           const float mu = rowA[lrow], rstd = rowB[lrow];
;           uint2* sp = (uint2*)(stg + lrow * STG + fl);
;           const uint2 sv = *sp;
;           const float sa[4] = {bflo(sv.x), bfhi(sv.x), bflo(sv.y), bfhi(sv.y)};
;           float y[4];
;           const float gg[4] = {bflo(gq[i][j][2 * q4]), bfhi(gq[i][j][2 * q4]), bflo(gq[i][j][2 * q4 + 1]), bfhi(gq[i][j][2 * q4 + 1])};
; #pragma unroll
;           for (int e = 0; e < 4; ++e) y[e] = (sa[e] - mu) * rstd * ga[e] + ba[e] + gg[e];
;           if (LAST) { f32x4 o = {y[0], y[1], y[2], y[3]}; *(f32x4*)(P.out + (size_t)(mt * 256 + lrow) * 1024 + f0) = o; }
;           else { uint2 pk; pk.x = pack2(y[0], y[1]); pk.y = pack2(y[2], y[3]); *sp = pk; }
;         }
;         __builtin_amdgcn_sched_barrier(0);
;       }
	v_pk_mul_f32 v[48:49], v[44:45], v[48:49] op_sel_hi:[0,1]
	v_pk_mul_f32 v[42:43], v[44:45], v[42:43] op_sel_hi:[0,1]
	v_lshlrev_b32_e32 v50, 16, v24
	v_and_b32_e32 v51, 0xffff0000, v24
	v_lshlrev_b32_e32 v52, 16, v26
	v_and_b32_e32 v53, 0xffff0000, v26
	v_pk_fma_f32 v[48:49], v[34:35], v[48:49], v[38:39]
	v_pk_fma_f32 v[42:43], v[36:37], v[42:43], v[40:41]
	v_pk_add_f32 v[48:49], v[48:49], v[50:51]
	v_pk_add_f32 v[42:43], v[42:43], v[52:53]
	v_cvt_pk_bf16_f32 v44, v48, v49
	v_cvt_pk_bf16_f32 v45, v42, v43
	ds_write_b64 v19, v[44:45] offset:160
	ds_read_b32 v24, v31
	ds_read_b32 v26, v33
	s_waitcnt lgkmcnt(3)
	v_lshlrev_b32_e32 v42, 16, v46
	v_and_b32_e32 v43, 0xffff0000, v46
	v_lshlrev_b32_e32 v44, 16, v47
	v_and_b32_e32 v45, 0xffff0000, v47
	v_lshlrev_b32_e32 v48, 16, v25
	v_and_b32_e32 v49, 0xffff0000, v25
	s_waitcnt lgkmcnt(1)
	v_pk_add_f32 v[42:43], v[42:43], v[24:25] op_sel_hi:[1,0] neg_lo:[0,1] neg_hi:[0,1]
	v_pk_add_f32 v[24:25], v[44:45], v[24:25] op_sel_hi:[1,0] neg_lo:[0,1] neg_hi:[0,1]
	s_waitcnt lgkmcnt(0)
	v_pk_mul_f32 v[42:43], v[26:27], v[42:43] op_sel_hi:[0,1]
	v_pk_mul_f32 v[24:25], v[26:27], v[24:25] op_sel_hi:[0,1]
	v_lshlrev_b32_e32 v46, 16, v23
	v_and_b32_e32 v47, 0xffff0000, v23
	v_pk_fma_f32 v[34:35], v[34:35], v[42:43], v[38:39]
	v_pk_fma_f32 v[24:25], v[36:37], v[24:25], v[40:41]
	v_pk_add_f32 v[34:35], v[34:35], v[46:47]
	v_pk_add_f32 v[24:25], v[24:25], v[48:49]
	v_cvt_pk_bf16_f32 v34, v34, v35
	v_cvt_pk_bf16_f32 v35, v24, v25
	ds_write_b64 v19, v[34:35] offset:16800
	v_add_u32_e32 v26, 0x25560, v27
	v_add_u32_e32 v23, 0x25160, v27
	ds_read_b64 v[24:25], v19 offset:176
	ds_read_b128 v[34:37], v23
	ds_read_b128 v[38:41], v26
	ds_read_b32 v26, v29
	ds_read_b32 v32, v30
	ds_read_b64 v[42:43], v19 offset:16816
	s_waitcnt lgkmcnt(5)
	v_lshlrev_b32_e32 v44, 16, v24
	v_and_b32_e32 v45, 0xffff0000, v24
	v_lshlrev_b32_e32 v24, 16, v25
	v_and_b32_e32 v25, 0xffff0000, v25
	v_lshlrev_b32_e32 v48, 16, v22
	v_and_b32_e32 v49, 0xffff0000, v22
	s_waitcnt lgkmcnt(2)
	v_pk_add_f32 v[22:23], v[44:45], v[26:27] op_sel_hi:[1,0] neg_lo:[0,1] neg_hi:[0,1]
	v_pk_add_f32 v[24:25], v[24:25], v[26:27] op_sel_hi:[1,0] neg_lo:[0,1] neg_hi:[0,1]
	s_waitcnt lgkmcnt(1)
	v_pk_mul_f32 v[22:23], v[32:33], v[22:23] op_sel_hi:[0,1]
	v_pk_mul_f32 v[24:25], v[32:33], v[24:25] op_sel_hi:[0,1]
	v_lshlrev_b32_e32 v46, 16, v20
	v_and_b32_e32 v47, 0xffff0000, v20
	v_pk_fma_f32 v[22:23], v[34:35], v[22:23], v[38:39]
	v_pk_fma_f32 v[24:25], v[36:37], v[24:25], v[40:41]
	v_pk_add_f32 v[22:23], v[22:23], v[46:47]
	v_pk_add_f32 v[24:25], v[24:25], v[48:49]
	v_cvt_pk_bf16_f32 v22, v22, v23
	v_cvt_pk_bf16_f32 v23, v24, v25
	ds_write_b64 v19, v[22:23] offset:176
	ds_read_b32 v20, v31
	ds_read_b32 v22, v33
	s_waitcnt lgkmcnt(3)
	v_lshlrev_b32_e32 v24, 16, v42
	v_and_b32_e32 v25, 0xffff0000, v42
	v_lshlrev_b32_e32 v42, 16, v43
	v_and_b32_e32 v43, 0xffff0000, v43
	v_lshlrev_b32_e32 v46, 16, v21
	v_and_b32_e32 v47, 0xffff0000, v21
	s_waitcnt lgkmcnt(1)
	v_pk_add_f32 v[24:25], v[24:25], v[20:21] op_sel_hi:[1,0] neg_lo:[0,1] neg_hi:[0,1]
	v_pk_add_f32 v[20:21], v[42:43], v[20:21] op_sel_hi:[1,0] neg_lo:[0,1] neg_hi:[0,1]
	s_waitcnt lgkmcnt(0)
	v_pk_mul_f32 v[24:25], v[22:23], v[24:25] op_sel_hi:[0,1]
	v_pk_mul_f32 v[20:21], v[22:23], v[20:21] op_sel_hi:[0,1]
	v_lshlrev_b32_e32 v44, 16, v18
	v_and_b32_e32 v45, 0xffff0000, v18
	v_pk_fma_f32 v[24:25], v[34:35], v[24:25], v[38:39]
	v_pk_fma_f32 v[20:21], v[36:37], v[20:21], v[40:41]
	v_pk_add_f32 v[24:25], v[24:25], v[44:45]
	v_pk_add_f32 v[20:21], v[20:21], v[46:47]
	v_cvt_pk_bf16_f32 v22, v24, v25
	v_cvt_pk_bf16_f32 v23, v20, v21
	ds_write_b64 v19, v[22:23] offset:16816
	v_add_u32_e32 v18, 0x25180, v27
	v_add_u32_e32 v26, 0x25580, v27
	ds_read_b64 v[24:25], v19 offset:192
	ds_read_b128 v[20:23], v18
	ds_read_b128 v[34:37], v26
	ds_read_b32 v18, v29
	ds_read_b32 v26, v30
	ds_read_b64 v[38:39], v19 offset:16832
	s_waitcnt lgkmcnt(5)
	v_lshlrev_b32_e32 v40, 16, v24
	v_and_b32_e32 v41, 0xffff0000, v24
	v_lshlrev_b32_e32 v24, 16, v25
	v_and_b32_e32 v25, 0xffff0000, v25
	s_waitcnt lgkmcnt(2)
	v_pk_add_f32 v[40:41], v[40:41], v[18:19] op_sel_hi:[1,0] neg_lo:[0,1] neg_hi:[0,1]
	v_pk_add_f32 v[24:25], v[24:25], v[18:19] op_sel_hi:[1,0] neg_lo:[0,1] neg_hi:[0,1]
	s_waitcnt lgkmcnt(1)
	v_pk_mul_f32 v[40:41], v[26:27], v[40:41] op_sel_hi:[0,1]
	v_pk_mul_f32 v[24:25], v[26:27], v[24:25] op_sel_hi:[0,1]
	v_lshlrev_b32_e32 v42, 16, v15
	v_and_b32_e32 v43, 0xffff0000, v15
	v_lshlrev_b32_e32 v44, 16, v17
	v_and_b32_e32 v45, 0xffff0000, v17
	v_pk_fma_f32 v[40:41], v[20:21], v[40:41], v[34:35]
	v_pk_fma_f32 v[24:25], v[22:23], v[24:25], v[36:37]
	v_pk_add_f32 v[40:41], v[40:41], v[42:43]
	v_pk_add_f32 v[24:25], v[24:25], v[44:45]
	v_cvt_pk_bf16_f32 v40, v40, v41
	v_cvt_pk_bf16_f32 v41, v24, v25
	ds_write_b64 v19, v[40:41] offset:192
	ds_read_b32 v18, v31
	ds_read_b32 v24, v33
	s_waitcnt lgkmcnt(3)
	v_lshlrev_b32_e32 v40, 16, v38
	v_and_b32_e32 v41, 0xffff0000, v38
	v_lshlrev_b32_e32 v42, 16, v14
	v_and_b32_e32 v43, 0xffff0000, v14
	v_lshlrev_b32_e32 v14, 16, v16
	v_and_b32_e32 v15, 0xffff0000, v16
	s_waitcnt lgkmcnt(1)
	v_pk_add_f32 v[16:17], v[40:41], v[18:19] op_sel_hi:[1,0] neg_lo:[0,1] neg_hi:[0,1]
	v_lshlrev_b32_e32 v38, 16, v39
	v_and_b32_e32 v39, 0xffff0000, v39
	s_waitcnt lgkmcnt(0)
; DI unsigned pack2(float a, float b) { f32x2_t v = {a, b}; bf16x2_t r = __builtin_convertvector(v, bf16x2_t); return __builtin_bit_cast(unsigned, r); }
; DI float bflo(unsigned u) { return __uint_as_float(u << 16); }
; DI float bfhi(unsigned u) { return __uint_as_float(u & 0xffff0000u); }
; template <bool LAST>
; DI void phase_gate(const Params& P, int layer, unsigned char* smem, int L, int G) {
;     ...
; #pragma unroll
;     for (int i = 0; i < 4; ++i)
; #pragma unroll
;       for (int q4 = 0; q4 < 4; ++q4) {
;         const int fl = wm2 * 128 + i * 32 + 8 * q4 + 4 * h2;
;         const int f0 = nt * 256 + fl;
;         const f32x4 gv = *(const f32x4*)(vecL + 512 + fl), bv = *(const f32x4*)(vecL + 768 + fl);
;         const float ga[4] = {gv.x, gv.y, gv.z, gv.w}, ba[4] = {bv.x, bv.y, bv.z, bv.w};
; #pragma unroll
;         for (int j = 0; j < 2; ++j) {
;           const int lrow = wn2 * 64 + j * 32 + r2;
;           const float mu = rowA[lrow], rstd = rowB[lrow];
;           uint2* sp = (uint2*)(stg + lrow * STG + fl);
;           const uint2 sv = *sp;
;           const float sa[4] = {bflo(sv.x), bfhi(sv.x), bflo(sv.y), bfhi(sv.y)};
;           float y[4];
;           const float gg[4] = {bflo(gq[i][j][2 * q4]), bfhi(gq[i][j][2 * q4]), bflo(gq[i][j][2 * q4 + 1]), bfhi(gq[i][j][2 * q4 + 1])};
; #pragma unroll
;           for (int e = 0; e < 4; ++e) y[e] = (sa[e] - mu) * rstd * ga[e] + ba[e] + gg[e];
;           if (LAST) { f32x4 o = {y[0], y[1], y[2], y[3]}; *(f32x4*)(P.out + (size_t)(mt * 256 + lrow) * 1024 + f0) = o; }
;           else { uint2 pk; pk.x = pack2(y[0], y[1]); pk.y = pack2(y[2], y[3]); *sp = pk; }
;         }
;         __builtin_amdgcn_sched_barrier(0);
;       }
;     __syncthreads();
	v_pk_mul_f32 v[16:17], v[24:25], v[16:17] op_sel_hi:[0,1]
	v_pk_fma_f32 v[16:17], v[20:21], v[16:17], v[34:35]
	v_pk_add_f32 v[20:21], v[38:39], v[18:19] op_sel_hi:[1,0] neg_lo:[0,1] neg_hi:[0,1]
	v_pk_add_f32 v[16:17], v[16:17], v[42:43]
	v_pk_mul_f32 v[20:21], v[24:25], v[20:21] op_sel_hi:[0,1]
	v_pk_fma_f32 v[20:21], v[22:23], v[20:21], v[36:37]
	v_cvt_pk_bf16_f32 v16, v16, v17
	v_pk_add_f32 v[14:15], v[20:21], v[14:15]
	s_nop 0
	v_cvt_pk_bf16_f32 v17, v14, v15
	ds_write_b64 v19, v[16:17] offset:16832
	v_add_u32_e32 v14, 0x251a0, v27
	v_add_u32_e32 v18, 0x255a0, v27
	ds_read_b64 v[24:25], v19 offset:208
	ds_read_b128 v[14:17], v14
	ds_read_b128 v[20:23], v18
	ds_read_b32 v18, v29
	ds_read_b32 v26, v30
	ds_read_b64 v[34:35], v19 offset:16848
	s_waitcnt lgkmcnt(5)
	v_lshlrev_b32_e32 v36, 16, v24
	v_and_b32_e32 v37, 0xffff0000, v24
	v_lshlrev_b32_e32 v24, 16, v25
	v_and_b32_e32 v25, 0xffff0000, v25
	s_waitcnt lgkmcnt(2)
	v_pk_add_f32 v[36:37], v[36:37], v[18:19] op_sel_hi:[1,0] neg_lo:[0,1] neg_hi:[0,1]
	v_pk_add_f32 v[24:25], v[24:25], v[18:19] op_sel_hi:[1,0] neg_lo:[0,1] neg_hi:[0,1]
	s_waitcnt lgkmcnt(1)
	v_pk_mul_f32 v[36:37], v[26:27], v[36:37] op_sel_hi:[0,1]
	v_pk_mul_f32 v[24:25], v[26:27], v[24:25] op_sel_hi:[0,1]
	v_lshlrev_b32_e32 v38, 16, v11
	v_and_b32_e32 v39, 0xffff0000, v11
	v_lshlrev_b32_e32 v40, 16, v13
	v_and_b32_e32 v41, 0xffff0000, v13
	v_pk_fma_f32 v[36:37], v[14:15], v[36:37], v[20:21]
	v_pk_fma_f32 v[24:25], v[16:17], v[24:25], v[22:23]
	v_pk_add_f32 v[36:37], v[36:37], v[38:39]
	v_pk_add_f32 v[24:25], v[24:25], v[40:41]
	v_cvt_pk_bf16_f32 v36, v36, v37
	v_cvt_pk_bf16_f32 v37, v24, v25
	ds_write_b64 v19, v[36:37] offset:208
	ds_read_b32 v18, v31
	ds_read_b32 v24, v33
	s_waitcnt lgkmcnt(3)
	v_lshlrev_b32_e32 v36, 16, v34
	v_and_b32_e32 v37, 0xffff0000, v34
	v_lshlrev_b32_e32 v38, 16, v10
	v_and_b32_e32 v39, 0xffff0000, v10
	v_lshlrev_b32_e32 v10, 16, v12
	v_and_b32_e32 v11, 0xffff0000, v12
	s_waitcnt lgkmcnt(1)
	v_pk_add_f32 v[12:13], v[36:37], v[18:19] op_sel_hi:[1,0] neg_lo:[0,1] neg_hi:[0,1]
	v_lshlrev_b32_e32 v34, 16, v35
	v_and_b32_e32 v35, 0xffff0000, v35
	s_waitcnt lgkmcnt(0)
	v_pk_mul_f32 v[12:13], v[24:25], v[12:13] op_sel_hi:[0,1]
	v_pk_fma_f32 v[12:13], v[14:15], v[12:13], v[20:21]
	v_pk_add_f32 v[14:15], v[34:35], v[18:19] op_sel_hi:[1,0] neg_lo:[0,1] neg_hi:[0,1]
	v_pk_add_f32 v[12:13], v[12:13], v[38:39]
	v_pk_mul_f32 v[14:15], v[24:25], v[14:15] op_sel_hi:[0,1]
	v_pk_fma_f32 v[14:15], v[16:17], v[14:15], v[22:23]
	v_cvt_pk_bf16_f32 v12, v12, v13
	v_pk_add_f32 v[10:11], v[14:15], v[10:11]
	s_nop 0
	v_cvt_pk_bf16_f32 v13, v10, v11
	ds_write_b64 v19, v[12:13] offset:16848
	v_add_u32_e32 v10, 0x251c0, v27
	v_add_u32_e32 v14, 0x255c0, v27
	ds_read_b64 v[20:21], v19 offset:224
	ds_read_b128 v[10:13], v10
	ds_read_b128 v[14:17], v14
	ds_read_b32 v18, v29
	ds_read_b32 v22, v30
	ds_read_b64 v[24:25], v19 offset:16864
	s_waitcnt lgkmcnt(5)
	v_lshlrev_b32_e32 v34, 16, v20
	v_and_b32_e32 v35, 0xffff0000, v20
	v_lshlrev_b32_e32 v20, 16, v21
	v_and_b32_e32 v21, 0xffff0000, v21
	s_waitcnt lgkmcnt(2)
	v_pk_add_f32 v[34:35], v[34:35], v[18:19] op_sel_hi:[1,0] neg_lo:[0,1] neg_hi:[0,1]
	v_pk_add_f32 v[20:21], v[20:21], v[18:19] op_sel_hi:[1,0] neg_lo:[0,1] neg_hi:[0,1]
	s_waitcnt lgkmcnt(1)
	v_pk_mul_f32 v[34:35], v[22:23], v[34:35] op_sel_hi:[0,1]
	v_pk_mul_f32 v[20:21], v[22:23], v[20:21] op_sel_hi:[0,1]
	v_lshlrev_b32_e32 v36, 16, v7
	v_and_b32_e32 v37, 0xffff0000, v7
	v_lshlrev_b32_e32 v38, 16, v9
	v_and_b32_e32 v39, 0xffff0000, v9
	v_pk_fma_f32 v[34:35], v[10:11], v[34:35], v[14:15]
	v_pk_fma_f32 v[20:21], v[12:13], v[20:21], v[16:17]
	v_pk_add_f32 v[34:35], v[34:35], v[36:37]
	v_pk_add_f32 v[20:21], v[20:21], v[38:39]
	v_cvt_pk_bf16_f32 v22, v34, v35
	v_cvt_pk_bf16_f32 v23, v20, v21
	ds_write_b64 v19, v[22:23] offset:224
	ds_read_b32 v18, v31
	ds_read_b32 v20, v33
	s_waitcnt lgkmcnt(3)
	v_lshlrev_b32_e32 v22, 16, v24
	v_and_b32_e32 v23, 0xffff0000, v24
	v_lshlrev_b32_e32 v34, 16, v6
	v_and_b32_e32 v35, 0xffff0000, v6
	v_lshlrev_b32_e32 v6, 16, v8
	v_and_b32_e32 v7, 0xffff0000, v8
	s_waitcnt lgkmcnt(1)
	v_pk_add_f32 v[8:9], v[22:23], v[18:19] op_sel_hi:[1,0] neg_lo:[0,1] neg_hi:[0,1]
	v_lshlrev_b32_e32 v24, 16, v25
	v_and_b32_e32 v25, 0xffff0000, v25
	s_waitcnt lgkmcnt(0)
	v_pk_mul_f32 v[8:9], v[20:21], v[8:9] op_sel_hi:[0,1]
	v_pk_fma_f32 v[8:9], v[10:11], v[8:9], v[14:15]
	v_pk_add_f32 v[10:11], v[24:25], v[18:19] op_sel_hi:[1,0] neg_lo:[0,1] neg_hi:[0,1]
	v_pk_add_f32 v[8:9], v[8:9], v[34:35]
	v_pk_mul_f32 v[10:11], v[20:21], v[10:11] op_sel_hi:[0,1]
	v_pk_fma_f32 v[10:11], v[12:13], v[10:11], v[16:17]
	v_cvt_pk_bf16_f32 v8, v8, v9
	v_pk_add_f32 v[6:7], v[10:11], v[6:7]
	s_nop 0
	v_cvt_pk_bf16_f32 v9, v6, v7
	ds_write_b64 v19, v[8:9] offset:16864
	ds_read_b128 v[6:9], v28 offset:480
	ds_read_b64 v[14:15], v19 offset:240
	ds_read_b32 v16, v29
	ds_read_b32 v18, v30
	v_add_u32_e32 v10, 0x255e0, v27
	ds_read_b128 v[10:13], v10
	s_waitcnt lgkmcnt(3)
	v_lshlrev_b32_e32 v20, 16, v14
	v_and_b32_e32 v21, 0xffff0000, v14
	v_lshlrev_b32_e32 v14, 16, v15
	v_and_b32_e32 v15, 0xffff0000, v15
	s_waitcnt lgkmcnt(2)
	v_pk_add_f32 v[20:21], v[20:21], v[16:17] op_sel_hi:[1,0] neg_lo:[0,1] neg_hi:[0,1]
	v_pk_add_f32 v[14:15], v[14:15], v[16:17] op_sel_hi:[1,0] neg_lo:[0,1] neg_hi:[0,1]
	s_waitcnt lgkmcnt(1)
	v_pk_mul_f32 v[20:21], v[18:19], v[20:21] op_sel_hi:[0,1]
	v_pk_mul_f32 v[14:15], v[18:19], v[14:15] op_sel_hi:[0,1]
	v_lshlrev_b32_e32 v22, 16, v4
	v_and_b32_e32 v23, 0xffff0000, v4
	v_lshlrev_b32_e32 v4, 16, v5
	v_and_b32_e32 v5, 0xffff0000, v5
	s_waitcnt lgkmcnt(0)
	v_pk_fma_f32 v[20:21], v[6:7], v[20:21], v[10:11]
	v_pk_fma_f32 v[14:15], v[8:9], v[14:15], v[12:13]
	v_pk_add_f32 v[20:21], v[20:21], v[22:23]
	v_pk_add_f32 v[4:5], v[14:15], v[4:5]
	v_cvt_pk_bf16_f32 v14, v20, v21
	v_cvt_pk_bf16_f32 v15, v4, v5
	ds_write_b64 v19, v[14:15] offset:240
	ds_read_b32 v4, v33
	ds_read_b64 v[14:15], v19 offset:16880
	ds_read_b32 v16, v31
	v_lshlrev_b32_e32 v22, 16, v2
	v_and_b32_e32 v23, 0xffff0000, v2
	v_lshlrev_b32_e32 v2, 16, v3
	s_waitcnt lgkmcnt(1)
	v_lshlrev_b32_e32 v20, 16, v14
	v_and_b32_e32 v21, 0xffff0000, v14
	s_waitcnt lgkmcnt(0)
	v_pk_add_f32 v[20:21], v[20:21], v[16:17] op_sel_hi:[1,0] neg_lo:[0,1] neg_hi:[0,1]
	v_lshlrev_b32_e32 v14, 16, v15
	v_and_b32_e32 v15, 0xffff0000, v15
	v_pk_mul_f32 v[20:21], v[4:5], v[20:21] op_sel_hi:[0,1]
	v_pk_fma_f32 v[6:7], v[6:7], v[20:21], v[10:11]
	v_pk_add_f32 v[10:11], v[14:15], v[16:17] op_sel_hi:[1,0] neg_lo:[0,1] neg_hi:[0,1]
	v_and_b32_e32 v3, 0xffff0000, v3
	v_pk_mul_f32 v[4:5], v[4:5], v[10:11] op_sel_hi:[0,1]
	v_pk_fma_f32 v[4:5], v[8:9], v[4:5], v[12:13]
	v_pk_add_f32 v[6:7], v[6:7], v[22:23]
	v_pk_add_f32 v[2:3], v[4:5], v[2:3]
	v_cvt_pk_bf16_f32 v4, v6, v7
	v_cvt_pk_bf16_f32 v5, v2, v3
	ds_write_b64 v19, v[4:5] offset:16880
	s_add_u32 s24, s80, s24
	s_addc_u32 s25, s81, s25
	v_lshl_add_u64 v[8:9], s[24:25], 0, v[0:1]
	v_mov_b32_e32 v0, v192
	s_waitcnt lgkmcnt(0)
	s_barrier
; DI int otid() { int t = threadIdx.x; asm volatile("" : "+v"(t)); return t; }
; DI void stg16_nt(void* p, u32x4 v) { __builtin_nontemporal_store(v, (u32x4*)p); }
; DI void stage_store_tile(const bf16_t* stg, bf16_t* tilebase) {
;   const int tid = otid();
;   const int r0 = tid >> 5, c = tid & 31;
;   const unsigned o0 = (unsigned)(r0 * 1024 + c * 8);
; #pragma unroll
;   for (int it = 0; it < 16; ++it) stg16_nt(tilebase + (o0 + (unsigned)(it * 16 * 1024)), stage_read16(stg, r0 + 16 * it, c));
; }
; template <bool LAST>
; DI void phase_gate(const Params& P, int layer, unsigned char* smem, int L, int G) {
;     ...
;     if (!LAST) stage_store_tile(stg, xb + (size_t)mt * 256 * 1024 + nt * 256);
;     __syncthreads();
	s_add_i32 s36, s36, s74
	v_ashrrev_i32_e32 v4, 5, v0
	v_and_b32_e32 v0, 31, v0
	v_mul_lo_u32 v1, v4, s44
	v_lshl_add_u32 v12, v0, 4, v1
	v_lshlrev_b32_e32 v5, 3, v0
	ds_read2_b64 v[0:3], v12 offset1:1
	v_lshl_or_b32 v160, v4, 10, v5
	v_add_u32_e32 v4, 0x2080, v12
	ds_read2_b64 v[4:7], v4 offset1:1
	v_lshl_add_u64 v[10:11], v[160:161], 1, v[8:9]
	s_waitcnt lgkmcnt(1)
	global_store_dwordx4 v[10:11], v[0:3], off nt
	s_add_i32 s33, s33, s69
	s_add_i32 s34, s34, s35
	v_add_u32_e32 v0, 0x4000, v160
	v_mov_b32_e32 v1, v161
	v_lshl_add_u64 v[0:1], v[0:1], 1, v[8:9]
	s_waitcnt lgkmcnt(0)
	global_store_dwordx4 v[0:1], v[4:7], off nt
	v_add_u32_e32 v0, 0x4100, v12
	ds_read2_b64 v[0:3], v0 offset1:1
	v_add_u32_e32 v4, 0x8000, v160
	v_mov_b32_e32 v5, v161
	v_lshl_add_u64 v[10:11], v[4:5], 1, v[8:9]
	v_add_u32_e32 v4, 0x6180, v12
	ds_read2_b64 v[4:7], v4 offset1:1
	s_waitcnt lgkmcnt(1)
	global_store_dwordx4 v[10:11], v[0:3], off nt
	s_add_i32 s24, s70, s36
	s_cmpk_lt_i32 s24, 0x400
	v_add_u32_e32 v0, 0xc000, v160
	v_mov_b32_e32 v1, v161
	v_lshl_add_u64 v[0:1], v[0:1], 1, v[8:9]
	s_waitcnt lgkmcnt(0)
	global_store_dwordx4 v[0:1], v[4:7], off nt
	v_add_u32_e32 v0, 0x8200, v12
	ds_read2_b64 v[0:3], v0 offset1:1
	v_add_u32_e32 v4, 0x10000, v160
	v_mov_b32_e32 v5, v161
	v_lshl_add_u64 v[10:11], v[4:5], 1, v[8:9]
	v_add_u32_e32 v4, 0xa280, v12
	ds_read2_b64 v[4:7], v4 offset1:1
	s_waitcnt lgkmcnt(1)
	global_store_dwordx4 v[10:11], v[0:3], off nt
	s_nop 1
	v_add_u32_e32 v0, 0x14000, v160
	v_mov_b32_e32 v1, v161
	v_lshl_add_u64 v[0:1], v[0:1], 1, v[8:9]
	s_waitcnt lgkmcnt(0)
	global_store_dwordx4 v[0:1], v[4:7], off nt
	v_add_u32_e32 v0, 0xc300, v12
	ds_read2_b64 v[0:3], v0 offset1:1
	v_add_u32_e32 v4, 0x18000, v160
	v_mov_b32_e32 v5, v161
	v_lshl_add_u64 v[10:11], v[4:5], 1, v[8:9]
	v_add_u32_e32 v4, 0xe380, v12
	ds_read2_b64 v[4:7], v4 offset1:1
	s_waitcnt lgkmcnt(1)
	global_store_dwordx4 v[10:11], v[0:3], off nt
	s_nop 1
	v_add_u32_e32 v0, 0x1c000, v160
	v_mov_b32_e32 v1, v161
	v_lshl_add_u64 v[0:1], v[0:1], 1, v[8:9]
	s_waitcnt lgkmcnt(0)
	global_store_dwordx4 v[0:1], v[4:7], off nt
	v_add_u32_e32 v0, 0x10400, v12
	ds_read2_b64 v[0:3], v0 offset1:1
	v_add_u32_e32 v4, 0x20000, v160
	v_mov_b32_e32 v5, v161
	v_lshl_add_u64 v[10:11], v[4:5], 1, v[8:9]
	v_add_u32_e32 v4, 0x12480, v12
	ds_read2_b64 v[4:7], v4 offset1:1
	s_waitcnt lgkmcnt(1)
	global_store_dwordx4 v[10:11], v[0:3], off nt
	s_nop 1
	v_add_u32_e32 v0, 0x24000, v160
	v_mov_b32_e32 v1, v161
	v_lshl_add_u64 v[0:1], v[0:1], 1, v[8:9]
	s_waitcnt lgkmcnt(0)
	global_store_dwordx4 v[0:1], v[4:7], off nt
	v_add_u32_e32 v0, 0x14500, v12
	ds_read2_b64 v[0:3], v0 offset1:1
	v_add_u32_e32 v4, 0x28000, v160
	v_mov_b32_e32 v5, v161
	v_lshl_add_u64 v[10:11], v[4:5], 1, v[8:9]
	v_add_u32_e32 v4, 0x16580, v12
	ds_read2_b64 v[4:7], v4 offset1:1
	s_waitcnt lgkmcnt(1)
	global_store_dwordx4 v[10:11], v[0:3], off nt
	s_nop 1
	v_add_u32_e32 v0, 0x2c000, v160
	v_mov_b32_e32 v1, v161
	v_lshl_add_u64 v[0:1], v[0:1], 1, v[8:9]
	s_waitcnt lgkmcnt(0)
	global_store_dwordx4 v[0:1], v[4:7], off nt
	v_add_u32_e32 v0, 0x18600, v12
	ds_read2_b64 v[0:3], v0 offset1:1
	v_add_u32_e32 v4, 0x30000, v160
	v_mov_b32_e32 v5, v161
	v_lshl_add_u64 v[10:11], v[4:5], 1, v[8:9]
	v_add_u32_e32 v4, 0x1a680, v12
	ds_read2_b64 v[4:7], v4 offset1:1
	s_waitcnt lgkmcnt(1)
	global_store_dwordx4 v[10:11], v[0:3], off nt
	v_add_u32_e32 v10, 0x38000, v160
	v_mov_b32_e32 v11, v161
	v_add_u32_e32 v0, 0x34000, v160
	v_mov_b32_e32 v1, v161
	v_lshl_add_u64 v[0:1], v[0:1], 1, v[8:9]
	s_waitcnt lgkmcnt(0)
	global_store_dwordx4 v[0:1], v[4:7], off nt
	v_add_u32_e32 v0, 0x1c700, v12
	ds_read2_b64 v[0:3], v0 offset1:1
	v_add_u32_e32 v4, 0x1e780, v12
	ds_read2_b64 v[4:7], v4 offset1:1
	v_lshl_add_u64 v[10:11], v[10:11], 1, v[8:9]
	v_add_u32_e32 v160, 0x3c000, v160
	s_waitcnt lgkmcnt(1)
	global_store_dwordx4 v[10:11], v[0:3], off nt
	s_nop 1
	v_lshl_add_u64 v[0:1], v[160:161], 1, v[8:9]
	s_waitcnt lgkmcnt(0)
	global_store_dwordx4 v[0:1], v[4:7], off nt
	s_barrier
	s_cbranch_scc0 .LBB0_488

; DI unsigned pack2(float a, float b) { f32x2_t v = {a, b}; bf16x2_t r = __builtin_convertvector(v, bf16x2_t); return __builtin_bit_cast(unsigned, r); }
; DI float sigmoidf_(float x) { return __builtin_amdgcn_rcpf(1.f + __expf(-x)); }
; DI int otid() { int t = threadIdx.x; asm volatile("" : "+v"(t)); return t; }
; template <bool NT>
; DI void stage_load_tile(bf16_t* stg, const bf16_t* tilebase) {
;   const int tid = otid();
;   const int r0 = tid >> 5, c = tid & 31;
;   const unsigned o0 = (unsigned)(r0 * 1024 + c * 8);
;   __builtin_amdgcn_sched_barrier(0);
; #pragma unroll
;   for (int hf = 0; hf < 2; ++hf) {
; #pragma unroll
;     for (int it = 8 * hf; it < 8 * hf + 8; ++it) {
;       const u32x4* gp = (const u32x4*)(tilebase + (o0 + (unsigned)(it * 16 * 1024)));
;       stage_write16(stg, r0 + 16 * it, c, NT ? __builtin_nontemporal_load(gp) : *gp);
;     }
;     __builtin_amdgcn_sched_barrier(0);
;   }
; template <bool LAST>
; DI void phase_gate(const Params& P, int layer, unsigned char* smem, int L, int G) {
;     ...
;     unsigned gq[4][2][8];
; #pragma unroll
;     for (int i = 0; i < 4; ++i)
; #pragma unroll
;       for (int q4 = 0; q4 < 4; ++q4) {
;         const int fl = wm * 128 + i * 32 + 8 * q4 + 4 * h;
;         const f32x4 c1v = *(const f32x4*)(vecL + fl), c2v = *(const f32x4*)(vecL + 256 + fl);
;         const float c1a[4] = {c1v.x, c1v.y, c1v.z, c1v.w}, c2a[4] = {c2v.x, c2v.y, c2v.z, c2v.w};
; #pragma unroll
;         for (int j = 0; j < 2; ++j) {
;           const int lrow = wn * 64 + j * 32 + r;
;           const float mu = rowA[lrow], rstd = rowB[lrow];
;           float sg4[4];
; #pragma unroll
;           for (int e = 0; e < 4; ++e) sg4[e] = sigmoidf_(rstd * (accu[i][j][4 * q4 + e] - mu * c1a[e]) + c2a[e]);
;           gq[i][j][2 * q4] = pack2(sg4[0], sg4[1]); gq[i][j][2 * q4 + 1] = pack2(sg4[2], sg4[3]);
;         }
;         __builtin_amdgcn_sched_barrier(0);
;       }
.LBB0_920:
	s_ashr_i32 s25, s24, 31
	s_lshl_b64 s[24:25], s[24:25], 19
	s_add_u32 s26, s66, s24
	s_addc_u32 s27, s67, s25
	v_and_b32_e32 v188, 31, v192
	v_ashrrev_i32_e32 v189, 5, v192
	v_lshlrev_b32_e32 v188, 3, v188
	v_lshl_or_b32 v188, v189, 10, v188
	v_add_u32_e32 v188, v188, v162
	v_lshlrev_b32_e32 v188, 1, v188
	global_load_dwordx4 v[180:183], v188, s[26:27] nt
	s_add_u32 s100, s26, 0x8000
	s_addc_u32 s101, s27, 0
	global_load_dwordx4 v[184:187], v188, s[100:101] nt
	s_add_u32 s100, s26, 0x10000
	s_addc_u32 s101, s27, 0
	global_load_dwordx4 v[194:197], v188, s[100:101] nt
	s_add_u32 s100, s26, 0x18000
	s_addc_u32 s101, s27, 0
	global_load_dwordx4 v[198:201], v188, s[100:101] nt
	s_add_u32 s100, s26, 0x20000
	s_addc_u32 s101, s27, 0
	global_load_dwordx4 v[202:205], v188, s[100:101] nt
	s_add_u32 s100, s26, 0x28000
	s_addc_u32 s101, s27, 0
	global_load_dwordx4 v[206:209], v188, s[100:101] nt
	s_add_u32 s100, s26, 0x30000
	s_addc_u32 s101, s27, 0
	global_load_dwordx4 v[210:213], v188, s[100:101] nt
	s_add_u32 s100, s26, 0x38000
	s_addc_u32 s101, s27, 0
	global_load_dwordx4 v[214:217], v188, s[100:101] nt
	s_add_u32 s100, s26, 0x40000
	s_addc_u32 s101, s27, 0
	global_load_dwordx4 v[218:221], v188, s[100:101] nt
	s_add_u32 s100, s26, 0x48000
	s_addc_u32 s101, s27, 0
	global_load_dwordx4 v[222:225], v188, s[100:101] nt
	s_add_u32 s100, s26, 0x50000
	s_addc_u32 s101, s27, 0
	global_load_dwordx4 v[226:229], v188, s[100:101] nt
	s_add_u32 s100, s26, 0x58000
	s_addc_u32 s101, s27, 0
	global_load_dwordx4 v[230:233], v188, s[100:101] nt
	s_add_u32 s100, s26, 0x60000
	s_addc_u32 s101, s27, 0
	global_load_dwordx4 v[234:237], v188, s[100:101] nt
	s_add_u32 s100, s26, 0x68000
	s_addc_u32 s101, s27, 0
	global_load_dwordx4 v[238:241], v188, s[100:101] nt
	s_add_u32 s100, s26, 0x70000
	s_addc_u32 s101, s27, 0
	global_load_dwordx4 v[242:245], v188, s[100:101] nt
	s_add_u32 s100, s26, 0x78000
	s_addc_u32 s101, s27, 0
	global_load_dwordx4 v[248:251], v188, s[100:101] nt
	v_lshrrev_b32_e32 v160, 1, v163
	v_lshrrev_b32_e32 v163, 3, v163
	v_and_b32_e32 v163, 4, v163
	v_and_or_b32 v160, v160, s39, v163
	v_lshlrev_b32_e32 v160, 2, v160
	v_add_u32_e32 v163, 0x24800, v160
	v_add_u32_e32 v164, 0x24c00, v160
	v_and_b32_e32 v167, 0x37c, v168
	ds_read_b128 v[170:173], v163
	ds_read_b128 v[174:177], v164
	v_or_b32_e32 v164, 0x24000, v167
	v_or_b32_e32 v166, 0x24080, v167
	v_or_b32_e32 v165, 0x24400, v167
	ds_read_b32 v168, v164
	ds_read_b32 v169, v165
	v_or_b32_e32 v167, 0x24480, v167
	ds_read_b32 v178, v166
	ds_read_b32 v179, v167
	s_waitcnt lgkmcnt(3)
	v_fma_f32 v112, -v170, v168, v112
	v_fma_f32 v113, -v171, v168, v113
	s_waitcnt lgkmcnt(1)
	v_fma_f32 v98, -v172, v178, v98
	v_fma_f32 v114, -v172, v168, v114
	v_fma_f32 v115, -v173, v168, v115
	v_fma_f32 v96, -v170, v178, v96
	v_fma_f32 v97, -v171, v178, v97
	s_waitcnt lgkmcnt(0)
	v_fma_f32 v98, v179, v98, v176
	v_fma_f32 v99, -v173, v178, v99
	v_fma_f32 v112, v169, v112, v174
	v_fma_f32 v113, v169, v113, v175
	v_fma_f32 v114, v169, v114, v176
	v_fma_f32 v115, v169, v115, v177
	v_fma_f32 v96, v179, v96, v174
	v_fma_f32 v97, v179, v97, v175
	v_mul_f32_e32 v98, 0xbfb8aa3b, v98
	v_fmac_f32_e32 v177, v179, v99
	v_mul_f32_e32 v112, 0xbfb8aa3b, v112
	v_mul_f32_e32 v113, 0xbfb8aa3b, v113
	v_mul_f32_e32 v114, 0xbfb8aa3b, v114
	v_mul_f32_e32 v115, 0xbfb8aa3b, v115
	v_mul_f32_e32 v96, 0xbfb8aa3b, v96
	v_mul_f32_e32 v97, 0xbfb8aa3b, v97
	v_exp_f32_e32 v98, v98
	v_mul_f32_e32 v99, 0xbfb8aa3b, v177
	v_exp_f32_e32 v112, v112
	v_exp_f32_e32 v113, v113
	v_exp_f32_e32 v114, v114
	v_exp_f32_e32 v115, v115
	v_exp_f32_e32 v96, v96
	v_exp_f32_e32 v97, v97
	v_exp_f32_e32 v99, v99
	v_add_f32_e32 v98, 1.0, v98
	v_add_f32_e32 v112, 1.0, v112
	v_add_f32_e32 v113, 1.0, v113
	v_add_f32_e32 v114, 1.0, v114
	v_add_f32_e32 v115, 1.0, v115
	v_add_f32_e32 v96, 1.0, v96
	v_add_f32_e32 v97, 1.0, v97
	v_rcp_f32_e32 v168, v98
	v_add_f32_e32 v98, 1.0, v99
	v_rcp_f32_e32 v112, v112
	v_rcp_f32_e32 v113, v113
	v_rcp_f32_e32 v114, v114
	v_rcp_f32_e32 v115, v115
	v_rcp_f32_e32 v96, v96
	v_rcp_f32_e32 v97, v97
	v_rcp_f32_e32 v169, v98
	v_cvt_pk_bf16_f32 v99, v112, v113
	v_cvt_pk_bf16_f32 v98, v114, v115
	v_cvt_pk_bf16_f32 v97, v96, v97
	v_cvt_pk_bf16_f32 v96, v168, v169
	v_add_u32_e32 v112, 0x24820, v160
	v_add_u32_e32 v168, 0x24c20, v160
	ds_read_b128 v[112:115], v112
	ds_read_b128 v[168:171], v168
	ds_read_b32 v172, v164
	ds_read_b32 v173, v165
	ds_read_b32 v174, v166
	ds_read_b32 v175, v167
	s_waitcnt lgkmcnt(3)
	v_fma_f32 v116, -v112, v172, v116
	v_fma_f32 v117, -v113, v172, v117
	s_waitcnt lgkmcnt(1)
	v_fma_f32 v102, -v114, v174, v102
	v_fma_f32 v118, -v114, v172, v118
	v_fma_f32 v119, -v115, v172, v119
	v_fma_f32 v100, -v112, v174, v100
	v_fma_f32 v101, -v113, v174, v101
	s_waitcnt lgkmcnt(0)
	v_fma_f32 v102, v175, v102, v170
	v_fma_f32 v103, -v115, v174, v103
	v_fma_f32 v116, v173, v116, v168
	v_fma_f32 v117, v173, v117, v169
	v_fma_f32 v118, v173, v118, v170
	v_fma_f32 v119, v173, v119, v171
	v_fma_f32 v100, v175, v100, v168
	v_fma_f32 v101, v175, v101, v169
	v_mul_f32_e32 v102, 0xbfb8aa3b, v102
	v_fmac_f32_e32 v171, v175, v103
	v_mul_f32_e32 v116, 0xbfb8aa3b, v116
	v_mul_f32_e32 v117, 0xbfb8aa3b, v117
	v_mul_f32_e32 v118, 0xbfb8aa3b, v118
	v_mul_f32_e32 v119, 0xbfb8aa3b, v119
	v_mul_f32_e32 v100, 0xbfb8aa3b, v100
	v_mul_f32_e32 v101, 0xbfb8aa3b, v101
	v_exp_f32_e32 v102, v102
	v_mul_f32_e32 v103, 0xbfb8aa3b, v171
	v_exp_f32_e32 v116, v116
	v_exp_f32_e32 v117, v117
	v_exp_f32_e32 v118, v118
	v_exp_f32_e32 v119, v119
	v_exp_f32_e32 v100, v100
	v_exp_f32_e32 v101, v101
	v_exp_f32_e32 v103, v103
	v_add_f32_e32 v102, 1.0, v102
	v_add_f32_e32 v116, 1.0, v116
	v_add_f32_e32 v117, 1.0, v117
	v_add_f32_e32 v118, 1.0, v118
	v_add_f32_e32 v119, 1.0, v119
	v_add_f32_e32 v100, 1.0, v100
	v_add_f32_e32 v101, 1.0, v101
	v_rcp_f32_e32 v113, v102
	v_add_f32_e32 v102, 1.0, v103
	v_rcp_f32_e32 v116, v116
	v_rcp_f32_e32 v117, v117
	v_rcp_f32_e32 v118, v118
	v_rcp_f32_e32 v112, v119
	v_rcp_f32_e32 v100, v100
	v_rcp_f32_e32 v101, v101
	v_rcp_f32_e32 v114, v102
	v_cvt_pk_bf16_f32 v103, v116, v117
	v_cvt_pk_bf16_f32 v102, v118, v112
	v_cvt_pk_bf16_f32 v101, v100, v101
	v_cvt_pk_bf16_f32 v100, v113, v114
	v_add_u32_e32 v112, 0x24840, v160
	v_add_u32_e32 v116, 0x24c40, v160
	ds_read_b128 v[112:115], v112
	ds_read_b128 v[116:119], v116
	ds_read_b32 v168, v164
	ds_read_b32 v169, v165
	ds_read_b32 v170, v166
	ds_read_b32 v171, v167
	s_waitcnt lgkmcnt(3)
; DI unsigned pack2(float a, float b) { f32x2_t v = {a, b}; bf16x2_t r = __builtin_convertvector(v, bf16x2_t); return __builtin_bit_cast(unsigned, r); }
; DI float sigmoidf_(float x) { return __builtin_amdgcn_rcpf(1.f + __expf(-x)); }
; template <bool LAST>
; DI void phase_gate(const Params& P, int layer, unsigned char* smem, int L, int G) {
;     ...
;     unsigned gq[4][2][8];
; #pragma unroll
;     for (int i = 0; i < 4; ++i)
; #pragma unroll
;       for (int q4 = 0; q4 < 4; ++q4) {
;         const int fl = wm * 128 + i * 32 + 8 * q4 + 4 * h;
;         const f32x4 c1v = *(const f32x4*)(vecL + fl), c2v = *(const f32x4*)(vecL + 256 + fl);
;         const float c1a[4] = {c1v.x, c1v.y, c1v.z, c1v.w}, c2a[4] = {c2v.x, c2v.y, c2v.z, c2v.w};
; #pragma unroll
;         for (int j = 0; j < 2; ++j) {
;           const int lrow = wn * 64 + j * 32 + r;
;           const float mu = rowA[lrow], rstd = rowB[lrow];
;           float sg4[4];
; #pragma unroll
;           for (int e = 0; e < 4; ++e) sg4[e] = sigmoidf_(rstd * (accu[i][j][4 * q4 + e] - mu * c1a[e]) + c2a[e]);
;           gq[i][j][2 * q4] = pack2(sg4[0], sg4[1]); gq[i][j][2 * q4 + 1] = pack2(sg4[2], sg4[3]);
;         }
;         __builtin_amdgcn_sched_barrier(0);
;       }
	v_fma_f32 v120, -v112, v168, v120
	v_fma_f32 v121, -v113, v168, v121
	s_waitcnt lgkmcnt(1)
	v_fma_f32 v106, -v114, v170, v106
	v_fma_f32 v122, -v114, v168, v122
	v_fma_f32 v123, -v115, v168, v123
	v_fma_f32 v104, -v112, v170, v104
	v_fma_f32 v105, -v113, v170, v105
	s_waitcnt lgkmcnt(0)
	v_fma_f32 v106, v171, v106, v118
	v_fma_f32 v107, -v115, v170, v107
	v_fma_f32 v120, v169, v120, v116
	v_fma_f32 v121, v169, v121, v117
	v_fma_f32 v122, v169, v122, v118
	v_fma_f32 v123, v169, v123, v119
	v_fma_f32 v104, v171, v104, v116
	v_fma_f32 v105, v171, v105, v117
	v_mul_f32_e32 v106, 0xbfb8aa3b, v106
	v_fmac_f32_e32 v119, v171, v107
	v_mul_f32_e32 v120, 0xbfb8aa3b, v120
	v_mul_f32_e32 v121, 0xbfb8aa3b, v121
	v_mul_f32_e32 v122, 0xbfb8aa3b, v122
	v_mul_f32_e32 v123, 0xbfb8aa3b, v123
	v_mul_f32_e32 v104, 0xbfb8aa3b, v104
	v_mul_f32_e32 v105, 0xbfb8aa3b, v105
	v_exp_f32_e32 v106, v106
	v_mul_f32_e32 v107, 0xbfb8aa3b, v119
	v_exp_f32_e32 v120, v120
	v_exp_f32_e32 v121, v121
	v_exp_f32_e32 v122, v122
	v_exp_f32_e32 v123, v123
	v_exp_f32_e32 v104, v104
	v_exp_f32_e32 v105, v105
	v_exp_f32_e32 v107, v107
	v_add_f32_e32 v106, 1.0, v106
	v_add_f32_e32 v120, 1.0, v120
	v_add_f32_e32 v121, 1.0, v121
	v_add_f32_e32 v122, 1.0, v122
	v_add_f32_e32 v123, 1.0, v123
	v_add_f32_e32 v104, 1.0, v104
	v_add_f32_e32 v105, 1.0, v105
	v_rcp_f32_e32 v113, v106
	v_add_f32_e32 v106, 1.0, v107
	v_rcp_f32_e32 v120, v120
	v_rcp_f32_e32 v121, v121
	v_rcp_f32_e32 v122, v122
	v_rcp_f32_e32 v112, v123
	v_rcp_f32_e32 v104, v104
	v_rcp_f32_e32 v105, v105
	v_rcp_f32_e32 v114, v106
	v_cvt_pk_bf16_f32 v107, v120, v121
	v_cvt_pk_bf16_f32 v106, v122, v112
	v_cvt_pk_bf16_f32 v105, v104, v105
	v_cvt_pk_bf16_f32 v104, v113, v114
	v_add_u32_e32 v112, 0x24860, v160
	v_add_u32_e32 v116, 0x24c60, v160
	ds_read_b128 v[112:115], v112
	ds_read_b128 v[116:119], v116
	ds_read_b32 v120, v164
	ds_read_b32 v121, v165
	ds_read_b32 v122, v166
	ds_read_b32 v123, v167
	s_waitcnt lgkmcnt(3)
	v_fma_f32 v125, -v113, v120, v125
	v_fma_f32 v124, -v112, v120, v124
	s_waitcnt lgkmcnt(1)
	v_fma_f32 v110, -v114, v122, v110
	v_fma_f32 v125, v121, v125, v117
	v_fma_f32 v126, -v114, v120, v126
	v_fma_f32 v120, -v115, v120, v127
	v_fma_f32 v108, -v112, v122, v108
	v_fma_f32 v109, -v113, v122, v109
	s_waitcnt lgkmcnt(0)
	v_fma_f32 v110, v123, v110, v118
	v_fma_f32 v111, -v115, v122, v111
	v_fma_f32 v124, v121, v124, v116
	v_mul_f32_e32 v125, 0xbfb8aa3b, v125
	v_fma_f32 v126, v121, v126, v118
	v_fma_f32 v120, v121, v120, v119
	v_fma_f32 v108, v123, v108, v116
	v_fma_f32 v109, v123, v109, v117
	v_mul_f32_e32 v110, 0xbfb8aa3b, v110
	v_fmac_f32_e32 v119, v123, v111
	v_mul_f32_e32 v124, 0xbfb8aa3b, v124
	v_exp_f32_e32 v125, v125
	v_mul_f32_e32 v126, 0xbfb8aa3b, v126
	v_mul_f32_e32 v120, 0xbfb8aa3b, v120
	v_mul_f32_e32 v108, 0xbfb8aa3b, v108
	v_mul_f32_e32 v109, 0xbfb8aa3b, v109
	v_exp_f32_e32 v110, v110
	v_mul_f32_e32 v111, 0xbfb8aa3b, v119
	v_exp_f32_e32 v124, v124
	v_exp_f32_e32 v126, v126
	v_exp_f32_e32 v120, v120
	v_exp_f32_e32 v108, v108
	v_exp_f32_e32 v109, v109
	v_exp_f32_e32 v111, v111
	v_add_f32_e32 v125, 1.0, v125
	v_add_f32_e32 v110, 1.0, v110
	v_add_f32_e32 v124, 1.0, v124
	v_rcp_f32_e32 v121, v125
	v_add_f32_e32 v125, 1.0, v126
	v_add_f32_e32 v120, 1.0, v120
	v_add_f32_e32 v108, 1.0, v108
	v_add_f32_e32 v109, 1.0, v109
	v_rcp_f32_e32 v113, v110
	v_add_f32_e32 v110, 1.0, v111
	v_rcp_f32_e32 v124, v124
	v_rcp_f32_e32 v125, v125
	v_rcp_f32_e32 v112, v120
	v_rcp_f32_e32 v108, v108
	v_rcp_f32_e32 v109, v109
	v_rcp_f32_e32 v114, v110
	v_cvt_pk_bf16_f32 v111, v124, v121
	v_cvt_pk_bf16_f32 v110, v125, v112
	v_cvt_pk_bf16_f32 v109, v108, v109
	v_cvt_pk_bf16_f32 v108, v113, v114
	v_add_u32_e32 v112, 0x24880, v160
	v_add_u32_e32 v116, 0x24c80, v160
	ds_read_b128 v[112:115], v112
	ds_read_b128 v[116:119], v116
	ds_read_b32 v120, v164
	ds_read_b32 v121, v165
	ds_read_b32 v122, v166
	ds_read_b32 v123, v167
	s_waitcnt lgkmcnt(3)
	v_fma_f32 v80, -v112, v120, v80
	v_fma_f32 v81, -v113, v120, v81
	s_waitcnt lgkmcnt(1)
	v_fma_f32 v66, -v114, v122, v66
	v_fma_f32 v82, -v114, v120, v82
	v_fma_f32 v83, -v115, v120, v83
	v_fma_f32 v64, -v112, v122, v64
	v_fma_f32 v65, -v113, v122, v65
	s_waitcnt lgkmcnt(0)
	v_fma_f32 v66, v123, v66, v118
	v_fma_f32 v67, -v115, v122, v67
	v_fma_f32 v80, v121, v80, v116
	v_fma_f32 v81, v121, v81, v117
	v_fma_f32 v82, v121, v82, v118
	v_fma_f32 v83, v121, v83, v119
	v_fma_f32 v64, v123, v64, v116
	v_fma_f32 v65, v123, v65, v117
	v_mul_f32_e32 v66, 0xbfb8aa3b, v66
	v_fmac_f32_e32 v119, v123, v67
	v_mul_f32_e32 v80, 0xbfb8aa3b, v80
	v_mul_f32_e32 v81, 0xbfb8aa3b, v81
	v_mul_f32_e32 v82, 0xbfb8aa3b, v82
	v_mul_f32_e32 v83, 0xbfb8aa3b, v83
	v_mul_f32_e32 v64, 0xbfb8aa3b, v64
	v_mul_f32_e32 v65, 0xbfb8aa3b, v65
	v_exp_f32_e32 v66, v66
	v_mul_f32_e32 v67, 0xbfb8aa3b, v119
	v_exp_f32_e32 v80, v80
	v_exp_f32_e32 v81, v81
	v_exp_f32_e32 v82, v82
	v_exp_f32_e32 v83, v83
	v_exp_f32_e32 v64, v64
	v_exp_f32_e32 v65, v65
	v_exp_f32_e32 v67, v67
	v_add_f32_e32 v66, 1.0, v66
	v_add_f32_e32 v80, 1.0, v80
	v_add_f32_e32 v81, 1.0, v81
	v_add_f32_e32 v82, 1.0, v82
	v_add_f32_e32 v83, 1.0, v83
	v_add_f32_e32 v64, 1.0, v64
	v_add_f32_e32 v65, 1.0, v65
	v_rcp_f32_e32 v112, v66
	v_add_f32_e32 v66, 1.0, v67
	v_rcp_f32_e32 v80, v80
	v_rcp_f32_e32 v81, v81
	v_rcp_f32_e32 v82, v82
	v_rcp_f32_e32 v83, v83
	v_rcp_f32_e32 v64, v64
	v_rcp_f32_e32 v65, v65
	v_rcp_f32_e32 v113, v66
	v_cvt_pk_bf16_f32 v67, v80, v81
	v_cvt_pk_bf16_f32 v66, v82, v83
	v_cvt_pk_bf16_f32 v65, v64, v65
	v_cvt_pk_bf16_f32 v64, v112, v113
	v_add_u32_e32 v80, 0x248a0, v160
	v_add_u32_e32 v112, 0x24ca0, v160
	ds_read_b128 v[80:83], v80
	ds_read_b128 v[112:115], v112
	ds_read_b32 v116, v164
	ds_read_b32 v117, v165
	ds_read_b32 v118, v166
	ds_read_b32 v119, v167
	s_waitcnt lgkmcnt(3)
; DI unsigned pack2(float a, float b) { f32x2_t v = {a, b}; bf16x2_t r = __builtin_convertvector(v, bf16x2_t); return __builtin_bit_cast(unsigned, r); }
; DI float sigmoidf_(float x) { return __builtin_amdgcn_rcpf(1.f + __expf(-x)); }
; template <bool LAST>
; DI void phase_gate(const Params& P, int layer, unsigned char* smem, int L, int G) {
;     ...
;     unsigned gq[4][2][8];
; #pragma unroll
;     for (int i = 0; i < 4; ++i)
; #pragma unroll
;       for (int q4 = 0; q4 < 4; ++q4) {
;         const int fl = wm * 128 + i * 32 + 8 * q4 + 4 * h;
;         const f32x4 c1v = *(const f32x4*)(vecL + fl), c2v = *(const f32x4*)(vecL + 256 + fl);
;         const float c1a[4] = {c1v.x, c1v.y, c1v.z, c1v.w}, c2a[4] = {c2v.x, c2v.y, c2v.z, c2v.w};
; #pragma unroll
;         for (int j = 0; j < 2; ++j) {
;           const int lrow = wn * 64 + j * 32 + r;
;           const float mu = rowA[lrow], rstd = rowB[lrow];
;           float sg4[4];
; #pragma unroll
;           for (int e = 0; e < 4; ++e) sg4[e] = sigmoidf_(rstd * (accu[i][j][4 * q4 + e] - mu * c1a[e]) + c2a[e]);
;           gq[i][j][2 * q4] = pack2(sg4[0], sg4[1]); gq[i][j][2 * q4 + 1] = pack2(sg4[2], sg4[3]);
;         }
;         __builtin_amdgcn_sched_barrier(0);
;       }
	v_fma_f32 v84, -v80, v116, v84
	v_fma_f32 v85, -v81, v116, v85
	s_waitcnt lgkmcnt(1)
	v_fma_f32 v70, -v82, v118, v70
	v_fma_f32 v86, -v82, v116, v86
	v_fma_f32 v87, -v83, v116, v87
	v_fma_f32 v68, -v80, v118, v68
	v_fma_f32 v69, -v81, v118, v69
	s_waitcnt lgkmcnt(0)
	v_fma_f32 v70, v119, v70, v114
	v_fma_f32 v71, -v83, v118, v71
	v_fma_f32 v84, v117, v84, v112
	v_fma_f32 v85, v117, v85, v113
	v_fma_f32 v86, v117, v86, v114
	v_fma_f32 v87, v117, v87, v115
	v_fma_f32 v68, v119, v68, v112
	v_fma_f32 v69, v119, v69, v113
	v_mul_f32_e32 v70, 0xbfb8aa3b, v70
	v_fmac_f32_e32 v115, v119, v71
	v_mul_f32_e32 v84, 0xbfb8aa3b, v84
	v_mul_f32_e32 v85, 0xbfb8aa3b, v85
	v_mul_f32_e32 v86, 0xbfb8aa3b, v86
	v_mul_f32_e32 v87, 0xbfb8aa3b, v87
	v_mul_f32_e32 v68, 0xbfb8aa3b, v68
	v_mul_f32_e32 v69, 0xbfb8aa3b, v69
	v_exp_f32_e32 v70, v70
	v_mul_f32_e32 v71, 0xbfb8aa3b, v115
	v_exp_f32_e32 v84, v84
	v_exp_f32_e32 v85, v85
	v_exp_f32_e32 v86, v86
	v_exp_f32_e32 v87, v87
	v_exp_f32_e32 v68, v68
	v_exp_f32_e32 v69, v69
	v_exp_f32_e32 v71, v71
	v_add_f32_e32 v70, 1.0, v70
	v_add_f32_e32 v84, 1.0, v84
	v_add_f32_e32 v85, 1.0, v85
	v_add_f32_e32 v86, 1.0, v86
	v_add_f32_e32 v87, 1.0, v87
	v_add_f32_e32 v68, 1.0, v68
	v_add_f32_e32 v69, 1.0, v69
	v_rcp_f32_e32 v81, v70
	v_add_f32_e32 v70, 1.0, v71
	v_rcp_f32_e32 v84, v84
	v_rcp_f32_e32 v85, v85
	v_rcp_f32_e32 v86, v86
	v_rcp_f32_e32 v80, v87
	v_rcp_f32_e32 v68, v68
	v_rcp_f32_e32 v69, v69
	v_rcp_f32_e32 v82, v70
	v_cvt_pk_bf16_f32 v71, v84, v85
	v_cvt_pk_bf16_f32 v70, v86, v80
	v_cvt_pk_bf16_f32 v69, v68, v69
	v_cvt_pk_bf16_f32 v68, v81, v82
	v_add_u32_e32 v80, 0x248c0, v160
	v_add_u32_e32 v84, 0x24cc0, v160
	ds_read_b128 v[80:83], v80
	ds_read_b128 v[84:87], v84
	ds_read_b32 v112, v164
	ds_read_b32 v113, v165
	ds_read_b32 v114, v166
	ds_read_b32 v115, v167
	s_waitcnt lgkmcnt(3)
	v_fma_f32 v88, -v80, v112, v88
	v_fma_f32 v89, -v81, v112, v89
	s_waitcnt lgkmcnt(1)
	v_fma_f32 v74, -v82, v114, v74
	v_fma_f32 v90, -v82, v112, v90
	v_fma_f32 v91, -v83, v112, v91
	v_fma_f32 v72, -v80, v114, v72
	v_fma_f32 v73, -v81, v114, v73
	s_waitcnt lgkmcnt(0)
	v_fma_f32 v74, v115, v74, v86
	v_fma_f32 v75, -v83, v114, v75
	v_fma_f32 v88, v113, v88, v84
	v_fma_f32 v89, v113, v89, v85
	v_fma_f32 v90, v113, v90, v86
	v_fma_f32 v91, v113, v91, v87
	v_fma_f32 v72, v115, v72, v84
	v_fma_f32 v73, v115, v73, v85
	v_mul_f32_e32 v74, 0xbfb8aa3b, v74
	v_fmac_f32_e32 v87, v115, v75
	v_mul_f32_e32 v88, 0xbfb8aa3b, v88
	v_mul_f32_e32 v89, 0xbfb8aa3b, v89
	v_mul_f32_e32 v90, 0xbfb8aa3b, v90
	v_mul_f32_e32 v91, 0xbfb8aa3b, v91
	v_mul_f32_e32 v72, 0xbfb8aa3b, v72
	v_mul_f32_e32 v73, 0xbfb8aa3b, v73
	v_exp_f32_e32 v74, v74
	v_mul_f32_e32 v75, 0xbfb8aa3b, v87
	v_exp_f32_e32 v88, v88
	v_exp_f32_e32 v89, v89
	v_exp_f32_e32 v90, v90
	v_exp_f32_e32 v91, v91
	v_exp_f32_e32 v72, v72
	v_exp_f32_e32 v73, v73
	v_exp_f32_e32 v75, v75
	v_add_f32_e32 v74, 1.0, v74
	v_add_f32_e32 v88, 1.0, v88
	v_add_f32_e32 v89, 1.0, v89
	v_add_f32_e32 v90, 1.0, v90
	v_add_f32_e32 v91, 1.0, v91
	v_add_f32_e32 v72, 1.0, v72
	v_add_f32_e32 v73, 1.0, v73
	v_rcp_f32_e32 v81, v74
	v_add_f32_e32 v74, 1.0, v75
	v_rcp_f32_e32 v88, v88
	v_rcp_f32_e32 v89, v89
	v_rcp_f32_e32 v90, v90
	v_rcp_f32_e32 v80, v91
	v_rcp_f32_e32 v72, v72
	v_rcp_f32_e32 v73, v73
	v_rcp_f32_e32 v82, v74
	v_cvt_pk_bf16_f32 v75, v88, v89
	v_cvt_pk_bf16_f32 v74, v90, v80
	v_cvt_pk_bf16_f32 v73, v72, v73
	v_cvt_pk_bf16_f32 v72, v81, v82
	v_add_u32_e32 v80, 0x248e0, v160
	v_add_u32_e32 v84, 0x24ce0, v160
	ds_read_b128 v[80:83], v80
	ds_read_b128 v[84:87], v84
	ds_read_b32 v88, v164
	ds_read_b32 v89, v165
	ds_read_b32 v90, v166
	ds_read_b32 v91, v167
	s_waitcnt lgkmcnt(3)
	v_fma_f32 v93, -v81, v88, v93
	v_fma_f32 v92, -v80, v88, v92
	s_waitcnt lgkmcnt(1)
	v_fma_f32 v78, -v82, v90, v78
	v_fma_f32 v93, v89, v93, v85
	v_fma_f32 v94, -v82, v88, v94
	v_fma_f32 v88, -v83, v88, v95
	v_fma_f32 v76, -v80, v90, v76
	v_fma_f32 v77, -v81, v90, v77
	s_waitcnt lgkmcnt(0)
	v_fma_f32 v78, v91, v78, v86
	v_fma_f32 v79, -v83, v90, v79
	v_fma_f32 v92, v89, v92, v84
	v_mul_f32_e32 v93, 0xbfb8aa3b, v93
	v_fma_f32 v94, v89, v94, v86
	v_fma_f32 v88, v89, v88, v87
	v_fma_f32 v76, v91, v76, v84
	v_fma_f32 v77, v91, v77, v85
	v_mul_f32_e32 v78, 0xbfb8aa3b, v78
	v_fmac_f32_e32 v87, v91, v79
	v_mul_f32_e32 v92, 0xbfb8aa3b, v92
	v_exp_f32_e32 v93, v93
	v_mul_f32_e32 v94, 0xbfb8aa3b, v94
	v_mul_f32_e32 v88, 0xbfb8aa3b, v88
	v_mul_f32_e32 v76, 0xbfb8aa3b, v76
	v_mul_f32_e32 v77, 0xbfb8aa3b, v77
	v_exp_f32_e32 v78, v78
	v_mul_f32_e32 v79, 0xbfb8aa3b, v87
	v_exp_f32_e32 v92, v92
	v_exp_f32_e32 v94, v94
	v_exp_f32_e32 v88, v88
	v_exp_f32_e32 v76, v76
	v_exp_f32_e32 v77, v77
	v_exp_f32_e32 v79, v79
	v_add_f32_e32 v93, 1.0, v93
	v_add_f32_e32 v78, 1.0, v78
	v_add_f32_e32 v92, 1.0, v92
	v_rcp_f32_e32 v89, v93
	v_add_f32_e32 v93, 1.0, v94
	v_add_f32_e32 v88, 1.0, v88
	v_add_f32_e32 v76, 1.0, v76
	v_add_f32_e32 v77, 1.0, v77
	v_rcp_f32_e32 v81, v78
	v_add_f32_e32 v78, 1.0, v79
	v_rcp_f32_e32 v92, v92
	v_rcp_f32_e32 v93, v93
	v_rcp_f32_e32 v80, v88
	v_rcp_f32_e32 v76, v76
	v_rcp_f32_e32 v77, v77
	v_rcp_f32_e32 v82, v78
	v_cvt_pk_bf16_f32 v79, v92, v89
	v_cvt_pk_bf16_f32 v78, v93, v80
	v_cvt_pk_bf16_f32 v77, v76, v77
	v_cvt_pk_bf16_f32 v76, v81, v82
	v_add_u32_e32 v80, 0x24900, v160
	v_add_u32_e32 v84, 0x24d00, v160
	ds_read_b128 v[80:83], v80
	ds_read_b128 v[84:87], v84
	ds_read_b32 v88, v164
	ds_read_b32 v89, v165
	ds_read_b32 v90, v166
	ds_read_b32 v91, v167
	s_waitcnt lgkmcnt(3)
	v_fma_f32 v48, -v80, v88, v48
	v_fma_f32 v49, -v81, v88, v49
	s_waitcnt lgkmcnt(1)
	v_fma_f32 v34, -v82, v90, v34
	v_fma_f32 v50, -v82, v88, v50
	v_fma_f32 v51, -v83, v88, v51
	v_fma_f32 v32, -v80, v90, v32
	v_fma_f32 v33, -v81, v90, v33
	s_waitcnt lgkmcnt(0)
; DI unsigned pack2(float a, float b) { f32x2_t v = {a, b}; bf16x2_t r = __builtin_convertvector(v, bf16x2_t); return __builtin_bit_cast(unsigned, r); }
; DI float sigmoidf_(float x) { return __builtin_amdgcn_rcpf(1.f + __expf(-x)); }
; template <bool LAST>
; DI void phase_gate(const Params& P, int layer, unsigned char* smem, int L, int G) {
;     ...
;     unsigned gq[4][2][8];
; #pragma unroll
;     for (int i = 0; i < 4; ++i)
; #pragma unroll
;       for (int q4 = 0; q4 < 4; ++q4) {
;         const int fl = wm * 128 + i * 32 + 8 * q4 + 4 * h;
;         const f32x4 c1v = *(const f32x4*)(vecL + fl), c2v = *(const f32x4*)(vecL + 256 + fl);
;         const float c1a[4] = {c1v.x, c1v.y, c1v.z, c1v.w}, c2a[4] = {c2v.x, c2v.y, c2v.z, c2v.w};
; #pragma unroll
;         for (int j = 0; j < 2; ++j) {
;           const int lrow = wn * 64 + j * 32 + r;
;           const float mu = rowA[lrow], rstd = rowB[lrow];
;           float sg4[4];
; #pragma unroll
;           for (int e = 0; e < 4; ++e) sg4[e] = sigmoidf_(rstd * (accu[i][j][4 * q4 + e] - mu * c1a[e]) + c2a[e]);
;           gq[i][j][2 * q4] = pack2(sg4[0], sg4[1]); gq[i][j][2 * q4 + 1] = pack2(sg4[2], sg4[3]);
;         }
;         __builtin_amdgcn_sched_barrier(0);
;       }
	v_fma_f32 v34, v91, v34, v86
	v_fma_f32 v35, -v83, v90, v35
	v_fma_f32 v48, v89, v48, v84
	v_fma_f32 v49, v89, v49, v85
	v_fma_f32 v50, v89, v50, v86
	v_fma_f32 v51, v89, v51, v87
	v_fma_f32 v32, v91, v32, v84
	v_fma_f32 v33, v91, v33, v85
	v_mul_f32_e32 v34, 0xbfb8aa3b, v34
	v_fmac_f32_e32 v87, v91, v35
	v_mul_f32_e32 v48, 0xbfb8aa3b, v48
	v_mul_f32_e32 v49, 0xbfb8aa3b, v49
	v_mul_f32_e32 v50, 0xbfb8aa3b, v50
	v_mul_f32_e32 v51, 0xbfb8aa3b, v51
	v_mul_f32_e32 v32, 0xbfb8aa3b, v32
	v_mul_f32_e32 v33, 0xbfb8aa3b, v33
	v_exp_f32_e32 v34, v34
	v_mul_f32_e32 v35, 0xbfb8aa3b, v87
	v_exp_f32_e32 v48, v48
	v_exp_f32_e32 v49, v49
	v_exp_f32_e32 v50, v50
	v_exp_f32_e32 v51, v51
	v_exp_f32_e32 v32, v32
	v_exp_f32_e32 v33, v33
	v_exp_f32_e32 v35, v35
	v_add_f32_e32 v34, 1.0, v34
	v_add_f32_e32 v48, 1.0, v48
	v_add_f32_e32 v49, 1.0, v49
	v_add_f32_e32 v50, 1.0, v50
	v_add_f32_e32 v51, 1.0, v51
	v_add_f32_e32 v32, 1.0, v32
	v_add_f32_e32 v33, 1.0, v33
	v_rcp_f32_e32 v80, v34
	v_add_f32_e32 v34, 1.0, v35
	v_rcp_f32_e32 v48, v48
	v_rcp_f32_e32 v49, v49
	v_rcp_f32_e32 v50, v50
	v_rcp_f32_e32 v51, v51
	v_rcp_f32_e32 v32, v32
	v_rcp_f32_e32 v33, v33
	v_rcp_f32_e32 v81, v34
	v_cvt_pk_bf16_f32 v35, v48, v49
	v_cvt_pk_bf16_f32 v34, v50, v51
	v_cvt_pk_bf16_f32 v33, v32, v33
	v_cvt_pk_bf16_f32 v32, v80, v81
	v_add_u32_e32 v48, 0x24920, v160
	v_add_u32_e32 v80, 0x24d20, v160
	ds_read_b128 v[48:51], v48
	ds_read_b128 v[80:83], v80
	ds_read_b32 v84, v164
	ds_read_b32 v85, v165
	ds_read_b32 v86, v166
	ds_read_b32 v87, v167
	s_waitcnt lgkmcnt(3)
	v_fma_f32 v53, -v49, v84, v53
	v_fma_f32 v52, -v48, v84, v52
	s_waitcnt lgkmcnt(1)
	v_fma_f32 v36, -v48, v86, v36
	s_waitcnt lgkmcnt(0)
	v_fma_f32 v36, v87, v36, v80
	v_fma_f32 v37, -v49, v86, v37
	v_mul_f32_e32 v36, 0xbfb8aa3b, v36
	v_fma_f32 v37, v87, v37, v81
	v_exp_f32_e32 v36, v36
	v_mul_f32_e32 v37, 0xbfb8aa3b, v37
	v_exp_f32_e32 v37, v37
	v_fma_f32 v54, -v50, v84, v54
	v_add_f32_e32 v36, 1.0, v36
	v_rcp_f32_e32 v49, v36
	v_add_f32_e32 v36, 1.0, v37
	v_fma_f32 v37, -v50, v86, v38
	v_fma_f32 v55, -v51, v84, v55
	v_fma_f32 v37, v87, v37, v82
	v_fma_f32 v38, -v51, v86, v39
	v_fma_f32 v52, v85, v52, v80
	v_fma_f32 v53, v85, v53, v81
	v_fma_f32 v54, v85, v54, v82
	v_fma_f32 v55, v85, v55, v83
	v_mul_f32_e32 v37, 0xbfb8aa3b, v37
	v_fmac_f32_e32 v83, v87, v38
	v_mul_f32_e32 v52, 0xbfb8aa3b, v52
	v_mul_f32_e32 v53, 0xbfb8aa3b, v53
	v_mul_f32_e32 v54, 0xbfb8aa3b, v54
	v_mul_f32_e32 v55, 0xbfb8aa3b, v55
	v_exp_f32_e32 v37, v37
	v_mul_f32_e32 v38, 0xbfb8aa3b, v83
	v_exp_f32_e32 v52, v52
	v_exp_f32_e32 v53, v53
	v_exp_f32_e32 v54, v54
	v_exp_f32_e32 v55, v55
	v_exp_f32_e32 v38, v38
	v_rcp_f32_e32 v39, v36
	v_add_f32_e32 v36, 1.0, v37
	v_add_f32_e32 v52, 1.0, v52
	v_add_f32_e32 v53, 1.0, v53
	v_add_f32_e32 v54, 1.0, v54
	v_add_f32_e32 v55, 1.0, v55
	v_rcp_f32_e32 v37, v36
	v_add_f32_e32 v36, 1.0, v38
	v_rcp_f32_e32 v52, v52
	v_rcp_f32_e32 v53, v53
	v_rcp_f32_e32 v54, v54
	v_rcp_f32_e32 v48, v55
	v_rcp_f32_e32 v38, v36
	v_cvt_pk_bf16_f32 v80, v52, v53
	v_cvt_pk_bf16_f32 v55, v49, v39
	v_cvt_pk_bf16_f32 v36, v54, v48
	v_cvt_pk_bf16_f32 v53, v37, v38
	v_add_u32_e32 v37, 0x24940, v160
	v_add_u32_e32 v38, 0x24d40, v160
	ds_read_b128 v[48:51], v37
	ds_read_b128 v[82:85], v38
	ds_read_b32 v37, v164
	ds_read_b32 v38, v165
	ds_read_b32 v39, v166
	ds_read_b32 v52, v167
	s_waitcnt lgkmcnt(3)
	v_fma_f32 v54, -v48, v37, v56
	v_fma_f32 v56, -v49, v37, v57
	s_waitcnt lgkmcnt(2)
	v_fma_f32 v56, v38, v56, v83
	v_fma_f32 v57, -v50, v37, v58
	v_fma_f32 v37, -v51, v37, v59
	s_waitcnt lgkmcnt(1)
	v_fma_f32 v40, -v48, v39, v40
	v_fma_f32 v41, -v49, v39, v41
	v_fma_f32 v42, -v50, v39, v42
	v_fma_f32 v39, -v51, v39, v43
	v_fma_f32 v54, v38, v54, v82
	v_mul_f32_e32 v56, 0xbfb8aa3b, v56
	v_fma_f32 v57, v38, v57, v84
	v_fma_f32 v37, v38, v37, v85
	s_waitcnt lgkmcnt(0)
	v_fma_f32 v40, v52, v40, v82
	v_fma_f32 v41, v52, v41, v83
	v_fma_f32 v42, v52, v42, v84
	v_fmac_f32_e32 v85, v52, v39
	v_mul_f32_e32 v54, 0xbfb8aa3b, v54
	v_exp_f32_e32 v56, v56
	v_mul_f32_e32 v57, 0xbfb8aa3b, v57
	v_mul_f32_e32 v37, 0xbfb8aa3b, v37
	v_mul_f32_e32 v40, 0xbfb8aa3b, v40
	v_mul_f32_e32 v41, 0xbfb8aa3b, v41
	v_mul_f32_e32 v42, 0xbfb8aa3b, v42
	v_mul_f32_e32 v39, 0xbfb8aa3b, v85
	v_exp_f32_e32 v54, v54
	v_exp_f32_e32 v57, v57
	v_exp_f32_e32 v37, v37
	v_exp_f32_e32 v40, v40
	v_exp_f32_e32 v41, v41
	v_exp_f32_e32 v42, v42
	v_exp_f32_e32 v39, v39
	v_add_f32_e32 v56, 1.0, v56
	v_add_f32_e32 v54, 1.0, v54
	v_rcp_f32_e32 v38, v56
	v_add_f32_e32 v56, 1.0, v57
	v_add_f32_e32 v37, 1.0, v37
	v_add_f32_e32 v40, 1.0, v40
	v_add_f32_e32 v41, 1.0, v41
	v_add_f32_e32 v42, 1.0, v42
	v_add_f32_e32 v39, 1.0, v39
	v_rcp_f32_e32 v54, v54
	v_rcp_f32_e32 v56, v56
	v_rcp_f32_e32 v37, v37
	v_rcp_f32_e32 v40, v40
	v_rcp_f32_e32 v41, v41
	v_rcp_f32_e32 v42, v42
	v_rcp_f32_e32 v39, v39
	v_cvt_pk_bf16_f32 v83, v54, v38
	v_cvt_pk_bf16_f32 v82, v56, v37
	v_cvt_pk_bf16_f32 v81, v40, v41
	v_cvt_pk_bf16_f32 v59, v42, v39
	v_add_u32_e32 v37, 0x24960, v160
	v_add_u32_e32 v42, 0x24d60, v160
	ds_read_b128 v[38:41], v37
	ds_read_b128 v[48:51], v42
	ds_read_b32 v37, v164
	ds_read_b32 v42, v165
	ds_read_b32 v43, v166
	ds_read_b32 v52, v167
	s_waitcnt lgkmcnt(3)
	v_fma_f32 v56, -v39, v37, v61
	v_fma_f32 v54, -v38, v37, v60
	s_waitcnt lgkmcnt(2)
	v_fma_f32 v56, v42, v56, v49
	v_fma_f32 v57, -v40, v37, v62
	v_fma_f32 v37, -v41, v37, v63
	s_waitcnt lgkmcnt(1)
	v_fma_f32 v38, -v38, v43, v44
	v_fma_f32 v39, -v39, v43, v45
	v_fma_f32 v40, -v40, v43, v46
	v_fma_f32 v41, -v41, v43, v47
	v_fma_f32 v54, v42, v54, v48
	v_mul_f32_e32 v56, 0xbfb8aa3b, v56
	v_fma_f32 v57, v42, v57, v50
	v_fma_f32 v37, v42, v37, v51
	s_waitcnt lgkmcnt(0)
; DI unsigned pack2(float a, float b) { f32x2_t v = {a, b}; bf16x2_t r = __builtin_convertvector(v, bf16x2_t); return __builtin_bit_cast(unsigned, r); }
; DI float sigmoidf_(float x) { return __builtin_amdgcn_rcpf(1.f + __expf(-x)); }
; template <bool LAST>
; DI void phase_gate(const Params& P, int layer, unsigned char* smem, int L, int G) {
;     ...
;     unsigned gq[4][2][8];
; #pragma unroll
;     for (int i = 0; i < 4; ++i)
; #pragma unroll
;       for (int q4 = 0; q4 < 4; ++q4) {
;         const int fl = wm * 128 + i * 32 + 8 * q4 + 4 * h;
;         const f32x4 c1v = *(const f32x4*)(vecL + fl), c2v = *(const f32x4*)(vecL + 256 + fl);
;         const float c1a[4] = {c1v.x, c1v.y, c1v.z, c1v.w}, c2a[4] = {c2v.x, c2v.y, c2v.z, c2v.w};
; #pragma unroll
;         for (int j = 0; j < 2; ++j) {
;           const int lrow = wn * 64 + j * 32 + r;
;           const float mu = rowA[lrow], rstd = rowB[lrow];
;           float sg4[4];
; #pragma unroll
;           for (int e = 0; e < 4; ++e) sg4[e] = sigmoidf_(rstd * (accu[i][j][4 * q4 + e] - mu * c1a[e]) + c2a[e]);
;           gq[i][j][2 * q4] = pack2(sg4[0], sg4[1]); gq[i][j][2 * q4 + 1] = pack2(sg4[2], sg4[3]);
;         }
;         __builtin_amdgcn_sched_barrier(0);
;       }
	v_fma_f32 v38, v52, v38, v48
	v_fma_f32 v39, v52, v39, v49
	v_fma_f32 v40, v52, v40, v50
	v_fmac_f32_e32 v51, v52, v41
	v_mul_f32_e32 v54, 0xbfb8aa3b, v54
	v_exp_f32_e32 v56, v56
	v_mul_f32_e32 v57, 0xbfb8aa3b, v57
	v_mul_f32_e32 v37, 0xbfb8aa3b, v37
	v_mul_f32_e32 v38, 0xbfb8aa3b, v38
	v_mul_f32_e32 v39, 0xbfb8aa3b, v39
	v_mul_f32_e32 v40, 0xbfb8aa3b, v40
	v_mul_f32_e32 v41, 0xbfb8aa3b, v51
	v_exp_f32_e32 v54, v54
	v_exp_f32_e32 v57, v57
	v_exp_f32_e32 v37, v37
	v_exp_f32_e32 v38, v38
	v_exp_f32_e32 v39, v39
	v_exp_f32_e32 v40, v40
	v_exp_f32_e32 v41, v41
	v_add_f32_e32 v56, 1.0, v56
	v_add_f32_e32 v54, 1.0, v54
	v_rcp_f32_e32 v42, v56
	v_add_f32_e32 v56, 1.0, v57
	v_add_f32_e32 v37, 1.0, v37
	v_add_f32_e32 v38, 1.0, v38
	v_add_f32_e32 v39, 1.0, v39
	v_add_f32_e32 v40, 1.0, v40
	v_add_f32_e32 v41, 1.0, v41
	v_rcp_f32_e32 v54, v54
	v_rcp_f32_e32 v56, v56
	v_rcp_f32_e32 v37, v37
	v_rcp_f32_e32 v38, v38
	v_rcp_f32_e32 v39, v39
	v_rcp_f32_e32 v40, v40
	v_rcp_f32_e32 v41, v41
	v_cvt_pk_bf16_f32 v91, v54, v42
	v_cvt_pk_bf16_f32 v86, v56, v37
	v_cvt_pk_bf16_f32 v85, v38, v39
	v_cvt_pk_bf16_f32 v84, v40, v41
	v_add_u32_e32 v37, 0x24980, v160
	v_add_u32_e32 v42, 0x24d80, v160
	ds_read_b128 v[38:41], v37
	ds_read_b128 v[42:45], v42
	ds_read_b32 v37, v164
	ds_read_b32 v46, v165
	ds_read_b32 v47, v166
	ds_read_b32 v48, v167
	s_waitcnt lgkmcnt(3)
	v_fma_f32 v16, -v38, v37, v16
	v_fma_f32 v17, -v39, v37, v17
	v_fma_f32 v18, -v40, v37, v18
	v_fma_f32 v19, -v41, v37, v19
	s_waitcnt lgkmcnt(1)
	v_fma_f32 v0, -v38, v47, v0
	v_fma_f32 v1, -v39, v47, v1
	v_fma_f32 v2, -v40, v47, v2
	v_fma_f32 v3, -v41, v47, v3
	v_fma_f32 v16, v46, v16, v42
	v_fma_f32 v17, v46, v17, v43
	v_fma_f32 v18, v46, v18, v44
	v_fma_f32 v19, v46, v19, v45
	s_waitcnt lgkmcnt(0)
	v_fma_f32 v0, v48, v0, v42
	v_fma_f32 v1, v48, v1, v43
	v_fma_f32 v2, v48, v2, v44
	v_fmac_f32_e32 v45, v48, v3
	v_mul_f32_e32 v16, 0xbfb8aa3b, v16
	v_mul_f32_e32 v17, 0xbfb8aa3b, v17
	v_mul_f32_e32 v18, 0xbfb8aa3b, v18
	v_mul_f32_e32 v19, 0xbfb8aa3b, v19
	v_mul_f32_e32 v0, 0xbfb8aa3b, v0
	v_mul_f32_e32 v1, 0xbfb8aa3b, v1
	v_mul_f32_e32 v2, 0xbfb8aa3b, v2
	v_mul_f32_e32 v3, 0xbfb8aa3b, v45
	v_exp_f32_e32 v16, v16
	v_exp_f32_e32 v17, v17
	v_exp_f32_e32 v18, v18
	v_exp_f32_e32 v19, v19
	v_exp_f32_e32 v0, v0
	v_exp_f32_e32 v1, v1
	v_exp_f32_e32 v2, v2
	v_exp_f32_e32 v3, v3
	v_add_f32_e32 v16, 1.0, v16
	v_add_f32_e32 v17, 1.0, v17
	v_add_f32_e32 v18, 1.0, v18
	v_add_f32_e32 v19, 1.0, v19
	v_add_f32_e32 v0, 1.0, v0
	v_add_f32_e32 v1, 1.0, v1
	v_add_f32_e32 v2, 1.0, v2
	v_add_f32_e32 v3, 1.0, v3
	v_rcp_f32_e32 v16, v16
	v_rcp_f32_e32 v17, v17
	v_rcp_f32_e32 v18, v18
	v_rcp_f32_e32 v19, v19
	v_rcp_f32_e32 v0, v0
	v_rcp_f32_e32 v1, v1
	v_rcp_f32_e32 v2, v2
	v_rcp_f32_e32 v37, v3
	v_cvt_pk_bf16_f32 v17, v16, v17
	v_cvt_pk_bf16_f32 v16, v18, v19
	v_cvt_pk_bf16_f32 v3, v0, v1
	v_cvt_pk_bf16_f32 v2, v2, v37
	v_add_u32_e32 v0, 0x249a0, v160
	v_add_u32_e32 v1, 0x24da0, v160
	ds_read_b128 v[38:41], v0
	ds_read_b128 v[42:45], v1
	ds_read_b32 v0, v164
	ds_read_b32 v1, v165
	ds_read_b32 v18, v166
	ds_read_b32 v19, v167
	s_waitcnt lgkmcnt(3)
	v_fma_f32 v21, -v39, v0, v21
	v_fma_f32 v20, -v38, v0, v20
	s_waitcnt lgkmcnt(1)
	v_fma_f32 v6, -v40, v18, v6
	v_fma_f32 v21, v1, v21, v43
	v_fma_f32 v22, -v40, v0, v22
	v_fma_f32 v0, -v41, v0, v23
	v_fma_f32 v4, -v38, v18, v4
	v_fma_f32 v5, -v39, v18, v5
	s_waitcnt lgkmcnt(0)
	v_fma_f32 v6, v19, v6, v44
	v_fma_f32 v7, -v41, v18, v7
	v_fma_f32 v20, v1, v20, v42
	v_mul_f32_e32 v21, 0xbfb8aa3b, v21
	v_fma_f32 v22, v1, v22, v44
	v_fma_f32 v0, v1, v0, v45
	v_fma_f32 v4, v19, v4, v42
	v_fma_f32 v5, v19, v5, v43
	v_mul_f32_e32 v6, 0xbfb8aa3b, v6
	v_fmac_f32_e32 v45, v19, v7
	v_mul_f32_e32 v20, 0xbfb8aa3b, v20
	v_exp_f32_e32 v21, v21
	v_mul_f32_e32 v22, 0xbfb8aa3b, v22
	v_mul_f32_e32 v0, 0xbfb8aa3b, v0
	v_mul_f32_e32 v4, 0xbfb8aa3b, v4
	v_mul_f32_e32 v5, 0xbfb8aa3b, v5
	v_exp_f32_e32 v6, v6
	v_mul_f32_e32 v7, 0xbfb8aa3b, v45
	v_exp_f32_e32 v20, v20
	v_exp_f32_e32 v22, v22
	v_exp_f32_e32 v0, v0
	v_exp_f32_e32 v4, v4
	v_exp_f32_e32 v5, v5
	v_exp_f32_e32 v7, v7
	v_add_f32_e32 v21, 1.0, v21
	v_add_f32_e32 v6, 1.0, v6
	v_add_f32_e32 v20, 1.0, v20
	v_rcp_f32_e32 v1, v21
	v_add_f32_e32 v21, 1.0, v22
	v_add_f32_e32 v0, 1.0, v0
	v_add_f32_e32 v4, 1.0, v4
	v_add_f32_e32 v5, 1.0, v5
	v_rcp_f32_e32 v18, v6
	v_add_f32_e32 v6, 1.0, v7
	v_rcp_f32_e32 v20, v20
	v_rcp_f32_e32 v21, v21
	v_rcp_f32_e32 v0, v0
	v_rcp_f32_e32 v4, v4
	v_rcp_f32_e32 v5, v5
	v_rcp_f32_e32 v19, v6
	v_cvt_pk_bf16_f32 v7, v20, v1
	v_cvt_pk_bf16_f32 v6, v21, v0
	v_cvt_pk_bf16_f32 v5, v4, v5
	v_cvt_pk_bf16_f32 v4, v18, v19
	v_add_u32_e32 v0, 0x249c0, v160
	v_add_u32_e32 v1, 0x24dc0, v160
	ds_read_b128 v[18:21], v0
	ds_read_b128 v[38:41], v1
	ds_read_b32 v0, v164
	ds_read_b32 v1, v165
	ds_read_b32 v22, v166
	ds_read_b32 v23, v167
	s_waitcnt lgkmcnt(3)
	v_fma_f32 v25, -v19, v0, v25
	v_fma_f32 v24, -v18, v0, v24
	s_waitcnt lgkmcnt(1)
	v_fma_f32 v9, -v19, v22, v9
	s_waitcnt lgkmcnt(0)
; DI unsigned pack2(float a, float b) { f32x2_t v = {a, b}; bf16x2_t r = __builtin_convertvector(v, bf16x2_t); return __builtin_bit_cast(unsigned, r); }
; DI float sigmoidf_(float x) { return __builtin_amdgcn_rcpf(1.f + __expf(-x)); }
; DI int otid() { int t = threadIdx.x; asm volatile("" : "+v"(t)); return t; }
; DI void stage_write16(bf16_t* stg, int rr, int c, u32x4 v) {
;   *(uint2*)(stg + rr * STG + c * 8) = make_uint2(v.x, v.y);
;   *(uint2*)(stg + rr * STG + c * 8 + 4) = make_uint2(v.z, v.w);
; }
; template <bool NT>
; DI void stage_load_tile(bf16_t* stg, const bf16_t* tilebase) {
;   const int tid = otid();
;   const int r0 = tid >> 5, c = tid & 31;
;   const unsigned o0 = (unsigned)(r0 * 1024 + c * 8);
;   __builtin_amdgcn_sched_barrier(0);
; #pragma unroll
;   for (int hf = 0; hf < 2; ++hf) {
; #pragma unroll
;     for (int it = 8 * hf; it < 8 * hf + 8; ++it) {
;       const u32x4* gp = (const u32x4*)(tilebase + (o0 + (unsigned)(it * 16 * 1024)));
;       stage_write16(stg, r0 + 16 * it, c, NT ? __builtin_nontemporal_load(gp) : *gp);
;     }
;     __builtin_amdgcn_sched_barrier(0);
;   }
; template <bool LAST>
; DI void phase_gate(const Params& P, int layer, unsigned char* smem, int L, int G) {
;     ...
;     unsigned gq[4][2][8];
; #pragma unroll
;     for (int i = 0; i < 4; ++i)
; #pragma unroll
;       for (int q4 = 0; q4 < 4; ++q4) {
;         const int fl = wm * 128 + i * 32 + 8 * q4 + 4 * h;
;         const f32x4 c1v = *(const f32x4*)(vecL + fl), c2v = *(const f32x4*)(vecL + 256 + fl);
;         const float c1a[4] = {c1v.x, c1v.y, c1v.z, c1v.w}, c2a[4] = {c2v.x, c2v.y, c2v.z, c2v.w};
; #pragma unroll
;         for (int j = 0; j < 2; ++j) {
;           const int lrow = wn * 64 + j * 32 + r;
;           const float mu = rowA[lrow], rstd = rowB[lrow];
;           float sg4[4];
; #pragma unroll
;           for (int e = 0; e < 4; ++e) sg4[e] = sigmoidf_(rstd * (accu[i][j][4 * q4 + e] - mu * c1a[e]) + c2a[e]);
;           gq[i][j][2 * q4] = pack2(sg4[0], sg4[1]); gq[i][j][2 * q4 + 1] = pack2(sg4[2], sg4[3]);
;         }
;         __builtin_amdgcn_sched_barrier(0);
;       }
	v_fma_f32 v9, v23, v9, v39
	v_fma_f32 v10, -v20, v22, v10
	v_fma_f32 v25, v1, v25, v39
	v_fma_f32 v26, -v20, v0, v26
	v_fma_f32 v0, -v21, v0, v27
	v_fma_f32 v8, -v18, v22, v8
	v_mul_f32_e32 v9, 0xbfb8aa3b, v9
	v_fma_f32 v10, v23, v10, v40
	v_fma_f32 v11, -v21, v22, v11
	v_fma_f32 v24, v1, v24, v38
	v_mul_f32_e32 v25, 0xbfb8aa3b, v25
	v_fma_f32 v26, v1, v26, v40
	v_fma_f32 v0, v1, v0, v41
	v_fma_f32 v8, v23, v8, v38
	v_exp_f32_e32 v9, v9
	v_mul_f32_e32 v10, 0xbfb8aa3b, v10
	v_fmac_f32_e32 v41, v23, v11
	v_mul_f32_e32 v24, 0xbfb8aa3b, v24
	v_exp_f32_e32 v25, v25
	v_mul_f32_e32 v26, 0xbfb8aa3b, v26
	v_mul_f32_e32 v0, 0xbfb8aa3b, v0
	v_mul_f32_e32 v8, 0xbfb8aa3b, v8
	v_exp_f32_e32 v10, v10
	v_mul_f32_e32 v11, 0xbfb8aa3b, v41
	v_exp_f32_e32 v24, v24
	v_exp_f32_e32 v26, v26
	v_exp_f32_e32 v0, v0
	v_exp_f32_e32 v8, v8
	v_exp_f32_e32 v11, v11
	v_add_f32_e32 v9, 1.0, v9
	v_add_f32_e32 v25, 1.0, v25
	v_rcp_f32_e32 v18, v9
	v_add_f32_e32 v9, 1.0, v10
	v_add_f32_e32 v24, 1.0, v24
	v_rcp_f32_e32 v1, v25
	v_add_f32_e32 v25, 1.0, v26
	v_add_f32_e32 v0, 1.0, v0
	v_add_f32_e32 v8, 1.0, v8
	v_rcp_f32_e32 v10, v9
	v_add_f32_e32 v9, 1.0, v11
	v_rcp_f32_e32 v24, v24
	v_rcp_f32_e32 v25, v25
	v_rcp_f32_e32 v0, v0
	v_rcp_f32_e32 v8, v8
	v_rcp_f32_e32 v11, v9
	v_cvt_pk_bf16_f32 v27, v24, v1
	v_cvt_pk_bf16_f32 v9, v25, v0
	v_cvt_pk_bf16_f32 v19, v8, v18
	v_cvt_pk_bf16_f32 v8, v10, v11
	v_add_u32_e32 v0, 0x24de0, v160
	ds_read_b128 v[20:23], v163 offset:480
	ds_read_b32 v1, v164
	ds_read_b128 v[38:41], v0
	ds_read_b32 v0, v165
	ds_read_b32 v10, v166
	ds_read_b32 v18, v167
	s_waitcnt lgkmcnt(4)
	v_fma_f32 v24, -v21, v1, v29
	v_fma_f32 v11, -v20, v1, v28
	s_waitcnt lgkmcnt(2)
	v_fma_f32 v24, v0, v24, v39
	v_fma_f32 v25, -v22, v1, v30
	v_fma_f32 v1, -v23, v1, v31
	s_waitcnt lgkmcnt(1)
	v_fma_f32 v12, -v20, v10, v12
	v_fma_f32 v13, -v21, v10, v13
	v_fma_f32 v14, -v22, v10, v14
	v_fma_f32 v10, -v23, v10, v15
	v_fma_f32 v11, v0, v11, v38
	v_mul_f32_e32 v24, 0xbfb8aa3b, v24
	v_fma_f32 v25, v0, v25, v40
	v_fma_f32 v0, v0, v1, v41
	s_waitcnt lgkmcnt(0)
	v_fma_f32 v12, v18, v12, v38
	v_fma_f32 v13, v18, v13, v39
	v_fma_f32 v14, v18, v14, v40
	v_fmac_f32_e32 v41, v18, v10
	v_mul_f32_e32 v11, 0xbfb8aa3b, v11
	v_exp_f32_e32 v24, v24
	v_mul_f32_e32 v25, 0xbfb8aa3b, v25
	v_mul_f32_e32 v0, 0xbfb8aa3b, v0
	v_mul_f32_e32 v12, 0xbfb8aa3b, v12
	v_mul_f32_e32 v13, 0xbfb8aa3b, v13
	v_mul_f32_e32 v14, 0xbfb8aa3b, v14
	v_mul_f32_e32 v10, 0xbfb8aa3b, v41
	v_exp_f32_e32 v11, v11
	v_exp_f32_e32 v25, v25
	v_exp_f32_e32 v0, v0
	v_exp_f32_e32 v12, v12
	v_exp_f32_e32 v13, v13
	v_exp_f32_e32 v14, v14
	v_exp_f32_e32 v10, v10
	v_add_f32_e32 v24, 1.0, v24
	v_add_f32_e32 v11, 1.0, v11
	v_rcp_f32_e32 v1, v24
	v_add_f32_e32 v24, 1.0, v25
	v_add_f32_e32 v0, 1.0, v0
	v_add_f32_e32 v12, 1.0, v12
	v_add_f32_e32 v13, 1.0, v13
	v_add_f32_e32 v14, 1.0, v14
	v_add_f32_e32 v10, 1.0, v10
	v_rcp_f32_e32 v11, v11
	v_rcp_f32_e32 v24, v24
	v_rcp_f32_e32 v0, v0
	v_rcp_f32_e32 v12, v12
	v_rcp_f32_e32 v13, v13
	v_rcp_f32_e32 v14, v14
	v_rcp_f32_e32 v10, v10
	v_cvt_pk_bf16_f32 v112, v11, v1
	v_cvt_pk_bf16_f32 v30, v24, v0
	v_cvt_pk_bf16_f32 v29, v12, v13
	v_cvt_pk_bf16_f32 v28, v14, v10
	v_mov_b32_e32 v163, v161
	v_lshlrev_b64 v[0:1], 1, v[162:163]
	v_and_b32_e32 v26, 31, v192
	v_ashrrev_i32_e32 v18, 5, v192
	v_mul_lo_u32 v18, v18, s40
	v_lshl_add_u32 v18, v26, 4, v18
	v_add_u32_e32 v24, 0x2080, v18
	v_add_u32_e32 v25, 0x4100, v18
	v_add_u32_e32 v26, 0x6180, v18
	v_add_u32_e32 v31, 0x8200, v18
	v_add_u32_e32 v37, 0xa280, v18
	v_add_u32_e32 v50, 0xc300, v18
	v_add_u32_e32 v51, 0xe380, v18
	s_waitcnt vmcnt(15)
	ds_write2_b64 v18, v[180:181], v[182:183] offset1:1
	s_waitcnt vmcnt(14)
	ds_write2_b64 v24, v[184:185], v[186:187] offset1:1
	s_waitcnt vmcnt(13)
	ds_write2_b64 v25, v[194:195], v[196:197] offset1:1
	s_waitcnt vmcnt(12)
	ds_write2_b64 v26, v[198:199], v[200:201] offset1:1
	s_waitcnt vmcnt(11)
	ds_write2_b64 v31, v[202:203], v[204:205] offset1:1
	s_waitcnt vmcnt(10)
	ds_write2_b64 v37, v[206:207], v[208:209] offset1:1
	s_waitcnt vmcnt(9)
	ds_write2_b64 v50, v[210:211], v[212:213] offset1:1
	s_waitcnt vmcnt(8)
	ds_write2_b64 v51, v[214:215], v[216:217] offset1:1
	v_add_u32_e32 v14, 0x10400, v18
	v_add_u32_e32 v15, 0x12480, v18
	v_add_u32_e32 v24, 0x14500, v18
	v_add_u32_e32 v25, 0x16580, v18
	v_add_u32_e32 v26, 0x18600, v18
	v_add_u32_e32 v31, 0x1a680, v18
	v_add_u32_e32 v37, 0x1c700, v18
	v_add_u32_e32 v18, 0x1e780, v18
	s_waitcnt vmcnt(7)
	ds_write2_b64 v14, v[218:219], v[220:221] offset1:1
	s_waitcnt vmcnt(6)
	ds_write2_b64 v15, v[222:223], v[224:225] offset1:1
	s_waitcnt vmcnt(5)
	ds_write2_b64 v24, v[226:227], v[228:229] offset1:1
	s_waitcnt vmcnt(4)
	ds_write2_b64 v25, v[230:231], v[232:233] offset1:1
	s_waitcnt vmcnt(3)
	ds_write2_b64 v26, v[234:235], v[236:237] offset1:1
	s_waitcnt vmcnt(2)
	ds_write2_b64 v31, v[238:239], v[240:241] offset1:1
	s_waitcnt vmcnt(1)
	ds_write2_b64 v37, v[242:243], v[244:245] offset1:1
	s_waitcnt vmcnt(0)
	ds_write2_b64 v18, v[248:249], v[250:251] offset1:1
	v_mov_b32_e32 v10, v192
	s_waitcnt lgkmcnt(0)
	s_barrier
; DI unsigned pack2(float a, float b) { f32x2_t v = {a, b}; bf16x2_t r = __builtin_convertvector(v, bf16x2_t); return __builtin_bit_cast(unsigned, r); }
; DI float bflo(unsigned u) { return __uint_as_float(u << 16); }
; DI float bfhi(unsigned u) { return __uint_as_float(u & 0xffff0000u); }
; DI int otid() { int t = threadIdx.x; asm volatile("" : "+v"(t)); return t; }
; template <bool LAST>
; DI void phase_gate(const Params& P, int layer, unsigned char* smem, int L, int G) {
;     ...
;     {
;       const int tid1 = otid();
;       const int lane1 = tid1 & 63, w1 = tid1 >> 6, r1 = lane1 & 31, h1 = lane1 >> 5, wm1 = w1 >> 2, wn1 = w1 & 3;
; #pragma unroll
;       for (int i = 0; i < 4; ++i)
; #pragma unroll
;         for (int q4 = 0; q4 < 4; ++q4) {
; #pragma unroll
;           for (int j = 0; j < 2; ++j) {
;             const uint2 pv = *(const uint2*)(stg + (wn1 * 64 + j * 32 + r1) * STG + wm1 * 128 + i * 32 + 8 * q4 + 4 * h1);
;             const unsigned g0 = gq[i][j][2 * q4], g1 = gq[i][j][2 * q4 + 1];
;             gq[i][j][2 * q4] = pack2(bflo(g0) * bflo(pv.x), bfhi(g0) * bfhi(pv.x));
;             gq[i][j][2 * q4 + 1] = pack2(bflo(g1) * bflo(pv.y), bfhi(g1) * bfhi(pv.y));
;           }
;           __builtin_amdgcn_sched_barrier(0);
;         }
;     }
;     __syncthreads();
	v_and_b32_e32 v13, 0xffff0000, v99
	v_lshrrev_b32_e32 v12, 2, v10
	v_and_b32_e32 v12, 8, v12
	v_and_b32_e32 v11, 0xdf, v10
	v_and_or_b32 v10, v10, s38, v12
	v_mad_u32_u24 v113, v11, s40, v10
	ds_read_b64 v[10:11], v113
	ds_read_b64 v[14:15], v113 offset:16640
	v_lshlrev_b32_e32 v12, 16, v99
	s_waitcnt lgkmcnt(1)
	v_lshlrev_b32_e32 v20, 16, v10
	v_and_b32_e32 v21, 0xffff0000, v10
	v_pk_mul_f32 v[12:13], v[12:13], v[20:21]
	v_lshlrev_b32_e32 v10, 16, v11
	v_cvt_pk_bf16_f32 v31, v12, v13
	v_lshlrev_b32_e32 v12, 16, v98
	v_and_b32_e32 v13, 0xffff0000, v98
	v_and_b32_e32 v11, 0xffff0000, v11
	v_pk_mul_f32 v[10:11], v[12:13], v[10:11]
	s_waitcnt lgkmcnt(0)
	v_lshlrev_b32_e32 v12, 16, v14
	v_cvt_pk_bf16_f32 v98, v10, v11
	v_lshlrev_b32_e32 v10, 16, v97
	v_and_b32_e32 v11, 0xffff0000, v97
	v_and_b32_e32 v13, 0xffff0000, v14
	v_pk_mul_f32 v[10:11], v[10:11], v[12:13]
	v_lshlrev_b32_e32 v12, 16, v15
	v_cvt_pk_bf16_f32 v97, v10, v11
	v_lshlrev_b32_e32 v10, 16, v96
	v_and_b32_e32 v11, 0xffff0000, v96
	v_and_b32_e32 v13, 0xffff0000, v15
	v_pk_mul_f32 v[10:11], v[10:11], v[12:13]
	s_nop 0
	v_cvt_pk_bf16_f32 v96, v10, v11
	ds_read_b64 v[10:11], v113 offset:16
	ds_read_b64 v[14:15], v113 offset:16656
	v_lshlrev_b32_e32 v12, 16, v103
	v_and_b32_e32 v13, 0xffff0000, v103
	s_waitcnt lgkmcnt(1)
	v_lshlrev_b32_e32 v20, 16, v10
	v_and_b32_e32 v21, 0xffff0000, v10
	v_pk_mul_f32 v[12:13], v[12:13], v[20:21]
	v_lshlrev_b32_e32 v10, 16, v11
	v_cvt_pk_bf16_f32 v93, v12, v13
	v_lshlrev_b32_e32 v12, 16, v102
	v_and_b32_e32 v13, 0xffff0000, v102
	v_and_b32_e32 v11, 0xffff0000, v11
	v_pk_mul_f32 v[10:11], v[12:13], v[10:11]
	s_waitcnt lgkmcnt(0)
	v_lshlrev_b32_e32 v12, 16, v14
	v_cvt_pk_bf16_f32 v95, v10, v11
	v_lshlrev_b32_e32 v10, 16, v101
	v_and_b32_e32 v11, 0xffff0000, v101
	v_and_b32_e32 v13, 0xffff0000, v14
	v_pk_mul_f32 v[10:11], v[10:11], v[12:13]
	v_lshlrev_b32_e32 v12, 16, v15
	v_cvt_pk_bf16_f32 v92, v10, v11
	v_lshlrev_b32_e32 v10, 16, v100
	v_and_b32_e32 v11, 0xffff0000, v100
	v_and_b32_e32 v13, 0xffff0000, v15
	v_pk_mul_f32 v[10:11], v[10:11], v[12:13]
	s_nop 0
	v_cvt_pk_bf16_f32 v94, v10, v11
	ds_read_b64 v[10:11], v113 offset:32
	ds_read_b64 v[14:15], v113 offset:16672
	v_lshlrev_b32_e32 v12, 16, v107
	v_and_b32_e32 v13, 0xffff0000, v107
	s_waitcnt lgkmcnt(1)
	v_lshlrev_b32_e32 v20, 16, v10
	v_and_b32_e32 v21, 0xffff0000, v10
	v_pk_mul_f32 v[12:13], v[12:13], v[20:21]
	v_lshlrev_b32_e32 v10, 16, v11
	v_cvt_pk_bf16_f32 v88, v12, v13
	v_lshlrev_b32_e32 v12, 16, v106
	v_and_b32_e32 v13, 0xffff0000, v106
	v_and_b32_e32 v11, 0xffff0000, v11
	v_pk_mul_f32 v[10:11], v[12:13], v[10:11]
	s_waitcnt lgkmcnt(0)
	v_lshlrev_b32_e32 v12, 16, v14
	v_cvt_pk_bf16_f32 v90, v10, v11
	v_lshlrev_b32_e32 v10, 16, v105
	v_and_b32_e32 v11, 0xffff0000, v105
	v_and_b32_e32 v13, 0xffff0000, v14
	v_pk_mul_f32 v[10:11], v[10:11], v[12:13]
	v_lshlrev_b32_e32 v12, 16, v15
	v_cvt_pk_bf16_f32 v87, v10, v11
	v_lshlrev_b32_e32 v10, 16, v104
	v_and_b32_e32 v11, 0xffff0000, v104
	v_and_b32_e32 v13, 0xffff0000, v15
	v_pk_mul_f32 v[10:11], v[10:11], v[12:13]
	s_nop 0
	v_cvt_pk_bf16_f32 v89, v10, v11
	ds_read_b64 v[10:11], v113 offset:48
	ds_read_b64 v[14:15], v113 offset:16688
	v_lshlrev_b32_e32 v12, 16, v111
	v_and_b32_e32 v13, 0xffff0000, v111
	s_waitcnt lgkmcnt(1)
	v_lshlrev_b32_e32 v20, 16, v10
	v_and_b32_e32 v21, 0xffff0000, v10
	v_pk_mul_f32 v[12:13], v[12:13], v[20:21]
	v_lshlrev_b32_e32 v10, 16, v11
	v_cvt_pk_bf16_f32 v61, v12, v13
	v_lshlrev_b32_e32 v12, 16, v110
	v_and_b32_e32 v13, 0xffff0000, v110
	v_and_b32_e32 v11, 0xffff0000, v11
	v_pk_mul_f32 v[10:11], v[12:13], v[10:11]
	s_waitcnt lgkmcnt(0)
	v_lshlrev_b32_e32 v12, 16, v14
	v_cvt_pk_bf16_f32 v63, v10, v11
	v_lshlrev_b32_e32 v10, 16, v109
	v_and_b32_e32 v11, 0xffff0000, v109
	v_and_b32_e32 v13, 0xffff0000, v14
	v_pk_mul_f32 v[10:11], v[10:11], v[12:13]
	v_lshlrev_b32_e32 v12, 16, v15
	v_cvt_pk_bf16_f32 v60, v10, v11
	v_lshlrev_b32_e32 v10, 16, v108
	v_and_b32_e32 v11, 0xffff0000, v108
	v_and_b32_e32 v13, 0xffff0000, v15
	v_pk_mul_f32 v[10:11], v[10:11], v[12:13]
	s_nop 0
	v_cvt_pk_bf16_f32 v62, v10, v11
	ds_read_b64 v[10:11], v113 offset:64
	ds_read_b64 v[14:15], v113 offset:16704
	v_lshlrev_b32_e32 v12, 16, v67
	v_and_b32_e32 v13, 0xffff0000, v67
	s_waitcnt lgkmcnt(1)
	v_lshlrev_b32_e32 v20, 16, v10
	v_and_b32_e32 v21, 0xffff0000, v10
	v_pk_mul_f32 v[12:13], v[12:13], v[20:21]
	v_lshlrev_b32_e32 v10, 16, v11
	v_cvt_pk_bf16_f32 v56, v12, v13
	v_lshlrev_b32_e32 v12, 16, v66
	v_and_b32_e32 v13, 0xffff0000, v66
	v_and_b32_e32 v11, 0xffff0000, v11
	v_pk_mul_f32 v[10:11], v[12:13], v[10:11]
	s_waitcnt lgkmcnt(0)
	v_lshlrev_b32_e32 v12, 16, v14
	v_cvt_pk_bf16_f32 v58, v10, v11
	v_lshlrev_b32_e32 v10, 16, v65
	v_and_b32_e32 v11, 0xffff0000, v65
	v_and_b32_e32 v13, 0xffff0000, v14
	v_pk_mul_f32 v[10:11], v[10:11], v[12:13]
	v_lshlrev_b32_e32 v12, 16, v15
	v_cvt_pk_bf16_f32 v54, v10, v11
	v_lshlrev_b32_e32 v10, 16, v64
	v_and_b32_e32 v11, 0xffff0000, v64
	v_and_b32_e32 v13, 0xffff0000, v15
	v_pk_mul_f32 v[10:11], v[10:11], v[12:13]
	s_nop 0
	v_cvt_pk_bf16_f32 v57, v10, v11
	ds_read_b64 v[10:11], v113 offset:80
	ds_read_b64 v[14:15], v113 offset:16720
	v_lshlrev_b32_e32 v12, 16, v71
	v_and_b32_e32 v13, 0xffff0000, v71
	s_waitcnt lgkmcnt(1)
	v_lshlrev_b32_e32 v20, 16, v10
	v_and_b32_e32 v21, 0xffff0000, v10
	v_pk_mul_f32 v[12:13], v[12:13], v[20:21]
	v_lshlrev_b32_e32 v10, 16, v11
	v_cvt_pk_bf16_f32 v50, v12, v13
	v_lshlrev_b32_e32 v12, 16, v70
	v_and_b32_e32 v13, 0xffff0000, v70
	v_and_b32_e32 v11, 0xffff0000, v11
	v_pk_mul_f32 v[10:11], v[12:13], v[10:11]
	s_waitcnt lgkmcnt(0)
; DI unsigned pack2(float a, float b) { f32x2_t v = {a, b}; bf16x2_t r = __builtin_convertvector(v, bf16x2_t); return __builtin_bit_cast(unsigned, r); }
; DI float bflo(unsigned u) { return __uint_as_float(u << 16); }
; DI float bfhi(unsigned u) { return __uint_as_float(u & 0xffff0000u); }
; DI int otid() { int t = threadIdx.x; asm volatile("" : "+v"(t)); return t; }
; template <bool LAST>
; DI void phase_gate(const Params& P, int layer, unsigned char* smem, int L, int G) {
;     ...
;     {
;       const int tid1 = otid();
;       const int lane1 = tid1 & 63, w1 = tid1 >> 6, r1 = lane1 & 31, h1 = lane1 >> 5, wm1 = w1 >> 2, wn1 = w1 & 3;
; #pragma unroll
;       for (int i = 0; i < 4; ++i)
; #pragma unroll
;         for (int q4 = 0; q4 < 4; ++q4) {
; #pragma unroll
;           for (int j = 0; j < 2; ++j) {
;             const uint2 pv = *(const uint2*)(stg + (wn1 * 64 + j * 32 + r1) * STG + wm1 * 128 + i * 32 + 8 * q4 + 4 * h1);
;             const unsigned g0 = gq[i][j][2 * q4], g1 = gq[i][j][2 * q4 + 1];
;             gq[i][j][2 * q4] = pack2(bflo(g0) * bflo(pv.x), bfhi(g0) * bfhi(pv.x));
;             gq[i][j][2 * q4 + 1] = pack2(bflo(g1) * bflo(pv.y), bfhi(g1) * bfhi(pv.y));
;           }
;           __builtin_amdgcn_sched_barrier(0);
;         }
;     }
;     __syncthreads();
	v_lshlrev_b32_e32 v12, 16, v14
	v_cvt_pk_bf16_f32 v52, v10, v11
	v_lshlrev_b32_e32 v10, 16, v69
	v_and_b32_e32 v11, 0xffff0000, v69
	v_and_b32_e32 v13, 0xffff0000, v14
	v_pk_mul_f32 v[10:11], v[10:11], v[12:13]
	v_lshlrev_b32_e32 v12, 16, v15
	v_cvt_pk_bf16_f32 v49, v10, v11
	v_lshlrev_b32_e32 v10, 16, v68
	v_and_b32_e32 v11, 0xffff0000, v68
	v_and_b32_e32 v13, 0xffff0000, v15
	v_pk_mul_f32 v[10:11], v[10:11], v[12:13]
	s_nop 0
	v_cvt_pk_bf16_f32 v51, v10, v11
	ds_read_b64 v[10:11], v113 offset:96
	ds_read_b64 v[14:15], v113 offset:16736
	v_lshlrev_b32_e32 v12, 16, v75
	v_and_b32_e32 v13, 0xffff0000, v75
	s_waitcnt lgkmcnt(1)
	v_lshlrev_b32_e32 v20, 16, v10
	v_and_b32_e32 v21, 0xffff0000, v10
	v_pk_mul_f32 v[12:13], v[12:13], v[20:21]
	v_lshlrev_b32_e32 v10, 16, v11
	v_cvt_pk_bf16_f32 v46, v12, v13
	v_lshlrev_b32_e32 v12, 16, v74
	v_and_b32_e32 v13, 0xffff0000, v74
	v_and_b32_e32 v11, 0xffff0000, v11
	v_pk_mul_f32 v[10:11], v[12:13], v[10:11]
	s_waitcnt lgkmcnt(0)
	v_lshlrev_b32_e32 v12, 16, v14
	v_cvt_pk_bf16_f32 v48, v10, v11
	v_lshlrev_b32_e32 v10, 16, v73
	v_and_b32_e32 v11, 0xffff0000, v73
	v_and_b32_e32 v13, 0xffff0000, v14
	v_pk_mul_f32 v[10:11], v[10:11], v[12:13]
	v_lshlrev_b32_e32 v12, 16, v15
	v_cvt_pk_bf16_f32 v45, v10, v11
	v_lshlrev_b32_e32 v10, 16, v72
	v_and_b32_e32 v11, 0xffff0000, v72
	v_and_b32_e32 v13, 0xffff0000, v15
	v_pk_mul_f32 v[10:11], v[10:11], v[12:13]
	s_nop 0
	v_cvt_pk_bf16_f32 v47, v10, v11
	ds_read_b64 v[10:11], v113 offset:112
	ds_read_b64 v[14:15], v113 offset:16752
	v_lshlrev_b32_e32 v12, 16, v79
	v_and_b32_e32 v13, 0xffff0000, v79
	s_waitcnt lgkmcnt(1)
	v_lshlrev_b32_e32 v20, 16, v10
	v_and_b32_e32 v21, 0xffff0000, v10
	v_pk_mul_f32 v[12:13], v[12:13], v[20:21]
	v_lshlrev_b32_e32 v10, 16, v11
	v_cvt_pk_bf16_f32 v42, v12, v13
	v_lshlrev_b32_e32 v12, 16, v78
	v_and_b32_e32 v13, 0xffff0000, v78
	v_and_b32_e32 v11, 0xffff0000, v11
	v_pk_mul_f32 v[10:11], v[12:13], v[10:11]
	s_waitcnt lgkmcnt(0)
	v_lshlrev_b32_e32 v12, 16, v14
	v_cvt_pk_bf16_f32 v44, v10, v11
	v_lshlrev_b32_e32 v10, 16, v77
	v_and_b32_e32 v11, 0xffff0000, v77
	v_and_b32_e32 v13, 0xffff0000, v14
	v_pk_mul_f32 v[10:11], v[10:11], v[12:13]
	v_lshlrev_b32_e32 v12, 16, v15
	v_cvt_pk_bf16_f32 v41, v10, v11
	v_lshlrev_b32_e32 v10, 16, v76
	v_and_b32_e32 v11, 0xffff0000, v76
	v_and_b32_e32 v13, 0xffff0000, v15
	v_pk_mul_f32 v[10:11], v[10:11], v[12:13]
	s_nop 0
	v_cvt_pk_bf16_f32 v43, v10, v11
	ds_read_b64 v[10:11], v113 offset:128
	ds_read_b64 v[14:15], v113 offset:16768
	v_lshlrev_b32_e32 v12, 16, v35
	v_and_b32_e32 v13, 0xffff0000, v35
	s_waitcnt lgkmcnt(1)
	v_lshlrev_b32_e32 v20, 16, v10
	v_and_b32_e32 v21, 0xffff0000, v10
	v_pk_mul_f32 v[12:13], v[12:13], v[20:21]
	v_lshlrev_b32_e32 v10, 16, v11
	v_cvt_pk_bf16_f32 v38, v12, v13
	v_lshlrev_b32_e32 v12, 16, v34
	v_and_b32_e32 v13, 0xffff0000, v34
	v_and_b32_e32 v11, 0xffff0000, v11
	v_pk_mul_f32 v[10:11], v[12:13], v[10:11]
	s_waitcnt lgkmcnt(0)
	v_lshlrev_b32_e32 v12, 16, v14
	v_cvt_pk_bf16_f32 v40, v10, v11
	v_lshlrev_b32_e32 v10, 16, v33
	v_and_b32_e32 v11, 0xffff0000, v33
	v_and_b32_e32 v13, 0xffff0000, v14
	v_pk_mul_f32 v[10:11], v[10:11], v[12:13]
	v_lshlrev_b32_e32 v12, 16, v15
	v_cvt_pk_bf16_f32 v37, v10, v11
	v_lshlrev_b32_e32 v10, 16, v32
	v_and_b32_e32 v11, 0xffff0000, v32
	v_and_b32_e32 v13, 0xffff0000, v15
	v_pk_mul_f32 v[10:11], v[10:11], v[12:13]
	s_nop 0
	v_cvt_pk_bf16_f32 v39, v10, v11
	ds_read_b64 v[10:11], v113 offset:144
	ds_read_b64 v[14:15], v113 offset:16784
	v_lshlrev_b32_e32 v12, 16, v80
	v_and_b32_e32 v13, 0xffff0000, v80
	s_waitcnt lgkmcnt(1)
	v_lshlrev_b32_e32 v20, 16, v10
	v_and_b32_e32 v21, 0xffff0000, v10
	v_pk_mul_f32 v[12:13], v[12:13], v[20:21]
	v_lshlrev_b32_e32 v10, 16, v11
	v_cvt_pk_bf16_f32 v34, v12, v13
	v_lshlrev_b32_e32 v12, 16, v36
	v_and_b32_e32 v13, 0xffff0000, v36
	v_and_b32_e32 v11, 0xffff0000, v11
	v_pk_mul_f32 v[10:11], v[12:13], v[10:11]
	s_waitcnt lgkmcnt(0)
	v_lshlrev_b32_e32 v12, 16, v14
	v_cvt_pk_bf16_f32 v36, v10, v11
	v_lshlrev_b32_e32 v10, 16, v55
	v_and_b32_e32 v11, 0xffff0000, v55
	v_and_b32_e32 v13, 0xffff0000, v14
	v_pk_mul_f32 v[10:11], v[10:11], v[12:13]
	v_lshlrev_b32_e32 v12, 16, v15
	v_cvt_pk_bf16_f32 v32, v10, v11
	v_lshlrev_b32_e32 v10, 16, v53
	v_and_b32_e32 v11, 0xffff0000, v53
	v_and_b32_e32 v13, 0xffff0000, v15
	v_pk_mul_f32 v[10:11], v[10:11], v[12:13]
	s_nop 0
	v_cvt_pk_bf16_f32 v35, v10, v11
	ds_read_b64 v[10:11], v113 offset:160
	ds_read_b64 v[14:15], v113 offset:16800
	v_lshlrev_b32_e32 v12, 16, v83
	v_and_b32_e32 v13, 0xffff0000, v83
	s_waitcnt lgkmcnt(1)
	v_lshlrev_b32_e32 v20, 16, v10
	v_and_b32_e32 v21, 0xffff0000, v10
	v_pk_mul_f32 v[12:13], v[12:13], v[20:21]
	v_lshlrev_b32_e32 v10, 16, v11
	v_cvt_pk_bf16_f32 v24, v12, v13
	v_lshlrev_b32_e32 v12, 16, v82
	v_and_b32_e32 v13, 0xffff0000, v82
	v_and_b32_e32 v11, 0xffff0000, v11
	v_pk_mul_f32 v[10:11], v[12:13], v[10:11]
	s_waitcnt lgkmcnt(0)
	v_lshlrev_b32_e32 v12, 16, v14
	v_cvt_pk_bf16_f32 v26, v10, v11
	v_lshlrev_b32_e32 v10, 16, v81
	v_and_b32_e32 v11, 0xffff0000, v81
	v_and_b32_e32 v13, 0xffff0000, v14
	v_pk_mul_f32 v[10:11], v[10:11], v[12:13]
	v_lshlrev_b32_e32 v12, 16, v15
	v_cvt_pk_bf16_f32 v23, v10, v11
	v_lshlrev_b32_e32 v10, 16, v59
	v_and_b32_e32 v11, 0xffff0000, v59
	v_and_b32_e32 v13, 0xffff0000, v15
	v_pk_mul_f32 v[10:11], v[10:11], v[12:13]
	s_nop 0
	v_cvt_pk_bf16_f32 v25, v10, v11
	ds_read_b64 v[10:11], v113 offset:176
	ds_read_b64 v[14:15], v113 offset:16816
	v_lshlrev_b32_e32 v12, 16, v91
	v_and_b32_e32 v13, 0xffff0000, v91
	s_waitcnt lgkmcnt(1)
; DI unsigned pack2(float a, float b) { f32x2_t v = {a, b}; bf16x2_t r = __builtin_convertvector(v, bf16x2_t); return __builtin_bit_cast(unsigned, r); }
; DI float bflo(unsigned u) { return __uint_as_float(u << 16); }
; DI float bfhi(unsigned u) { return __uint_as_float(u & 0xffff0000u); }
; DI int otid() { int t = threadIdx.x; asm volatile("" : "+v"(t)); return t; }
; template <bool LAST>
; DI void phase_gate(const Params& P, int layer, unsigned char* smem, int L, int G) {
;     ...
;     {
;       const int tid1 = otid();
;       const int lane1 = tid1 & 63, w1 = tid1 >> 6, r1 = lane1 & 31, h1 = lane1 >> 5, wm1 = w1 >> 2, wn1 = w1 & 3;
; #pragma unroll
;       for (int i = 0; i < 4; ++i)
; #pragma unroll
;         for (int q4 = 0; q4 < 4; ++q4) {
; #pragma unroll
;           for (int j = 0; j < 2; ++j) {
;             const uint2 pv = *(const uint2*)(stg + (wn1 * 64 + j * 32 + r1) * STG + wm1 * 128 + i * 32 + 8 * q4 + 4 * h1);
;             const unsigned g0 = gq[i][j][2 * q4], g1 = gq[i][j][2 * q4 + 1];
;             gq[i][j][2 * q4] = pack2(bflo(g0) * bflo(pv.x), bfhi(g0) * bfhi(pv.x));
;             gq[i][j][2 * q4 + 1] = pack2(bflo(g1) * bflo(pv.y), bfhi(g1) * bfhi(pv.y));
;           }
;           __builtin_amdgcn_sched_barrier(0);
;         }
;     }
;     __syncthreads();
	v_lshlrev_b32_e32 v20, 16, v10
	v_and_b32_e32 v21, 0xffff0000, v10
	v_pk_mul_f32 v[12:13], v[12:13], v[20:21]
	v_lshlrev_b32_e32 v10, 16, v11
	v_cvt_pk_bf16_f32 v20, v12, v13
	v_lshlrev_b32_e32 v12, 16, v86
	v_and_b32_e32 v13, 0xffff0000, v86
	v_and_b32_e32 v11, 0xffff0000, v11
	v_pk_mul_f32 v[10:11], v[12:13], v[10:11]
	s_waitcnt lgkmcnt(0)
	v_lshlrev_b32_e32 v12, 16, v14
	v_cvt_pk_bf16_f32 v22, v10, v11
	v_lshlrev_b32_e32 v10, 16, v85
	v_and_b32_e32 v11, 0xffff0000, v85
	v_and_b32_e32 v13, 0xffff0000, v14
	v_pk_mul_f32 v[10:11], v[10:11], v[12:13]
	v_lshlrev_b32_e32 v12, 16, v15
	v_cvt_pk_bf16_f32 v18, v10, v11
	v_lshlrev_b32_e32 v10, 16, v84
	v_and_b32_e32 v11, 0xffff0000, v84
	v_and_b32_e32 v13, 0xffff0000, v15
	v_pk_mul_f32 v[10:11], v[10:11], v[12:13]
	s_nop 0
	v_cvt_pk_bf16_f32 v21, v10, v11
	ds_read_b64 v[10:11], v113 offset:192
	ds_read_b64 v[64:65], v113 offset:16832
	v_lshlrev_b32_e32 v12, 16, v17
	v_and_b32_e32 v13, 0xffff0000, v17
	s_waitcnt lgkmcnt(1)
	v_lshlrev_b32_e32 v14, 16, v10
	v_and_b32_e32 v15, 0xffff0000, v10
	v_pk_mul_f32 v[12:13], v[12:13], v[14:15]
	v_lshlrev_b32_e32 v10, 16, v11
	v_cvt_pk_bf16_f32 v15, v12, v13
	v_lshlrev_b32_e32 v12, 16, v16
	v_and_b32_e32 v13, 0xffff0000, v16
	v_and_b32_e32 v11, 0xffff0000, v11
	v_pk_mul_f32 v[10:11], v[12:13], v[10:11]
	s_waitcnt lgkmcnt(0)
	v_lshlrev_b32_e32 v12, 16, v64
	v_cvt_pk_bf16_f32 v17, v10, v11
	v_lshlrev_b32_e32 v10, 16, v3
	v_and_b32_e32 v11, 0xffff0000, v3
	v_and_b32_e32 v13, 0xffff0000, v64
	v_pk_mul_f32 v[10:11], v[10:11], v[12:13]
	v_lshlrev_b32_e32 v12, 16, v65
	v_cvt_pk_bf16_f32 v14, v10, v11
	v_lshlrev_b32_e32 v10, 16, v2
	v_and_b32_e32 v11, 0xffff0000, v2
	v_and_b32_e32 v13, 0xffff0000, v65
	v_pk_mul_f32 v[2:3], v[10:11], v[12:13]
	s_nop 0
	v_cvt_pk_bf16_f32 v16, v2, v3
	ds_read_b64 v[2:3], v113 offset:208
	ds_read_b64 v[64:65], v113 offset:16848
	v_lshlrev_b32_e32 v10, 16, v7
	v_and_b32_e32 v11, 0xffff0000, v7
	s_waitcnt lgkmcnt(1)
	v_lshlrev_b32_e32 v12, 16, v2
	v_and_b32_e32 v13, 0xffff0000, v2
	v_pk_mul_f32 v[10:11], v[10:11], v[12:13]
	v_lshlrev_b32_e32 v12, 16, v6
	v_lshlrev_b32_e32 v2, 16, v3
	v_and_b32_e32 v13, 0xffff0000, v6
	v_and_b32_e32 v3, 0xffff0000, v3
	v_pk_mul_f32 v[2:3], v[12:13], v[2:3]
	s_waitcnt lgkmcnt(0)
	v_lshlrev_b32_e32 v6, 16, v64
	v_cvt_pk_bf16_f32 v13, v2, v3
	v_lshlrev_b32_e32 v2, 16, v5
	v_and_b32_e32 v3, 0xffff0000, v5
	v_and_b32_e32 v7, 0xffff0000, v64
	v_pk_mul_f32 v[2:3], v[2:3], v[6:7]
	v_cvt_pk_bf16_f32 v11, v10, v11
	v_cvt_pk_bf16_f32 v10, v2, v3
	v_lshlrev_b32_e32 v2, 16, v4
	v_lshlrev_b32_e32 v6, 16, v65
	v_and_b32_e32 v3, 0xffff0000, v4
	v_and_b32_e32 v7, 0xffff0000, v65
	v_pk_mul_f32 v[2:3], v[2:3], v[6:7]
	s_nop 0
	v_cvt_pk_bf16_f32 v12, v2, v3
	ds_read_b64 v[2:3], v113 offset:224
	ds_read_b64 v[64:65], v113 offset:16864
	v_lshlrev_b32_e32 v4, 16, v27
	v_and_b32_e32 v5, 0xffff0000, v27
	s_waitcnt lgkmcnt(1)
	v_lshlrev_b32_e32 v6, 16, v2
	v_and_b32_e32 v7, 0xffff0000, v2
	v_pk_mul_f32 v[4:5], v[4:5], v[6:7]
	v_lshlrev_b32_e32 v2, 16, v3
	v_cvt_pk_bf16_f32 v7, v4, v5
	v_lshlrev_b32_e32 v4, 16, v9
	v_and_b32_e32 v5, 0xffff0000, v9
	v_and_b32_e32 v3, 0xffff0000, v3
	v_pk_mul_f32 v[2:3], v[4:5], v[2:3]
	s_waitcnt lgkmcnt(0)
	v_lshlrev_b32_e32 v4, 16, v64
	v_cvt_pk_bf16_f32 v9, v2, v3
	v_lshlrev_b32_e32 v2, 16, v19
	v_and_b32_e32 v3, 0xffff0000, v19
	v_and_b32_e32 v5, 0xffff0000, v64
	v_pk_mul_f32 v[2:3], v[2:3], v[4:5]
	v_lshlrev_b32_e32 v4, 16, v65
	v_cvt_pk_bf16_f32 v6, v2, v3
	v_lshlrev_b32_e32 v2, 16, v8
	v_and_b32_e32 v3, 0xffff0000, v8
	v_and_b32_e32 v5, 0xffff0000, v65
	v_pk_mul_f32 v[2:3], v[2:3], v[4:5]
	s_nop 0
	v_cvt_pk_bf16_f32 v8, v2, v3
	ds_read_b64 v[2:3], v113 offset:240
	ds_read_b64 v[64:65], v113 offset:16880
	v_lshlrev_b32_e32 v4, 16, v112
	v_and_b32_e32 v5, 0xffff0000, v112
	s_waitcnt lgkmcnt(1)
	v_lshlrev_b32_e32 v66, 16, v2
	v_and_b32_e32 v67, 0xffff0000, v2
	v_pk_mul_f32 v[4:5], v[4:5], v[66:67]
	v_lshlrev_b32_e32 v66, 16, v30
	v_lshlrev_b32_e32 v2, 16, v3
	v_and_b32_e32 v67, 0xffff0000, v30
	v_and_b32_e32 v3, 0xffff0000, v3
	v_pk_mul_f32 v[2:3], v[66:67], v[2:3]
	v_cvt_pk_bf16_f32 v4, v4, v5
	v_cvt_pk_bf16_f32 v5, v2, v3
	v_lshlrev_b32_e32 v2, 16, v29
	s_waitcnt lgkmcnt(0)
	v_lshlrev_b32_e32 v66, 16, v64
	v_and_b32_e32 v3, 0xffff0000, v29
	v_and_b32_e32 v67, 0xffff0000, v64
	v_pk_mul_f32 v[2:3], v[2:3], v[66:67]
	v_lshlrev_b32_e32 v66, 16, v28
	v_lshlrev_b32_e32 v64, 16, v65
	v_and_b32_e32 v67, 0xffff0000, v28
	v_and_b32_e32 v65, 0xffff0000, v65
	v_pk_mul_f32 v[28:29], v[66:67], v[64:65]
	v_cvt_pk_bf16_f32 v2, v2, v3
	v_cvt_pk_bf16_f32 v3, v28, v29
	v_mov_b32_e32 v19, v192
	s_barrier
; DI int otid() { int t = threadIdx.x; asm volatile("" : "+v"(t)); return t; }
; template <bool NT>
; DI void stage_load_tile(bf16_t* stg, const bf16_t* tilebase) {
;   const int tid = otid();
;   const int r0 = tid >> 5, c = tid & 31;
;   const unsigned o0 = (unsigned)(r0 * 1024 + c * 8);
;   __builtin_amdgcn_sched_barrier(0);
; #pragma unroll
;   for (int hf = 0; hf < 2; ++hf) {
; #pragma unroll
;     for (int it = 8 * hf; it < 8 * hf + 8; ++it) {
;       const u32x4* gp = (const u32x4*)(tilebase + (o0 + (unsigned)(it * 16 * 1024)));
;       stage_write16(stg, r0 + 16 * it, c, NT ? __builtin_nontemporal_load(gp) : *gp);
;     }
;     __builtin_amdgcn_sched_barrier(0);
;   }
; template <bool LAST>
; DI void phase_gate(const Params& P, int layer, unsigned char* smem, int L, int G) {
;     ...
;     stage_load_tile<false>(stg, Sb + (size_t)mt * 256 * 1024 + nt * 256);
;     __syncthreads();
	s_add_u32 s26, s76, s24
	v_ashrrev_i32_e32 v27, 5, v19
	v_and_b32_e32 v19, 31, v19
	s_addc_u32 s27, s77, s25
	v_lshlrev_b32_e32 v30, 3, v19
	v_lshl_add_u64 v[28:29], s[26:27], 0, v[0:1]
	v_lshl_or_b32 v160, v27, 10, v30
	v_add_u32_e32 v66, 0x4000, v160
	v_mov_b32_e32 v67, v161
	v_add_u32_e32 v72, 0x8000, v160
	v_mov_b32_e32 v73, v161
	v_add_u32_e32 v74, 0xc000, v160
	v_mov_b32_e32 v75, v161
	v_add_u32_e32 v80, 0x10000, v160
	v_mov_b32_e32 v81, v161
	v_add_u32_e32 v82, 0x14000, v160
	v_mov_b32_e32 v83, v161
	v_lshl_add_u64 v[64:65], v[160:161], 1, v[28:29]
	v_lshl_add_u64 v[68:69], v[66:67], 1, v[28:29]
	v_lshl_add_u64 v[72:73], v[72:73], 1, v[28:29]
	v_lshl_add_u64 v[76:77], v[74:75], 1, v[28:29]
	v_lshl_add_u64 v[80:81], v[80:81], 1, v[28:29]
	v_lshl_add_u64 v[84:85], v[82:83], 1, v[28:29]
	global_load_dwordx4 v[64:67], v[64:65], off
	s_nop 0
	global_load_dwordx4 v[68:71], v[68:69], off
	s_nop 0
	global_load_dwordx4 v[72:75], v[72:73], off
	s_nop 0
	global_load_dwordx4 v[76:79], v[76:77], off
	s_nop 0
	global_load_dwordx4 v[80:83], v[80:81], off
	s_nop 0
	global_load_dwordx4 v[100:103], v[84:85], off
	v_add_u32_e32 v84, 0x18000, v160
	v_mov_b32_e32 v85, v161
	v_add_u32_e32 v104, 0x1c000, v160
	v_mov_b32_e32 v105, v161
	v_lshl_add_u64 v[84:85], v[84:85], 1, v[28:29]
	v_lshl_add_u64 v[108:109], v[104:105], 1, v[28:29]
	global_load_dwordx4 v[104:107], v[84:85], off
	s_nop 0
	global_load_dwordx4 v[108:111], v[108:109], off
	v_add_u32_e32 v218, 0x20000, v160
	v_mov_b32_e32 v219, v161
	v_add_u32_e32 v220, 0x24000, v160
	v_mov_b32_e32 v221, v161
	v_add_u32_e32 v226, 0x28000, v160
	v_mov_b32_e32 v227, v161
	v_add_u32_e32 v228, 0x2c000, v160
	v_mov_b32_e32 v229, v161
	v_add_u32_e32 v234, 0x30000, v160
	v_mov_b32_e32 v235, v161
	v_add_u32_e32 v236, 0x34000, v160
	v_mov_b32_e32 v237, v161
	v_lshl_add_u64 v[218:219], v[218:219], 1, v[28:29]
	v_lshl_add_u64 v[222:223], v[220:221], 1, v[28:29]
	v_lshl_add_u64 v[226:227], v[226:227], 1, v[28:29]
	v_lshl_add_u64 v[230:231], v[228:229], 1, v[28:29]
	v_lshl_add_u64 v[234:235], v[234:235], 1, v[28:29]
	v_lshl_add_u64 v[252:253], v[236:237], 1, v[28:29]
	global_load_dwordx4 v[218:221], v[218:219], off
	s_nop 0
	global_load_dwordx4 v[222:225], v[222:223], off
	s_nop 0
	global_load_dwordx4 v[226:229], v[226:227], off
	s_nop 0
	global_load_dwordx4 v[230:233], v[230:231], off
	s_nop 0
	global_load_dwordx4 v[234:237], v[234:235], off
	s_nop 0
	global_load_dwordx4 v[238:241], v[252:253], off
	v_add_u32_e32 v252, 0x38000, v160
	v_mov_b32_e32 v253, v161
	v_lshl_add_u64 v[252:253], v[252:253], 1, v[28:29]
	v_add_u32_e32 v160, 0x3c000, v160
	v_lshl_add_u64 v[190:191], v[160:161], 1, v[28:29]
	global_load_dwordx4 v[242:245], v[252:253], off
	global_load_dwordx4 v[248:251], v[190:191], off
	v_mul_lo_u32 v27, v27, s40
	v_lshl_add_u32 v19, v19, 4, v27
	v_add_u32_e32 v27, 0x2080, v19
	v_add_u32_e32 v30, 0x4100, v19
	v_add_u32_e32 v33, 0x6180, v19
	v_add_u32_e32 v53, 0x8200, v19
	v_add_u32_e32 v55, 0xa280, v19
	v_add_u32_e32 v59, 0xc300, v19
	v_add_u32_e32 v84, 0xe380, v19
	s_waitcnt vmcnt(15)
	ds_write2_b64 v19, v[64:65], v[66:67] offset1:1
	s_waitcnt vmcnt(14)
	ds_write2_b64 v27, v[68:69], v[70:71] offset1:1
	s_waitcnt vmcnt(13)
	ds_write2_b64 v30, v[72:73], v[74:75] offset1:1
	s_waitcnt vmcnt(12)
	ds_write2_b64 v33, v[76:77], v[78:79] offset1:1
	s_waitcnt vmcnt(11)
	ds_write2_b64 v53, v[80:81], v[82:83] offset1:1
	s_waitcnt vmcnt(10)
	ds_write2_b64 v55, v[100:101], v[102:103] offset1:1
	s_waitcnt vmcnt(9)
	ds_write2_b64 v59, v[104:105], v[106:107] offset1:1
	s_waitcnt vmcnt(8)
	ds_write2_b64 v84, v[108:109], v[110:111] offset1:1
	v_add_u32_e32 v27, 0x10400, v19
	v_add_u32_e32 v28, 0x12480, v19
	v_add_u32_e32 v29, 0x14500, v19
	v_add_u32_e32 v30, 0x16580, v19
	v_add_u32_e32 v33, 0x18600, v19
	v_add_u32_e32 v53, 0x1a680, v19
	v_add_u32_e32 v55, 0x1c700, v19
	v_add_u32_e32 v19, 0x1e780, v19
	s_waitcnt vmcnt(7)
	ds_write2_b64 v27, v[218:219], v[220:221] offset1:1
	s_waitcnt vmcnt(6)
	ds_write2_b64 v28, v[222:223], v[224:225] offset1:1
	s_waitcnt vmcnt(5)
	ds_write2_b64 v29, v[226:227], v[228:229] offset1:1
	s_waitcnt vmcnt(4)
	ds_write2_b64 v30, v[230:231], v[232:233] offset1:1
	s_waitcnt vmcnt(3)
	ds_write2_b64 v33, v[234:235], v[236:237] offset1:1
	s_waitcnt vmcnt(2)
	ds_write2_b64 v53, v[238:239], v[240:241] offset1:1
	s_waitcnt vmcnt(1)
	ds_write2_b64 v55, v[242:243], v[244:245] offset1:1
	s_waitcnt vmcnt(0)
	ds_write2_b64 v19, v[248:249], v[250:251] offset1:1
	v_mov_b32_e32 v19, v192
	s_waitcnt lgkmcnt(0)
	s_barrier
; DI unsigned pack2(float a, float b) { f32x2_t v = {a, b}; bf16x2_t r = __builtin_convertvector(v, bf16x2_t); return __builtin_bit_cast(unsigned, r); }
; DI float bflo(unsigned u) { return __uint_as_float(u << 16); }
; DI float bfhi(unsigned u) { return __uint_as_float(u & 0xffff0000u); }
; DI int otid() { int t = threadIdx.x; asm volatile("" : "+v"(t)); return t; }
; template <bool LAST>
; DI void phase_gate(const Params& P, int layer, unsigned char* smem, int L, int G) {
;     ...
;     const int tid2 = otid();
;     const int lane2 = tid2 & 63, w2 = tid2 >> 6, r2 = lane2 & 31, h2 = lane2 >> 5, wm2 = w2 >> 2, wn2 = w2 & 3;
; #pragma unroll
;     for (int i = 0; i < 4; ++i)
; #pragma unroll
;       for (int q4 = 0; q4 < 4; ++q4) {
;         const int fl = wm2 * 128 + i * 32 + 8 * q4 + 4 * h2;
;         const int f0 = nt * 256 + fl;
;         const f32x4 gv = *(const f32x4*)(vecL + 512 + fl), bv = *(const f32x4*)(vecL + 768 + fl);
;         const float ga[4] = {gv.x, gv.y, gv.z, gv.w}, ba[4] = {bv.x, bv.y, bv.z, bv.w};
; #pragma unroll
;         for (int j = 0; j < 2; ++j) {
;           const int lrow = wn2 * 64 + j * 32 + r2;
;           const float mu = rowA[lrow], rstd = rowB[lrow];
;           uint2* sp = (uint2*)(stg + lrow * STG + fl);
;           const uint2 sv = *sp;
;           const float sa[4] = {bflo(sv.x), bfhi(sv.x), bflo(sv.y), bfhi(sv.y)};
;           float y[4];
;           const float gg[4] = {bflo(gq[i][j][2 * q4]), bfhi(gq[i][j][2 * q4]), bflo(gq[i][j][2 * q4 + 1]), bfhi(gq[i][j][2 * q4 + 1])};
; #pragma unroll
;           for (int e = 0; e < 4; ++e) y[e] = (sa[e] - mu) * rstd * ga[e] + ba[e] + gg[e];
;           if (LAST) { f32x4 o = {y[0], y[1], y[2], y[3]}; *(f32x4*)(P.out + (size_t)(mt * 256 + lrow) * 1024 + f0) = o; }
;           else { uint2 pk; pk.x = pack2(y[0], y[1]); pk.y = pack2(y[2], y[3]); *sp = pk; }
;         }
;         __builtin_amdgcn_sched_barrier(0);
	v_lshlrev_b32_e32 v82, 16, v31
	v_lshrrev_b32_e32 v28, 3, v19
	v_ashrrev_i32_e32 v27, 1, v19
	v_and_b32_e32 v28, 4, v28
	v_and_or_b32 v30, v27, s41, v28
	v_and_b32_e32 v19, 0xdf, v19
	v_lshlrev_b32_e32 v27, 2, v30
	v_lshlrev_b32_e32 v33, 2, v19
	v_mul_u32_u24_e32 v19, 0x208, v19
	v_add_u32_e32 v28, 0x25000, v27
	v_lshl_add_u32 v19, v30, 1, v19
	v_add_u32_e32 v29, 0x25400, v27
	ds_read_b128 v[64:67], v28
	ds_read_b128 v[68:71], v29
	ds_read_b64 v[72:73], v19
	v_or_b32_e32 v29, 0x24000, v33
	v_or_b32_e32 v30, 0x24400, v33
	ds_read_b32 v74, v29
	ds_read_b32 v76, v30
	ds_read_b64 v[78:79], v19 offset:16640
	v_and_b32_e32 v83, 0xffff0000, v31
	s_waitcnt lgkmcnt(3)
	v_lshlrev_b32_e32 v80, 16, v72
	v_and_b32_e32 v81, 0xffff0000, v72
	v_lshlrev_b32_e32 v72, 16, v73
	v_and_b32_e32 v73, 0xffff0000, v73
	s_waitcnt lgkmcnt(2)
	v_pk_add_f32 v[80:81], v[80:81], v[74:75] op_sel_hi:[1,0] neg_lo:[0,1] neg_hi:[0,1]
	v_pk_add_f32 v[72:73], v[72:73], v[74:75] op_sel_hi:[1,0] neg_lo:[0,1] neg_hi:[0,1]
	s_waitcnt lgkmcnt(1)
	v_pk_mul_f32 v[80:81], v[76:77], v[80:81] op_sel_hi:[0,1]
	v_pk_mul_f32 v[72:73], v[76:77], v[72:73] op_sel_hi:[0,1]
	v_lshlrev_b32_e32 v84, 16, v98
	v_and_b32_e32 v85, 0xffff0000, v98
	v_pk_fma_f32 v[80:81], v[64:65], v[80:81], v[68:69]
	v_pk_fma_f32 v[72:73], v[66:67], v[72:73], v[70:71]
	v_pk_add_f32 v[80:81], v[80:81], v[82:83]
	v_pk_add_f32 v[72:73], v[72:73], v[84:85]
	v_cvt_pk_bf16_f32 v74, v80, v81
	v_cvt_pk_bf16_f32 v75, v72, v73
	ds_write_b64 v19, v[74:75]
	v_or_b32_e32 v31, 0x24080, v33
	v_or_b32_e32 v33, 0x24480, v33
	ds_read_b32 v72, v31
	ds_read_b32 v74, v33
	s_waitcnt lgkmcnt(3)
	v_lshlrev_b32_e32 v76, 16, v78
	v_and_b32_e32 v77, 0xffff0000, v78
	v_lshlrev_b32_e32 v78, 16, v79
	s_waitcnt lgkmcnt(1)
	v_pk_add_f32 v[76:77], v[76:77], v[72:73] op_sel_hi:[1,0] neg_lo:[0,1] neg_hi:[0,1]
	v_and_b32_e32 v79, 0xffff0000, v79
	s_waitcnt lgkmcnt(0)
	v_pk_mul_f32 v[76:77], v[74:75], v[76:77] op_sel_hi:[0,1]
	v_pk_fma_f32 v[64:65], v[64:65], v[76:77], v[68:69]
	v_pk_add_f32 v[68:69], v[78:79], v[72:73] op_sel_hi:[1,0] neg_lo:[0,1] neg_hi:[0,1]
	v_lshlrev_b32_e32 v80, 16, v97
	v_pk_mul_f32 v[68:69], v[74:75], v[68:69] op_sel_hi:[0,1]
	v_and_b32_e32 v81, 0xffff0000, v97
	v_lshlrev_b32_e32 v82, 16, v96
	v_and_b32_e32 v83, 0xffff0000, v96
	v_pk_fma_f32 v[66:67], v[66:67], v[68:69], v[70:71]
	v_pk_add_f32 v[64:65], v[64:65], v[80:81]
	v_pk_add_f32 v[66:67], v[66:67], v[82:83]
	v_cvt_pk_bf16_f32 v64, v64, v65
	v_cvt_pk_bf16_f32 v65, v66, v67
	ds_write_b64 v19, v[64:65] offset:16640
	v_add_u32_e32 v53, 0x25020, v27
	v_add_u32_e32 v55, 0x25420, v27
	ds_read_b64 v[72:73], v19 offset:16
	ds_read_b128 v[64:67], v53
	ds_read_b128 v[68:71], v55
	ds_read_b32 v74, v29
	ds_read_b32 v76, v30
	ds_read_b64 v[78:79], v19 offset:16656
	s_waitcnt lgkmcnt(5)
	v_lshlrev_b32_e32 v80, 16, v72
	v_and_b32_e32 v81, 0xffff0000, v72
	v_lshlrev_b32_e32 v72, 16, v73
	v_and_b32_e32 v73, 0xffff0000, v73
	s_waitcnt lgkmcnt(2)
	v_pk_add_f32 v[80:81], v[80:81], v[74:75] op_sel_hi:[1,0] neg_lo:[0,1] neg_hi:[0,1]
	v_pk_add_f32 v[72:73], v[72:73], v[74:75] op_sel_hi:[1,0] neg_lo:[0,1] neg_hi:[0,1]
	s_waitcnt lgkmcnt(1)
	v_pk_mul_f32 v[80:81], v[76:77], v[80:81] op_sel_hi:[0,1]
	v_pk_mul_f32 v[72:73], v[76:77], v[72:73] op_sel_hi:[0,1]
	v_lshlrev_b32_e32 v82, 16, v93
	v_and_b32_e32 v83, 0xffff0000, v93
	v_lshlrev_b32_e32 v84, 16, v95
	v_and_b32_e32 v85, 0xffff0000, v95
	v_pk_fma_f32 v[80:81], v[64:65], v[80:81], v[68:69]
	v_pk_fma_f32 v[72:73], v[66:67], v[72:73], v[70:71]
	v_pk_add_f32 v[80:81], v[80:81], v[82:83]
	v_pk_add_f32 v[72:73], v[72:73], v[84:85]
	v_cvt_pk_bf16_f32 v74, v80, v81
	v_cvt_pk_bf16_f32 v75, v72, v73
	ds_write_b64 v19, v[74:75] offset:16
	ds_read_b32 v72, v31
	ds_read_b32 v74, v33
	s_waitcnt lgkmcnt(3)
	v_lshlrev_b32_e32 v76, 16, v78
	v_and_b32_e32 v77, 0xffff0000, v78
	v_lshlrev_b32_e32 v78, 16, v79
	s_waitcnt lgkmcnt(1)
	v_pk_add_f32 v[76:77], v[76:77], v[72:73] op_sel_hi:[1,0] neg_lo:[0,1] neg_hi:[0,1]
	v_and_b32_e32 v79, 0xffff0000, v79
	s_waitcnt lgkmcnt(0)
	v_pk_mul_f32 v[76:77], v[74:75], v[76:77] op_sel_hi:[0,1]
	v_pk_fma_f32 v[64:65], v[64:65], v[76:77], v[68:69]
	v_pk_add_f32 v[68:69], v[78:79], v[72:73] op_sel_hi:[1,0] neg_lo:[0,1] neg_hi:[0,1]
	v_lshlrev_b32_e32 v80, 16, v92
	v_pk_mul_f32 v[68:69], v[74:75], v[68:69] op_sel_hi:[0,1]
	v_and_b32_e32 v81, 0xffff0000, v92
	v_lshlrev_b32_e32 v82, 16, v94
	v_and_b32_e32 v83, 0xffff0000, v94
	v_pk_fma_f32 v[66:67], v[66:67], v[68:69], v[70:71]
	v_pk_add_f32 v[64:65], v[64:65], v[80:81]
	v_pk_add_f32 v[66:67], v[66:67], v[82:83]
	v_cvt_pk_bf16_f32 v64, v64, v65
	v_cvt_pk_bf16_f32 v65, v66, v67
	ds_write_b64 v19, v[64:65] offset:16656
	v_add_u32_e32 v53, 0x25040, v27
	v_add_u32_e32 v55, 0x25440, v27
	ds_read_b64 v[72:73], v19 offset:32
	ds_read_b128 v[64:67], v53
	ds_read_b128 v[68:71], v55
	ds_read_b32 v74, v29
	ds_read_b32 v76, v30
	ds_read_b64 v[78:79], v19 offset:16672
	s_waitcnt lgkmcnt(5)
	v_lshlrev_b32_e32 v80, 16, v72
	v_and_b32_e32 v81, 0xffff0000, v72
	v_lshlrev_b32_e32 v72, 16, v73
	v_and_b32_e32 v73, 0xffff0000, v73
	s_waitcnt lgkmcnt(2)
	v_pk_add_f32 v[80:81], v[80:81], v[74:75] op_sel_hi:[1,0] neg_lo:[0,1] neg_hi:[0,1]
	v_pk_add_f32 v[72:73], v[72:73], v[74:75] op_sel_hi:[1,0] neg_lo:[0,1] neg_hi:[0,1]
	s_waitcnt lgkmcnt(1)
	v_pk_mul_f32 v[80:81], v[76:77], v[80:81] op_sel_hi:[0,1]
	v_pk_mul_f32 v[72:73], v[76:77], v[72:73] op_sel_hi:[0,1]
	v_lshlrev_b32_e32 v82, 16, v88
	v_and_b32_e32 v83, 0xffff0000, v88
	v_lshlrev_b32_e32 v84, 16, v90
	v_and_b32_e32 v85, 0xffff0000, v90
	v_pk_fma_f32 v[80:81], v[64:65], v[80:81], v[68:69]
	v_pk_fma_f32 v[72:73], v[66:67], v[72:73], v[70:71]
	v_pk_add_f32 v[80:81], v[80:81], v[82:83]
	v_pk_add_f32 v[72:73], v[72:73], v[84:85]
	v_cvt_pk_bf16_f32 v74, v80, v81
	v_cvt_pk_bf16_f32 v75, v72, v73
	ds_write_b64 v19, v[74:75] offset:32
	ds_read_b32 v72, v31
	ds_read_b32 v74, v33
	s_waitcnt lgkmcnt(3)
; DI unsigned pack2(float a, float b) { f32x2_t v = {a, b}; bf16x2_t r = __builtin_convertvector(v, bf16x2_t); return __builtin_bit_cast(unsigned, r); }
; DI float bflo(unsigned u) { return __uint_as_float(u << 16); }
; DI float bfhi(unsigned u) { return __uint_as_float(u & 0xffff0000u); }
; DI int otid() { int t = threadIdx.x; asm volatile("" : "+v"(t)); return t; }
; template <bool LAST>
; DI void phase_gate(const Params& P, int layer, unsigned char* smem, int L, int G) {
;     ...
;     const int tid2 = otid();
;     const int lane2 = tid2 & 63, w2 = tid2 >> 6, r2 = lane2 & 31, h2 = lane2 >> 5, wm2 = w2 >> 2, wn2 = w2 & 3;
; #pragma unroll
;     for (int i = 0; i < 4; ++i)
; #pragma unroll
;       for (int q4 = 0; q4 < 4; ++q4) {
;         const int fl = wm2 * 128 + i * 32 + 8 * q4 + 4 * h2;
;         const int f0 = nt * 256 + fl;
;         const f32x4 gv = *(const f32x4*)(vecL + 512 + fl), bv = *(const f32x4*)(vecL + 768 + fl);
;         const float ga[4] = {gv.x, gv.y, gv.z, gv.w}, ba[4] = {bv.x, bv.y, bv.z, bv.w};
; #pragma unroll
;         for (int j = 0; j < 2; ++j) {
;           const int lrow = wn2 * 64 + j * 32 + r2;
;           const float mu = rowA[lrow], rstd = rowB[lrow];
;           uint2* sp = (uint2*)(stg + lrow * STG + fl);
;           const uint2 sv = *sp;
;           const float sa[4] = {bflo(sv.x), bfhi(sv.x), bflo(sv.y), bfhi(sv.y)};
;           float y[4];
;           const float gg[4] = {bflo(gq[i][j][2 * q4]), bfhi(gq[i][j][2 * q4]), bflo(gq[i][j][2 * q4 + 1]), bfhi(gq[i][j][2 * q4 + 1])};
; #pragma unroll
;           for (int e = 0; e < 4; ++e) y[e] = (sa[e] - mu) * rstd * ga[e] + ba[e] + gg[e];
;           if (LAST) { f32x4 o = {y[0], y[1], y[2], y[3]}; *(f32x4*)(P.out + (size_t)(mt * 256 + lrow) * 1024 + f0) = o; }
;           else { uint2 pk; pk.x = pack2(y[0], y[1]); pk.y = pack2(y[2], y[3]); *sp = pk; }
;         }
;         __builtin_amdgcn_sched_barrier(0);
	v_lshlrev_b32_e32 v76, 16, v78
	v_and_b32_e32 v77, 0xffff0000, v78
	v_lshlrev_b32_e32 v78, 16, v79
	s_waitcnt lgkmcnt(1)
	v_pk_add_f32 v[76:77], v[76:77], v[72:73] op_sel_hi:[1,0] neg_lo:[0,1] neg_hi:[0,1]
	v_and_b32_e32 v79, 0xffff0000, v79
	s_waitcnt lgkmcnt(0)
	v_pk_mul_f32 v[76:77], v[74:75], v[76:77] op_sel_hi:[0,1]
	v_pk_fma_f32 v[64:65], v[64:65], v[76:77], v[68:69]
	v_pk_add_f32 v[68:69], v[78:79], v[72:73] op_sel_hi:[1,0] neg_lo:[0,1] neg_hi:[0,1]
	v_lshlrev_b32_e32 v80, 16, v87
	v_pk_mul_f32 v[68:69], v[74:75], v[68:69] op_sel_hi:[0,1]
	v_and_b32_e32 v81, 0xffff0000, v87
	v_lshlrev_b32_e32 v82, 16, v89
	v_and_b32_e32 v83, 0xffff0000, v89
	v_pk_fma_f32 v[66:67], v[66:67], v[68:69], v[70:71]
	v_pk_add_f32 v[64:65], v[64:65], v[80:81]
	v_pk_add_f32 v[66:67], v[66:67], v[82:83]
	v_cvt_pk_bf16_f32 v64, v64, v65
	v_cvt_pk_bf16_f32 v65, v66, v67
	ds_write_b64 v19, v[64:65] offset:16672
	v_add_u32_e32 v53, 0x25060, v27
	v_add_u32_e32 v55, 0x25460, v27
	ds_read_b64 v[72:73], v19 offset:48
	ds_read_b128 v[64:67], v53
	ds_read_b128 v[68:71], v55
	ds_read_b32 v74, v29
	ds_read_b32 v76, v30
	ds_read_b64 v[78:79], v19 offset:16688
	s_waitcnt lgkmcnt(5)
	v_lshlrev_b32_e32 v80, 16, v72
	v_and_b32_e32 v81, 0xffff0000, v72
	v_lshlrev_b32_e32 v72, 16, v73
	v_and_b32_e32 v73, 0xffff0000, v73
	s_waitcnt lgkmcnt(2)
	v_pk_add_f32 v[80:81], v[80:81], v[74:75] op_sel_hi:[1,0] neg_lo:[0,1] neg_hi:[0,1]
	v_pk_add_f32 v[72:73], v[72:73], v[74:75] op_sel_hi:[1,0] neg_lo:[0,1] neg_hi:[0,1]
	s_waitcnt lgkmcnt(1)
	v_pk_mul_f32 v[80:81], v[76:77], v[80:81] op_sel_hi:[0,1]
	v_pk_mul_f32 v[72:73], v[76:77], v[72:73] op_sel_hi:[0,1]
	v_lshlrev_b32_e32 v82, 16, v61
	v_and_b32_e32 v83, 0xffff0000, v61
	v_lshlrev_b32_e32 v84, 16, v63
	v_and_b32_e32 v85, 0xffff0000, v63
	v_pk_fma_f32 v[80:81], v[64:65], v[80:81], v[68:69]
	v_pk_fma_f32 v[72:73], v[66:67], v[72:73], v[70:71]
	v_pk_add_f32 v[80:81], v[80:81], v[82:83]
	v_pk_add_f32 v[72:73], v[72:73], v[84:85]
	v_cvt_pk_bf16_f32 v74, v80, v81
	v_cvt_pk_bf16_f32 v75, v72, v73
	ds_write_b64 v19, v[74:75] offset:48
	ds_read_b32 v72, v31
	ds_read_b32 v74, v33
	s_waitcnt lgkmcnt(3)
	v_lshlrev_b32_e32 v76, 16, v78
	v_and_b32_e32 v77, 0xffff0000, v78
	v_lshlrev_b32_e32 v80, 16, v60
	v_and_b32_e32 v81, 0xffff0000, v60
	v_lshlrev_b32_e32 v60, 16, v62
	v_and_b32_e32 v61, 0xffff0000, v62
	s_waitcnt lgkmcnt(1)
	v_pk_add_f32 v[62:63], v[76:77], v[72:73] op_sel_hi:[1,0] neg_lo:[0,1] neg_hi:[0,1]
	v_lshlrev_b32_e32 v78, 16, v79
	v_and_b32_e32 v79, 0xffff0000, v79
	s_waitcnt lgkmcnt(0)
	v_pk_mul_f32 v[62:63], v[74:75], v[62:63] op_sel_hi:[0,1]
	v_pk_fma_f32 v[62:63], v[64:65], v[62:63], v[68:69]
	v_pk_add_f32 v[64:65], v[78:79], v[72:73] op_sel_hi:[1,0] neg_lo:[0,1] neg_hi:[0,1]
	v_pk_add_f32 v[62:63], v[62:63], v[80:81]
	v_pk_mul_f32 v[64:65], v[74:75], v[64:65] op_sel_hi:[0,1]
	v_pk_fma_f32 v[64:65], v[66:67], v[64:65], v[70:71]
	v_cvt_pk_bf16_f32 v62, v62, v63
	v_pk_add_f32 v[60:61], v[64:65], v[60:61]
	s_nop 0
	v_cvt_pk_bf16_f32 v63, v60, v61
	ds_write_b64 v19, v[62:63] offset:16688
	v_add_u32_e32 v53, 0x25080, v27
	v_add_u32_e32 v55, 0x25480, v27
	ds_read_b64 v[68:69], v19 offset:64
	ds_read_b128 v[60:63], v53
	ds_read_b128 v[64:67], v55
	ds_read_b32 v70, v29
	ds_read_b32 v72, v30
	ds_read_b64 v[74:75], v19 offset:16704
	s_waitcnt lgkmcnt(5)
	v_lshlrev_b32_e32 v76, 16, v68
	v_and_b32_e32 v77, 0xffff0000, v68
	v_lshlrev_b32_e32 v68, 16, v69
	v_and_b32_e32 v69, 0xffff0000, v69
	v_lshlrev_b32_e32 v80, 16, v58
	v_and_b32_e32 v81, 0xffff0000, v58
	s_waitcnt lgkmcnt(2)
	v_pk_add_f32 v[58:59], v[76:77], v[70:71] op_sel_hi:[1,0] neg_lo:[0,1] neg_hi:[0,1]
	v_pk_add_f32 v[68:69], v[68:69], v[70:71] op_sel_hi:[1,0] neg_lo:[0,1] neg_hi:[0,1]
	s_waitcnt lgkmcnt(1)
	v_pk_mul_f32 v[58:59], v[72:73], v[58:59] op_sel_hi:[0,1]
	v_pk_mul_f32 v[68:69], v[72:73], v[68:69] op_sel_hi:[0,1]
	v_lshlrev_b32_e32 v78, 16, v56
	v_and_b32_e32 v79, 0xffff0000, v56
	v_pk_fma_f32 v[58:59], v[60:61], v[58:59], v[64:65]
	v_pk_fma_f32 v[68:69], v[62:63], v[68:69], v[66:67]
	v_pk_add_f32 v[58:59], v[58:59], v[78:79]
	v_pk_add_f32 v[68:69], v[68:69], v[80:81]
	v_cvt_pk_bf16_f32 v58, v58, v59
	v_cvt_pk_bf16_f32 v59, v68, v69
	ds_write_b64 v19, v[58:59] offset:64
	ds_read_b32 v56, v31
	ds_read_b32 v58, v33
	s_waitcnt lgkmcnt(3)
	v_lshlrev_b32_e32 v68, 16, v74
	v_and_b32_e32 v69, 0xffff0000, v74
	v_lshlrev_b32_e32 v70, 16, v75
	v_and_b32_e32 v71, 0xffff0000, v75
	v_lshlrev_b32_e32 v72, 16, v54
	v_and_b32_e32 v73, 0xffff0000, v54
	v_lshlrev_b32_e32 v54, 16, v57
	v_and_b32_e32 v55, 0xffff0000, v57
	s_waitcnt lgkmcnt(1)
	v_pk_add_f32 v[68:69], v[68:69], v[56:57] op_sel_hi:[1,0] neg_lo:[0,1] neg_hi:[0,1]
	v_pk_add_f32 v[56:57], v[70:71], v[56:57] op_sel_hi:[1,0] neg_lo:[0,1] neg_hi:[0,1]
	s_waitcnt lgkmcnt(0)
	v_pk_mul_f32 v[68:69], v[58:59], v[68:69] op_sel_hi:[0,1]
	v_pk_mul_f32 v[56:57], v[58:59], v[56:57] op_sel_hi:[0,1]
	v_pk_fma_f32 v[60:61], v[60:61], v[68:69], v[64:65]
	v_pk_fma_f32 v[56:57], v[62:63], v[56:57], v[66:67]
	v_pk_add_f32 v[60:61], v[60:61], v[72:73]
	v_pk_add_f32 v[54:55], v[56:57], v[54:55]
	v_cvt_pk_bf16_f32 v56, v60, v61
	v_cvt_pk_bf16_f32 v57, v54, v55
	ds_write_b64 v19, v[56:57] offset:16704
	v_add_u32_e32 v58, 0x254a0, v27
	v_add_u32_e32 v53, 0x250a0, v27
	ds_read_b64 v[62:63], v19 offset:80
	ds_read_b128 v[54:57], v53
	ds_read_b128 v[58:61], v58
	ds_read_b32 v64, v29
	ds_read_b32 v66, v30
	ds_read_b64 v[68:69], v19 offset:16720
	s_waitcnt lgkmcnt(5)
	v_lshlrev_b32_e32 v70, 16, v62
	v_and_b32_e32 v71, 0xffff0000, v62
	v_lshlrev_b32_e32 v62, 16, v63
	v_and_b32_e32 v63, 0xffff0000, v63
	v_lshlrev_b32_e32 v74, 16, v52
	v_and_b32_e32 v75, 0xffff0000, v52
	s_waitcnt lgkmcnt(2)
; DI unsigned pack2(float a, float b) { f32x2_t v = {a, b}; bf16x2_t r = __builtin_convertvector(v, bf16x2_t); return __builtin_bit_cast(unsigned, r); }
; DI float bflo(unsigned u) { return __uint_as_float(u << 16); }
; DI float bfhi(unsigned u) { return __uint_as_float(u & 0xffff0000u); }
; DI int otid() { int t = threadIdx.x; asm volatile("" : "+v"(t)); return t; }
; template <bool LAST>
; DI void phase_gate(const Params& P, int layer, unsigned char* smem, int L, int G) {
;     ...
;     const int tid2 = otid();
;     const int lane2 = tid2 & 63, w2 = tid2 >> 6, r2 = lane2 & 31, h2 = lane2 >> 5, wm2 = w2 >> 2, wn2 = w2 & 3;
; #pragma unroll
;     for (int i = 0; i < 4; ++i)
; #pragma unroll
;       for (int q4 = 0; q4 < 4; ++q4) {
;         const int fl = wm2 * 128 + i * 32 + 8 * q4 + 4 * h2;
;         const int f0 = nt * 256 + fl;
;         const f32x4 gv = *(const f32x4*)(vecL + 512 + fl), bv = *(const f32x4*)(vecL + 768 + fl);
;         const float ga[4] = {gv.x, gv.y, gv.z, gv.w}, ba[4] = {bv.x, bv.y, bv.z, bv.w};
; #pragma unroll
;         for (int j = 0; j < 2; ++j) {
;           const int lrow = wn2 * 64 + j * 32 + r2;
;           const float mu = rowA[lrow], rstd = rowB[lrow];
;           uint2* sp = (uint2*)(stg + lrow * STG + fl);
;           const uint2 sv = *sp;
;           const float sa[4] = {bflo(sv.x), bfhi(sv.x), bflo(sv.y), bfhi(sv.y)};
;           float y[4];
;           const float gg[4] = {bflo(gq[i][j][2 * q4]), bfhi(gq[i][j][2 * q4]), bflo(gq[i][j][2 * q4 + 1]), bfhi(gq[i][j][2 * q4 + 1])};
; #pragma unroll
;           for (int e = 0; e < 4; ++e) y[e] = (sa[e] - mu) * rstd * ga[e] + ba[e] + gg[e];
;           if (LAST) { f32x4 o = {y[0], y[1], y[2], y[3]}; *(f32x4*)(P.out + (size_t)(mt * 256 + lrow) * 1024 + f0) = o; }
;           else { uint2 pk; pk.x = pack2(y[0], y[1]); pk.y = pack2(y[2], y[3]); *sp = pk; }
;         }
;         __builtin_amdgcn_sched_barrier(0);
	v_pk_add_f32 v[52:53], v[70:71], v[64:65] op_sel_hi:[1,0] neg_lo:[0,1] neg_hi:[0,1]
	v_pk_add_f32 v[62:63], v[62:63], v[64:65] op_sel_hi:[1,0] neg_lo:[0,1] neg_hi:[0,1]
	s_waitcnt lgkmcnt(1)
	v_pk_mul_f32 v[52:53], v[66:67], v[52:53] op_sel_hi:[0,1]
	v_pk_mul_f32 v[62:63], v[66:67], v[62:63] op_sel_hi:[0,1]
	v_lshlrev_b32_e32 v72, 16, v50
	v_and_b32_e32 v73, 0xffff0000, v50
	v_pk_fma_f32 v[52:53], v[54:55], v[52:53], v[58:59]
	v_pk_fma_f32 v[62:63], v[56:57], v[62:63], v[60:61]
	v_pk_add_f32 v[52:53], v[52:53], v[72:73]
	v_pk_add_f32 v[62:63], v[62:63], v[74:75]
	v_cvt_pk_bf16_f32 v52, v52, v53
	v_cvt_pk_bf16_f32 v53, v62, v63
	ds_write_b64 v19, v[52:53] offset:80
	ds_read_b32 v50, v31
	ds_read_b32 v52, v33
	s_waitcnt lgkmcnt(3)
	v_lshlrev_b32_e32 v62, 16, v68
	v_and_b32_e32 v63, 0xffff0000, v68
	v_lshlrev_b32_e32 v64, 16, v69
	v_and_b32_e32 v65, 0xffff0000, v69
	v_lshlrev_b32_e32 v68, 16, v51
	v_and_b32_e32 v69, 0xffff0000, v51
	s_waitcnt lgkmcnt(1)
	v_pk_add_f32 v[62:63], v[62:63], v[50:51] op_sel_hi:[1,0] neg_lo:[0,1] neg_hi:[0,1]
	v_pk_add_f32 v[50:51], v[64:65], v[50:51] op_sel_hi:[1,0] neg_lo:[0,1] neg_hi:[0,1]
	s_waitcnt lgkmcnt(0)
	v_pk_mul_f32 v[62:63], v[52:53], v[62:63] op_sel_hi:[0,1]
	v_pk_mul_f32 v[50:51], v[52:53], v[50:51] op_sel_hi:[0,1]
	v_lshlrev_b32_e32 v66, 16, v49
	v_and_b32_e32 v67, 0xffff0000, v49
	v_pk_fma_f32 v[54:55], v[54:55], v[62:63], v[58:59]
	v_pk_fma_f32 v[50:51], v[56:57], v[50:51], v[60:61]
	v_pk_add_f32 v[54:55], v[54:55], v[66:67]
	v_pk_add_f32 v[50:51], v[50:51], v[68:69]
	v_cvt_pk_bf16_f32 v52, v54, v55
	v_cvt_pk_bf16_f32 v53, v50, v51
	ds_write_b64 v19, v[52:53] offset:16720
	v_add_u32_e32 v54, 0x254c0, v27
	v_add_u32_e32 v49, 0x250c0, v27
	ds_read_b64 v[58:59], v19 offset:96
	ds_read_b128 v[50:53], v49
	ds_read_b128 v[54:57], v54
	ds_read_b32 v60, v29
	ds_read_b32 v62, v30
	ds_read_b64 v[64:65], v19 offset:16736
	s_waitcnt lgkmcnt(5)
	v_lshlrev_b32_e32 v66, 16, v58
	v_and_b32_e32 v67, 0xffff0000, v58
	v_lshlrev_b32_e32 v58, 16, v59
	v_and_b32_e32 v59, 0xffff0000, v59
	v_lshlrev_b32_e32 v70, 16, v48
	v_and_b32_e32 v71, 0xffff0000, v48
	s_waitcnt lgkmcnt(2)
	v_pk_add_f32 v[48:49], v[66:67], v[60:61] op_sel_hi:[1,0] neg_lo:[0,1] neg_hi:[0,1]
	v_pk_add_f32 v[58:59], v[58:59], v[60:61] op_sel_hi:[1,0] neg_lo:[0,1] neg_hi:[0,1]
	s_waitcnt lgkmcnt(1)
	v_pk_mul_f32 v[48:49], v[62:63], v[48:49] op_sel_hi:[0,1]
	v_pk_mul_f32 v[58:59], v[62:63], v[58:59] op_sel_hi:[0,1]
	v_lshlrev_b32_e32 v68, 16, v46
	v_and_b32_e32 v69, 0xffff0000, v46
	v_pk_fma_f32 v[48:49], v[50:51], v[48:49], v[54:55]
	v_pk_fma_f32 v[58:59], v[52:53], v[58:59], v[56:57]
	v_pk_add_f32 v[48:49], v[48:49], v[68:69]
	v_pk_add_f32 v[58:59], v[58:59], v[70:71]
	v_cvt_pk_bf16_f32 v48, v48, v49
	v_cvt_pk_bf16_f32 v49, v58, v59
	ds_write_b64 v19, v[48:49] offset:96
	ds_read_b32 v46, v31
	ds_read_b32 v48, v33
	s_waitcnt lgkmcnt(3)
	v_lshlrev_b32_e32 v58, 16, v64
	v_and_b32_e32 v59, 0xffff0000, v64
	v_lshlrev_b32_e32 v60, 16, v65
	v_and_b32_e32 v61, 0xffff0000, v65
	v_lshlrev_b32_e32 v64, 16, v47
	v_and_b32_e32 v65, 0xffff0000, v47
	s_waitcnt lgkmcnt(1)
	v_pk_add_f32 v[58:59], v[58:59], v[46:47] op_sel_hi:[1,0] neg_lo:[0,1] neg_hi:[0,1]
	v_pk_add_f32 v[46:47], v[60:61], v[46:47] op_sel_hi:[1,0] neg_lo:[0,1] neg_hi:[0,1]
	s_waitcnt lgkmcnt(0)
	v_pk_mul_f32 v[58:59], v[48:49], v[58:59] op_sel_hi:[0,1]
	v_pk_mul_f32 v[46:47], v[48:49], v[46:47] op_sel_hi:[0,1]
	v_lshlrev_b32_e32 v62, 16, v45
	v_and_b32_e32 v63, 0xffff0000, v45
	v_pk_fma_f32 v[50:51], v[50:51], v[58:59], v[54:55]
	v_pk_fma_f32 v[46:47], v[52:53], v[46:47], v[56:57]
	v_pk_add_f32 v[50:51], v[50:51], v[62:63]
	v_pk_add_f32 v[46:47], v[46:47], v[64:65]
	v_cvt_pk_bf16_f32 v48, v50, v51
	v_cvt_pk_bf16_f32 v49, v46, v47
	ds_write_b64 v19, v[48:49] offset:16736
	v_add_u32_e32 v50, 0x254e0, v27
	v_add_u32_e32 v45, 0x250e0, v27
	ds_read_b64 v[54:55], v19 offset:112
	ds_read_b128 v[46:49], v45
	ds_read_b128 v[50:53], v50
	ds_read_b32 v56, v29
	ds_read_b32 v58, v30
	ds_read_b64 v[60:61], v19 offset:16752
	s_waitcnt lgkmcnt(5)
	v_lshlrev_b32_e32 v62, 16, v54
	v_and_b32_e32 v63, 0xffff0000, v54
	v_lshlrev_b32_e32 v54, 16, v55
	v_and_b32_e32 v55, 0xffff0000, v55
	v_lshlrev_b32_e32 v66, 16, v44
	v_and_b32_e32 v67, 0xffff0000, v44
	s_waitcnt lgkmcnt(2)
	v_pk_add_f32 v[44:45], v[62:63], v[56:57] op_sel_hi:[1,0] neg_lo:[0,1] neg_hi:[0,1]
	v_pk_add_f32 v[54:55], v[54:55], v[56:57] op_sel_hi:[1,0] neg_lo:[0,1] neg_hi:[0,1]
	s_waitcnt lgkmcnt(1)
	v_pk_mul_f32 v[44:45], v[58:59], v[44:45] op_sel_hi:[0,1]
	v_pk_mul_f32 v[54:55], v[58:59], v[54:55] op_sel_hi:[0,1]
	v_lshlrev_b32_e32 v64, 16, v42
	v_and_b32_e32 v65, 0xffff0000, v42
	v_pk_fma_f32 v[44:45], v[46:47], v[44:45], v[50:51]
	v_pk_fma_f32 v[54:55], v[48:49], v[54:55], v[52:53]
	v_pk_add_f32 v[44:45], v[44:45], v[64:65]
	v_pk_add_f32 v[54:55], v[54:55], v[66:67]
	v_cvt_pk_bf16_f32 v44, v44, v45
	v_cvt_pk_bf16_f32 v45, v54, v55
	ds_write_b64 v19, v[44:45] offset:112
	ds_read_b32 v42, v31
	ds_read_b32 v44, v33
	s_waitcnt lgkmcnt(3)
	v_lshlrev_b32_e32 v54, 16, v60
	v_and_b32_e32 v55, 0xffff0000, v60
	v_lshlrev_b32_e32 v56, 16, v61
	v_and_b32_e32 v57, 0xffff0000, v61
	v_lshlrev_b32_e32 v60, 16, v43
	v_and_b32_e32 v61, 0xffff0000, v43
	s_waitcnt lgkmcnt(1)
	v_pk_add_f32 v[54:55], v[54:55], v[42:43] op_sel_hi:[1,0] neg_lo:[0,1] neg_hi:[0,1]
	v_pk_add_f32 v[42:43], v[56:57], v[42:43] op_sel_hi:[1,0] neg_lo:[0,1] neg_hi:[0,1]
	s_waitcnt lgkmcnt(0)
; DI unsigned pack2(float a, float b) { f32x2_t v = {a, b}; bf16x2_t r = __builtin_convertvector(v, bf16x2_t); return __builtin_bit_cast(unsigned, r); }
; DI float bflo(unsigned u) { return __uint_as_float(u << 16); }
; DI float bfhi(unsigned u) { return __uint_as_float(u & 0xffff0000u); }
; DI int otid() { int t = threadIdx.x; asm volatile("" : "+v"(t)); return t; }
; template <bool LAST>
; DI void phase_gate(const Params& P, int layer, unsigned char* smem, int L, int G) {
;     ...
;     const int tid2 = otid();
;     const int lane2 = tid2 & 63, w2 = tid2 >> 6, r2 = lane2 & 31, h2 = lane2 >> 5, wm2 = w2 >> 2, wn2 = w2 & 3;
; #pragma unroll
;     for (int i = 0; i < 4; ++i)
; #pragma unroll
;       for (int q4 = 0; q4 < 4; ++q4) {
;         const int fl = wm2 * 128 + i * 32 + 8 * q4 + 4 * h2;
;         const int f0 = nt * 256 + fl;
;         const f32x4 gv = *(const f32x4*)(vecL + 512 + fl), bv = *(const f32x4*)(vecL + 768 + fl);
;         const float ga[4] = {gv.x, gv.y, gv.z, gv.w}, ba[4] = {bv.x, bv.y, bv.z, bv.w};
; #pragma unroll
;         for (int j = 0; j < 2; ++j) {
;           const int lrow = wn2 * 64 + j * 32 + r2;
;           const float mu = rowA[lrow], rstd = rowB[lrow];
;           uint2* sp = (uint2*)(stg + lrow * STG + fl);
;           const uint2 sv = *sp;
;           const float sa[4] = {bflo(sv.x), bfhi(sv.x), bflo(sv.y), bfhi(sv.y)};
;           float y[4];
;           const float gg[4] = {bflo(gq[i][j][2 * q4]), bfhi(gq[i][j][2 * q4]), bflo(gq[i][j][2 * q4 + 1]), bfhi(gq[i][j][2 * q4 + 1])};
; #pragma unroll
;           for (int e = 0; e < 4; ++e) y[e] = (sa[e] - mu) * rstd * ga[e] + ba[e] + gg[e];
;           if (LAST) { f32x4 o = {y[0], y[1], y[2], y[3]}; *(f32x4*)(P.out + (size_t)(mt * 256 + lrow) * 1024 + f0) = o; }
;           else { uint2 pk; pk.x = pack2(y[0], y[1]); pk.y = pack2(y[2], y[3]); *sp = pk; }
;         }
;         __builtin_amdgcn_sched_barrier(0);
	v_pk_mul_f32 v[54:55], v[44:45], v[54:55] op_sel_hi:[0,1]
	v_pk_mul_f32 v[42:43], v[44:45], v[42:43] op_sel_hi:[0,1]
	v_lshlrev_b32_e32 v58, 16, v41
	v_and_b32_e32 v59, 0xffff0000, v41
	v_pk_fma_f32 v[46:47], v[46:47], v[54:55], v[50:51]
	v_pk_fma_f32 v[42:43], v[48:49], v[42:43], v[52:53]
	v_pk_add_f32 v[46:47], v[46:47], v[58:59]
	v_pk_add_f32 v[42:43], v[42:43], v[60:61]
	v_cvt_pk_bf16_f32 v44, v46, v47
	v_cvt_pk_bf16_f32 v45, v42, v43
	ds_write_b64 v19, v[44:45] offset:16752
	v_add_u32_e32 v46, 0x25500, v27
	v_add_u32_e32 v41, 0x25100, v27
	ds_read_b64 v[50:51], v19 offset:128
	ds_read_b128 v[42:45], v41
	ds_read_b128 v[46:49], v46
	ds_read_b32 v52, v29
	ds_read_b32 v54, v30
	ds_read_b64 v[56:57], v19 offset:16768
	s_waitcnt lgkmcnt(5)
	v_lshlrev_b32_e32 v58, 16, v50
	v_and_b32_e32 v59, 0xffff0000, v50
	v_lshlrev_b32_e32 v50, 16, v51
	v_and_b32_e32 v51, 0xffff0000, v51
	v_lshlrev_b32_e32 v62, 16, v40
	v_and_b32_e32 v63, 0xffff0000, v40
	s_waitcnt lgkmcnt(2)
	v_pk_add_f32 v[40:41], v[58:59], v[52:53] op_sel_hi:[1,0] neg_lo:[0,1] neg_hi:[0,1]
	v_pk_add_f32 v[50:51], v[50:51], v[52:53] op_sel_hi:[1,0] neg_lo:[0,1] neg_hi:[0,1]
	s_waitcnt lgkmcnt(1)
	v_pk_mul_f32 v[40:41], v[54:55], v[40:41] op_sel_hi:[0,1]
	v_pk_mul_f32 v[50:51], v[54:55], v[50:51] op_sel_hi:[0,1]
	v_lshlrev_b32_e32 v60, 16, v38
	v_and_b32_e32 v61, 0xffff0000, v38
	v_pk_fma_f32 v[40:41], v[42:43], v[40:41], v[46:47]
	v_pk_fma_f32 v[50:51], v[44:45], v[50:51], v[48:49]
	v_pk_add_f32 v[40:41], v[40:41], v[60:61]
	v_pk_add_f32 v[50:51], v[50:51], v[62:63]
	v_cvt_pk_bf16_f32 v40, v40, v41
	v_cvt_pk_bf16_f32 v41, v50, v51
	ds_write_b64 v19, v[40:41] offset:128
	ds_read_b32 v38, v31
	ds_read_b32 v40, v33
	s_waitcnt lgkmcnt(3)
	v_lshlrev_b32_e32 v50, 16, v56
	v_and_b32_e32 v51, 0xffff0000, v56
	v_lshlrev_b32_e32 v52, 16, v57
	v_and_b32_e32 v53, 0xffff0000, v57
	v_lshlrev_b32_e32 v56, 16, v39
	v_and_b32_e32 v57, 0xffff0000, v39
	s_waitcnt lgkmcnt(1)
	v_pk_add_f32 v[50:51], v[50:51], v[38:39] op_sel_hi:[1,0] neg_lo:[0,1] neg_hi:[0,1]
	v_pk_add_f32 v[38:39], v[52:53], v[38:39] op_sel_hi:[1,0] neg_lo:[0,1] neg_hi:[0,1]
	s_waitcnt lgkmcnt(0)
	v_pk_mul_f32 v[50:51], v[40:41], v[50:51] op_sel_hi:[0,1]
	v_pk_mul_f32 v[38:39], v[40:41], v[38:39] op_sel_hi:[0,1]
	v_lshlrev_b32_e32 v54, 16, v37
	v_and_b32_e32 v55, 0xffff0000, v37
	v_pk_fma_f32 v[42:43], v[42:43], v[50:51], v[46:47]
	v_pk_fma_f32 v[38:39], v[44:45], v[38:39], v[48:49]
	v_pk_add_f32 v[42:43], v[42:43], v[54:55]
	v_pk_add_f32 v[38:39], v[38:39], v[56:57]
	v_cvt_pk_bf16_f32 v40, v42, v43
	v_cvt_pk_bf16_f32 v41, v38, v39
	ds_write_b64 v19, v[40:41] offset:16768
	v_add_u32_e32 v42, 0x25520, v27
	v_add_u32_e32 v37, 0x25120, v27
	ds_read_b64 v[46:47], v19 offset:144
	ds_read_b128 v[38:41], v37
	ds_read_b128 v[42:45], v42
	ds_read_b32 v48, v29
	ds_read_b32 v50, v30
	ds_read_b64 v[52:53], v19 offset:16784
	s_waitcnt lgkmcnt(5)
	v_lshlrev_b32_e32 v54, 16, v46
	v_and_b32_e32 v55, 0xffff0000, v46
	v_lshlrev_b32_e32 v46, 16, v47
	v_and_b32_e32 v47, 0xffff0000, v47
	v_lshlrev_b32_e32 v58, 16, v36
	v_and_b32_e32 v59, 0xffff0000, v36
	s_waitcnt lgkmcnt(2)
	v_pk_add_f32 v[36:37], v[54:55], v[48:49] op_sel_hi:[1,0] neg_lo:[0,1] neg_hi:[0,1]
	v_pk_add_f32 v[46:47], v[46:47], v[48:49] op_sel_hi:[1,0] neg_lo:[0,1] neg_hi:[0,1]
	s_waitcnt lgkmcnt(1)
	v_pk_mul_f32 v[36:37], v[50:51], v[36:37] op_sel_hi:[0,1]
	v_pk_mul_f32 v[46:47], v[50:51], v[46:47] op_sel_hi:[0,1]
	v_lshlrev_b32_e32 v56, 16, v34
	v_and_b32_e32 v57, 0xffff0000, v34
	v_pk_fma_f32 v[36:37], v[38:39], v[36:37], v[42:43]
	v_pk_fma_f32 v[46:47], v[40:41], v[46:47], v[44:45]
	v_pk_add_f32 v[36:37], v[36:37], v[56:57]
	v_pk_add_f32 v[46:47], v[46:47], v[58:59]
	v_cvt_pk_bf16_f32 v36, v36, v37
	v_cvt_pk_bf16_f32 v37, v46, v47
	ds_write_b64 v19, v[36:37] offset:144
	ds_read_b32 v34, v31
	ds_read_b32 v36, v33
	s_waitcnt lgkmcnt(3)
	v_lshlrev_b32_e32 v46, 16, v52
	v_and_b32_e32 v47, 0xffff0000, v52
	v_lshlrev_b32_e32 v48, 16, v53
	v_and_b32_e32 v49, 0xffff0000, v53
	v_lshlrev_b32_e32 v52, 16, v35
	v_and_b32_e32 v53, 0xffff0000, v35
	s_waitcnt lgkmcnt(1)
	v_pk_add_f32 v[46:47], v[46:47], v[34:35] op_sel_hi:[1,0] neg_lo:[0,1] neg_hi:[0,1]
	v_pk_add_f32 v[34:35], v[48:49], v[34:35] op_sel_hi:[1,0] neg_lo:[0,1] neg_hi:[0,1]
	s_waitcnt lgkmcnt(0)
	v_pk_mul_f32 v[46:47], v[36:37], v[46:47] op_sel_hi:[0,1]
	v_pk_mul_f32 v[34:35], v[36:37], v[34:35] op_sel_hi:[0,1]
	v_lshlrev_b32_e32 v50, 16, v32
	v_and_b32_e32 v51, 0xffff0000, v32
	v_pk_fma_f32 v[38:39], v[38:39], v[46:47], v[42:43]
	v_pk_fma_f32 v[34:35], v[40:41], v[34:35], v[44:45]
	v_pk_add_f32 v[38:39], v[38:39], v[50:51]
	v_pk_add_f32 v[34:35], v[34:35], v[52:53]
	v_cvt_pk_bf16_f32 v36, v38, v39
	v_cvt_pk_bf16_f32 v37, v34, v35
	ds_write_b64 v19, v[36:37] offset:16784
	v_add_u32_e32 v32, 0x25140, v27
	v_add_u32_e32 v38, 0x25540, v27
	ds_read_b64 v[42:43], v19 offset:160
	ds_read_b128 v[34:37], v32
	ds_read_b128 v[38:41], v38
	ds_read_b32 v32, v29
	ds_read_b32 v44, v30
	ds_read_b64 v[46:47], v19 offset:16800
	s_waitcnt lgkmcnt(5)
	v_lshlrev_b32_e32 v48, 16, v42
	v_and_b32_e32 v49, 0xffff0000, v42
	v_lshlrev_b32_e32 v42, 16, v43
	v_and_b32_e32 v43, 0xffff0000, v43
	s_waitcnt lgkmcnt(2)
	v_pk_add_f32 v[48:49], v[48:49], v[32:33] op_sel_hi:[1,0] neg_lo:[0,1] neg_hi:[0,1]
	v_pk_add_f32 v[42:43], v[42:43], v[32:33] op_sel_hi:[1,0] neg_lo:[0,1] neg_hi:[0,1]
	s_waitcnt lgkmcnt(1)
; DI unsigned pack2(float a, float b) { f32x2_t v = {a, b}; bf16x2_t r = __builtin_convertvector(v, bf16x2_t); return __builtin_bit_cast(unsigned, r); }
; DI float bflo(unsigned u) { return __uint_as_float(u << 16); }
; DI float bfhi(unsigned u) { return __uint_as_float(u & 0xffff0000u); }
; DI int otid() { int t = threadIdx.x; asm volatile("" : "+v"(t)); return t; }
; template <bool LAST>
; DI void phase_gate(const Params& P, int layer, unsigned char* smem, int L, int G) {
;     ...
;     const int tid2 = otid();
;     const int lane2 = tid2 & 63, w2 = tid2 >> 6, r2 = lane2 & 31, h2 = lane2 >> 5, wm2 = w2 >> 2, wn2 = w2 & 3;
; #pragma unroll
;     for (int i = 0; i < 4; ++i)
; #pragma unroll
;       for (int q4 = 0; q4 < 4; ++q4) {
;         const int fl = wm2 * 128 + i * 32 + 8 * q4 + 4 * h2;
;         const int f0 = nt * 256 + fl;
;         const f32x4 gv = *(const f32x4*)(vecL + 512 + fl), bv = *(const f32x4*)(vecL + 768 + fl);
;         const float ga[4] = {gv.x, gv.y, gv.z, gv.w}, ba[4] = {bv.x, bv.y, bv.z, bv.w};
; #pragma unroll
;         for (int j = 0; j < 2; ++j) {
;           const int lrow = wn2 * 64 + j * 32 + r2;
;           const float mu = rowA[lrow], rstd = rowB[lrow];
;           uint2* sp = (uint2*)(stg + lrow * STG + fl);
;           const uint2 sv = *sp;
;           const float sa[4] = {bflo(sv.x), bfhi(sv.x), bflo(sv.y), bfhi(sv.y)};
;           float y[4];
;           const float gg[4] = {bflo(gq[i][j][2 * q4]), bfhi(gq[i][j][2 * q4]), bflo(gq[i][j][2 * q4 + 1]), bfhi(gq[i][j][2 * q4 + 1])};
; #pragma unroll
;           for (int e = 0; e < 4; ++e) y[e] = (sa[e] - mu) * rstd * ga[e] + ba[e] + gg[e];
;           if (LAST) { f32x4 o = {y[0], y[1], y[2], y[3]}; *(f32x4*)(P.out + (size_t)(mt * 256 + lrow) * 1024 + f0) = o; }
;           else { uint2 pk; pk.x = pack2(y[0], y[1]); pk.y = pack2(y[2], y[3]); *sp = pk; }
;         }
;         __builtin_amdgcn_sched_barrier(0);
	v_pk_mul_f32 v[48:49], v[44:45], v[48:49] op_sel_hi:[0,1]
	v_pk_mul_f32 v[42:43], v[44:45], v[42:43] op_sel_hi:[0,1]
	v_lshlrev_b32_e32 v50, 16, v24
	v_and_b32_e32 v51, 0xffff0000, v24
	v_lshlrev_b32_e32 v52, 16, v26
	v_and_b32_e32 v53, 0xffff0000, v26
	v_pk_fma_f32 v[48:49], v[34:35], v[48:49], v[38:39]
	v_pk_fma_f32 v[42:43], v[36:37], v[42:43], v[40:41]
	v_pk_add_f32 v[48:49], v[48:49], v[50:51]
	v_pk_add_f32 v[42:43], v[42:43], v[52:53]
	v_cvt_pk_bf16_f32 v44, v48, v49
	v_cvt_pk_bf16_f32 v45, v42, v43
	ds_write_b64 v19, v[44:45] offset:160
	ds_read_b32 v24, v31
	ds_read_b32 v26, v33
	s_waitcnt lgkmcnt(3)
	v_lshlrev_b32_e32 v42, 16, v46
	v_and_b32_e32 v43, 0xffff0000, v46
	v_lshlrev_b32_e32 v44, 16, v47
	v_and_b32_e32 v45, 0xffff0000, v47
	v_lshlrev_b32_e32 v48, 16, v25
	v_and_b32_e32 v49, 0xffff0000, v25
	s_waitcnt lgkmcnt(1)
	v_pk_add_f32 v[42:43], v[42:43], v[24:25] op_sel_hi:[1,0] neg_lo:[0,1] neg_hi:[0,1]
	v_pk_add_f32 v[24:25], v[44:45], v[24:25] op_sel_hi:[1,0] neg_lo:[0,1] neg_hi:[0,1]
	s_waitcnt lgkmcnt(0)
	v_pk_mul_f32 v[42:43], v[26:27], v[42:43] op_sel_hi:[0,1]
	v_pk_mul_f32 v[24:25], v[26:27], v[24:25] op_sel_hi:[0,1]
	v_lshlrev_b32_e32 v46, 16, v23
	v_and_b32_e32 v47, 0xffff0000, v23
	v_pk_fma_f32 v[34:35], v[34:35], v[42:43], v[38:39]
	v_pk_fma_f32 v[24:25], v[36:37], v[24:25], v[40:41]
	v_pk_add_f32 v[34:35], v[34:35], v[46:47]
	v_pk_add_f32 v[24:25], v[24:25], v[48:49]
	v_cvt_pk_bf16_f32 v34, v34, v35
	v_cvt_pk_bf16_f32 v35, v24, v25
	ds_write_b64 v19, v[34:35] offset:16800
	v_add_u32_e32 v26, 0x25560, v27
	v_add_u32_e32 v23, 0x25160, v27
	ds_read_b64 v[24:25], v19 offset:176
	ds_read_b128 v[34:37], v23
	ds_read_b128 v[38:41], v26
	ds_read_b32 v26, v29
	ds_read_b32 v32, v30
	ds_read_b64 v[42:43], v19 offset:16816
	s_waitcnt lgkmcnt(5)
	v_lshlrev_b32_e32 v44, 16, v24
	v_and_b32_e32 v45, 0xffff0000, v24
	v_lshlrev_b32_e32 v24, 16, v25
	v_and_b32_e32 v25, 0xffff0000, v25
	v_lshlrev_b32_e32 v48, 16, v22
	v_and_b32_e32 v49, 0xffff0000, v22
	s_waitcnt lgkmcnt(2)
	v_pk_add_f32 v[22:23], v[44:45], v[26:27] op_sel_hi:[1,0] neg_lo:[0,1] neg_hi:[0,1]
	v_pk_add_f32 v[24:25], v[24:25], v[26:27] op_sel_hi:[1,0] neg_lo:[0,1] neg_hi:[0,1]
	s_waitcnt lgkmcnt(1)
	v_pk_mul_f32 v[22:23], v[32:33], v[22:23] op_sel_hi:[0,1]
	v_pk_mul_f32 v[24:25], v[32:33], v[24:25] op_sel_hi:[0,1]
	v_lshlrev_b32_e32 v46, 16, v20
	v_and_b32_e32 v47, 0xffff0000, v20
	v_pk_fma_f32 v[22:23], v[34:35], v[22:23], v[38:39]
	v_pk_fma_f32 v[24:25], v[36:37], v[24:25], v[40:41]
	v_pk_add_f32 v[22:23], v[22:23], v[46:47]
	v_pk_add_f32 v[24:25], v[24:25], v[48:49]
	v_cvt_pk_bf16_f32 v22, v22, v23
	v_cvt_pk_bf16_f32 v23, v24, v25
	ds_write_b64 v19, v[22:23] offset:176
	ds_read_b32 v20, v31
	ds_read_b32 v22, v33
	s_waitcnt lgkmcnt(3)
	v_lshlrev_b32_e32 v24, 16, v42
	v_and_b32_e32 v25, 0xffff0000, v42
	v_lshlrev_b32_e32 v42, 16, v43
	v_and_b32_e32 v43, 0xffff0000, v43
	v_lshlrev_b32_e32 v46, 16, v21
	v_and_b32_e32 v47, 0xffff0000, v21
	s_waitcnt lgkmcnt(1)
	v_pk_add_f32 v[24:25], v[24:25], v[20:21] op_sel_hi:[1,0] neg_lo:[0,1] neg_hi:[0,1]
	v_pk_add_f32 v[20:21], v[42:43], v[20:21] op_sel_hi:[1,0] neg_lo:[0,1] neg_hi:[0,1]
	s_waitcnt lgkmcnt(0)
	v_pk_mul_f32 v[24:25], v[22:23], v[24:25] op_sel_hi:[0,1]
	v_pk_mul_f32 v[20:21], v[22:23], v[20:21] op_sel_hi:[0,1]
	v_lshlrev_b32_e32 v44, 16, v18
	v_and_b32_e32 v45, 0xffff0000, v18
	v_pk_fma_f32 v[24:25], v[34:35], v[24:25], v[38:39]
	v_pk_fma_f32 v[20:21], v[36:37], v[20:21], v[40:41]
	v_pk_add_f32 v[24:25], v[24:25], v[44:45]
	v_pk_add_f32 v[20:21], v[20:21], v[46:47]
	v_cvt_pk_bf16_f32 v22, v24, v25
	v_cvt_pk_bf16_f32 v23, v20, v21
	ds_write_b64 v19, v[22:23] offset:16816
	v_add_u32_e32 v18, 0x25180, v27
	v_add_u32_e32 v26, 0x25580, v27
	ds_read_b64 v[24:25], v19 offset:192
	ds_read_b128 v[20:23], v18
	ds_read_b128 v[34:37], v26
	ds_read_b32 v18, v29
	ds_read_b32 v26, v30
	ds_read_b64 v[38:39], v19 offset:16832
	s_waitcnt lgkmcnt(5)
	v_lshlrev_b32_e32 v40, 16, v24
	v_and_b32_e32 v41, 0xffff0000, v24
	v_lshlrev_b32_e32 v24, 16, v25
	v_and_b32_e32 v25, 0xffff0000, v25
	s_waitcnt lgkmcnt(2)
	v_pk_add_f32 v[40:41], v[40:41], v[18:19] op_sel_hi:[1,0] neg_lo:[0,1] neg_hi:[0,1]
	v_pk_add_f32 v[24:25], v[24:25], v[18:19] op_sel_hi:[1,0] neg_lo:[0,1] neg_hi:[0,1]
	s_waitcnt lgkmcnt(1)
	v_pk_mul_f32 v[40:41], v[26:27], v[40:41] op_sel_hi:[0,1]
	v_pk_mul_f32 v[24:25], v[26:27], v[24:25] op_sel_hi:[0,1]
	v_lshlrev_b32_e32 v42, 16, v15
	v_and_b32_e32 v43, 0xffff0000, v15
	v_lshlrev_b32_e32 v44, 16, v17
	v_and_b32_e32 v45, 0xffff0000, v17
	v_pk_fma_f32 v[40:41], v[20:21], v[40:41], v[34:35]
	v_pk_fma_f32 v[24:25], v[22:23], v[24:25], v[36:37]
	v_pk_add_f32 v[40:41], v[40:41], v[42:43]
	v_pk_add_f32 v[24:25], v[24:25], v[44:45]
	v_cvt_pk_bf16_f32 v40, v40, v41
	v_cvt_pk_bf16_f32 v41, v24, v25
	ds_write_b64 v19, v[40:41] offset:192
	ds_read_b32 v18, v31
	ds_read_b32 v24, v33
	s_waitcnt lgkmcnt(3)
	v_lshlrev_b32_e32 v40, 16, v38
	v_and_b32_e32 v41, 0xffff0000, v38
	v_lshlrev_b32_e32 v42, 16, v14
	v_and_b32_e32 v43, 0xffff0000, v14
	v_lshlrev_b32_e32 v14, 16, v16
	v_and_b32_e32 v15, 0xffff0000, v16
	s_waitcnt lgkmcnt(1)
	v_pk_add_f32 v[16:17], v[40:41], v[18:19] op_sel_hi:[1,0] neg_lo:[0,1] neg_hi:[0,1]
	v_lshlrev_b32_e32 v38, 16, v39
	v_and_b32_e32 v39, 0xffff0000, v39
	s_waitcnt lgkmcnt(0)
; DI unsigned pack2(float a, float b) { f32x2_t v = {a, b}; bf16x2_t r = __builtin_convertvector(v, bf16x2_t); return __builtin_bit_cast(unsigned, r); }
; DI float bflo(unsigned u) { return __uint_as_float(u << 16); }
; DI float bfhi(unsigned u) { return __uint_as_float(u & 0xffff0000u); }
; template <bool LAST>
; DI void phase_gate(const Params& P, int layer, unsigned char* smem, int L, int G) {
;     ...
; #pragma unroll
;     for (int i = 0; i < 4; ++i)
; #pragma unroll
;       for (int q4 = 0; q4 < 4; ++q4) {
;         const int fl = wm2 * 128 + i * 32 + 8 * q4 + 4 * h2;
;         const int f0 = nt * 256 + fl;
;         const f32x4 gv = *(const f32x4*)(vecL + 512 + fl), bv = *(const f32x4*)(vecL + 768 + fl);
;         const float ga[4] = {gv.x, gv.y, gv.z, gv.w}, ba[4] = {bv.x, bv.y, bv.z, bv.w};
; #pragma unroll
;         for (int j = 0; j < 2; ++j) {
;           const int lrow = wn2 * 64 + j * 32 + r2;
;           const float mu = rowA[lrow], rstd = rowB[lrow];
;           uint2* sp = (uint2*)(stg + lrow * STG + fl);
;           const uint2 sv = *sp;
;           const float sa[4] = {bflo(sv.x), bfhi(sv.x), bflo(sv.y), bfhi(sv.y)};
;           float y[4];
;           const float gg[4] = {bflo(gq[i][j][2 * q4]), bfhi(gq[i][j][2 * q4]), bflo(gq[i][j][2 * q4 + 1]), bfhi(gq[i][j][2 * q4 + 1])};
; #pragma unroll
;           for (int e = 0; e < 4; ++e) y[e] = (sa[e] - mu) * rstd * ga[e] + ba[e] + gg[e];
;           if (LAST) { f32x4 o = {y[0], y[1], y[2], y[3]}; *(f32x4*)(P.out + (size_t)(mt * 256 + lrow) * 1024 + f0) = o; }
;           else { uint2 pk; pk.x = pack2(y[0], y[1]); pk.y = pack2(y[2], y[3]); *sp = pk; }
;         }
;         __builtin_amdgcn_sched_barrier(0);
;       }
;     __syncthreads();
	v_pk_mul_f32 v[16:17], v[24:25], v[16:17] op_sel_hi:[0,1]
	v_pk_fma_f32 v[16:17], v[20:21], v[16:17], v[34:35]
	v_pk_add_f32 v[20:21], v[38:39], v[18:19] op_sel_hi:[1,0] neg_lo:[0,1] neg_hi:[0,1]
	v_pk_add_f32 v[16:17], v[16:17], v[42:43]
	v_pk_mul_f32 v[20:21], v[24:25], v[20:21] op_sel_hi:[0,1]
	v_pk_fma_f32 v[20:21], v[22:23], v[20:21], v[36:37]
	v_cvt_pk_bf16_f32 v16, v16, v17
	v_pk_add_f32 v[14:15], v[20:21], v[14:15]
	s_nop 0
	v_cvt_pk_bf16_f32 v17, v14, v15
	ds_write_b64 v19, v[16:17] offset:16832
	v_add_u32_e32 v14, 0x251a0, v27
	v_add_u32_e32 v18, 0x255a0, v27
	ds_read_b64 v[24:25], v19 offset:208
	ds_read_b128 v[14:17], v14
	ds_read_b128 v[20:23], v18
	ds_read_b32 v18, v29
	ds_read_b32 v26, v30
	ds_read_b64 v[34:35], v19 offset:16848
	s_waitcnt lgkmcnt(5)
	v_lshlrev_b32_e32 v36, 16, v24
	v_and_b32_e32 v37, 0xffff0000, v24
	v_lshlrev_b32_e32 v24, 16, v25
	v_and_b32_e32 v25, 0xffff0000, v25
	s_waitcnt lgkmcnt(2)
	v_pk_add_f32 v[36:37], v[36:37], v[18:19] op_sel_hi:[1,0] neg_lo:[0,1] neg_hi:[0,1]
	v_pk_add_f32 v[24:25], v[24:25], v[18:19] op_sel_hi:[1,0] neg_lo:[0,1] neg_hi:[0,1]
	s_waitcnt lgkmcnt(1)
	v_pk_mul_f32 v[36:37], v[26:27], v[36:37] op_sel_hi:[0,1]
	v_pk_mul_f32 v[24:25], v[26:27], v[24:25] op_sel_hi:[0,1]
	v_lshlrev_b32_e32 v38, 16, v11
	v_and_b32_e32 v39, 0xffff0000, v11
	v_lshlrev_b32_e32 v40, 16, v13
	v_and_b32_e32 v41, 0xffff0000, v13
	v_pk_fma_f32 v[36:37], v[14:15], v[36:37], v[20:21]
	v_pk_fma_f32 v[24:25], v[16:17], v[24:25], v[22:23]
	v_pk_add_f32 v[36:37], v[36:37], v[38:39]
	v_pk_add_f32 v[24:25], v[24:25], v[40:41]
	v_cvt_pk_bf16_f32 v36, v36, v37
	v_cvt_pk_bf16_f32 v37, v24, v25
	ds_write_b64 v19, v[36:37] offset:208
	ds_read_b32 v18, v31
	ds_read_b32 v24, v33
	s_waitcnt lgkmcnt(3)
	v_lshlrev_b32_e32 v36, 16, v34
	v_and_b32_e32 v37, 0xffff0000, v34
	v_lshlrev_b32_e32 v38, 16, v10
	v_and_b32_e32 v39, 0xffff0000, v10
	v_lshlrev_b32_e32 v10, 16, v12
	v_and_b32_e32 v11, 0xffff0000, v12
	s_waitcnt lgkmcnt(1)
	v_pk_add_f32 v[12:13], v[36:37], v[18:19] op_sel_hi:[1,0] neg_lo:[0,1] neg_hi:[0,1]
	v_lshlrev_b32_e32 v34, 16, v35
	v_and_b32_e32 v35, 0xffff0000, v35
	s_waitcnt lgkmcnt(0)
	v_pk_mul_f32 v[12:13], v[24:25], v[12:13] op_sel_hi:[0,1]
	v_pk_fma_f32 v[12:13], v[14:15], v[12:13], v[20:21]
	v_pk_add_f32 v[14:15], v[34:35], v[18:19] op_sel_hi:[1,0] neg_lo:[0,1] neg_hi:[0,1]
	v_pk_add_f32 v[12:13], v[12:13], v[38:39]
	v_pk_mul_f32 v[14:15], v[24:25], v[14:15] op_sel_hi:[0,1]
	v_pk_fma_f32 v[14:15], v[16:17], v[14:15], v[22:23]
	v_cvt_pk_bf16_f32 v12, v12, v13
	v_pk_add_f32 v[10:11], v[14:15], v[10:11]
	s_nop 0
	v_cvt_pk_bf16_f32 v13, v10, v11
	ds_write_b64 v19, v[12:13] offset:16848
	v_add_u32_e32 v10, 0x251c0, v27
	v_add_u32_e32 v14, 0x255c0, v27
	ds_read_b64 v[20:21], v19 offset:224
	ds_read_b128 v[10:13], v10
	ds_read_b128 v[14:17], v14
	ds_read_b32 v18, v29
	ds_read_b32 v22, v30
	ds_read_b64 v[24:25], v19 offset:16864
	s_waitcnt lgkmcnt(5)
	v_lshlrev_b32_e32 v34, 16, v20
	v_and_b32_e32 v35, 0xffff0000, v20
	v_lshlrev_b32_e32 v20, 16, v21
	v_and_b32_e32 v21, 0xffff0000, v21
	s_waitcnt lgkmcnt(2)
	v_pk_add_f32 v[34:35], v[34:35], v[18:19] op_sel_hi:[1,0] neg_lo:[0,1] neg_hi:[0,1]
	v_pk_add_f32 v[20:21], v[20:21], v[18:19] op_sel_hi:[1,0] neg_lo:[0,1] neg_hi:[0,1]
	s_waitcnt lgkmcnt(1)
	v_pk_mul_f32 v[34:35], v[22:23], v[34:35] op_sel_hi:[0,1]
	v_pk_mul_f32 v[20:21], v[22:23], v[20:21] op_sel_hi:[0,1]
	v_lshlrev_b32_e32 v36, 16, v7
	v_and_b32_e32 v37, 0xffff0000, v7
	v_lshlrev_b32_e32 v38, 16, v9
	v_and_b32_e32 v39, 0xffff0000, v9
	v_pk_fma_f32 v[34:35], v[10:11], v[34:35], v[14:15]
	v_pk_fma_f32 v[20:21], v[12:13], v[20:21], v[16:17]
	v_pk_add_f32 v[34:35], v[34:35], v[36:37]
	v_pk_add_f32 v[20:21], v[20:21], v[38:39]
	v_cvt_pk_bf16_f32 v22, v34, v35
	v_cvt_pk_bf16_f32 v23, v20, v21
	ds_write_b64 v19, v[22:23] offset:224
	ds_read_b32 v18, v31
	ds_read_b32 v20, v33
	s_waitcnt lgkmcnt(3)
	v_lshlrev_b32_e32 v22, 16, v24
	v_and_b32_e32 v23, 0xffff0000, v24
	v_lshlrev_b32_e32 v34, 16, v6
	v_and_b32_e32 v35, 0xffff0000, v6
	v_lshlrev_b32_e32 v6, 16, v8
	v_and_b32_e32 v7, 0xffff0000, v8
	s_waitcnt lgkmcnt(1)
	v_pk_add_f32 v[8:9], v[22:23], v[18:19] op_sel_hi:[1,0] neg_lo:[0,1] neg_hi:[0,1]
	v_lshlrev_b32_e32 v24, 16, v25
	v_and_b32_e32 v25, 0xffff0000, v25
	s_waitcnt lgkmcnt(0)
	v_pk_mul_f32 v[8:9], v[20:21], v[8:9] op_sel_hi:[0,1]
	v_pk_fma_f32 v[8:9], v[10:11], v[8:9], v[14:15]
	v_pk_add_f32 v[10:11], v[24:25], v[18:19] op_sel_hi:[1,0] neg_lo:[0,1] neg_hi:[0,1]
	v_pk_add_f32 v[8:9], v[8:9], v[34:35]
	v_pk_mul_f32 v[10:11], v[20:21], v[10:11] op_sel_hi:[0,1]
	v_pk_fma_f32 v[10:11], v[12:13], v[10:11], v[16:17]
	v_cvt_pk_bf16_f32 v8, v8, v9
	v_pk_add_f32 v[6:7], v[10:11], v[6:7]
	s_nop 0
	v_cvt_pk_bf16_f32 v9, v6, v7
	ds_write_b64 v19, v[8:9] offset:16864
	ds_read_b128 v[6:9], v28 offset:480
	ds_read_b64 v[14:15], v19 offset:240
	ds_read_b32 v16, v29
	ds_read_b32 v18, v30
	v_add_u32_e32 v10, 0x255e0, v27
	ds_read_b128 v[10:13], v10
	s_waitcnt lgkmcnt(3)
	v_lshlrev_b32_e32 v20, 16, v14
	v_and_b32_e32 v21, 0xffff0000, v14
	v_lshlrev_b32_e32 v14, 16, v15
	v_and_b32_e32 v15, 0xffff0000, v15
	s_waitcnt lgkmcnt(2)
	v_pk_add_f32 v[20:21], v[20:21], v[16:17] op_sel_hi:[1,0] neg_lo:[0,1] neg_hi:[0,1]
	v_pk_add_f32 v[14:15], v[14:15], v[16:17] op_sel_hi:[1,0] neg_lo:[0,1] neg_hi:[0,1]
	s_waitcnt lgkmcnt(1)
	v_pk_mul_f32 v[20:21], v[18:19], v[20:21] op_sel_hi:[0,1]
	v_pk_mul_f32 v[14:15], v[18:19], v[14:15] op_sel_hi:[0,1]
	v_lshlrev_b32_e32 v22, 16, v4
	v_and_b32_e32 v23, 0xffff0000, v4
	v_lshlrev_b32_e32 v4, 16, v5
	v_and_b32_e32 v5, 0xffff0000, v5
	s_waitcnt lgkmcnt(0)
	v_pk_fma_f32 v[20:21], v[6:7], v[20:21], v[10:11]
	v_pk_fma_f32 v[14:15], v[8:9], v[14:15], v[12:13]
	v_pk_add_f32 v[20:21], v[20:21], v[22:23]
	v_pk_add_f32 v[4:5], v[14:15], v[4:5]
	v_cvt_pk_bf16_f32 v14, v20, v21
	v_cvt_pk_bf16_f32 v15, v4, v5
	ds_write_b64 v19, v[14:15] offset:240
	ds_read_b32 v4, v33
	ds_read_b64 v[14:15], v19 offset:16880
	ds_read_b32 v16, v31
	v_lshlrev_b32_e32 v22, 16, v2
	v_and_b32_e32 v23, 0xffff0000, v2
	v_lshlrev_b32_e32 v2, 16, v3
	s_waitcnt lgkmcnt(1)
	v_lshlrev_b32_e32 v20, 16, v14
	v_and_b32_e32 v21, 0xffff0000, v14
	s_waitcnt lgkmcnt(0)
	v_pk_add_f32 v[20:21], v[20:21], v[16:17] op_sel_hi:[1,0] neg_lo:[0,1] neg_hi:[0,1]
	v_lshlrev_b32_e32 v14, 16, v15
	v_and_b32_e32 v15, 0xffff0000, v15
	v_pk_mul_f32 v[20:21], v[4:5], v[20:21] op_sel_hi:[0,1]
	v_pk_fma_f32 v[6:7], v[6:7], v[20:21], v[10:11]
	v_pk_add_f32 v[10:11], v[14:15], v[16:17] op_sel_hi:[1,0] neg_lo:[0,1] neg_hi:[0,1]
	v_and_b32_e32 v3, 0xffff0000, v3
	v_pk_mul_f32 v[4:5], v[4:5], v[10:11] op_sel_hi:[0,1]
	v_pk_fma_f32 v[4:5], v[8:9], v[4:5], v[12:13]
	v_pk_add_f32 v[6:7], v[6:7], v[22:23]
	v_pk_add_f32 v[2:3], v[4:5], v[2:3]
	v_cvt_pk_bf16_f32 v4, v6, v7
	v_cvt_pk_bf16_f32 v5, v2, v3
	ds_write_b64 v19, v[4:5] offset:16880
	s_add_u32 s24, s80, s24
	s_addc_u32 s25, s81, s25
	v_lshl_add_u64 v[8:9], s[24:25], 0, v[0:1]
	v_mov_b32_e32 v0, v192
	s_waitcnt lgkmcnt(0)
	s_barrier
; DI int otid() { int t = threadIdx.x; asm volatile("" : "+v"(t)); return t; }
; DI void stg16_nt(void* p, u32x4 v) { __builtin_nontemporal_store(v, (u32x4*)p); }
; DI void stage_store_tile(const bf16_t* stg, bf16_t* tilebase) {
;   const int tid = otid();
;   const int r0 = tid >> 5, c = tid & 31;
;   const unsigned o0 = (unsigned)(r0 * 1024 + c * 8);
; #pragma unroll
;   for (int it = 0; it < 16; ++it) stg16_nt(tilebase + (o0 + (unsigned)(it * 16 * 1024)), stage_read16(stg, r0 + 16 * it, c));
; }
; template <bool LAST>
; DI void phase_gate(const Params& P, int layer, unsigned char* smem, int L, int G) {
;     ...
;     if (!LAST) stage_store_tile(stg, xb + (size_t)mt * 256 * 1024 + nt * 256);
;     __syncthreads();
	s_add_i32 s31, s31, s74
	v_ashrrev_i32_e32 v4, 5, v0
	v_and_b32_e32 v0, 31, v0
	v_mul_lo_u32 v1, v4, s40
	v_lshl_add_u32 v12, v0, 4, v1
	v_lshlrev_b32_e32 v5, 3, v0
	ds_read2_b64 v[0:3], v12 offset1:1
	v_lshl_or_b32 v160, v4, 10, v5
	v_add_u32_e32 v4, 0x2080, v12
	ds_read2_b64 v[4:7], v4 offset1:1
	v_lshl_add_u64 v[10:11], v[160:161], 1, v[8:9]
	s_waitcnt lgkmcnt(1)
	global_store_dwordx4 v[10:11], v[0:3], off nt
	s_add_i32 s28, s28, s69
	s_add_i32 s29, s29, s30
	v_add_u32_e32 v0, 0x4000, v160
	v_mov_b32_e32 v1, v161
	v_lshl_add_u64 v[0:1], v[0:1], 1, v[8:9]
	s_waitcnt lgkmcnt(0)
	global_store_dwordx4 v[0:1], v[4:7], off nt
	v_add_u32_e32 v0, 0x4100, v12
	ds_read2_b64 v[0:3], v0 offset1:1
	v_add_u32_e32 v4, 0x8000, v160
	v_mov_b32_e32 v5, v161
	v_lshl_add_u64 v[10:11], v[4:5], 1, v[8:9]
	v_add_u32_e32 v4, 0x6180, v12
	ds_read2_b64 v[4:7], v4 offset1:1
	s_waitcnt lgkmcnt(1)
	global_store_dwordx4 v[10:11], v[0:3], off nt
	s_add_i32 s24, s70, s31
	s_cmpk_lt_i32 s24, 0x400
	v_add_u32_e32 v0, 0xc000, v160
	v_mov_b32_e32 v1, v161
	v_lshl_add_u64 v[0:1], v[0:1], 1, v[8:9]
	s_waitcnt lgkmcnt(0)
	global_store_dwordx4 v[0:1], v[4:7], off nt
	v_add_u32_e32 v0, 0x8200, v12
	ds_read2_b64 v[0:3], v0 offset1:1
	v_add_u32_e32 v4, 0x10000, v160
	v_mov_b32_e32 v5, v161
	v_lshl_add_u64 v[10:11], v[4:5], 1, v[8:9]
	v_add_u32_e32 v4, 0xa280, v12
	ds_read2_b64 v[4:7], v4 offset1:1
	s_waitcnt lgkmcnt(1)
	global_store_dwordx4 v[10:11], v[0:3], off nt
	s_nop 1
	v_add_u32_e32 v0, 0x14000, v160
	v_mov_b32_e32 v1, v161
	v_lshl_add_u64 v[0:1], v[0:1], 1, v[8:9]
	s_waitcnt lgkmcnt(0)
	global_store_dwordx4 v[0:1], v[4:7], off nt
	v_add_u32_e32 v0, 0xc300, v12
	ds_read2_b64 v[0:3], v0 offset1:1
	v_add_u32_e32 v4, 0x18000, v160
	v_mov_b32_e32 v5, v161
	v_lshl_add_u64 v[10:11], v[4:5], 1, v[8:9]
	v_add_u32_e32 v4, 0xe380, v12
	ds_read2_b64 v[4:7], v4 offset1:1
	s_waitcnt lgkmcnt(1)
	global_store_dwordx4 v[10:11], v[0:3], off nt
	s_nop 1
	v_add_u32_e32 v0, 0x1c000, v160
	v_mov_b32_e32 v1, v161
	v_lshl_add_u64 v[0:1], v[0:1], 1, v[8:9]
	s_waitcnt lgkmcnt(0)
	global_store_dwordx4 v[0:1], v[4:7], off nt
	v_add_u32_e32 v0, 0x10400, v12
	ds_read2_b64 v[0:3], v0 offset1:1
	v_add_u32_e32 v4, 0x20000, v160
	v_mov_b32_e32 v5, v161
	v_lshl_add_u64 v[10:11], v[4:5], 1, v[8:9]
	v_add_u32_e32 v4, 0x12480, v12
	ds_read2_b64 v[4:7], v4 offset1:1
	s_waitcnt lgkmcnt(1)
	global_store_dwordx4 v[10:11], v[0:3], off nt
	s_nop 1
	v_add_u32_e32 v0, 0x24000, v160
	v_mov_b32_e32 v1, v161
	v_lshl_add_u64 v[0:1], v[0:1], 1, v[8:9]
	s_waitcnt lgkmcnt(0)
	global_store_dwordx4 v[0:1], v[4:7], off nt
	v_add_u32_e32 v0, 0x14500, v12
	ds_read2_b64 v[0:3], v0 offset1:1
	v_add_u32_e32 v4, 0x28000, v160
	v_mov_b32_e32 v5, v161
	v_lshl_add_u64 v[10:11], v[4:5], 1, v[8:9]
	v_add_u32_e32 v4, 0x16580, v12
	ds_read2_b64 v[4:7], v4 offset1:1
	s_waitcnt lgkmcnt(1)
	global_store_dwordx4 v[10:11], v[0:3], off nt
	s_nop 1
	v_add_u32_e32 v0, 0x2c000, v160
	v_mov_b32_e32 v1, v161
	v_lshl_add_u64 v[0:1], v[0:1], 1, v[8:9]
	s_waitcnt lgkmcnt(0)
	global_store_dwordx4 v[0:1], v[4:7], off nt
	v_add_u32_e32 v0, 0x18600, v12
	ds_read2_b64 v[0:3], v0 offset1:1
	v_add_u32_e32 v4, 0x30000, v160
	v_mov_b32_e32 v5, v161
	v_lshl_add_u64 v[10:11], v[4:5], 1, v[8:9]
	v_add_u32_e32 v4, 0x1a680, v12
	ds_read2_b64 v[4:7], v4 offset1:1
	s_waitcnt lgkmcnt(1)
	global_store_dwordx4 v[10:11], v[0:3], off nt
	v_add_u32_e32 v10, 0x38000, v160
	v_mov_b32_e32 v11, v161
	v_add_u32_e32 v0, 0x34000, v160
	v_mov_b32_e32 v1, v161
	v_lshl_add_u64 v[0:1], v[0:1], 1, v[8:9]
	s_waitcnt lgkmcnt(0)
	global_store_dwordx4 v[0:1], v[4:7], off nt
	v_add_u32_e32 v0, 0x1c700, v12
	ds_read2_b64 v[0:3], v0 offset1:1
	v_add_u32_e32 v4, 0x1e780, v12
	ds_read2_b64 v[4:7], v4 offset1:1
	v_lshl_add_u64 v[10:11], v[10:11], 1, v[8:9]
	v_add_u32_e32 v160, 0x3c000, v160
	s_waitcnt lgkmcnt(1)
	global_store_dwordx4 v[10:11], v[0:3], off nt
	s_nop 1
	v_lshl_add_u64 v[0:1], v[160:161], 1, v[8:9]
	s_waitcnt lgkmcnt(0)
	global_store_dwordx4 v[0:1], v[4:7], off nt
	s_barrier
	s_cbranch_scc0 .LBB0_929

; DI unsigned pack2(float a, float b) { f32x2_t v = {a, b}; bf16x2_t r = __builtin_convertvector(v, bf16x2_t); return __builtin_bit_cast(unsigned, r); }
; DI float sigmoidf_(float x) { return __builtin_amdgcn_rcpf(1.f + __expf(-x)); }
; DI int otid() { int t = threadIdx.x; asm volatile("" : "+v"(t)); return t; }
; template <bool NT>
; DI void stage_load_tile(bf16_t* stg, const bf16_t* tilebase) {
;   const int tid = otid();
;   const int r0 = tid >> 5, c = tid & 31;
;   const unsigned o0 = (unsigned)(r0 * 1024 + c * 8);
;   __builtin_amdgcn_sched_barrier(0);
; #pragma unroll
;   for (int hf = 0; hf < 2; ++hf) {
; #pragma unroll
;     for (int it = 8 * hf; it < 8 * hf + 8; ++it) {
;       const u32x4* gp = (const u32x4*)(tilebase + (o0 + (unsigned)(it * 16 * 1024)));
;       stage_write16(stg, r0 + 16 * it, c, NT ? __builtin_nontemporal_load(gp) : *gp);
;     }
;     __builtin_amdgcn_sched_barrier(0);
;   }
; template <bool LAST>
; DI void phase_gate(const Params& P, int layer, unsigned char* smem, int L, int G) {
;     ...
;     unsigned gq[4][2][8];
; #pragma unroll
;     for (int i = 0; i < 4; ++i)
; #pragma unroll
;       for (int q4 = 0; q4 < 4; ++q4) {
;         const int fl = wm * 128 + i * 32 + 8 * q4 + 4 * h;
;         const f32x4 c1v = *(const f32x4*)(vecL + fl), c2v = *(const f32x4*)(vecL + 256 + fl);
;         const float c1a[4] = {c1v.x, c1v.y, c1v.z, c1v.w}, c2a[4] = {c2v.x, c2v.y, c2v.z, c2v.w};
; #pragma unroll
;         for (int j = 0; j < 2; ++j) {
;           const int lrow = wn * 64 + j * 32 + r;
;           const float mu = rowA[lrow], rstd = rowB[lrow];
;           float sg4[4];
; #pragma unroll
;           for (int e = 0; e < 4; ++e) sg4[e] = sigmoidf_(rstd * (accu[i][j][4 * q4 + e] - mu * c1a[e]) + c2a[e]);
;           gq[i][j][2 * q4] = pack2(sg4[0], sg4[1]); gq[i][j][2 * q4 + 1] = pack2(sg4[2], sg4[3]);
;         }
;         __builtin_amdgcn_sched_barrier(0);
;       }
.LBB0_1498:
	s_ashr_i32 s19, s18, 31
	s_lshl_b64 s[18:19], s[18:19], 19
	s_add_u32 s20, s66, s18
	s_addc_u32 s21, s67, s19
	v_and_b32_e32 v188, 31, v192
	v_ashrrev_i32_e32 v189, 5, v192
	v_lshlrev_b32_e32 v188, 3, v188
	v_lshl_or_b32 v188, v189, 10, v188
	v_add_u32_e32 v188, v188, v162
	v_lshlrev_b32_e32 v188, 1, v188
	global_load_dwordx4 v[180:183], v188, s[20:21] nt
	s_add_u32 s100, s20, 0x8000
	s_addc_u32 s101, s21, 0
	global_load_dwordx4 v[184:187], v188, s[100:101] nt
	s_add_u32 s100, s20, 0x10000
	s_addc_u32 s101, s21, 0
	global_load_dwordx4 v[194:197], v188, s[100:101] nt
	s_add_u32 s100, s20, 0x18000
	s_addc_u32 s101, s21, 0
	global_load_dwordx4 v[198:201], v188, s[100:101] nt
	s_add_u32 s100, s20, 0x20000
	s_addc_u32 s101, s21, 0
	global_load_dwordx4 v[202:205], v188, s[100:101] nt
	s_add_u32 s100, s20, 0x28000
	s_addc_u32 s101, s21, 0
	global_load_dwordx4 v[206:209], v188, s[100:101] nt
	s_add_u32 s100, s20, 0x30000
	s_addc_u32 s101, s21, 0
	global_load_dwordx4 v[210:213], v188, s[100:101] nt
	s_add_u32 s100, s20, 0x38000
	s_addc_u32 s101, s21, 0
	global_load_dwordx4 v[214:217], v188, s[100:101] nt
	s_add_u32 s100, s20, 0x40000
	s_addc_u32 s101, s21, 0
	global_load_dwordx4 v[218:221], v188, s[100:101] nt
	s_add_u32 s100, s20, 0x48000
	s_addc_u32 s101, s21, 0
	global_load_dwordx4 v[222:225], v188, s[100:101] nt
	s_add_u32 s100, s20, 0x50000
	s_addc_u32 s101, s21, 0
	global_load_dwordx4 v[226:229], v188, s[100:101] nt
	s_add_u32 s100, s20, 0x58000
	s_addc_u32 s101, s21, 0
	global_load_dwordx4 v[230:233], v188, s[100:101] nt
	s_add_u32 s100, s20, 0x60000
	s_addc_u32 s101, s21, 0
	global_load_dwordx4 v[234:237], v188, s[100:101] nt
	s_add_u32 s100, s20, 0x68000
	s_addc_u32 s101, s21, 0
	global_load_dwordx4 v[238:241], v188, s[100:101] nt
	s_add_u32 s100, s20, 0x70000
	s_addc_u32 s101, s21, 0
	global_load_dwordx4 v[242:245], v188, s[100:101] nt
	s_add_u32 s100, s20, 0x78000
	s_addc_u32 s101, s21, 0
	global_load_dwordx4 v[248:251], v188, s[100:101] nt
	v_lshrrev_b32_e32 v160, 1, v163
	v_lshrrev_b32_e32 v163, 3, v163
	v_and_b32_e32 v163, 4, v163
	v_and_or_b32 v160, v160, s33, v163
	v_lshlrev_b32_e32 v160, 2, v160
	v_add_u32_e32 v163, 0x24800, v160
	v_add_u32_e32 v164, 0x24c00, v160
	v_and_b32_e32 v167, 0x37c, v168
	ds_read_b128 v[170:173], v163
	ds_read_b128 v[174:177], v164
	v_or_b32_e32 v164, 0x24000, v167
	v_or_b32_e32 v166, 0x24080, v167
	v_or_b32_e32 v165, 0x24400, v167
	ds_read_b32 v168, v164
	ds_read_b32 v169, v165
	v_or_b32_e32 v167, 0x24480, v167
	ds_read_b32 v178, v166
	ds_read_b32 v179, v167
	s_waitcnt lgkmcnt(3)
	v_fma_f32 v112, -v170, v168, v112
	v_fma_f32 v113, -v171, v168, v113
	s_waitcnt lgkmcnt(1)
	v_fma_f32 v98, -v172, v178, v98
	v_fma_f32 v114, -v172, v168, v114
	v_fma_f32 v115, -v173, v168, v115
	v_fma_f32 v96, -v170, v178, v96
	v_fma_f32 v97, -v171, v178, v97
	s_waitcnt lgkmcnt(0)
	v_fma_f32 v98, v179, v98, v176
	v_fma_f32 v99, -v173, v178, v99
	v_fma_f32 v112, v169, v112, v174
	v_fma_f32 v113, v169, v113, v175
	v_fma_f32 v114, v169, v114, v176
	v_fma_f32 v115, v169, v115, v177
	v_fma_f32 v96, v179, v96, v174
	v_fma_f32 v97, v179, v97, v175
	v_mul_f32_e32 v98, 0xbfb8aa3b, v98
	v_fmac_f32_e32 v177, v179, v99
	v_mul_f32_e32 v112, 0xbfb8aa3b, v112
	v_mul_f32_e32 v113, 0xbfb8aa3b, v113
	v_mul_f32_e32 v114, 0xbfb8aa3b, v114
	v_mul_f32_e32 v115, 0xbfb8aa3b, v115
	v_mul_f32_e32 v96, 0xbfb8aa3b, v96
	v_mul_f32_e32 v97, 0xbfb8aa3b, v97
	v_exp_f32_e32 v98, v98
	v_mul_f32_e32 v99, 0xbfb8aa3b, v177
	v_exp_f32_e32 v112, v112
	v_exp_f32_e32 v113, v113
	v_exp_f32_e32 v114, v114
	v_exp_f32_e32 v115, v115
	v_exp_f32_e32 v96, v96
	v_exp_f32_e32 v97, v97
	v_exp_f32_e32 v99, v99
	v_add_f32_e32 v98, 1.0, v98
	v_add_f32_e32 v112, 1.0, v112
	v_add_f32_e32 v113, 1.0, v113
	v_add_f32_e32 v114, 1.0, v114
	v_add_f32_e32 v115, 1.0, v115
	v_add_f32_e32 v96, 1.0, v96
	v_add_f32_e32 v97, 1.0, v97
	v_rcp_f32_e32 v168, v98
	v_add_f32_e32 v98, 1.0, v99
	v_rcp_f32_e32 v112, v112
	v_rcp_f32_e32 v113, v113
	v_rcp_f32_e32 v114, v114
	v_rcp_f32_e32 v115, v115
	v_rcp_f32_e32 v96, v96
	v_rcp_f32_e32 v97, v97
	v_rcp_f32_e32 v169, v98
	v_cvt_pk_bf16_f32 v99, v112, v113
	v_cvt_pk_bf16_f32 v98, v114, v115
	v_cvt_pk_bf16_f32 v97, v96, v97
	v_cvt_pk_bf16_f32 v96, v168, v169
	v_add_u32_e32 v112, 0x24820, v160
	v_add_u32_e32 v168, 0x24c20, v160
	ds_read_b128 v[112:115], v112
	ds_read_b128 v[168:171], v168
	ds_read_b32 v172, v164
	ds_read_b32 v173, v165
	ds_read_b32 v174, v166
	ds_read_b32 v175, v167
	s_waitcnt lgkmcnt(3)
	v_fma_f32 v116, -v112, v172, v116
	v_fma_f32 v117, -v113, v172, v117
	s_waitcnt lgkmcnt(1)
	v_fma_f32 v102, -v114, v174, v102
	v_fma_f32 v118, -v114, v172, v118
	v_fma_f32 v119, -v115, v172, v119
	v_fma_f32 v100, -v112, v174, v100
	v_fma_f32 v101, -v113, v174, v101
	s_waitcnt lgkmcnt(0)
	v_fma_f32 v102, v175, v102, v170
	v_fma_f32 v103, -v115, v174, v103
	v_fma_f32 v116, v173, v116, v168
	v_fma_f32 v117, v173, v117, v169
	v_fma_f32 v118, v173, v118, v170
	v_fma_f32 v119, v173, v119, v171
	v_fma_f32 v100, v175, v100, v168
	v_fma_f32 v101, v175, v101, v169
	v_mul_f32_e32 v102, 0xbfb8aa3b, v102
	v_fmac_f32_e32 v171, v175, v103
	v_mul_f32_e32 v116, 0xbfb8aa3b, v116
	v_mul_f32_e32 v117, 0xbfb8aa3b, v117
	v_mul_f32_e32 v118, 0xbfb8aa3b, v118
	v_mul_f32_e32 v119, 0xbfb8aa3b, v119
	v_mul_f32_e32 v100, 0xbfb8aa3b, v100
	v_mul_f32_e32 v101, 0xbfb8aa3b, v101
	v_exp_f32_e32 v102, v102
	v_mul_f32_e32 v103, 0xbfb8aa3b, v171
	v_exp_f32_e32 v116, v116
	v_exp_f32_e32 v117, v117
	v_exp_f32_e32 v118, v118
	v_exp_f32_e32 v119, v119
	v_exp_f32_e32 v100, v100
	v_exp_f32_e32 v101, v101
	v_exp_f32_e32 v103, v103
	v_add_f32_e32 v102, 1.0, v102
	v_add_f32_e32 v116, 1.0, v116
	v_add_f32_e32 v117, 1.0, v117
	v_add_f32_e32 v118, 1.0, v118
	v_add_f32_e32 v119, 1.0, v119
	v_add_f32_e32 v100, 1.0, v100
	v_add_f32_e32 v101, 1.0, v101
	v_rcp_f32_e32 v113, v102
	v_add_f32_e32 v102, 1.0, v103
	v_rcp_f32_e32 v116, v116
	v_rcp_f32_e32 v117, v117
	v_rcp_f32_e32 v118, v118
	v_rcp_f32_e32 v112, v119
	v_rcp_f32_e32 v100, v100
	v_rcp_f32_e32 v101, v101
	v_rcp_f32_e32 v114, v102
	v_cvt_pk_bf16_f32 v103, v116, v117
	v_cvt_pk_bf16_f32 v102, v118, v112
	v_cvt_pk_bf16_f32 v101, v100, v101
	v_cvt_pk_bf16_f32 v100, v113, v114
	v_add_u32_e32 v112, 0x24840, v160
	v_add_u32_e32 v116, 0x24c40, v160
	ds_read_b128 v[112:115], v112
	ds_read_b128 v[116:119], v116
	ds_read_b32 v168, v164
	ds_read_b32 v169, v165
	ds_read_b32 v170, v166
	ds_read_b32 v171, v167
	s_waitcnt lgkmcnt(3)
; DI unsigned pack2(float a, float b) { f32x2_t v = {a, b}; bf16x2_t r = __builtin_convertvector(v, bf16x2_t); return __builtin_bit_cast(unsigned, r); }
; DI float sigmoidf_(float x) { return __builtin_amdgcn_rcpf(1.f + __expf(-x)); }
; template <bool LAST>
; DI void phase_gate(const Params& P, int layer, unsigned char* smem, int L, int G) {
;     ...
;     unsigned gq[4][2][8];
; #pragma unroll
;     for (int i = 0; i < 4; ++i)
; #pragma unroll
;       for (int q4 = 0; q4 < 4; ++q4) {
;         const int fl = wm * 128 + i * 32 + 8 * q4 + 4 * h;
;         const f32x4 c1v = *(const f32x4*)(vecL + fl), c2v = *(const f32x4*)(vecL + 256 + fl);
;         const float c1a[4] = {c1v.x, c1v.y, c1v.z, c1v.w}, c2a[4] = {c2v.x, c2v.y, c2v.z, c2v.w};
; #pragma unroll
;         for (int j = 0; j < 2; ++j) {
;           const int lrow = wn * 64 + j * 32 + r;
;           const float mu = rowA[lrow], rstd = rowB[lrow];
;           float sg4[4];
; #pragma unroll
;           for (int e = 0; e < 4; ++e) sg4[e] = sigmoidf_(rstd * (accu[i][j][4 * q4 + e] - mu * c1a[e]) + c2a[e]);
;           gq[i][j][2 * q4] = pack2(sg4[0], sg4[1]); gq[i][j][2 * q4 + 1] = pack2(sg4[2], sg4[3]);
;         }
;         __builtin_amdgcn_sched_barrier(0);
;       }
	v_fma_f32 v120, -v112, v168, v120
	v_fma_f32 v121, -v113, v168, v121
	s_waitcnt lgkmcnt(1)
	v_fma_f32 v106, -v114, v170, v106
	v_fma_f32 v122, -v114, v168, v122
	v_fma_f32 v123, -v115, v168, v123
	v_fma_f32 v104, -v112, v170, v104
	v_fma_f32 v105, -v113, v170, v105
	s_waitcnt lgkmcnt(0)
	v_fma_f32 v106, v171, v106, v118
	v_fma_f32 v107, -v115, v170, v107
	v_fma_f32 v120, v169, v120, v116
	v_fma_f32 v121, v169, v121, v117
	v_fma_f32 v122, v169, v122, v118
	v_fma_f32 v123, v169, v123, v119
	v_fma_f32 v104, v171, v104, v116
	v_fma_f32 v105, v171, v105, v117
	v_mul_f32_e32 v106, 0xbfb8aa3b, v106
	v_fmac_f32_e32 v119, v171, v107
	v_mul_f32_e32 v120, 0xbfb8aa3b, v120
	v_mul_f32_e32 v121, 0xbfb8aa3b, v121
	v_mul_f32_e32 v122, 0xbfb8aa3b, v122
	v_mul_f32_e32 v123, 0xbfb8aa3b, v123
	v_mul_f32_e32 v104, 0xbfb8aa3b, v104
	v_mul_f32_e32 v105, 0xbfb8aa3b, v105
	v_exp_f32_e32 v106, v106
	v_mul_f32_e32 v107, 0xbfb8aa3b, v119
	v_exp_f32_e32 v120, v120
	v_exp_f32_e32 v121, v121
	v_exp_f32_e32 v122, v122
	v_exp_f32_e32 v123, v123
	v_exp_f32_e32 v104, v104
	v_exp_f32_e32 v105, v105
	v_exp_f32_e32 v107, v107
	v_add_f32_e32 v106, 1.0, v106
	v_add_f32_e32 v120, 1.0, v120
	v_add_f32_e32 v121, 1.0, v121
	v_add_f32_e32 v122, 1.0, v122
	v_add_f32_e32 v123, 1.0, v123
	v_add_f32_e32 v104, 1.0, v104
	v_add_f32_e32 v105, 1.0, v105
	v_rcp_f32_e32 v113, v106
	v_add_f32_e32 v106, 1.0, v107
	v_rcp_f32_e32 v120, v120
	v_rcp_f32_e32 v121, v121
	v_rcp_f32_e32 v122, v122
	v_rcp_f32_e32 v112, v123
	v_rcp_f32_e32 v104, v104
	v_rcp_f32_e32 v105, v105
	v_rcp_f32_e32 v114, v106
	v_cvt_pk_bf16_f32 v107, v120, v121
	v_cvt_pk_bf16_f32 v106, v122, v112
	v_cvt_pk_bf16_f32 v105, v104, v105
	v_cvt_pk_bf16_f32 v104, v113, v114
	v_add_u32_e32 v112, 0x24860, v160
	v_add_u32_e32 v116, 0x24c60, v160
	ds_read_b128 v[112:115], v112
	ds_read_b128 v[116:119], v116
	ds_read_b32 v120, v164
	ds_read_b32 v121, v165
	ds_read_b32 v122, v166
	ds_read_b32 v123, v167
	s_waitcnt lgkmcnt(3)
	v_fma_f32 v125, -v113, v120, v125
	v_fma_f32 v124, -v112, v120, v124
	s_waitcnt lgkmcnt(1)
	v_fma_f32 v110, -v114, v122, v110
	v_fma_f32 v125, v121, v125, v117
	v_fma_f32 v126, -v114, v120, v126
	v_fma_f32 v120, -v115, v120, v127
	v_fma_f32 v108, -v112, v122, v108
	v_fma_f32 v109, -v113, v122, v109
	s_waitcnt lgkmcnt(0)
	v_fma_f32 v110, v123, v110, v118
	v_fma_f32 v111, -v115, v122, v111
	v_fma_f32 v124, v121, v124, v116
	v_mul_f32_e32 v125, 0xbfb8aa3b, v125
	v_fma_f32 v126, v121, v126, v118
	v_fma_f32 v120, v121, v120, v119
	v_fma_f32 v108, v123, v108, v116
	v_fma_f32 v109, v123, v109, v117
	v_mul_f32_e32 v110, 0xbfb8aa3b, v110
	v_fmac_f32_e32 v119, v123, v111
	v_mul_f32_e32 v124, 0xbfb8aa3b, v124
	v_exp_f32_e32 v125, v125
	v_mul_f32_e32 v126, 0xbfb8aa3b, v126
	v_mul_f32_e32 v120, 0xbfb8aa3b, v120
	v_mul_f32_e32 v108, 0xbfb8aa3b, v108
	v_mul_f32_e32 v109, 0xbfb8aa3b, v109
	v_exp_f32_e32 v110, v110
	v_mul_f32_e32 v111, 0xbfb8aa3b, v119
	v_exp_f32_e32 v124, v124
	v_exp_f32_e32 v126, v126
	v_exp_f32_e32 v120, v120
	v_exp_f32_e32 v108, v108
	v_exp_f32_e32 v109, v109
	v_exp_f32_e32 v111, v111
	v_add_f32_e32 v125, 1.0, v125
	v_add_f32_e32 v110, 1.0, v110
	v_add_f32_e32 v124, 1.0, v124
	v_rcp_f32_e32 v121, v125
	v_add_f32_e32 v125, 1.0, v126
	v_add_f32_e32 v120, 1.0, v120
	v_add_f32_e32 v108, 1.0, v108
	v_add_f32_e32 v109, 1.0, v109
	v_rcp_f32_e32 v113, v110
	v_add_f32_e32 v110, 1.0, v111
	v_rcp_f32_e32 v124, v124
	v_rcp_f32_e32 v125, v125
	v_rcp_f32_e32 v112, v120
	v_rcp_f32_e32 v108, v108
	v_rcp_f32_e32 v109, v109
	v_rcp_f32_e32 v114, v110
	v_cvt_pk_bf16_f32 v111, v124, v121
	v_cvt_pk_bf16_f32 v110, v125, v112
	v_cvt_pk_bf16_f32 v109, v108, v109
	v_cvt_pk_bf16_f32 v108, v113, v114
	v_add_u32_e32 v112, 0x24880, v160
	v_add_u32_e32 v116, 0x24c80, v160
	ds_read_b128 v[112:115], v112
	ds_read_b128 v[116:119], v116
	ds_read_b32 v120, v164
	ds_read_b32 v121, v165
	ds_read_b32 v122, v166
	ds_read_b32 v123, v167
	s_waitcnt lgkmcnt(3)
	v_fma_f32 v80, -v112, v120, v80
	v_fma_f32 v81, -v113, v120, v81
	s_waitcnt lgkmcnt(1)
	v_fma_f32 v66, -v114, v122, v66
	v_fma_f32 v82, -v114, v120, v82
	v_fma_f32 v83, -v115, v120, v83
	v_fma_f32 v64, -v112, v122, v64
	v_fma_f32 v65, -v113, v122, v65
	s_waitcnt lgkmcnt(0)
	v_fma_f32 v66, v123, v66, v118
	v_fma_f32 v67, -v115, v122, v67
	v_fma_f32 v80, v121, v80, v116
	v_fma_f32 v81, v121, v81, v117
	v_fma_f32 v82, v121, v82, v118
	v_fma_f32 v83, v121, v83, v119
	v_fma_f32 v64, v123, v64, v116
	v_fma_f32 v65, v123, v65, v117
	v_mul_f32_e32 v66, 0xbfb8aa3b, v66
	v_fmac_f32_e32 v119, v123, v67
	v_mul_f32_e32 v80, 0xbfb8aa3b, v80
	v_mul_f32_e32 v81, 0xbfb8aa3b, v81
	v_mul_f32_e32 v82, 0xbfb8aa3b, v82
	v_mul_f32_e32 v83, 0xbfb8aa3b, v83
	v_mul_f32_e32 v64, 0xbfb8aa3b, v64
	v_mul_f32_e32 v65, 0xbfb8aa3b, v65
	v_exp_f32_e32 v66, v66
	v_mul_f32_e32 v67, 0xbfb8aa3b, v119
	v_exp_f32_e32 v80, v80
	v_exp_f32_e32 v81, v81
	v_exp_f32_e32 v82, v82
	v_exp_f32_e32 v83, v83
	v_exp_f32_e32 v64, v64
	v_exp_f32_e32 v65, v65
	v_exp_f32_e32 v67, v67
	v_add_f32_e32 v66, 1.0, v66
	v_add_f32_e32 v80, 1.0, v80
	v_add_f32_e32 v81, 1.0, v81
	v_add_f32_e32 v82, 1.0, v82
	v_add_f32_e32 v83, 1.0, v83
	v_add_f32_e32 v64, 1.0, v64
	v_add_f32_e32 v65, 1.0, v65
	v_rcp_f32_e32 v112, v66
	v_add_f32_e32 v66, 1.0, v67
	v_rcp_f32_e32 v80, v80
	v_rcp_f32_e32 v81, v81
	v_rcp_f32_e32 v82, v82
	v_rcp_f32_e32 v83, v83
	v_rcp_f32_e32 v64, v64
	v_rcp_f32_e32 v65, v65
	v_rcp_f32_e32 v113, v66
	v_cvt_pk_bf16_f32 v67, v80, v81
	v_cvt_pk_bf16_f32 v66, v82, v83
	v_cvt_pk_bf16_f32 v65, v64, v65
	v_cvt_pk_bf16_f32 v64, v112, v113
	v_add_u32_e32 v80, 0x248a0, v160
	v_add_u32_e32 v112, 0x24ca0, v160
	ds_read_b128 v[80:83], v80
	ds_read_b128 v[112:115], v112
	ds_read_b32 v116, v164
	ds_read_b32 v117, v165
	ds_read_b32 v118, v166
	ds_read_b32 v119, v167
	s_waitcnt lgkmcnt(3)
; DI unsigned pack2(float a, float b) { f32x2_t v = {a, b}; bf16x2_t r = __builtin_convertvector(v, bf16x2_t); return __builtin_bit_cast(unsigned, r); }
; DI float sigmoidf_(float x) { return __builtin_amdgcn_rcpf(1.f + __expf(-x)); }
; template <bool LAST>
; DI void phase_gate(const Params& P, int layer, unsigned char* smem, int L, int G) {
;     ...
;     unsigned gq[4][2][8];
; #pragma unroll
;     for (int i = 0; i < 4; ++i)
; #pragma unroll
;       for (int q4 = 0; q4 < 4; ++q4) {
;         const int fl = wm * 128 + i * 32 + 8 * q4 + 4 * h;
;         const f32x4 c1v = *(const f32x4*)(vecL + fl), c2v = *(const f32x4*)(vecL + 256 + fl);
;         const float c1a[4] = {c1v.x, c1v.y, c1v.z, c1v.w}, c2a[4] = {c2v.x, c2v.y, c2v.z, c2v.w};
; #pragma unroll
;         for (int j = 0; j < 2; ++j) {
;           const int lrow = wn * 64 + j * 32 + r;
;           const float mu = rowA[lrow], rstd = rowB[lrow];
;           float sg4[4];
; #pragma unroll
;           for (int e = 0; e < 4; ++e) sg4[e] = sigmoidf_(rstd * (accu[i][j][4 * q4 + e] - mu * c1a[e]) + c2a[e]);
;           gq[i][j][2 * q4] = pack2(sg4[0], sg4[1]); gq[i][j][2 * q4 + 1] = pack2(sg4[2], sg4[3]);
;         }
;         __builtin_amdgcn_sched_barrier(0);
;       }
	v_fma_f32 v84, -v80, v116, v84
	v_fma_f32 v85, -v81, v116, v85
	s_waitcnt lgkmcnt(1)
	v_fma_f32 v70, -v82, v118, v70
	v_fma_f32 v86, -v82, v116, v86
	v_fma_f32 v87, -v83, v116, v87
	v_fma_f32 v68, -v80, v118, v68
	v_fma_f32 v69, -v81, v118, v69
	s_waitcnt lgkmcnt(0)
	v_fma_f32 v70, v119, v70, v114
	v_fma_f32 v71, -v83, v118, v71
	v_fma_f32 v84, v117, v84, v112
	v_fma_f32 v85, v117, v85, v113
	v_fma_f32 v86, v117, v86, v114
	v_fma_f32 v87, v117, v87, v115
	v_fma_f32 v68, v119, v68, v112
	v_fma_f32 v69, v119, v69, v113
	v_mul_f32_e32 v70, 0xbfb8aa3b, v70
	v_fmac_f32_e32 v115, v119, v71
	v_mul_f32_e32 v84, 0xbfb8aa3b, v84
	v_mul_f32_e32 v85, 0xbfb8aa3b, v85
	v_mul_f32_e32 v86, 0xbfb8aa3b, v86
	v_mul_f32_e32 v87, 0xbfb8aa3b, v87
	v_mul_f32_e32 v68, 0xbfb8aa3b, v68
	v_mul_f32_e32 v69, 0xbfb8aa3b, v69
	v_exp_f32_e32 v70, v70
	v_mul_f32_e32 v71, 0xbfb8aa3b, v115
	v_exp_f32_e32 v84, v84
	v_exp_f32_e32 v85, v85
	v_exp_f32_e32 v86, v86
	v_exp_f32_e32 v87, v87
	v_exp_f32_e32 v68, v68
	v_exp_f32_e32 v69, v69
	v_exp_f32_e32 v71, v71
	v_add_f32_e32 v70, 1.0, v70
	v_add_f32_e32 v84, 1.0, v84
	v_add_f32_e32 v85, 1.0, v85
	v_add_f32_e32 v86, 1.0, v86
	v_add_f32_e32 v87, 1.0, v87
	v_add_f32_e32 v68, 1.0, v68
	v_add_f32_e32 v69, 1.0, v69
	v_rcp_f32_e32 v81, v70
	v_add_f32_e32 v70, 1.0, v71
	v_rcp_f32_e32 v84, v84
	v_rcp_f32_e32 v85, v85
	v_rcp_f32_e32 v86, v86
	v_rcp_f32_e32 v80, v87
	v_rcp_f32_e32 v68, v68
	v_rcp_f32_e32 v69, v69
	v_rcp_f32_e32 v82, v70
	v_cvt_pk_bf16_f32 v71, v84, v85
	v_cvt_pk_bf16_f32 v70, v86, v80
	v_cvt_pk_bf16_f32 v69, v68, v69
	v_cvt_pk_bf16_f32 v68, v81, v82
	v_add_u32_e32 v80, 0x248c0, v160
	v_add_u32_e32 v84, 0x24cc0, v160
	ds_read_b128 v[80:83], v80
	ds_read_b128 v[84:87], v84
	ds_read_b32 v112, v164
	ds_read_b32 v113, v165
	ds_read_b32 v114, v166
	ds_read_b32 v115, v167
	s_waitcnt lgkmcnt(3)
	v_fma_f32 v88, -v80, v112, v88
	v_fma_f32 v89, -v81, v112, v89
	s_waitcnt lgkmcnt(1)
	v_fma_f32 v74, -v82, v114, v74
	v_fma_f32 v90, -v82, v112, v90
	v_fma_f32 v91, -v83, v112, v91
	v_fma_f32 v72, -v80, v114, v72
	v_fma_f32 v73, -v81, v114, v73
	s_waitcnt lgkmcnt(0)
	v_fma_f32 v74, v115, v74, v86
	v_fma_f32 v75, -v83, v114, v75
	v_fma_f32 v88, v113, v88, v84
	v_fma_f32 v89, v113, v89, v85
	v_fma_f32 v90, v113, v90, v86
	v_fma_f32 v91, v113, v91, v87
	v_fma_f32 v72, v115, v72, v84
	v_fma_f32 v73, v115, v73, v85
	v_mul_f32_e32 v74, 0xbfb8aa3b, v74
	v_fmac_f32_e32 v87, v115, v75
	v_mul_f32_e32 v88, 0xbfb8aa3b, v88
	v_mul_f32_e32 v89, 0xbfb8aa3b, v89
	v_mul_f32_e32 v90, 0xbfb8aa3b, v90
	v_mul_f32_e32 v91, 0xbfb8aa3b, v91
	v_mul_f32_e32 v72, 0xbfb8aa3b, v72
	v_mul_f32_e32 v73, 0xbfb8aa3b, v73
	v_exp_f32_e32 v74, v74
	v_mul_f32_e32 v75, 0xbfb8aa3b, v87
	v_exp_f32_e32 v88, v88
	v_exp_f32_e32 v89, v89
	v_exp_f32_e32 v90, v90
	v_exp_f32_e32 v91, v91
	v_exp_f32_e32 v72, v72
	v_exp_f32_e32 v73, v73
	v_exp_f32_e32 v75, v75
	v_add_f32_e32 v74, 1.0, v74
	v_add_f32_e32 v88, 1.0, v88
	v_add_f32_e32 v89, 1.0, v89
	v_add_f32_e32 v90, 1.0, v90
	v_add_f32_e32 v91, 1.0, v91
	v_add_f32_e32 v72, 1.0, v72
	v_add_f32_e32 v73, 1.0, v73
	v_rcp_f32_e32 v81, v74
	v_add_f32_e32 v74, 1.0, v75
	v_rcp_f32_e32 v88, v88
	v_rcp_f32_e32 v89, v89
	v_rcp_f32_e32 v90, v90
	v_rcp_f32_e32 v80, v91
	v_rcp_f32_e32 v72, v72
	v_rcp_f32_e32 v73, v73
	v_rcp_f32_e32 v82, v74
	v_cvt_pk_bf16_f32 v75, v88, v89
	v_cvt_pk_bf16_f32 v74, v90, v80
	v_cvt_pk_bf16_f32 v73, v72, v73
	v_cvt_pk_bf16_f32 v72, v81, v82
	v_add_u32_e32 v80, 0x248e0, v160
	v_add_u32_e32 v84, 0x24ce0, v160
	ds_read_b128 v[80:83], v80
	ds_read_b128 v[84:87], v84
	ds_read_b32 v88, v164
	ds_read_b32 v89, v165
	ds_read_b32 v90, v166
	ds_read_b32 v91, v167
	s_waitcnt lgkmcnt(3)
	v_fma_f32 v93, -v81, v88, v93
	v_fma_f32 v92, -v80, v88, v92
	s_waitcnt lgkmcnt(1)
	v_fma_f32 v78, -v82, v90, v78
	v_fma_f32 v93, v89, v93, v85
	v_fma_f32 v94, -v82, v88, v94
	v_fma_f32 v88, -v83, v88, v95
	v_fma_f32 v76, -v80, v90, v76
	v_fma_f32 v77, -v81, v90, v77
	s_waitcnt lgkmcnt(0)
	v_fma_f32 v78, v91, v78, v86
	v_fma_f32 v79, -v83, v90, v79
	v_fma_f32 v92, v89, v92, v84
	v_mul_f32_e32 v93, 0xbfb8aa3b, v93
	v_fma_f32 v94, v89, v94, v86
	v_fma_f32 v88, v89, v88, v87
	v_fma_f32 v76, v91, v76, v84
	v_fma_f32 v77, v91, v77, v85
	v_mul_f32_e32 v78, 0xbfb8aa3b, v78
	v_fmac_f32_e32 v87, v91, v79
	v_mul_f32_e32 v92, 0xbfb8aa3b, v92
	v_exp_f32_e32 v93, v93
	v_mul_f32_e32 v94, 0xbfb8aa3b, v94
	v_mul_f32_e32 v88, 0xbfb8aa3b, v88
	v_mul_f32_e32 v76, 0xbfb8aa3b, v76
	v_mul_f32_e32 v77, 0xbfb8aa3b, v77
	v_exp_f32_e32 v78, v78
	v_mul_f32_e32 v79, 0xbfb8aa3b, v87
	v_exp_f32_e32 v92, v92
	v_exp_f32_e32 v94, v94
	v_exp_f32_e32 v88, v88
	v_exp_f32_e32 v76, v76
	v_exp_f32_e32 v77, v77
	v_exp_f32_e32 v79, v79
	v_add_f32_e32 v93, 1.0, v93
	v_add_f32_e32 v78, 1.0, v78
	v_add_f32_e32 v92, 1.0, v92
	v_rcp_f32_e32 v89, v93
	v_add_f32_e32 v93, 1.0, v94
	v_add_f32_e32 v88, 1.0, v88
	v_add_f32_e32 v76, 1.0, v76
	v_add_f32_e32 v77, 1.0, v77
	v_rcp_f32_e32 v81, v78
	v_add_f32_e32 v78, 1.0, v79
	v_rcp_f32_e32 v92, v92
	v_rcp_f32_e32 v93, v93
	v_rcp_f32_e32 v80, v88
	v_rcp_f32_e32 v76, v76
	v_rcp_f32_e32 v77, v77
	v_rcp_f32_e32 v82, v78
	v_cvt_pk_bf16_f32 v79, v92, v89
	v_cvt_pk_bf16_f32 v78, v93, v80
	v_cvt_pk_bf16_f32 v77, v76, v77
	v_cvt_pk_bf16_f32 v76, v81, v82
	v_add_u32_e32 v80, 0x24900, v160
	v_add_u32_e32 v84, 0x24d00, v160
	ds_read_b128 v[80:83], v80
	ds_read_b128 v[84:87], v84
	ds_read_b32 v88, v164
	ds_read_b32 v89, v165
	ds_read_b32 v90, v166
	ds_read_b32 v91, v167
	s_waitcnt lgkmcnt(3)
	v_fma_f32 v48, -v80, v88, v48
	v_fma_f32 v49, -v81, v88, v49
	s_waitcnt lgkmcnt(1)
	v_fma_f32 v34, -v82, v90, v34
	v_fma_f32 v50, -v82, v88, v50
	v_fma_f32 v51, -v83, v88, v51
	v_fma_f32 v32, -v80, v90, v32
	v_fma_f32 v33, -v81, v90, v33
	s_waitcnt lgkmcnt(0)
; DI unsigned pack2(float a, float b) { f32x2_t v = {a, b}; bf16x2_t r = __builtin_convertvector(v, bf16x2_t); return __builtin_bit_cast(unsigned, r); }
; DI float sigmoidf_(float x) { return __builtin_amdgcn_rcpf(1.f + __expf(-x)); }
; template <bool LAST>
; DI void phase_gate(const Params& P, int layer, unsigned char* smem, int L, int G) {
;     ...
; #pragma unroll
;     for (int i = 0; i < 4; ++i)
; #pragma unroll
;       for (int q4 = 0; q4 < 4; ++q4) {
;         const int fl = wm * 128 + i * 32 + 8 * q4 + 4 * h;
;         const f32x4 c1v = *(const f32x4*)(vecL + fl), c2v = *(const f32x4*)(vecL + 256 + fl);
;         const float c1a[4] = {c1v.x, c1v.y, c1v.z, c1v.w}, c2a[4] = {c2v.x, c2v.y, c2v.z, c2v.w};
; #pragma unroll
;         for (int j = 0; j < 2; ++j) {
;           const int lrow = wn * 64 + j * 32 + r;
;           const float mu = rowA[lrow], rstd = rowB[lrow];
;           float sg4[4];
; #pragma unroll
;           for (int e = 0; e < 4; ++e) sg4[e] = sigmoidf_(rstd * (accu[i][j][4 * q4 + e] - mu * c1a[e]) + c2a[e]);
;           gq[i][j][2 * q4] = pack2(sg4[0], sg4[1]); gq[i][j][2 * q4 + 1] = pack2(sg4[2], sg4[3]);
;         }
;         __builtin_amdgcn_sched_barrier(0);
;       }
	v_fma_f32 v34, v91, v34, v86
	v_fma_f32 v35, -v83, v90, v35
	v_fma_f32 v48, v89, v48, v84
	v_fma_f32 v49, v89, v49, v85
	v_fma_f32 v50, v89, v50, v86
	v_fma_f32 v51, v89, v51, v87
	v_fma_f32 v32, v91, v32, v84
	v_fma_f32 v33, v91, v33, v85
	v_mul_f32_e32 v34, 0xbfb8aa3b, v34
	v_fmac_f32_e32 v87, v91, v35
	v_mul_f32_e32 v48, 0xbfb8aa3b, v48
	v_mul_f32_e32 v49, 0xbfb8aa3b, v49
	v_mul_f32_e32 v50, 0xbfb8aa3b, v50
	v_mul_f32_e32 v51, 0xbfb8aa3b, v51
	v_mul_f32_e32 v32, 0xbfb8aa3b, v32
	v_mul_f32_e32 v33, 0xbfb8aa3b, v33
	v_exp_f32_e32 v34, v34
	v_mul_f32_e32 v35, 0xbfb8aa3b, v87
	v_exp_f32_e32 v48, v48
	v_exp_f32_e32 v49, v49
	v_exp_f32_e32 v50, v50
	v_exp_f32_e32 v51, v51
	v_exp_f32_e32 v32, v32
	v_exp_f32_e32 v33, v33
	v_exp_f32_e32 v35, v35
	v_add_f32_e32 v34, 1.0, v34
	v_add_f32_e32 v48, 1.0, v48
	v_add_f32_e32 v49, 1.0, v49
	v_add_f32_e32 v50, 1.0, v50
	v_add_f32_e32 v51, 1.0, v51
	v_add_f32_e32 v32, 1.0, v32
	v_add_f32_e32 v33, 1.0, v33
	v_rcp_f32_e32 v80, v34
	v_add_f32_e32 v34, 1.0, v35
	v_rcp_f32_e32 v48, v48
	v_rcp_f32_e32 v49, v49
	v_rcp_f32_e32 v50, v50
	v_rcp_f32_e32 v51, v51
	v_rcp_f32_e32 v32, v32
	v_rcp_f32_e32 v33, v33
	v_rcp_f32_e32 v81, v34
	v_cvt_pk_bf16_f32 v35, v48, v49
	v_cvt_pk_bf16_f32 v34, v50, v51
	v_cvt_pk_bf16_f32 v33, v32, v33
	v_cvt_pk_bf16_f32 v32, v80, v81
	v_add_u32_e32 v48, 0x24920, v160
	v_add_u32_e32 v80, 0x24d20, v160
	ds_read_b128 v[48:51], v48
	ds_read_b128 v[80:83], v80
	ds_read_b32 v84, v164
	ds_read_b32 v85, v165
	ds_read_b32 v86, v166
	ds_read_b32 v87, v167
	s_waitcnt lgkmcnt(3)
	v_fma_f32 v53, -v49, v84, v53
	v_fma_f32 v52, -v48, v84, v52
	s_waitcnt lgkmcnt(1)
	v_fma_f32 v36, -v48, v86, v36
	s_waitcnt lgkmcnt(0)
	v_fma_f32 v36, v87, v36, v80
	v_fma_f32 v37, -v49, v86, v37
	v_mul_f32_e32 v36, 0xbfb8aa3b, v36
	v_fma_f32 v37, v87, v37, v81
	v_exp_f32_e32 v36, v36
	v_mul_f32_e32 v37, 0xbfb8aa3b, v37
	v_exp_f32_e32 v37, v37
	v_fma_f32 v54, -v50, v84, v54
	v_add_f32_e32 v36, 1.0, v36
	v_rcp_f32_e32 v49, v36
	v_add_f32_e32 v36, 1.0, v37
	v_fma_f32 v37, -v50, v86, v38
	v_fma_f32 v55, -v51, v84, v55
	v_fma_f32 v37, v87, v37, v82
	v_fma_f32 v38, -v51, v86, v39
	v_fma_f32 v52, v85, v52, v80
	v_fma_f32 v53, v85, v53, v81
	v_fma_f32 v54, v85, v54, v82
	v_fma_f32 v55, v85, v55, v83
	v_mul_f32_e32 v37, 0xbfb8aa3b, v37
	v_fmac_f32_e32 v83, v87, v38
	v_mul_f32_e32 v52, 0xbfb8aa3b, v52
	v_mul_f32_e32 v53, 0xbfb8aa3b, v53
	v_mul_f32_e32 v54, 0xbfb8aa3b, v54
	v_mul_f32_e32 v55, 0xbfb8aa3b, v55
	v_exp_f32_e32 v37, v37
	v_mul_f32_e32 v38, 0xbfb8aa3b, v83
	v_exp_f32_e32 v52, v52
	v_exp_f32_e32 v53, v53
	v_exp_f32_e32 v54, v54
	v_exp_f32_e32 v55, v55
	v_exp_f32_e32 v38, v38
	v_rcp_f32_e32 v39, v36
	v_add_f32_e32 v36, 1.0, v37
	v_add_f32_e32 v52, 1.0, v52
	v_add_f32_e32 v53, 1.0, v53
	v_add_f32_e32 v54, 1.0, v54
	v_add_f32_e32 v55, 1.0, v55
	v_rcp_f32_e32 v37, v36
	v_add_f32_e32 v36, 1.0, v38
	v_rcp_f32_e32 v52, v52
	v_rcp_f32_e32 v53, v53
	v_rcp_f32_e32 v54, v54
	v_rcp_f32_e32 v48, v55
	v_rcp_f32_e32 v38, v36
	v_cvt_pk_bf16_f32 v80, v52, v53
	v_cvt_pk_bf16_f32 v55, v49, v39
	v_cvt_pk_bf16_f32 v36, v54, v48
	v_cvt_pk_bf16_f32 v53, v37, v38
	v_add_u32_e32 v37, 0x24940, v160
	v_add_u32_e32 v38, 0x24d40, v160
	ds_read_b128 v[48:51], v37
	ds_read_b128 v[82:85], v38
	ds_read_b32 v37, v164
	ds_read_b32 v38, v165
	ds_read_b32 v39, v166
	ds_read_b32 v52, v167
	s_waitcnt lgkmcnt(3)
	v_fma_f32 v54, -v48, v37, v56
	v_fma_f32 v56, -v49, v37, v57
	s_waitcnt lgkmcnt(2)
	v_fma_f32 v56, v38, v56, v83
	v_fma_f32 v57, -v50, v37, v58
	v_fma_f32 v37, -v51, v37, v59
	s_waitcnt lgkmcnt(1)
	v_fma_f32 v40, -v48, v39, v40
	v_fma_f32 v41, -v49, v39, v41
	v_fma_f32 v42, -v50, v39, v42
	v_fma_f32 v39, -v51, v39, v43
	v_fma_f32 v54, v38, v54, v82
	v_mul_f32_e32 v56, 0xbfb8aa3b, v56
	v_fma_f32 v57, v38, v57, v84
	v_fma_f32 v37, v38, v37, v85
	s_waitcnt lgkmcnt(0)
	v_fma_f32 v40, v52, v40, v82
	v_fma_f32 v41, v52, v41, v83
	v_fma_f32 v42, v52, v42, v84
	v_fmac_f32_e32 v85, v52, v39
	v_mul_f32_e32 v54, 0xbfb8aa3b, v54
	v_exp_f32_e32 v56, v56
	v_mul_f32_e32 v57, 0xbfb8aa3b, v57
	v_mul_f32_e32 v37, 0xbfb8aa3b, v37
	v_mul_f32_e32 v40, 0xbfb8aa3b, v40
	v_mul_f32_e32 v41, 0xbfb8aa3b, v41
	v_mul_f32_e32 v42, 0xbfb8aa3b, v42
	v_mul_f32_e32 v39, 0xbfb8aa3b, v85
	v_exp_f32_e32 v54, v54
	v_exp_f32_e32 v57, v57
	v_exp_f32_e32 v37, v37
	v_exp_f32_e32 v40, v40
	v_exp_f32_e32 v41, v41
	v_exp_f32_e32 v42, v42
	v_exp_f32_e32 v39, v39
	v_add_f32_e32 v56, 1.0, v56
	v_add_f32_e32 v54, 1.0, v54
	v_rcp_f32_e32 v38, v56
	v_add_f32_e32 v56, 1.0, v57
	v_add_f32_e32 v37, 1.0, v37
	v_add_f32_e32 v40, 1.0, v40
	v_add_f32_e32 v41, 1.0, v41
	v_add_f32_e32 v42, 1.0, v42
	v_add_f32_e32 v39, 1.0, v39
	v_rcp_f32_e32 v54, v54
	v_rcp_f32_e32 v56, v56
	v_rcp_f32_e32 v37, v37
	v_rcp_f32_e32 v40, v40
	v_rcp_f32_e32 v41, v41
	v_rcp_f32_e32 v42, v42
	v_rcp_f32_e32 v39, v39
	v_cvt_pk_bf16_f32 v83, v54, v38
	v_cvt_pk_bf16_f32 v82, v56, v37
	v_cvt_pk_bf16_f32 v81, v40, v41
	v_cvt_pk_bf16_f32 v59, v42, v39
	v_add_u32_e32 v37, 0x24960, v160
	v_add_u32_e32 v42, 0x24d60, v160
	ds_read_b128 v[38:41], v37
	ds_read_b128 v[48:51], v42
	ds_read_b32 v37, v164
	ds_read_b32 v42, v165
	ds_read_b32 v43, v166
	ds_read_b32 v52, v167
	s_waitcnt lgkmcnt(3)
	v_fma_f32 v56, -v39, v37, v61
	v_fma_f32 v54, -v38, v37, v60
	s_waitcnt lgkmcnt(2)
	v_fma_f32 v56, v42, v56, v49
	v_fma_f32 v57, -v40, v37, v62
	v_fma_f32 v37, -v41, v37, v63
	s_waitcnt lgkmcnt(1)
	v_fma_f32 v38, -v38, v43, v44
	v_fma_f32 v39, -v39, v43, v45
	v_fma_f32 v40, -v40, v43, v46
	v_fma_f32 v41, -v41, v43, v47
	v_fma_f32 v54, v42, v54, v48
	v_mul_f32_e32 v56, 0xbfb8aa3b, v56
	v_fma_f32 v57, v42, v57, v50
	v_fma_f32 v37, v42, v37, v51
	s_waitcnt lgkmcnt(0)
; DI unsigned pack2(float a, float b) { f32x2_t v = {a, b}; bf16x2_t r = __builtin_convertvector(v, bf16x2_t); return __builtin_bit_cast(unsigned, r); }
; DI float sigmoidf_(float x) { return __builtin_amdgcn_rcpf(1.f + __expf(-x)); }
; template <bool LAST>
; DI void phase_gate(const Params& P, int layer, unsigned char* smem, int L, int G) {
;     ...
; #pragma unroll
;     for (int i = 0; i < 4; ++i)
; #pragma unroll
;       for (int q4 = 0; q4 < 4; ++q4) {
;         const int fl = wm * 128 + i * 32 + 8 * q4 + 4 * h;
;         const f32x4 c1v = *(const f32x4*)(vecL + fl), c2v = *(const f32x4*)(vecL + 256 + fl);
;         const float c1a[4] = {c1v.x, c1v.y, c1v.z, c1v.w}, c2a[4] = {c2v.x, c2v.y, c2v.z, c2v.w};
; #pragma unroll
;         for (int j = 0; j < 2; ++j) {
;           const int lrow = wn * 64 + j * 32 + r;
;           const float mu = rowA[lrow], rstd = rowB[lrow];
;           float sg4[4];
; #pragma unroll
;           for (int e = 0; e < 4; ++e) sg4[e] = sigmoidf_(rstd * (accu[i][j][4 * q4 + e] - mu * c1a[e]) + c2a[e]);
;           gq[i][j][2 * q4] = pack2(sg4[0], sg4[1]); gq[i][j][2 * q4 + 1] = pack2(sg4[2], sg4[3]);
;         }
;         __builtin_amdgcn_sched_barrier(0);
;       }
	v_fma_f32 v38, v52, v38, v48
	v_fma_f32 v39, v52, v39, v49
	v_fma_f32 v40, v52, v40, v50
	v_fmac_f32_e32 v51, v52, v41
	v_mul_f32_e32 v54, 0xbfb8aa3b, v54
	v_exp_f32_e32 v56, v56
	v_mul_f32_e32 v57, 0xbfb8aa3b, v57
	v_mul_f32_e32 v37, 0xbfb8aa3b, v37
	v_mul_f32_e32 v38, 0xbfb8aa3b, v38
	v_mul_f32_e32 v39, 0xbfb8aa3b, v39
	v_mul_f32_e32 v40, 0xbfb8aa3b, v40
	v_mul_f32_e32 v41, 0xbfb8aa3b, v51
	v_exp_f32_e32 v54, v54
	v_exp_f32_e32 v57, v57
	v_exp_f32_e32 v37, v37
	v_exp_f32_e32 v38, v38
	v_exp_f32_e32 v39, v39
	v_exp_f32_e32 v40, v40
	v_exp_f32_e32 v41, v41
	v_add_f32_e32 v56, 1.0, v56
	v_add_f32_e32 v54, 1.0, v54
	v_rcp_f32_e32 v42, v56
	v_add_f32_e32 v56, 1.0, v57
	v_add_f32_e32 v37, 1.0, v37
	v_add_f32_e32 v38, 1.0, v38
	v_add_f32_e32 v39, 1.0, v39
	v_add_f32_e32 v40, 1.0, v40
	v_add_f32_e32 v41, 1.0, v41
	v_rcp_f32_e32 v54, v54
	v_rcp_f32_e32 v56, v56
	v_rcp_f32_e32 v37, v37
	v_rcp_f32_e32 v38, v38
	v_rcp_f32_e32 v39, v39
	v_rcp_f32_e32 v40, v40
	v_rcp_f32_e32 v41, v41
	v_cvt_pk_bf16_f32 v91, v54, v42
	v_cvt_pk_bf16_f32 v86, v56, v37
	v_cvt_pk_bf16_f32 v85, v38, v39
	v_cvt_pk_bf16_f32 v84, v40, v41
	v_add_u32_e32 v37, 0x24980, v160
	v_add_u32_e32 v42, 0x24d80, v160
	ds_read_b128 v[38:41], v37
	ds_read_b128 v[42:45], v42
	ds_read_b32 v37, v164
	ds_read_b32 v46, v165
	ds_read_b32 v47, v166
	ds_read_b32 v48, v167
	s_waitcnt lgkmcnt(3)
	v_fma_f32 v16, -v38, v37, v16
	v_fma_f32 v17, -v39, v37, v17
	v_fma_f32 v18, -v40, v37, v18
	v_fma_f32 v19, -v41, v37, v19
	s_waitcnt lgkmcnt(1)
	v_fma_f32 v0, -v38, v47, v0
	v_fma_f32 v1, -v39, v47, v1
	v_fma_f32 v2, -v40, v47, v2
	v_fma_f32 v3, -v41, v47, v3
	v_fma_f32 v16, v46, v16, v42
	v_fma_f32 v17, v46, v17, v43
	v_fma_f32 v18, v46, v18, v44
	v_fma_f32 v19, v46, v19, v45
	s_waitcnt lgkmcnt(0)
	v_fma_f32 v0, v48, v0, v42
	v_fma_f32 v1, v48, v1, v43
	v_fma_f32 v2, v48, v2, v44
	v_fmac_f32_e32 v45, v48, v3
	v_mul_f32_e32 v16, 0xbfb8aa3b, v16
	v_mul_f32_e32 v17, 0xbfb8aa3b, v17
	v_mul_f32_e32 v18, 0xbfb8aa3b, v18
	v_mul_f32_e32 v19, 0xbfb8aa3b, v19
	v_mul_f32_e32 v0, 0xbfb8aa3b, v0
	v_mul_f32_e32 v1, 0xbfb8aa3b, v1
	v_mul_f32_e32 v2, 0xbfb8aa3b, v2
	v_mul_f32_e32 v3, 0xbfb8aa3b, v45
	v_exp_f32_e32 v16, v16
	v_exp_f32_e32 v17, v17
	v_exp_f32_e32 v18, v18
	v_exp_f32_e32 v19, v19
	v_exp_f32_e32 v0, v0
	v_exp_f32_e32 v1, v1
	v_exp_f32_e32 v2, v2
	v_exp_f32_e32 v3, v3
	v_add_f32_e32 v16, 1.0, v16
	v_add_f32_e32 v17, 1.0, v17
	v_add_f32_e32 v18, 1.0, v18
	v_add_f32_e32 v19, 1.0, v19
	v_add_f32_e32 v0, 1.0, v0
	v_add_f32_e32 v1, 1.0, v1
	v_add_f32_e32 v2, 1.0, v2
	v_add_f32_e32 v3, 1.0, v3
	v_rcp_f32_e32 v16, v16
	v_rcp_f32_e32 v17, v17
	v_rcp_f32_e32 v18, v18
	v_rcp_f32_e32 v19, v19
	v_rcp_f32_e32 v0, v0
	v_rcp_f32_e32 v1, v1
	v_rcp_f32_e32 v2, v2
	v_rcp_f32_e32 v37, v3
	v_cvt_pk_bf16_f32 v17, v16, v17
	v_cvt_pk_bf16_f32 v16, v18, v19
	v_cvt_pk_bf16_f32 v3, v0, v1
	v_cvt_pk_bf16_f32 v2, v2, v37
	v_add_u32_e32 v0, 0x249a0, v160
	v_add_u32_e32 v1, 0x24da0, v160
	ds_read_b128 v[38:41], v0
	ds_read_b128 v[42:45], v1
	ds_read_b32 v0, v164
	ds_read_b32 v1, v165
	ds_read_b32 v18, v166
	ds_read_b32 v19, v167
	s_waitcnt lgkmcnt(3)
	v_fma_f32 v21, -v39, v0, v21
	v_fma_f32 v20, -v38, v0, v20
	s_waitcnt lgkmcnt(1)
	v_fma_f32 v6, -v40, v18, v6
	v_fma_f32 v21, v1, v21, v43
	v_fma_f32 v22, -v40, v0, v22
	v_fma_f32 v0, -v41, v0, v23
	v_fma_f32 v4, -v38, v18, v4
	v_fma_f32 v5, -v39, v18, v5
	s_waitcnt lgkmcnt(0)
	v_fma_f32 v6, v19, v6, v44
	v_fma_f32 v7, -v41, v18, v7
	v_fma_f32 v20, v1, v20, v42
	v_mul_f32_e32 v21, 0xbfb8aa3b, v21
	v_fma_f32 v22, v1, v22, v44
	v_fma_f32 v0, v1, v0, v45
	v_fma_f32 v4, v19, v4, v42
	v_fma_f32 v5, v19, v5, v43
	v_mul_f32_e32 v6, 0xbfb8aa3b, v6
	v_fmac_f32_e32 v45, v19, v7
	v_mul_f32_e32 v20, 0xbfb8aa3b, v20
	v_exp_f32_e32 v21, v21
	v_mul_f32_e32 v22, 0xbfb8aa3b, v22
	v_mul_f32_e32 v0, 0xbfb8aa3b, v0
	v_mul_f32_e32 v4, 0xbfb8aa3b, v4
	v_mul_f32_e32 v5, 0xbfb8aa3b, v5
	v_exp_f32_e32 v6, v6
	v_mul_f32_e32 v7, 0xbfb8aa3b, v45
	v_exp_f32_e32 v20, v20
	v_exp_f32_e32 v22, v22
	v_exp_f32_e32 v0, v0
	v_exp_f32_e32 v4, v4
	v_exp_f32_e32 v5, v5
	v_exp_f32_e32 v7, v7
	v_add_f32_e32 v21, 1.0, v21
	v_add_f32_e32 v6, 1.0, v6
	v_add_f32_e32 v20, 1.0, v20
	v_rcp_f32_e32 v1, v21
	v_add_f32_e32 v21, 1.0, v22
	v_add_f32_e32 v0, 1.0, v0
	v_add_f32_e32 v4, 1.0, v4
	v_add_f32_e32 v5, 1.0, v5
	v_rcp_f32_e32 v18, v6
	v_add_f32_e32 v6, 1.0, v7
	v_rcp_f32_e32 v20, v20
	v_rcp_f32_e32 v21, v21
	v_rcp_f32_e32 v0, v0
	v_rcp_f32_e32 v4, v4
	v_rcp_f32_e32 v5, v5
	v_rcp_f32_e32 v19, v6
	v_cvt_pk_bf16_f32 v7, v20, v1
	v_cvt_pk_bf16_f32 v6, v21, v0
	v_cvt_pk_bf16_f32 v5, v4, v5
	v_cvt_pk_bf16_f32 v4, v18, v19
	v_add_u32_e32 v0, 0x249c0, v160
	v_add_u32_e32 v1, 0x24dc0, v160
	ds_read_b128 v[18:21], v0
	ds_read_b128 v[38:41], v1
	ds_read_b32 v0, v164
	ds_read_b32 v1, v165
	ds_read_b32 v22, v166
	ds_read_b32 v23, v167
	s_waitcnt lgkmcnt(3)
	v_fma_f32 v25, -v19, v0, v25
	v_fma_f32 v24, -v18, v0, v24
	s_waitcnt lgkmcnt(1)
	v_fma_f32 v9, -v19, v22, v9
	s_waitcnt lgkmcnt(0)
; DI unsigned pack2(float a, float b) { f32x2_t v = {a, b}; bf16x2_t r = __builtin_convertvector(v, bf16x2_t); return __builtin_bit_cast(unsigned, r); }
; DI float sigmoidf_(float x) { return __builtin_amdgcn_rcpf(1.f + __expf(-x)); }
; DI int otid() { int t = threadIdx.x; asm volatile("" : "+v"(t)); return t; }
; template <bool NT>
; DI void stage_load_tile(bf16_t* stg, const bf16_t* tilebase) {
;   const int tid = otid();
;   const int r0 = tid >> 5, c = tid & 31;
;   const unsigned o0 = (unsigned)(r0 * 1024 + c * 8);
;   __builtin_amdgcn_sched_barrier(0);
; #pragma unroll
;   for (int hf = 0; hf < 2; ++hf) {
; #pragma unroll
;     for (int it = 8 * hf; it < 8 * hf + 8; ++it) {
;       const u32x4* gp = (const u32x4*)(tilebase + (o0 + (unsigned)(it * 16 * 1024)));
;       stage_write16(stg, r0 + 16 * it, c, NT ? __builtin_nontemporal_load(gp) : *gp);
;     }
;     __builtin_amdgcn_sched_barrier(0);
;   }
; template <bool LAST>
; DI void phase_gate(const Params& P, int layer, unsigned char* smem, int L, int G) {
;     ...
;           for (int e = 0; e < 4; ++e) sg4[e] = sigmoidf_(rstd * (accu[i][j][4 * q4 + e] - mu * c1a[e]) + c2a[e]);
;           gq[i][j][2 * q4] = pack2(sg4[0], sg4[1]); gq[i][j][2 * q4 + 1] = pack2(sg4[2], sg4[3]);
;         }
;         __builtin_amdgcn_sched_barrier(0);
;       }
;     stage_load_tile<true>(stg, PPb + (size_t)mt * 256 * 1024 + nt * 256);
	v_fma_f32 v9, v23, v9, v39
	v_fma_f32 v10, -v20, v22, v10
	v_fma_f32 v25, v1, v25, v39
	v_fma_f32 v26, -v20, v0, v26
	v_fma_f32 v0, -v21, v0, v27
	v_fma_f32 v8, -v18, v22, v8
	v_mul_f32_e32 v9, 0xbfb8aa3b, v9
	v_fma_f32 v10, v23, v10, v40
	v_fma_f32 v11, -v21, v22, v11
	v_fma_f32 v24, v1, v24, v38
	v_mul_f32_e32 v25, 0xbfb8aa3b, v25
	v_fma_f32 v26, v1, v26, v40
	v_fma_f32 v0, v1, v0, v41
	v_fma_f32 v8, v23, v8, v38
	v_exp_f32_e32 v9, v9
	v_mul_f32_e32 v10, 0xbfb8aa3b, v10
	v_fmac_f32_e32 v41, v23, v11
	v_mul_f32_e32 v24, 0xbfb8aa3b, v24
	v_exp_f32_e32 v25, v25
	v_mul_f32_e32 v26, 0xbfb8aa3b, v26
	v_mul_f32_e32 v0, 0xbfb8aa3b, v0
	v_mul_f32_e32 v8, 0xbfb8aa3b, v8
	v_exp_f32_e32 v10, v10
	v_mul_f32_e32 v11, 0xbfb8aa3b, v41
	v_exp_f32_e32 v24, v24
	v_exp_f32_e32 v26, v26
	v_exp_f32_e32 v0, v0
	v_exp_f32_e32 v8, v8
	v_exp_f32_e32 v11, v11
	v_add_f32_e32 v9, 1.0, v9
	v_add_f32_e32 v25, 1.0, v25
	v_rcp_f32_e32 v18, v9
	v_add_f32_e32 v9, 1.0, v10
	v_add_f32_e32 v24, 1.0, v24
	v_rcp_f32_e32 v1, v25
	v_add_f32_e32 v25, 1.0, v26
	v_add_f32_e32 v0, 1.0, v0
	v_add_f32_e32 v8, 1.0, v8
	v_rcp_f32_e32 v10, v9
	v_add_f32_e32 v9, 1.0, v11
	v_rcp_f32_e32 v24, v24
	v_rcp_f32_e32 v25, v25
	v_rcp_f32_e32 v0, v0
	v_rcp_f32_e32 v8, v8
	v_rcp_f32_e32 v11, v9
	v_cvt_pk_bf16_f32 v27, v24, v1
	v_cvt_pk_bf16_f32 v9, v25, v0
	v_cvt_pk_bf16_f32 v19, v8, v18
	v_cvt_pk_bf16_f32 v8, v10, v11
	v_add_u32_e32 v0, 0x24de0, v160
	ds_read_b128 v[20:23], v163 offset:480
	ds_read_b32 v1, v164
	ds_read_b128 v[38:41], v0
	ds_read_b32 v0, v165
	ds_read_b32 v10, v166
	ds_read_b32 v18, v167
	s_waitcnt lgkmcnt(4)
	v_fma_f32 v24, -v21, v1, v29
	v_fma_f32 v11, -v20, v1, v28
	s_waitcnt lgkmcnt(2)
	v_fma_f32 v24, v0, v24, v39
	v_fma_f32 v25, -v22, v1, v30
	v_fma_f32 v1, -v23, v1, v31
	s_waitcnt lgkmcnt(1)
	v_fma_f32 v12, -v20, v10, v12
	v_fma_f32 v13, -v21, v10, v13
	v_fma_f32 v14, -v22, v10, v14
	v_fma_f32 v10, -v23, v10, v15
	v_fma_f32 v11, v0, v11, v38
	v_mul_f32_e32 v24, 0xbfb8aa3b, v24
	v_fma_f32 v25, v0, v25, v40
	v_fma_f32 v0, v0, v1, v41
	s_waitcnt lgkmcnt(0)
	v_fma_f32 v12, v18, v12, v38
	v_fma_f32 v13, v18, v13, v39
	v_fma_f32 v14, v18, v14, v40
	v_fmac_f32_e32 v41, v18, v10
	v_mul_f32_e32 v11, 0xbfb8aa3b, v11
	v_exp_f32_e32 v24, v24
	v_mul_f32_e32 v25, 0xbfb8aa3b, v25
	v_mul_f32_e32 v0, 0xbfb8aa3b, v0
	v_mul_f32_e32 v12, 0xbfb8aa3b, v12
	v_mul_f32_e32 v13, 0xbfb8aa3b, v13
	v_mul_f32_e32 v14, 0xbfb8aa3b, v14
	v_mul_f32_e32 v10, 0xbfb8aa3b, v41
	v_exp_f32_e32 v11, v11
	v_exp_f32_e32 v25, v25
	v_exp_f32_e32 v0, v0
	v_exp_f32_e32 v12, v12
	v_exp_f32_e32 v13, v13
	v_exp_f32_e32 v14, v14
	v_exp_f32_e32 v10, v10
	v_add_f32_e32 v24, 1.0, v24
	v_add_f32_e32 v11, 1.0, v11
	v_rcp_f32_e32 v1, v24
	v_add_f32_e32 v24, 1.0, v25
	v_add_f32_e32 v0, 1.0, v0
	v_add_f32_e32 v12, 1.0, v12
	v_add_f32_e32 v13, 1.0, v13
	v_add_f32_e32 v14, 1.0, v14
	v_add_f32_e32 v10, 1.0, v10
	v_rcp_f32_e32 v11, v11
	v_rcp_f32_e32 v24, v24
	v_rcp_f32_e32 v0, v0
	v_rcp_f32_e32 v12, v12
	v_rcp_f32_e32 v13, v13
	v_rcp_f32_e32 v14, v14
	v_rcp_f32_e32 v10, v10
	v_cvt_pk_bf16_f32 v112, v11, v1
	v_cvt_pk_bf16_f32 v30, v24, v0
	v_cvt_pk_bf16_f32 v29, v12, v13
	v_cvt_pk_bf16_f32 v28, v14, v10
	v_mov_b32_e32 v163, v161
	v_lshlrev_b64 v[0:1], 1, v[162:163]
	v_and_b32_e32 v26, 31, v192
	v_ashrrev_i32_e32 v18, 5, v192
	v_mul_lo_u32 v18, v18, s34
	v_lshl_add_u32 v18, v26, 4, v18
	v_add_u32_e32 v24, 0x2080, v18
	v_add_u32_e32 v25, 0x4100, v18
	v_add_u32_e32 v26, 0x6180, v18
	v_add_u32_e32 v31, 0x8200, v18
	v_add_u32_e32 v37, 0xa280, v18
	v_add_u32_e32 v50, 0xc300, v18
	v_add_u32_e32 v51, 0xe380, v18
	s_waitcnt vmcnt(15)
	ds_write2_b64 v18, v[180:181], v[182:183] offset1:1
	s_waitcnt vmcnt(14)
	ds_write2_b64 v24, v[184:185], v[186:187] offset1:1
	s_waitcnt vmcnt(13)
	ds_write2_b64 v25, v[194:195], v[196:197] offset1:1
	s_waitcnt vmcnt(12)
	ds_write2_b64 v26, v[198:199], v[200:201] offset1:1
	s_waitcnt vmcnt(11)
	ds_write2_b64 v31, v[202:203], v[204:205] offset1:1
	s_waitcnt vmcnt(10)
	ds_write2_b64 v37, v[206:207], v[208:209] offset1:1
	s_waitcnt vmcnt(9)
	ds_write2_b64 v50, v[210:211], v[212:213] offset1:1
	s_waitcnt vmcnt(8)
	ds_write2_b64 v51, v[214:215], v[216:217] offset1:1
	v_add_u32_e32 v14, 0x10400, v18
	v_add_u32_e32 v15, 0x12480, v18
	v_add_u32_e32 v24, 0x14500, v18
	v_add_u32_e32 v25, 0x16580, v18
	v_add_u32_e32 v26, 0x18600, v18
	v_add_u32_e32 v31, 0x1a680, v18
	v_add_u32_e32 v37, 0x1c700, v18
	v_add_u32_e32 v18, 0x1e780, v18
	s_waitcnt vmcnt(7)
	ds_write2_b64 v14, v[218:219], v[220:221] offset1:1
	s_waitcnt vmcnt(6)
	ds_write2_b64 v15, v[222:223], v[224:225] offset1:1
	s_waitcnt vmcnt(5)
	ds_write2_b64 v24, v[226:227], v[228:229] offset1:1
	s_waitcnt vmcnt(4)
	ds_write2_b64 v25, v[230:231], v[232:233] offset1:1
	s_waitcnt vmcnt(3)
	ds_write2_b64 v26, v[234:235], v[236:237] offset1:1
	s_waitcnt vmcnt(2)
	ds_write2_b64 v31, v[238:239], v[240:241] offset1:1
	s_waitcnt vmcnt(1)
	ds_write2_b64 v37, v[242:243], v[244:245] offset1:1
	s_waitcnt vmcnt(0)
	ds_write2_b64 v18, v[248:249], v[250:251] offset1:1
	v_mov_b32_e32 v10, v192
	s_waitcnt lgkmcnt(0)
	s_barrier
; DI unsigned pack2(float a, float b) { f32x2_t v = {a, b}; bf16x2_t r = __builtin_convertvector(v, bf16x2_t); return __builtin_bit_cast(unsigned, r); }
; DI float bflo(unsigned u) { return __uint_as_float(u << 16); }
; DI float bfhi(unsigned u) { return __uint_as_float(u & 0xffff0000u); }
; template <bool LAST>
; DI void phase_gate(const Params& P, int layer, unsigned char* smem, int L, int G) {
;     ...
; #pragma unroll
;       for (int i = 0; i < 4; ++i)
; #pragma unroll
;         for (int q4 = 0; q4 < 4; ++q4) {
; #pragma unroll
;           for (int j = 0; j < 2; ++j) {
;             const uint2 pv = *(const uint2*)(stg + (wn1 * 64 + j * 32 + r1) * STG + wm1 * 128 + i * 32 + 8 * q4 + 4 * h1);
;             const unsigned g0 = gq[i][j][2 * q4], g1 = gq[i][j][2 * q4 + 1];
;             gq[i][j][2 * q4] = pack2(bflo(g0) * bflo(pv.x), bfhi(g0) * bfhi(pv.x));
;             gq[i][j][2 * q4 + 1] = pack2(bflo(g1) * bflo(pv.y), bfhi(g1) * bfhi(pv.y));
;           }
;           __builtin_amdgcn_sched_barrier(0);
;         }
	v_and_b32_e32 v13, 0xffff0000, v99
	v_lshrrev_b32_e32 v12, 2, v10
	v_and_b32_e32 v12, 8, v12
	v_and_b32_e32 v11, 0xdf, v10
	v_and_or_b32 v10, v10, s31, v12
	v_mad_u32_u24 v113, v11, s34, v10
	ds_read_b64 v[10:11], v113
	ds_read_b64 v[14:15], v113 offset:16640
	v_lshlrev_b32_e32 v12, 16, v99
	s_waitcnt lgkmcnt(1)
	v_lshlrev_b32_e32 v20, 16, v10
	v_and_b32_e32 v21, 0xffff0000, v10
	v_pk_mul_f32 v[12:13], v[12:13], v[20:21]
	v_lshlrev_b32_e32 v10, 16, v11
	v_cvt_pk_bf16_f32 v31, v12, v13
	v_lshlrev_b32_e32 v12, 16, v98
	v_and_b32_e32 v13, 0xffff0000, v98
	v_and_b32_e32 v11, 0xffff0000, v11
	v_pk_mul_f32 v[10:11], v[12:13], v[10:11]
	s_waitcnt lgkmcnt(0)
	v_lshlrev_b32_e32 v12, 16, v14
	v_cvt_pk_bf16_f32 v98, v10, v11
	v_lshlrev_b32_e32 v10, 16, v97
	v_and_b32_e32 v11, 0xffff0000, v97
	v_and_b32_e32 v13, 0xffff0000, v14
	v_pk_mul_f32 v[10:11], v[10:11], v[12:13]
	v_lshlrev_b32_e32 v12, 16, v15
	v_cvt_pk_bf16_f32 v97, v10, v11
	v_lshlrev_b32_e32 v10, 16, v96
	v_and_b32_e32 v11, 0xffff0000, v96
	v_and_b32_e32 v13, 0xffff0000, v15
	v_pk_mul_f32 v[10:11], v[10:11], v[12:13]
	s_nop 0
	v_cvt_pk_bf16_f32 v96, v10, v11
	ds_read_b64 v[10:11], v113 offset:16
	ds_read_b64 v[14:15], v113 offset:16656
	v_lshlrev_b32_e32 v12, 16, v103
	v_and_b32_e32 v13, 0xffff0000, v103
	s_waitcnt lgkmcnt(1)
	v_lshlrev_b32_e32 v20, 16, v10
	v_and_b32_e32 v21, 0xffff0000, v10
	v_pk_mul_f32 v[12:13], v[12:13], v[20:21]
	v_lshlrev_b32_e32 v10, 16, v11
	v_cvt_pk_bf16_f32 v93, v12, v13
	v_lshlrev_b32_e32 v12, 16, v102
	v_and_b32_e32 v13, 0xffff0000, v102
	v_and_b32_e32 v11, 0xffff0000, v11
	v_pk_mul_f32 v[10:11], v[12:13], v[10:11]
	s_waitcnt lgkmcnt(0)
	v_lshlrev_b32_e32 v12, 16, v14
	v_cvt_pk_bf16_f32 v95, v10, v11
	v_lshlrev_b32_e32 v10, 16, v101
	v_and_b32_e32 v11, 0xffff0000, v101
	v_and_b32_e32 v13, 0xffff0000, v14
	v_pk_mul_f32 v[10:11], v[10:11], v[12:13]
	v_lshlrev_b32_e32 v12, 16, v15
	v_cvt_pk_bf16_f32 v92, v10, v11
	v_lshlrev_b32_e32 v10, 16, v100
	v_and_b32_e32 v11, 0xffff0000, v100
	v_and_b32_e32 v13, 0xffff0000, v15
	v_pk_mul_f32 v[10:11], v[10:11], v[12:13]
	s_nop 0
	v_cvt_pk_bf16_f32 v94, v10, v11
	ds_read_b64 v[10:11], v113 offset:32
	ds_read_b64 v[14:15], v113 offset:16672
	v_lshlrev_b32_e32 v12, 16, v107
	v_and_b32_e32 v13, 0xffff0000, v107
	s_waitcnt lgkmcnt(1)
	v_lshlrev_b32_e32 v20, 16, v10
	v_and_b32_e32 v21, 0xffff0000, v10
	v_pk_mul_f32 v[12:13], v[12:13], v[20:21]
	v_lshlrev_b32_e32 v10, 16, v11
	v_cvt_pk_bf16_f32 v88, v12, v13
	v_lshlrev_b32_e32 v12, 16, v106
	v_and_b32_e32 v13, 0xffff0000, v106
	v_and_b32_e32 v11, 0xffff0000, v11
	v_pk_mul_f32 v[10:11], v[12:13], v[10:11]
	s_waitcnt lgkmcnt(0)
	v_lshlrev_b32_e32 v12, 16, v14
	v_cvt_pk_bf16_f32 v90, v10, v11
	v_lshlrev_b32_e32 v10, 16, v105
	v_and_b32_e32 v11, 0xffff0000, v105
	v_and_b32_e32 v13, 0xffff0000, v14
	v_pk_mul_f32 v[10:11], v[10:11], v[12:13]
	v_lshlrev_b32_e32 v12, 16, v15
	v_cvt_pk_bf16_f32 v87, v10, v11
	v_lshlrev_b32_e32 v10, 16, v104
	v_and_b32_e32 v11, 0xffff0000, v104
	v_and_b32_e32 v13, 0xffff0000, v15
	v_pk_mul_f32 v[10:11], v[10:11], v[12:13]
	s_nop 0
	v_cvt_pk_bf16_f32 v89, v10, v11
	ds_read_b64 v[10:11], v113 offset:48
	ds_read_b64 v[14:15], v113 offset:16688
	v_lshlrev_b32_e32 v12, 16, v111
	v_and_b32_e32 v13, 0xffff0000, v111
	s_waitcnt lgkmcnt(1)
	v_lshlrev_b32_e32 v20, 16, v10
	v_and_b32_e32 v21, 0xffff0000, v10
	v_pk_mul_f32 v[12:13], v[12:13], v[20:21]
	v_lshlrev_b32_e32 v10, 16, v11
	v_cvt_pk_bf16_f32 v61, v12, v13
	v_lshlrev_b32_e32 v12, 16, v110
	v_and_b32_e32 v13, 0xffff0000, v110
	v_and_b32_e32 v11, 0xffff0000, v11
	v_pk_mul_f32 v[10:11], v[12:13], v[10:11]
	s_waitcnt lgkmcnt(0)
	v_lshlrev_b32_e32 v12, 16, v14
	v_cvt_pk_bf16_f32 v63, v10, v11
	v_lshlrev_b32_e32 v10, 16, v109
	v_and_b32_e32 v11, 0xffff0000, v109
	v_and_b32_e32 v13, 0xffff0000, v14
	v_pk_mul_f32 v[10:11], v[10:11], v[12:13]
	v_lshlrev_b32_e32 v12, 16, v15
	v_cvt_pk_bf16_f32 v60, v10, v11
	v_lshlrev_b32_e32 v10, 16, v108
	v_and_b32_e32 v11, 0xffff0000, v108
	v_and_b32_e32 v13, 0xffff0000, v15
	v_pk_mul_f32 v[10:11], v[10:11], v[12:13]
	s_nop 0
	v_cvt_pk_bf16_f32 v62, v10, v11
	ds_read_b64 v[10:11], v113 offset:64
	ds_read_b64 v[14:15], v113 offset:16704
	v_lshlrev_b32_e32 v12, 16, v67
	v_and_b32_e32 v13, 0xffff0000, v67
	s_waitcnt lgkmcnt(1)
	v_lshlrev_b32_e32 v20, 16, v10
	v_and_b32_e32 v21, 0xffff0000, v10
	v_pk_mul_f32 v[12:13], v[12:13], v[20:21]
	v_lshlrev_b32_e32 v10, 16, v11
	v_cvt_pk_bf16_f32 v56, v12, v13
	v_lshlrev_b32_e32 v12, 16, v66
	v_and_b32_e32 v13, 0xffff0000, v66
	v_and_b32_e32 v11, 0xffff0000, v11
	v_pk_mul_f32 v[10:11], v[12:13], v[10:11]
	s_waitcnt lgkmcnt(0)
	v_lshlrev_b32_e32 v12, 16, v14
	v_cvt_pk_bf16_f32 v58, v10, v11
	v_lshlrev_b32_e32 v10, 16, v65
	v_and_b32_e32 v11, 0xffff0000, v65
	v_and_b32_e32 v13, 0xffff0000, v14
	v_pk_mul_f32 v[10:11], v[10:11], v[12:13]
	v_lshlrev_b32_e32 v12, 16, v15
	v_cvt_pk_bf16_f32 v54, v10, v11
	v_lshlrev_b32_e32 v10, 16, v64
	v_and_b32_e32 v11, 0xffff0000, v64
	v_and_b32_e32 v13, 0xffff0000, v15
	v_pk_mul_f32 v[10:11], v[10:11], v[12:13]
	s_nop 0
	v_cvt_pk_bf16_f32 v57, v10, v11
	ds_read_b64 v[10:11], v113 offset:80
	ds_read_b64 v[14:15], v113 offset:16720
	v_lshlrev_b32_e32 v12, 16, v71
	v_and_b32_e32 v13, 0xffff0000, v71
	s_waitcnt lgkmcnt(1)
	v_lshlrev_b32_e32 v20, 16, v10
	v_and_b32_e32 v21, 0xffff0000, v10
	v_pk_mul_f32 v[12:13], v[12:13], v[20:21]
	v_lshlrev_b32_e32 v10, 16, v11
	v_cvt_pk_bf16_f32 v50, v12, v13
	v_lshlrev_b32_e32 v12, 16, v70
	v_and_b32_e32 v13, 0xffff0000, v70
	v_and_b32_e32 v11, 0xffff0000, v11
	v_pk_mul_f32 v[10:11], v[12:13], v[10:11]
	s_waitcnt lgkmcnt(0)
; DI unsigned pack2(float a, float b) { f32x2_t v = {a, b}; bf16x2_t r = __builtin_convertvector(v, bf16x2_t); return __builtin_bit_cast(unsigned, r); }
; DI float bflo(unsigned u) { return __uint_as_float(u << 16); }
; DI float bfhi(unsigned u) { return __uint_as_float(u & 0xffff0000u); }
; template <bool LAST>
; DI void phase_gate(const Params& P, int layer, unsigned char* smem, int L, int G) {
;     ...
; #pragma unroll
;       for (int i = 0; i < 4; ++i)
; #pragma unroll
;         for (int q4 = 0; q4 < 4; ++q4) {
; #pragma unroll
;           for (int j = 0; j < 2; ++j) {
;             const uint2 pv = *(const uint2*)(stg + (wn1 * 64 + j * 32 + r1) * STG + wm1 * 128 + i * 32 + 8 * q4 + 4 * h1);
;             const unsigned g0 = gq[i][j][2 * q4], g1 = gq[i][j][2 * q4 + 1];
;             gq[i][j][2 * q4] = pack2(bflo(g0) * bflo(pv.x), bfhi(g0) * bfhi(pv.x));
;             gq[i][j][2 * q4 + 1] = pack2(bflo(g1) * bflo(pv.y), bfhi(g1) * bfhi(pv.y));
;           }
;           __builtin_amdgcn_sched_barrier(0);
;         }
	v_lshlrev_b32_e32 v12, 16, v14
	v_cvt_pk_bf16_f32 v52, v10, v11
	v_lshlrev_b32_e32 v10, 16, v69
	v_and_b32_e32 v11, 0xffff0000, v69
	v_and_b32_e32 v13, 0xffff0000, v14
	v_pk_mul_f32 v[10:11], v[10:11], v[12:13]
	v_lshlrev_b32_e32 v12, 16, v15
	v_cvt_pk_bf16_f32 v49, v10, v11
	v_lshlrev_b32_e32 v10, 16, v68
	v_and_b32_e32 v11, 0xffff0000, v68
	v_and_b32_e32 v13, 0xffff0000, v15
	v_pk_mul_f32 v[10:11], v[10:11], v[12:13]
	s_nop 0
	v_cvt_pk_bf16_f32 v51, v10, v11
	ds_read_b64 v[10:11], v113 offset:96
	ds_read_b64 v[14:15], v113 offset:16736
	v_lshlrev_b32_e32 v12, 16, v75
	v_and_b32_e32 v13, 0xffff0000, v75
	s_waitcnt lgkmcnt(1)
	v_lshlrev_b32_e32 v20, 16, v10
	v_and_b32_e32 v21, 0xffff0000, v10
	v_pk_mul_f32 v[12:13], v[12:13], v[20:21]
	v_lshlrev_b32_e32 v10, 16, v11
	v_cvt_pk_bf16_f32 v46, v12, v13
	v_lshlrev_b32_e32 v12, 16, v74
	v_and_b32_e32 v13, 0xffff0000, v74
	v_and_b32_e32 v11, 0xffff0000, v11
	v_pk_mul_f32 v[10:11], v[12:13], v[10:11]
	s_waitcnt lgkmcnt(0)
	v_lshlrev_b32_e32 v12, 16, v14
	v_cvt_pk_bf16_f32 v48, v10, v11
	v_lshlrev_b32_e32 v10, 16, v73
	v_and_b32_e32 v11, 0xffff0000, v73
	v_and_b32_e32 v13, 0xffff0000, v14
	v_pk_mul_f32 v[10:11], v[10:11], v[12:13]
	v_lshlrev_b32_e32 v12, 16, v15
	v_cvt_pk_bf16_f32 v45, v10, v11
	v_lshlrev_b32_e32 v10, 16, v72
	v_and_b32_e32 v11, 0xffff0000, v72
	v_and_b32_e32 v13, 0xffff0000, v15
	v_pk_mul_f32 v[10:11], v[10:11], v[12:13]
	s_nop 0
	v_cvt_pk_bf16_f32 v47, v10, v11
	ds_read_b64 v[10:11], v113 offset:112
	ds_read_b64 v[14:15], v113 offset:16752
	v_lshlrev_b32_e32 v12, 16, v79
	v_and_b32_e32 v13, 0xffff0000, v79
	s_waitcnt lgkmcnt(1)
	v_lshlrev_b32_e32 v20, 16, v10
	v_and_b32_e32 v21, 0xffff0000, v10
	v_pk_mul_f32 v[12:13], v[12:13], v[20:21]
	v_lshlrev_b32_e32 v10, 16, v11
	v_cvt_pk_bf16_f32 v42, v12, v13
	v_lshlrev_b32_e32 v12, 16, v78
	v_and_b32_e32 v13, 0xffff0000, v78
	v_and_b32_e32 v11, 0xffff0000, v11
	v_pk_mul_f32 v[10:11], v[12:13], v[10:11]
	s_waitcnt lgkmcnt(0)
	v_lshlrev_b32_e32 v12, 16, v14
	v_cvt_pk_bf16_f32 v44, v10, v11
	v_lshlrev_b32_e32 v10, 16, v77
	v_and_b32_e32 v11, 0xffff0000, v77
	v_and_b32_e32 v13, 0xffff0000, v14
	v_pk_mul_f32 v[10:11], v[10:11], v[12:13]
	v_lshlrev_b32_e32 v12, 16, v15
	v_cvt_pk_bf16_f32 v41, v10, v11
	v_lshlrev_b32_e32 v10, 16, v76
	v_and_b32_e32 v11, 0xffff0000, v76
	v_and_b32_e32 v13, 0xffff0000, v15
	v_pk_mul_f32 v[10:11], v[10:11], v[12:13]
	s_nop 0
	v_cvt_pk_bf16_f32 v43, v10, v11
	ds_read_b64 v[10:11], v113 offset:128
	ds_read_b64 v[14:15], v113 offset:16768
	v_lshlrev_b32_e32 v12, 16, v35
	v_and_b32_e32 v13, 0xffff0000, v35
	s_waitcnt lgkmcnt(1)
	v_lshlrev_b32_e32 v20, 16, v10
	v_and_b32_e32 v21, 0xffff0000, v10
	v_pk_mul_f32 v[12:13], v[12:13], v[20:21]
	v_lshlrev_b32_e32 v10, 16, v11
	v_cvt_pk_bf16_f32 v38, v12, v13
	v_lshlrev_b32_e32 v12, 16, v34
	v_and_b32_e32 v13, 0xffff0000, v34
	v_and_b32_e32 v11, 0xffff0000, v11
	v_pk_mul_f32 v[10:11], v[12:13], v[10:11]
	s_waitcnt lgkmcnt(0)
	v_lshlrev_b32_e32 v12, 16, v14
	v_cvt_pk_bf16_f32 v40, v10, v11
	v_lshlrev_b32_e32 v10, 16, v33
	v_and_b32_e32 v11, 0xffff0000, v33
	v_and_b32_e32 v13, 0xffff0000, v14
	v_pk_mul_f32 v[10:11], v[10:11], v[12:13]
	v_lshlrev_b32_e32 v12, 16, v15
	v_cvt_pk_bf16_f32 v37, v10, v11
	v_lshlrev_b32_e32 v10, 16, v32
	v_and_b32_e32 v11, 0xffff0000, v32
	v_and_b32_e32 v13, 0xffff0000, v15
	v_pk_mul_f32 v[10:11], v[10:11], v[12:13]
	s_nop 0
	v_cvt_pk_bf16_f32 v39, v10, v11
	ds_read_b64 v[10:11], v113 offset:144
	ds_read_b64 v[14:15], v113 offset:16784
	v_lshlrev_b32_e32 v12, 16, v80
	v_and_b32_e32 v13, 0xffff0000, v80
	s_waitcnt lgkmcnt(1)
	v_lshlrev_b32_e32 v20, 16, v10
	v_and_b32_e32 v21, 0xffff0000, v10
	v_pk_mul_f32 v[12:13], v[12:13], v[20:21]
	v_lshlrev_b32_e32 v10, 16, v11
	v_cvt_pk_bf16_f32 v34, v12, v13
	v_lshlrev_b32_e32 v12, 16, v36
	v_and_b32_e32 v13, 0xffff0000, v36
	v_and_b32_e32 v11, 0xffff0000, v11
	v_pk_mul_f32 v[10:11], v[12:13], v[10:11]
	s_waitcnt lgkmcnt(0)
	v_lshlrev_b32_e32 v12, 16, v14
	v_cvt_pk_bf16_f32 v36, v10, v11
	v_lshlrev_b32_e32 v10, 16, v55
	v_and_b32_e32 v11, 0xffff0000, v55
	v_and_b32_e32 v13, 0xffff0000, v14
	v_pk_mul_f32 v[10:11], v[10:11], v[12:13]
	v_lshlrev_b32_e32 v12, 16, v15
	v_cvt_pk_bf16_f32 v32, v10, v11
	v_lshlrev_b32_e32 v10, 16, v53
	v_and_b32_e32 v11, 0xffff0000, v53
	v_and_b32_e32 v13, 0xffff0000, v15
	v_pk_mul_f32 v[10:11], v[10:11], v[12:13]
	s_nop 0
	v_cvt_pk_bf16_f32 v35, v10, v11
	ds_read_b64 v[10:11], v113 offset:160
	ds_read_b64 v[14:15], v113 offset:16800
	v_lshlrev_b32_e32 v12, 16, v83
	v_and_b32_e32 v13, 0xffff0000, v83
	s_waitcnt lgkmcnt(1)
	v_lshlrev_b32_e32 v20, 16, v10
	v_and_b32_e32 v21, 0xffff0000, v10
	v_pk_mul_f32 v[12:13], v[12:13], v[20:21]
	v_lshlrev_b32_e32 v10, 16, v11
	v_cvt_pk_bf16_f32 v24, v12, v13
	v_lshlrev_b32_e32 v12, 16, v82
	v_and_b32_e32 v13, 0xffff0000, v82
	v_and_b32_e32 v11, 0xffff0000, v11
	v_pk_mul_f32 v[10:11], v[12:13], v[10:11]
	s_waitcnt lgkmcnt(0)
	v_lshlrev_b32_e32 v12, 16, v14
	v_cvt_pk_bf16_f32 v26, v10, v11
	v_lshlrev_b32_e32 v10, 16, v81
	v_and_b32_e32 v11, 0xffff0000, v81
	v_and_b32_e32 v13, 0xffff0000, v14
	v_pk_mul_f32 v[10:11], v[10:11], v[12:13]
	v_lshlrev_b32_e32 v12, 16, v15
	v_cvt_pk_bf16_f32 v23, v10, v11
	v_lshlrev_b32_e32 v10, 16, v59
	v_and_b32_e32 v11, 0xffff0000, v59
	v_and_b32_e32 v13, 0xffff0000, v15
	v_pk_mul_f32 v[10:11], v[10:11], v[12:13]
	s_nop 0
	v_cvt_pk_bf16_f32 v25, v10, v11
	ds_read_b64 v[10:11], v113 offset:176
	ds_read_b64 v[14:15], v113 offset:16816
	v_lshlrev_b32_e32 v12, 16, v91
	v_and_b32_e32 v13, 0xffff0000, v91
	s_waitcnt lgkmcnt(1)
; DI unsigned pack2(float a, float b) { f32x2_t v = {a, b}; bf16x2_t r = __builtin_convertvector(v, bf16x2_t); return __builtin_bit_cast(unsigned, r); }
; DI float bflo(unsigned u) { return __uint_as_float(u << 16); }
; DI float bfhi(unsigned u) { return __uint_as_float(u & 0xffff0000u); }
; template <bool LAST>
; DI void phase_gate(const Params& P, int layer, unsigned char* smem, int L, int G) {
;     ...
; #pragma unroll
;       for (int i = 0; i < 4; ++i)
; #pragma unroll
;         for (int q4 = 0; q4 < 4; ++q4) {
; #pragma unroll
;           for (int j = 0; j < 2; ++j) {
;             const uint2 pv = *(const uint2*)(stg + (wn1 * 64 + j * 32 + r1) * STG + wm1 * 128 + i * 32 + 8 * q4 + 4 * h1);
;             const unsigned g0 = gq[i][j][2 * q4], g1 = gq[i][j][2 * q4 + 1];
;             gq[i][j][2 * q4] = pack2(bflo(g0) * bflo(pv.x), bfhi(g0) * bfhi(pv.x));
;             gq[i][j][2 * q4 + 1] = pack2(bflo(g1) * bflo(pv.y), bfhi(g1) * bfhi(pv.y));
;           }
;           __builtin_amdgcn_sched_barrier(0);
;         }
;     }
;     __syncthreads();
	v_lshlrev_b32_e32 v20, 16, v10
	v_and_b32_e32 v21, 0xffff0000, v10
	v_pk_mul_f32 v[12:13], v[12:13], v[20:21]
	v_lshlrev_b32_e32 v10, 16, v11
	v_cvt_pk_bf16_f32 v20, v12, v13
	v_lshlrev_b32_e32 v12, 16, v86
	v_and_b32_e32 v13, 0xffff0000, v86
	v_and_b32_e32 v11, 0xffff0000, v11
	v_pk_mul_f32 v[10:11], v[12:13], v[10:11]
	s_waitcnt lgkmcnt(0)
	v_lshlrev_b32_e32 v12, 16, v14
	v_cvt_pk_bf16_f32 v22, v10, v11
	v_lshlrev_b32_e32 v10, 16, v85
	v_and_b32_e32 v11, 0xffff0000, v85
	v_and_b32_e32 v13, 0xffff0000, v14
	v_pk_mul_f32 v[10:11], v[10:11], v[12:13]
	v_lshlrev_b32_e32 v12, 16, v15
	v_cvt_pk_bf16_f32 v18, v10, v11
	v_lshlrev_b32_e32 v10, 16, v84
	v_and_b32_e32 v11, 0xffff0000, v84
	v_and_b32_e32 v13, 0xffff0000, v15
	v_pk_mul_f32 v[10:11], v[10:11], v[12:13]
	s_nop 0
	v_cvt_pk_bf16_f32 v21, v10, v11
	ds_read_b64 v[10:11], v113 offset:192
	ds_read_b64 v[64:65], v113 offset:16832
	v_lshlrev_b32_e32 v12, 16, v17
	v_and_b32_e32 v13, 0xffff0000, v17
	s_waitcnt lgkmcnt(1)
	v_lshlrev_b32_e32 v14, 16, v10
	v_and_b32_e32 v15, 0xffff0000, v10
	v_pk_mul_f32 v[12:13], v[12:13], v[14:15]
	v_lshlrev_b32_e32 v10, 16, v11
	v_cvt_pk_bf16_f32 v15, v12, v13
	v_lshlrev_b32_e32 v12, 16, v16
	v_and_b32_e32 v13, 0xffff0000, v16
	v_and_b32_e32 v11, 0xffff0000, v11
	v_pk_mul_f32 v[10:11], v[12:13], v[10:11]
	s_waitcnt lgkmcnt(0)
	v_lshlrev_b32_e32 v12, 16, v64
	v_cvt_pk_bf16_f32 v17, v10, v11
	v_lshlrev_b32_e32 v10, 16, v3
	v_and_b32_e32 v11, 0xffff0000, v3
	v_and_b32_e32 v13, 0xffff0000, v64
	v_pk_mul_f32 v[10:11], v[10:11], v[12:13]
	v_lshlrev_b32_e32 v12, 16, v65
	v_cvt_pk_bf16_f32 v14, v10, v11
	v_lshlrev_b32_e32 v10, 16, v2
	v_and_b32_e32 v11, 0xffff0000, v2
	v_and_b32_e32 v13, 0xffff0000, v65
	v_pk_mul_f32 v[2:3], v[10:11], v[12:13]
	s_nop 0
	v_cvt_pk_bf16_f32 v16, v2, v3
	ds_read_b64 v[2:3], v113 offset:208
	ds_read_b64 v[64:65], v113 offset:16848
	v_lshlrev_b32_e32 v10, 16, v7
	v_and_b32_e32 v11, 0xffff0000, v7
	s_waitcnt lgkmcnt(1)
	v_lshlrev_b32_e32 v12, 16, v2
	v_and_b32_e32 v13, 0xffff0000, v2
	v_pk_mul_f32 v[10:11], v[10:11], v[12:13]
	v_lshlrev_b32_e32 v12, 16, v6
	v_lshlrev_b32_e32 v2, 16, v3
	v_and_b32_e32 v13, 0xffff0000, v6
	v_and_b32_e32 v3, 0xffff0000, v3
	v_pk_mul_f32 v[2:3], v[12:13], v[2:3]
	s_waitcnt lgkmcnt(0)
	v_lshlrev_b32_e32 v6, 16, v64
	v_cvt_pk_bf16_f32 v13, v2, v3
	v_lshlrev_b32_e32 v2, 16, v5
	v_and_b32_e32 v3, 0xffff0000, v5
	v_and_b32_e32 v7, 0xffff0000, v64
	v_pk_mul_f32 v[2:3], v[2:3], v[6:7]
	v_cvt_pk_bf16_f32 v11, v10, v11
	v_cvt_pk_bf16_f32 v10, v2, v3
	v_lshlrev_b32_e32 v2, 16, v4
	v_lshlrev_b32_e32 v6, 16, v65
	v_and_b32_e32 v3, 0xffff0000, v4
	v_and_b32_e32 v7, 0xffff0000, v65
	v_pk_mul_f32 v[2:3], v[2:3], v[6:7]
	s_nop 0
	v_cvt_pk_bf16_f32 v12, v2, v3
	ds_read_b64 v[2:3], v113 offset:224
	ds_read_b64 v[64:65], v113 offset:16864
	v_lshlrev_b32_e32 v4, 16, v27
	v_and_b32_e32 v5, 0xffff0000, v27
	s_waitcnt lgkmcnt(1)
	v_lshlrev_b32_e32 v6, 16, v2
	v_and_b32_e32 v7, 0xffff0000, v2
	v_pk_mul_f32 v[4:5], v[4:5], v[6:7]
	v_lshlrev_b32_e32 v2, 16, v3
	v_cvt_pk_bf16_f32 v7, v4, v5
	v_lshlrev_b32_e32 v4, 16, v9
	v_and_b32_e32 v5, 0xffff0000, v9
	v_and_b32_e32 v3, 0xffff0000, v3
	v_pk_mul_f32 v[2:3], v[4:5], v[2:3]
	s_waitcnt lgkmcnt(0)
	v_lshlrev_b32_e32 v4, 16, v64
	v_cvt_pk_bf16_f32 v9, v2, v3
	v_lshlrev_b32_e32 v2, 16, v19
	v_and_b32_e32 v3, 0xffff0000, v19
	v_and_b32_e32 v5, 0xffff0000, v64
	v_pk_mul_f32 v[2:3], v[2:3], v[4:5]
	v_lshlrev_b32_e32 v4, 16, v65
	v_cvt_pk_bf16_f32 v6, v2, v3
	v_lshlrev_b32_e32 v2, 16, v8
	v_and_b32_e32 v3, 0xffff0000, v8
	v_and_b32_e32 v5, 0xffff0000, v65
	v_pk_mul_f32 v[2:3], v[2:3], v[4:5]
	s_nop 0
	v_cvt_pk_bf16_f32 v8, v2, v3
	ds_read_b64 v[2:3], v113 offset:240
	ds_read_b64 v[64:65], v113 offset:16880
	v_lshlrev_b32_e32 v4, 16, v112
	v_and_b32_e32 v5, 0xffff0000, v112
	s_waitcnt lgkmcnt(1)
	v_lshlrev_b32_e32 v66, 16, v2
	v_and_b32_e32 v67, 0xffff0000, v2
	v_pk_mul_f32 v[4:5], v[4:5], v[66:67]
	v_lshlrev_b32_e32 v66, 16, v30
	v_lshlrev_b32_e32 v2, 16, v3
	v_and_b32_e32 v67, 0xffff0000, v30
	v_and_b32_e32 v3, 0xffff0000, v3
	v_pk_mul_f32 v[2:3], v[66:67], v[2:3]
	v_cvt_pk_bf16_f32 v4, v4, v5
	v_cvt_pk_bf16_f32 v5, v2, v3
	v_lshlrev_b32_e32 v2, 16, v29
	s_waitcnt lgkmcnt(0)
	v_lshlrev_b32_e32 v66, 16, v64
	v_and_b32_e32 v3, 0xffff0000, v29
	v_and_b32_e32 v67, 0xffff0000, v64
	v_pk_mul_f32 v[2:3], v[2:3], v[66:67]
	v_lshlrev_b32_e32 v66, 16, v28
	v_lshlrev_b32_e32 v64, 16, v65
	v_and_b32_e32 v67, 0xffff0000, v28
	v_and_b32_e32 v65, 0xffff0000, v65
	v_pk_mul_f32 v[28:29], v[66:67], v[64:65]
	v_cvt_pk_bf16_f32 v2, v2, v3
	v_cvt_pk_bf16_f32 v3, v28, v29
	v_mov_b32_e32 v19, v192
	s_barrier
; DI int otid() { int t = threadIdx.x; asm volatile("" : "+v"(t)); return t; }
; template <bool NT>
; DI void stage_load_tile(bf16_t* stg, const bf16_t* tilebase) {
;   const int tid = otid();
;   const int r0 = tid >> 5, c = tid & 31;
;   const unsigned o0 = (unsigned)(r0 * 1024 + c * 8);
;   __builtin_amdgcn_sched_barrier(0);
; #pragma unroll
;   for (int hf = 0; hf < 2; ++hf) {
; #pragma unroll
;     for (int it = 8 * hf; it < 8 * hf + 8; ++it) {
;       const u32x4* gp = (const u32x4*)(tilebase + (o0 + (unsigned)(it * 16 * 1024)));
;       stage_write16(stg, r0 + 16 * it, c, NT ? __builtin_nontemporal_load(gp) : *gp);
;     }
;     __builtin_amdgcn_sched_barrier(0);
;   }
; template <bool LAST>
; DI void phase_gate(const Params& P, int layer, unsigned char* smem, int L, int G) {
;     ...
;     stage_load_tile<false>(stg, Sb + (size_t)mt * 256 * 1024 + nt * 256);
;     __syncthreads();
	s_add_u32 s20, s76, s18
	v_ashrrev_i32_e32 v27, 5, v19
	v_and_b32_e32 v19, 31, v19
	s_addc_u32 s21, s77, s19
	v_lshlrev_b32_e32 v30, 3, v19
	v_lshl_add_u64 v[28:29], s[20:21], 0, v[0:1]
	v_lshl_or_b32 v160, v27, 10, v30
	v_add_u32_e32 v66, 0x4000, v160
	v_mov_b32_e32 v67, v161
	v_add_u32_e32 v72, 0x8000, v160
	v_mov_b32_e32 v73, v161
	v_add_u32_e32 v74, 0xc000, v160
	v_mov_b32_e32 v75, v161
	v_add_u32_e32 v80, 0x10000, v160
	v_mov_b32_e32 v81, v161
	v_add_u32_e32 v82, 0x14000, v160
	v_mov_b32_e32 v83, v161
	v_lshl_add_u64 v[64:65], v[160:161], 1, v[28:29]
	v_lshl_add_u64 v[68:69], v[66:67], 1, v[28:29]
	v_lshl_add_u64 v[72:73], v[72:73], 1, v[28:29]
	v_lshl_add_u64 v[76:77], v[74:75], 1, v[28:29]
	v_lshl_add_u64 v[80:81], v[80:81], 1, v[28:29]
	v_lshl_add_u64 v[84:85], v[82:83], 1, v[28:29]
	global_load_dwordx4 v[64:67], v[64:65], off
	s_nop 0
	global_load_dwordx4 v[68:71], v[68:69], off
	s_nop 0
	global_load_dwordx4 v[72:75], v[72:73], off
	s_nop 0
	global_load_dwordx4 v[76:79], v[76:77], off
	s_nop 0
	global_load_dwordx4 v[80:83], v[80:81], off
	s_nop 0
	global_load_dwordx4 v[100:103], v[84:85], off
	v_add_u32_e32 v84, 0x18000, v160
	v_mov_b32_e32 v85, v161
	v_add_u32_e32 v104, 0x1c000, v160
	v_mov_b32_e32 v105, v161
	v_lshl_add_u64 v[84:85], v[84:85], 1, v[28:29]
	v_lshl_add_u64 v[108:109], v[104:105], 1, v[28:29]
	global_load_dwordx4 v[104:107], v[84:85], off
	s_nop 0
	global_load_dwordx4 v[108:111], v[108:109], off
	v_add_u32_e32 v218, 0x20000, v160
	v_mov_b32_e32 v219, v161
	v_add_u32_e32 v220, 0x24000, v160
	v_mov_b32_e32 v221, v161
	v_add_u32_e32 v226, 0x28000, v160
	v_mov_b32_e32 v227, v161
	v_add_u32_e32 v228, 0x2c000, v160
	v_mov_b32_e32 v229, v161
	v_add_u32_e32 v234, 0x30000, v160
	v_mov_b32_e32 v235, v161
	v_add_u32_e32 v236, 0x34000, v160
	v_mov_b32_e32 v237, v161
	v_lshl_add_u64 v[218:219], v[218:219], 1, v[28:29]
	v_lshl_add_u64 v[222:223], v[220:221], 1, v[28:29]
	v_lshl_add_u64 v[226:227], v[226:227], 1, v[28:29]
	v_lshl_add_u64 v[230:231], v[228:229], 1, v[28:29]
	v_lshl_add_u64 v[234:235], v[234:235], 1, v[28:29]
	v_lshl_add_u64 v[252:253], v[236:237], 1, v[28:29]
	global_load_dwordx4 v[218:221], v[218:219], off
	s_nop 0
	global_load_dwordx4 v[222:225], v[222:223], off
	s_nop 0
	global_load_dwordx4 v[226:229], v[226:227], off
	s_nop 0
	global_load_dwordx4 v[230:233], v[230:231], off
	s_nop 0
	global_load_dwordx4 v[234:237], v[234:235], off
	s_nop 0
	global_load_dwordx4 v[238:241], v[252:253], off
	v_add_u32_e32 v252, 0x38000, v160
	v_mov_b32_e32 v253, v161
	v_lshl_add_u64 v[252:253], v[252:253], 1, v[28:29]
	v_add_u32_e32 v160, 0x3c000, v160
	v_lshl_add_u64 v[190:191], v[160:161], 1, v[28:29]
	global_load_dwordx4 v[242:245], v[252:253], off
	global_load_dwordx4 v[248:251], v[190:191], off
	v_mul_lo_u32 v27, v27, s34
	v_lshl_add_u32 v19, v19, 4, v27
	v_add_u32_e32 v27, 0x2080, v19
	v_add_u32_e32 v30, 0x4100, v19
	v_add_u32_e32 v33, 0x6180, v19
	v_add_u32_e32 v53, 0x8200, v19
	v_add_u32_e32 v55, 0xa280, v19
	v_add_u32_e32 v59, 0xc300, v19
	v_add_u32_e32 v84, 0xe380, v19
	s_waitcnt vmcnt(15)
	ds_write2_b64 v19, v[64:65], v[66:67] offset1:1
	s_waitcnt vmcnt(14)
	ds_write2_b64 v27, v[68:69], v[70:71] offset1:1
	s_waitcnt vmcnt(13)
	ds_write2_b64 v30, v[72:73], v[74:75] offset1:1
	s_waitcnt vmcnt(12)
	ds_write2_b64 v33, v[76:77], v[78:79] offset1:1
	s_waitcnt vmcnt(11)
	ds_write2_b64 v53, v[80:81], v[82:83] offset1:1
	s_waitcnt vmcnt(10)
	ds_write2_b64 v55, v[100:101], v[102:103] offset1:1
	s_waitcnt vmcnt(9)
	ds_write2_b64 v59, v[104:105], v[106:107] offset1:1
	s_waitcnt vmcnt(8)
	ds_write2_b64 v84, v[108:109], v[110:111] offset1:1
	v_add_u32_e32 v27, 0x10400, v19
	v_add_u32_e32 v28, 0x12480, v19
	v_add_u32_e32 v29, 0x14500, v19
	v_add_u32_e32 v30, 0x16580, v19
	v_add_u32_e32 v33, 0x18600, v19
	v_add_u32_e32 v53, 0x1a680, v19
	v_add_u32_e32 v55, 0x1c700, v19
	v_add_u32_e32 v19, 0x1e780, v19
	s_waitcnt vmcnt(7)
	ds_write2_b64 v27, v[218:219], v[220:221] offset1:1
	s_waitcnt vmcnt(6)
	ds_write2_b64 v28, v[222:223], v[224:225] offset1:1
	s_waitcnt vmcnt(5)
	ds_write2_b64 v29, v[226:227], v[228:229] offset1:1
	s_waitcnt vmcnt(4)
	ds_write2_b64 v30, v[230:231], v[232:233] offset1:1
	s_waitcnt vmcnt(3)
	ds_write2_b64 v33, v[234:235], v[236:237] offset1:1
	s_waitcnt vmcnt(2)
	ds_write2_b64 v53, v[238:239], v[240:241] offset1:1
	s_waitcnt vmcnt(1)
	ds_write2_b64 v55, v[242:243], v[244:245] offset1:1
	s_waitcnt vmcnt(0)
	ds_write2_b64 v19, v[248:249], v[250:251] offset1:1
	v_mov_b32_e32 v19, v192
	s_waitcnt lgkmcnt(0)
	s_barrier
; DI unsigned pack2(float a, float b) { f32x2_t v = {a, b}; bf16x2_t r = __builtin_convertvector(v, bf16x2_t); return __builtin_bit_cast(unsigned, r); }
; DI float bflo(unsigned u) { return __uint_as_float(u << 16); }
; DI float bfhi(unsigned u) { return __uint_as_float(u & 0xffff0000u); }
; template <bool LAST>
; DI void phase_gate(const Params& P, int layer, unsigned char* smem, int L, int G) {
;     ...
; #pragma unroll
;     for (int i = 0; i < 4; ++i)
; #pragma unroll
;       for (int q4 = 0; q4 < 4; ++q4) {
;         const int fl = wm2 * 128 + i * 32 + 8 * q4 + 4 * h2;
;         const int f0 = nt * 256 + fl;
;         const f32x4 gv = *(const f32x4*)(vecL + 512 + fl), bv = *(const f32x4*)(vecL + 768 + fl);
;         const float ga[4] = {gv.x, gv.y, gv.z, gv.w}, ba[4] = {bv.x, bv.y, bv.z, bv.w};
; #pragma unroll
;         for (int j = 0; j < 2; ++j) {
;           const int lrow = wn2 * 64 + j * 32 + r2;
;           const float mu = rowA[lrow], rstd = rowB[lrow];
;           uint2* sp = (uint2*)(stg + lrow * STG + fl);
;           const uint2 sv = *sp;
;           const float sa[4] = {bflo(sv.x), bfhi(sv.x), bflo(sv.y), bfhi(sv.y)};
;           float y[4];
;           const float gg[4] = {bflo(gq[i][j][2 * q4]), bfhi(gq[i][j][2 * q4]), bflo(gq[i][j][2 * q4 + 1]), bfhi(gq[i][j][2 * q4 + 1])};
; #pragma unroll
;           for (int e = 0; e < 4; ++e) y[e] = (sa[e] - mu) * rstd * ga[e] + ba[e] + gg[e];
;           if (LAST) { f32x4 o = {y[0], y[1], y[2], y[3]}; *(f32x4*)(P.out + (size_t)(mt * 256 + lrow) * 1024 + f0) = o; }
;           else { uint2 pk; pk.x = pack2(y[0], y[1]); pk.y = pack2(y[2], y[3]); *sp = pk; }
;         }
;         __builtin_amdgcn_sched_barrier(0);
;       }
	v_lshlrev_b32_e32 v82, 16, v31
	v_lshrrev_b32_e32 v28, 3, v19
	v_ashrrev_i32_e32 v27, 1, v19
	v_and_b32_e32 v28, 4, v28
	v_and_or_b32 v30, v27, s35, v28
	v_and_b32_e32 v19, 0xdf, v19
	v_lshlrev_b32_e32 v27, 2, v30
	v_lshlrev_b32_e32 v33, 2, v19
	v_mul_u32_u24_e32 v19, 0x208, v19
	v_add_u32_e32 v28, 0x25000, v27
	v_lshl_add_u32 v19, v30, 1, v19
	v_add_u32_e32 v29, 0x25400, v27
	ds_read_b128 v[64:67], v28
	ds_read_b128 v[68:71], v29
	ds_read_b64 v[72:73], v19
	v_or_b32_e32 v29, 0x24000, v33
	v_or_b32_e32 v30, 0x24400, v33
	ds_read_b32 v74, v29
	ds_read_b32 v76, v30
	ds_read_b64 v[78:79], v19 offset:16640
	v_and_b32_e32 v83, 0xffff0000, v31
	s_waitcnt lgkmcnt(3)
	v_lshlrev_b32_e32 v80, 16, v72
	v_and_b32_e32 v81, 0xffff0000, v72
	v_lshlrev_b32_e32 v72, 16, v73
	v_and_b32_e32 v73, 0xffff0000, v73
	s_waitcnt lgkmcnt(2)
	v_pk_add_f32 v[80:81], v[80:81], v[74:75] op_sel_hi:[1,0] neg_lo:[0,1] neg_hi:[0,1]
	v_pk_add_f32 v[72:73], v[72:73], v[74:75] op_sel_hi:[1,0] neg_lo:[0,1] neg_hi:[0,1]
	s_waitcnt lgkmcnt(1)
	v_pk_mul_f32 v[80:81], v[76:77], v[80:81] op_sel_hi:[0,1]
	v_pk_mul_f32 v[72:73], v[76:77], v[72:73] op_sel_hi:[0,1]
	v_lshlrev_b32_e32 v84, 16, v98
	v_and_b32_e32 v85, 0xffff0000, v98
	v_pk_fma_f32 v[80:81], v[64:65], v[80:81], v[68:69]
	v_pk_fma_f32 v[72:73], v[66:67], v[72:73], v[70:71]
	v_pk_add_f32 v[80:81], v[80:81], v[82:83]
	v_pk_add_f32 v[72:73], v[72:73], v[84:85]
	v_cvt_pk_bf16_f32 v74, v80, v81
	v_cvt_pk_bf16_f32 v75, v72, v73
	ds_write_b64 v19, v[74:75]
	v_or_b32_e32 v31, 0x24080, v33
	v_or_b32_e32 v33, 0x24480, v33
	ds_read_b32 v72, v31
	ds_read_b32 v74, v33
	s_waitcnt lgkmcnt(3)
	v_lshlrev_b32_e32 v76, 16, v78
	v_and_b32_e32 v77, 0xffff0000, v78
	v_lshlrev_b32_e32 v78, 16, v79
	s_waitcnt lgkmcnt(1)
	v_pk_add_f32 v[76:77], v[76:77], v[72:73] op_sel_hi:[1,0] neg_lo:[0,1] neg_hi:[0,1]
	v_and_b32_e32 v79, 0xffff0000, v79
	s_waitcnt lgkmcnt(0)
	v_pk_mul_f32 v[76:77], v[74:75], v[76:77] op_sel_hi:[0,1]
	v_pk_fma_f32 v[64:65], v[64:65], v[76:77], v[68:69]
	v_pk_add_f32 v[68:69], v[78:79], v[72:73] op_sel_hi:[1,0] neg_lo:[0,1] neg_hi:[0,1]
	v_lshlrev_b32_e32 v80, 16, v97
	v_pk_mul_f32 v[68:69], v[74:75], v[68:69] op_sel_hi:[0,1]
	v_and_b32_e32 v81, 0xffff0000, v97
	v_lshlrev_b32_e32 v82, 16, v96
	v_and_b32_e32 v83, 0xffff0000, v96
	v_pk_fma_f32 v[66:67], v[66:67], v[68:69], v[70:71]
	v_pk_add_f32 v[64:65], v[64:65], v[80:81]
	v_pk_add_f32 v[66:67], v[66:67], v[82:83]
	v_cvt_pk_bf16_f32 v64, v64, v65
	v_cvt_pk_bf16_f32 v65, v66, v67
	ds_write_b64 v19, v[64:65] offset:16640
	v_add_u32_e32 v53, 0x25020, v27
	v_add_u32_e32 v55, 0x25420, v27
	ds_read_b64 v[72:73], v19 offset:16
	ds_read_b128 v[64:67], v53
	ds_read_b128 v[68:71], v55
	ds_read_b32 v74, v29
	ds_read_b32 v76, v30
	ds_read_b64 v[78:79], v19 offset:16656
	s_waitcnt lgkmcnt(5)
	v_lshlrev_b32_e32 v80, 16, v72
	v_and_b32_e32 v81, 0xffff0000, v72
	v_lshlrev_b32_e32 v72, 16, v73
	v_and_b32_e32 v73, 0xffff0000, v73
	s_waitcnt lgkmcnt(2)
	v_pk_add_f32 v[80:81], v[80:81], v[74:75] op_sel_hi:[1,0] neg_lo:[0,1] neg_hi:[0,1]
	v_pk_add_f32 v[72:73], v[72:73], v[74:75] op_sel_hi:[1,0] neg_lo:[0,1] neg_hi:[0,1]
	s_waitcnt lgkmcnt(1)
	v_pk_mul_f32 v[80:81], v[76:77], v[80:81] op_sel_hi:[0,1]
	v_pk_mul_f32 v[72:73], v[76:77], v[72:73] op_sel_hi:[0,1]
	v_lshlrev_b32_e32 v82, 16, v93
	v_and_b32_e32 v83, 0xffff0000, v93
	v_lshlrev_b32_e32 v84, 16, v95
	v_and_b32_e32 v85, 0xffff0000, v95
	v_pk_fma_f32 v[80:81], v[64:65], v[80:81], v[68:69]
	v_pk_fma_f32 v[72:73], v[66:67], v[72:73], v[70:71]
	v_pk_add_f32 v[80:81], v[80:81], v[82:83]
	v_pk_add_f32 v[72:73], v[72:73], v[84:85]
	v_cvt_pk_bf16_f32 v74, v80, v81
	v_cvt_pk_bf16_f32 v75, v72, v73
	ds_write_b64 v19, v[74:75] offset:16
	ds_read_b32 v72, v31
	ds_read_b32 v74, v33
	s_waitcnt lgkmcnt(3)
	v_lshlrev_b32_e32 v76, 16, v78
	v_and_b32_e32 v77, 0xffff0000, v78
	v_lshlrev_b32_e32 v78, 16, v79
	s_waitcnt lgkmcnt(1)
	v_pk_add_f32 v[76:77], v[76:77], v[72:73] op_sel_hi:[1,0] neg_lo:[0,1] neg_hi:[0,1]
	v_and_b32_e32 v79, 0xffff0000, v79
	s_waitcnt lgkmcnt(0)
	v_pk_mul_f32 v[76:77], v[74:75], v[76:77] op_sel_hi:[0,1]
	v_pk_fma_f32 v[64:65], v[64:65], v[76:77], v[68:69]
	v_pk_add_f32 v[68:69], v[78:79], v[72:73] op_sel_hi:[1,0] neg_lo:[0,1] neg_hi:[0,1]
	v_lshlrev_b32_e32 v80, 16, v92
	v_pk_mul_f32 v[68:69], v[74:75], v[68:69] op_sel_hi:[0,1]
	v_and_b32_e32 v81, 0xffff0000, v92
	v_lshlrev_b32_e32 v82, 16, v94
	v_and_b32_e32 v83, 0xffff0000, v94
	v_pk_fma_f32 v[66:67], v[66:67], v[68:69], v[70:71]
	v_pk_add_f32 v[64:65], v[64:65], v[80:81]
	v_pk_add_f32 v[66:67], v[66:67], v[82:83]
	v_cvt_pk_bf16_f32 v64, v64, v65
	v_cvt_pk_bf16_f32 v65, v66, v67
	ds_write_b64 v19, v[64:65] offset:16656
	v_add_u32_e32 v53, 0x25040, v27
	v_add_u32_e32 v55, 0x25440, v27
	ds_read_b64 v[72:73], v19 offset:32
	ds_read_b128 v[64:67], v53
	ds_read_b128 v[68:71], v55
	ds_read_b32 v74, v29
	ds_read_b32 v76, v30
	ds_read_b64 v[78:79], v19 offset:16672
	s_waitcnt lgkmcnt(5)
	v_lshlrev_b32_e32 v80, 16, v72
	v_and_b32_e32 v81, 0xffff0000, v72
	v_lshlrev_b32_e32 v72, 16, v73
	v_and_b32_e32 v73, 0xffff0000, v73
	s_waitcnt lgkmcnt(2)
	v_pk_add_f32 v[80:81], v[80:81], v[74:75] op_sel_hi:[1,0] neg_lo:[0,1] neg_hi:[0,1]
	v_pk_add_f32 v[72:73], v[72:73], v[74:75] op_sel_hi:[1,0] neg_lo:[0,1] neg_hi:[0,1]
	s_waitcnt lgkmcnt(1)
	v_pk_mul_f32 v[80:81], v[76:77], v[80:81] op_sel_hi:[0,1]
	v_pk_mul_f32 v[72:73], v[76:77], v[72:73] op_sel_hi:[0,1]
	v_lshlrev_b32_e32 v82, 16, v88
	v_and_b32_e32 v83, 0xffff0000, v88
	v_lshlrev_b32_e32 v84, 16, v90
	v_and_b32_e32 v85, 0xffff0000, v90
	v_pk_fma_f32 v[80:81], v[64:65], v[80:81], v[68:69]
	v_pk_fma_f32 v[72:73], v[66:67], v[72:73], v[70:71]
	v_pk_add_f32 v[80:81], v[80:81], v[82:83]
	v_pk_add_f32 v[72:73], v[72:73], v[84:85]
	v_cvt_pk_bf16_f32 v74, v80, v81
	v_cvt_pk_bf16_f32 v75, v72, v73
	ds_write_b64 v19, v[74:75] offset:32
	ds_read_b32 v72, v31
	ds_read_b32 v74, v33
	s_waitcnt lgkmcnt(3)
; DI unsigned pack2(float a, float b) { f32x2_t v = {a, b}; bf16x2_t r = __builtin_convertvector(v, bf16x2_t); return __builtin_bit_cast(unsigned, r); }
; DI float bflo(unsigned u) { return __uint_as_float(u << 16); }
; DI float bfhi(unsigned u) { return __uint_as_float(u & 0xffff0000u); }
; template <bool LAST>
; DI void phase_gate(const Params& P, int layer, unsigned char* smem, int L, int G) {
;     ...
; #pragma unroll
;     for (int i = 0; i < 4; ++i)
; #pragma unroll
;       for (int q4 = 0; q4 < 4; ++q4) {
;         const int fl = wm2 * 128 + i * 32 + 8 * q4 + 4 * h2;
;         const int f0 = nt * 256 + fl;
;         const f32x4 gv = *(const f32x4*)(vecL + 512 + fl), bv = *(const f32x4*)(vecL + 768 + fl);
;         const float ga[4] = {gv.x, gv.y, gv.z, gv.w}, ba[4] = {bv.x, bv.y, bv.z, bv.w};
; #pragma unroll
;         for (int j = 0; j < 2; ++j) {
;           const int lrow = wn2 * 64 + j * 32 + r2;
;           const float mu = rowA[lrow], rstd = rowB[lrow];
;           uint2* sp = (uint2*)(stg + lrow * STG + fl);
;           const uint2 sv = *sp;
;           const float sa[4] = {bflo(sv.x), bfhi(sv.x), bflo(sv.y), bfhi(sv.y)};
;           float y[4];
;           const float gg[4] = {bflo(gq[i][j][2 * q4]), bfhi(gq[i][j][2 * q4]), bflo(gq[i][j][2 * q4 + 1]), bfhi(gq[i][j][2 * q4 + 1])};
; #pragma unroll
;           for (int e = 0; e < 4; ++e) y[e] = (sa[e] - mu) * rstd * ga[e] + ba[e] + gg[e];
;           if (LAST) { f32x4 o = {y[0], y[1], y[2], y[3]}; *(f32x4*)(P.out + (size_t)(mt * 256 + lrow) * 1024 + f0) = o; }
;           else { uint2 pk; pk.x = pack2(y[0], y[1]); pk.y = pack2(y[2], y[3]); *sp = pk; }
;         }
;         __builtin_amdgcn_sched_barrier(0);
;       }
	v_lshlrev_b32_e32 v76, 16, v78
	v_and_b32_e32 v77, 0xffff0000, v78
	v_lshlrev_b32_e32 v78, 16, v79
	s_waitcnt lgkmcnt(1)
	v_pk_add_f32 v[76:77], v[76:77], v[72:73] op_sel_hi:[1,0] neg_lo:[0,1] neg_hi:[0,1]
	v_and_b32_e32 v79, 0xffff0000, v79
	s_waitcnt lgkmcnt(0)
	v_pk_mul_f32 v[76:77], v[74:75], v[76:77] op_sel_hi:[0,1]
	v_pk_fma_f32 v[64:65], v[64:65], v[76:77], v[68:69]
	v_pk_add_f32 v[68:69], v[78:79], v[72:73] op_sel_hi:[1,0] neg_lo:[0,1] neg_hi:[0,1]
	v_lshlrev_b32_e32 v80, 16, v87
	v_pk_mul_f32 v[68:69], v[74:75], v[68:69] op_sel_hi:[0,1]
	v_and_b32_e32 v81, 0xffff0000, v87
	v_lshlrev_b32_e32 v82, 16, v89
	v_and_b32_e32 v83, 0xffff0000, v89
	v_pk_fma_f32 v[66:67], v[66:67], v[68:69], v[70:71]
	v_pk_add_f32 v[64:65], v[64:65], v[80:81]
	v_pk_add_f32 v[66:67], v[66:67], v[82:83]
	v_cvt_pk_bf16_f32 v64, v64, v65
	v_cvt_pk_bf16_f32 v65, v66, v67
	ds_write_b64 v19, v[64:65] offset:16672
	v_add_u32_e32 v53, 0x25060, v27
	v_add_u32_e32 v55, 0x25460, v27
	ds_read_b64 v[72:73], v19 offset:48
	ds_read_b128 v[64:67], v53
	ds_read_b128 v[68:71], v55
	ds_read_b32 v74, v29
	ds_read_b32 v76, v30
	ds_read_b64 v[78:79], v19 offset:16688
	s_waitcnt lgkmcnt(5)
	v_lshlrev_b32_e32 v80, 16, v72
	v_and_b32_e32 v81, 0xffff0000, v72
	v_lshlrev_b32_e32 v72, 16, v73
	v_and_b32_e32 v73, 0xffff0000, v73
	s_waitcnt lgkmcnt(2)
	v_pk_add_f32 v[80:81], v[80:81], v[74:75] op_sel_hi:[1,0] neg_lo:[0,1] neg_hi:[0,1]
	v_pk_add_f32 v[72:73], v[72:73], v[74:75] op_sel_hi:[1,0] neg_lo:[0,1] neg_hi:[0,1]
	s_waitcnt lgkmcnt(1)
	v_pk_mul_f32 v[80:81], v[76:77], v[80:81] op_sel_hi:[0,1]
	v_pk_mul_f32 v[72:73], v[76:77], v[72:73] op_sel_hi:[0,1]
	v_lshlrev_b32_e32 v82, 16, v61
	v_and_b32_e32 v83, 0xffff0000, v61
	v_lshlrev_b32_e32 v84, 16, v63
	v_and_b32_e32 v85, 0xffff0000, v63
	v_pk_fma_f32 v[80:81], v[64:65], v[80:81], v[68:69]
	v_pk_fma_f32 v[72:73], v[66:67], v[72:73], v[70:71]
	v_pk_add_f32 v[80:81], v[80:81], v[82:83]
	v_pk_add_f32 v[72:73], v[72:73], v[84:85]
	v_cvt_pk_bf16_f32 v74, v80, v81
	v_cvt_pk_bf16_f32 v75, v72, v73
	ds_write_b64 v19, v[74:75] offset:48
	ds_read_b32 v72, v31
	ds_read_b32 v74, v33
	s_waitcnt lgkmcnt(3)
	v_lshlrev_b32_e32 v76, 16, v78
	v_and_b32_e32 v77, 0xffff0000, v78
	v_lshlrev_b32_e32 v80, 16, v60
	v_and_b32_e32 v81, 0xffff0000, v60
	v_lshlrev_b32_e32 v60, 16, v62
	v_and_b32_e32 v61, 0xffff0000, v62
	s_waitcnt lgkmcnt(1)
	v_pk_add_f32 v[62:63], v[76:77], v[72:73] op_sel_hi:[1,0] neg_lo:[0,1] neg_hi:[0,1]
	v_lshlrev_b32_e32 v78, 16, v79
	v_and_b32_e32 v79, 0xffff0000, v79
	s_waitcnt lgkmcnt(0)
	v_pk_mul_f32 v[62:63], v[74:75], v[62:63] op_sel_hi:[0,1]
	v_pk_fma_f32 v[62:63], v[64:65], v[62:63], v[68:69]
	v_pk_add_f32 v[64:65], v[78:79], v[72:73] op_sel_hi:[1,0] neg_lo:[0,1] neg_hi:[0,1]
	v_pk_add_f32 v[62:63], v[62:63], v[80:81]
	v_pk_mul_f32 v[64:65], v[74:75], v[64:65] op_sel_hi:[0,1]
	v_pk_fma_f32 v[64:65], v[66:67], v[64:65], v[70:71]
	v_cvt_pk_bf16_f32 v62, v62, v63
	v_pk_add_f32 v[60:61], v[64:65], v[60:61]
	s_nop 0
	v_cvt_pk_bf16_f32 v63, v60, v61
	ds_write_b64 v19, v[62:63] offset:16688
	v_add_u32_e32 v53, 0x25080, v27
	v_add_u32_e32 v55, 0x25480, v27
	ds_read_b64 v[68:69], v19 offset:64
	ds_read_b128 v[60:63], v53
	ds_read_b128 v[64:67], v55
	ds_read_b32 v70, v29
	ds_read_b32 v72, v30
	ds_read_b64 v[74:75], v19 offset:16704
	s_waitcnt lgkmcnt(5)
	v_lshlrev_b32_e32 v76, 16, v68
	v_and_b32_e32 v77, 0xffff0000, v68
	v_lshlrev_b32_e32 v68, 16, v69
	v_and_b32_e32 v69, 0xffff0000, v69
	v_lshlrev_b32_e32 v80, 16, v58
	v_and_b32_e32 v81, 0xffff0000, v58
	s_waitcnt lgkmcnt(2)
	v_pk_add_f32 v[58:59], v[76:77], v[70:71] op_sel_hi:[1,0] neg_lo:[0,1] neg_hi:[0,1]
	v_pk_add_f32 v[68:69], v[68:69], v[70:71] op_sel_hi:[1,0] neg_lo:[0,1] neg_hi:[0,1]
	s_waitcnt lgkmcnt(1)
	v_pk_mul_f32 v[58:59], v[72:73], v[58:59] op_sel_hi:[0,1]
	v_pk_mul_f32 v[68:69], v[72:73], v[68:69] op_sel_hi:[0,1]
	v_lshlrev_b32_e32 v78, 16, v56
	v_and_b32_e32 v79, 0xffff0000, v56
	v_pk_fma_f32 v[58:59], v[60:61], v[58:59], v[64:65]
	v_pk_fma_f32 v[68:69], v[62:63], v[68:69], v[66:67]
	v_pk_add_f32 v[58:59], v[58:59], v[78:79]
	v_pk_add_f32 v[68:69], v[68:69], v[80:81]
	v_cvt_pk_bf16_f32 v58, v58, v59
	v_cvt_pk_bf16_f32 v59, v68, v69
	ds_write_b64 v19, v[58:59] offset:64
	ds_read_b32 v56, v31
	ds_read_b32 v58, v33
	s_waitcnt lgkmcnt(3)
	v_lshlrev_b32_e32 v68, 16, v74
	v_and_b32_e32 v69, 0xffff0000, v74
	v_lshlrev_b32_e32 v70, 16, v75
	v_and_b32_e32 v71, 0xffff0000, v75
	v_lshlrev_b32_e32 v72, 16, v54
	v_and_b32_e32 v73, 0xffff0000, v54
	v_lshlrev_b32_e32 v54, 16, v57
	v_and_b32_e32 v55, 0xffff0000, v57
	s_waitcnt lgkmcnt(1)
	v_pk_add_f32 v[68:69], v[68:69], v[56:57] op_sel_hi:[1,0] neg_lo:[0,1] neg_hi:[0,1]
	v_pk_add_f32 v[56:57], v[70:71], v[56:57] op_sel_hi:[1,0] neg_lo:[0,1] neg_hi:[0,1]
	s_waitcnt lgkmcnt(0)
	v_pk_mul_f32 v[68:69], v[58:59], v[68:69] op_sel_hi:[0,1]
	v_pk_mul_f32 v[56:57], v[58:59], v[56:57] op_sel_hi:[0,1]
	v_pk_fma_f32 v[60:61], v[60:61], v[68:69], v[64:65]
	v_pk_fma_f32 v[56:57], v[62:63], v[56:57], v[66:67]
	v_pk_add_f32 v[60:61], v[60:61], v[72:73]
	v_pk_add_f32 v[54:55], v[56:57], v[54:55]
	v_cvt_pk_bf16_f32 v56, v60, v61
	v_cvt_pk_bf16_f32 v57, v54, v55
	ds_write_b64 v19, v[56:57] offset:16704
	v_add_u32_e32 v58, 0x254a0, v27
	v_add_u32_e32 v53, 0x250a0, v27
	ds_read_b64 v[62:63], v19 offset:80
	ds_read_b128 v[54:57], v53
	ds_read_b128 v[58:61], v58
	ds_read_b32 v64, v29
	ds_read_b32 v66, v30
	ds_read_b64 v[68:69], v19 offset:16720
	s_waitcnt lgkmcnt(5)
	v_lshlrev_b32_e32 v70, 16, v62
	v_and_b32_e32 v71, 0xffff0000, v62
	v_lshlrev_b32_e32 v62, 16, v63
	v_and_b32_e32 v63, 0xffff0000, v63
	v_lshlrev_b32_e32 v74, 16, v52
	v_and_b32_e32 v75, 0xffff0000, v52
	s_waitcnt lgkmcnt(2)
; DI unsigned pack2(float a, float b) { f32x2_t v = {a, b}; bf16x2_t r = __builtin_convertvector(v, bf16x2_t); return __builtin_bit_cast(unsigned, r); }
; DI float bflo(unsigned u) { return __uint_as_float(u << 16); }
; DI float bfhi(unsigned u) { return __uint_as_float(u & 0xffff0000u); }
; template <bool LAST>
; DI void phase_gate(const Params& P, int layer, unsigned char* smem, int L, int G) {
;     ...
; #pragma unroll
;     for (int i = 0; i < 4; ++i)
; #pragma unroll
;       for (int q4 = 0; q4 < 4; ++q4) {
;         const int fl = wm2 * 128 + i * 32 + 8 * q4 + 4 * h2;
;         const int f0 = nt * 256 + fl;
;         const f32x4 gv = *(const f32x4*)(vecL + 512 + fl), bv = *(const f32x4*)(vecL + 768 + fl);
;         const float ga[4] = {gv.x, gv.y, gv.z, gv.w}, ba[4] = {bv.x, bv.y, bv.z, bv.w};
; #pragma unroll
;         for (int j = 0; j < 2; ++j) {
;           const int lrow = wn2 * 64 + j * 32 + r2;
;           const float mu = rowA[lrow], rstd = rowB[lrow];
;           uint2* sp = (uint2*)(stg + lrow * STG + fl);
;           const uint2 sv = *sp;
;           const float sa[4] = {bflo(sv.x), bfhi(sv.x), bflo(sv.y), bfhi(sv.y)};
;           float y[4];
;           const float gg[4] = {bflo(gq[i][j][2 * q4]), bfhi(gq[i][j][2 * q4]), bflo(gq[i][j][2 * q4 + 1]), bfhi(gq[i][j][2 * q4 + 1])};
; #pragma unroll
;           for (int e = 0; e < 4; ++e) y[e] = (sa[e] - mu) * rstd * ga[e] + ba[e] + gg[e];
;           if (LAST) { f32x4 o = {y[0], y[1], y[2], y[3]}; *(f32x4*)(P.out + (size_t)(mt * 256 + lrow) * 1024 + f0) = o; }
;           else { uint2 pk; pk.x = pack2(y[0], y[1]); pk.y = pack2(y[2], y[3]); *sp = pk; }
;         }
;         __builtin_amdgcn_sched_barrier(0);
;       }
	v_pk_add_f32 v[52:53], v[70:71], v[64:65] op_sel_hi:[1,0] neg_lo:[0,1] neg_hi:[0,1]
	v_pk_add_f32 v[62:63], v[62:63], v[64:65] op_sel_hi:[1,0] neg_lo:[0,1] neg_hi:[0,1]
	s_waitcnt lgkmcnt(1)
	v_pk_mul_f32 v[52:53], v[66:67], v[52:53] op_sel_hi:[0,1]
	v_pk_mul_f32 v[62:63], v[66:67], v[62:63] op_sel_hi:[0,1]
	v_lshlrev_b32_e32 v72, 16, v50
	v_and_b32_e32 v73, 0xffff0000, v50
	v_pk_fma_f32 v[52:53], v[54:55], v[52:53], v[58:59]
	v_pk_fma_f32 v[62:63], v[56:57], v[62:63], v[60:61]
	v_pk_add_f32 v[52:53], v[52:53], v[72:73]
	v_pk_add_f32 v[62:63], v[62:63], v[74:75]
	v_cvt_pk_bf16_f32 v52, v52, v53
	v_cvt_pk_bf16_f32 v53, v62, v63
	ds_write_b64 v19, v[52:53] offset:80
	ds_read_b32 v50, v31
	ds_read_b32 v52, v33
	s_waitcnt lgkmcnt(3)
	v_lshlrev_b32_e32 v62, 16, v68
	v_and_b32_e32 v63, 0xffff0000, v68
	v_lshlrev_b32_e32 v64, 16, v69
	v_and_b32_e32 v65, 0xffff0000, v69
	v_lshlrev_b32_e32 v68, 16, v51
	v_and_b32_e32 v69, 0xffff0000, v51
	s_waitcnt lgkmcnt(1)
	v_pk_add_f32 v[62:63], v[62:63], v[50:51] op_sel_hi:[1,0] neg_lo:[0,1] neg_hi:[0,1]
	v_pk_add_f32 v[50:51], v[64:65], v[50:51] op_sel_hi:[1,0] neg_lo:[0,1] neg_hi:[0,1]
	s_waitcnt lgkmcnt(0)
	v_pk_mul_f32 v[62:63], v[52:53], v[62:63] op_sel_hi:[0,1]
	v_pk_mul_f32 v[50:51], v[52:53], v[50:51] op_sel_hi:[0,1]
	v_lshlrev_b32_e32 v66, 16, v49
	v_and_b32_e32 v67, 0xffff0000, v49
	v_pk_fma_f32 v[54:55], v[54:55], v[62:63], v[58:59]
	v_pk_fma_f32 v[50:51], v[56:57], v[50:51], v[60:61]
	v_pk_add_f32 v[54:55], v[54:55], v[66:67]
	v_pk_add_f32 v[50:51], v[50:51], v[68:69]
	v_cvt_pk_bf16_f32 v52, v54, v55
	v_cvt_pk_bf16_f32 v53, v50, v51
	ds_write_b64 v19, v[52:53] offset:16720
	v_add_u32_e32 v54, 0x254c0, v27
	v_add_u32_e32 v49, 0x250c0, v27
	ds_read_b64 v[58:59], v19 offset:96
	ds_read_b128 v[50:53], v49
	ds_read_b128 v[54:57], v54
	ds_read_b32 v60, v29
	ds_read_b32 v62, v30
	ds_read_b64 v[64:65], v19 offset:16736
	s_waitcnt lgkmcnt(5)
	v_lshlrev_b32_e32 v66, 16, v58
	v_and_b32_e32 v67, 0xffff0000, v58
	v_lshlrev_b32_e32 v58, 16, v59
	v_and_b32_e32 v59, 0xffff0000, v59
	v_lshlrev_b32_e32 v70, 16, v48
	v_and_b32_e32 v71, 0xffff0000, v48
	s_waitcnt lgkmcnt(2)
	v_pk_add_f32 v[48:49], v[66:67], v[60:61] op_sel_hi:[1,0] neg_lo:[0,1] neg_hi:[0,1]
	v_pk_add_f32 v[58:59], v[58:59], v[60:61] op_sel_hi:[1,0] neg_lo:[0,1] neg_hi:[0,1]
	s_waitcnt lgkmcnt(1)
	v_pk_mul_f32 v[48:49], v[62:63], v[48:49] op_sel_hi:[0,1]
	v_pk_mul_f32 v[58:59], v[62:63], v[58:59] op_sel_hi:[0,1]
	v_lshlrev_b32_e32 v68, 16, v46
	v_and_b32_e32 v69, 0xffff0000, v46
	v_pk_fma_f32 v[48:49], v[50:51], v[48:49], v[54:55]
	v_pk_fma_f32 v[58:59], v[52:53], v[58:59], v[56:57]
	v_pk_add_f32 v[48:49], v[48:49], v[68:69]
	v_pk_add_f32 v[58:59], v[58:59], v[70:71]
	v_cvt_pk_bf16_f32 v48, v48, v49
	v_cvt_pk_bf16_f32 v49, v58, v59
	ds_write_b64 v19, v[48:49] offset:96
	ds_read_b32 v46, v31
	ds_read_b32 v48, v33
	s_waitcnt lgkmcnt(3)
	v_lshlrev_b32_e32 v58, 16, v64
	v_and_b32_e32 v59, 0xffff0000, v64
	v_lshlrev_b32_e32 v60, 16, v65
	v_and_b32_e32 v61, 0xffff0000, v65
	v_lshlrev_b32_e32 v64, 16, v47
	v_and_b32_e32 v65, 0xffff0000, v47
	s_waitcnt lgkmcnt(1)
	v_pk_add_f32 v[58:59], v[58:59], v[46:47] op_sel_hi:[1,0] neg_lo:[0,1] neg_hi:[0,1]
	v_pk_add_f32 v[46:47], v[60:61], v[46:47] op_sel_hi:[1,0] neg_lo:[0,1] neg_hi:[0,1]
	s_waitcnt lgkmcnt(0)
	v_pk_mul_f32 v[58:59], v[48:49], v[58:59] op_sel_hi:[0,1]
	v_pk_mul_f32 v[46:47], v[48:49], v[46:47] op_sel_hi:[0,1]
	v_lshlrev_b32_e32 v62, 16, v45
	v_and_b32_e32 v63, 0xffff0000, v45
	v_pk_fma_f32 v[50:51], v[50:51], v[58:59], v[54:55]
	v_pk_fma_f32 v[46:47], v[52:53], v[46:47], v[56:57]
	v_pk_add_f32 v[50:51], v[50:51], v[62:63]
	v_pk_add_f32 v[46:47], v[46:47], v[64:65]
	v_cvt_pk_bf16_f32 v48, v50, v51
	v_cvt_pk_bf16_f32 v49, v46, v47
	ds_write_b64 v19, v[48:49] offset:16736
	v_add_u32_e32 v50, 0x254e0, v27
	v_add_u32_e32 v45, 0x250e0, v27
	ds_read_b64 v[54:55], v19 offset:112
	ds_read_b128 v[46:49], v45
	ds_read_b128 v[50:53], v50
	ds_read_b32 v56, v29
	ds_read_b32 v58, v30
	ds_read_b64 v[60:61], v19 offset:16752
	s_waitcnt lgkmcnt(5)
	v_lshlrev_b32_e32 v62, 16, v54
	v_and_b32_e32 v63, 0xffff0000, v54
	v_lshlrev_b32_e32 v54, 16, v55
	v_and_b32_e32 v55, 0xffff0000, v55
	v_lshlrev_b32_e32 v66, 16, v44
	v_and_b32_e32 v67, 0xffff0000, v44
	s_waitcnt lgkmcnt(2)
	v_pk_add_f32 v[44:45], v[62:63], v[56:57] op_sel_hi:[1,0] neg_lo:[0,1] neg_hi:[0,1]
	v_pk_add_f32 v[54:55], v[54:55], v[56:57] op_sel_hi:[1,0] neg_lo:[0,1] neg_hi:[0,1]
	s_waitcnt lgkmcnt(1)
	v_pk_mul_f32 v[44:45], v[58:59], v[44:45] op_sel_hi:[0,1]
	v_pk_mul_f32 v[54:55], v[58:59], v[54:55] op_sel_hi:[0,1]
	v_lshlrev_b32_e32 v64, 16, v42
	v_and_b32_e32 v65, 0xffff0000, v42
	v_pk_fma_f32 v[44:45], v[46:47], v[44:45], v[50:51]
	v_pk_fma_f32 v[54:55], v[48:49], v[54:55], v[52:53]
	v_pk_add_f32 v[44:45], v[44:45], v[64:65]
	v_pk_add_f32 v[54:55], v[54:55], v[66:67]
	v_cvt_pk_bf16_f32 v44, v44, v45
	v_cvt_pk_bf16_f32 v45, v54, v55
	ds_write_b64 v19, v[44:45] offset:112
	ds_read_b32 v42, v31
	ds_read_b32 v44, v33
	s_waitcnt lgkmcnt(3)
	v_lshlrev_b32_e32 v54, 16, v60
	v_and_b32_e32 v55, 0xffff0000, v60
	v_lshlrev_b32_e32 v56, 16, v61
	v_and_b32_e32 v57, 0xffff0000, v61
	v_lshlrev_b32_e32 v60, 16, v43
	v_and_b32_e32 v61, 0xffff0000, v43
	s_waitcnt lgkmcnt(1)
	v_pk_add_f32 v[54:55], v[54:55], v[42:43] op_sel_hi:[1,0] neg_lo:[0,1] neg_hi:[0,1]
	v_pk_add_f32 v[42:43], v[56:57], v[42:43] op_sel_hi:[1,0] neg_lo:[0,1] neg_hi:[0,1]
	s_waitcnt lgkmcnt(0)
; DI unsigned pack2(float a, float b) { f32x2_t v = {a, b}; bf16x2_t r = __builtin_convertvector(v, bf16x2_t); return __builtin_bit_cast(unsigned, r); }
; DI float bflo(unsigned u) { return __uint_as_float(u << 16); }
; DI float bfhi(unsigned u) { return __uint_as_float(u & 0xffff0000u); }
; template <bool LAST>
; DI void phase_gate(const Params& P, int layer, unsigned char* smem, int L, int G) {
;     ...
; #pragma unroll
;     for (int i = 0; i < 4; ++i)
; #pragma unroll
;       for (int q4 = 0; q4 < 4; ++q4) {
;         const int fl = wm2 * 128 + i * 32 + 8 * q4 + 4 * h2;
;         const int f0 = nt * 256 + fl;
;         const f32x4 gv = *(const f32x4*)(vecL + 512 + fl), bv = *(const f32x4*)(vecL + 768 + fl);
;         const float ga[4] = {gv.x, gv.y, gv.z, gv.w}, ba[4] = {bv.x, bv.y, bv.z, bv.w};
; #pragma unroll
;         for (int j = 0; j < 2; ++j) {
;           const int lrow = wn2 * 64 + j * 32 + r2;
;           const float mu = rowA[lrow], rstd = rowB[lrow];
;           uint2* sp = (uint2*)(stg + lrow * STG + fl);
;           const uint2 sv = *sp;
;           const float sa[4] = {bflo(sv.x), bfhi(sv.x), bflo(sv.y), bfhi(sv.y)};
;           float y[4];
;           const float gg[4] = {bflo(gq[i][j][2 * q4]), bfhi(gq[i][j][2 * q4]), bflo(gq[i][j][2 * q4 + 1]), bfhi(gq[i][j][2 * q4 + 1])};
; #pragma unroll
;           for (int e = 0; e < 4; ++e) y[e] = (sa[e] - mu) * rstd * ga[e] + ba[e] + gg[e];
;           if (LAST) { f32x4 o = {y[0], y[1], y[2], y[3]}; *(f32x4*)(P.out + (size_t)(mt * 256 + lrow) * 1024 + f0) = o; }
;           else { uint2 pk; pk.x = pack2(y[0], y[1]); pk.y = pack2(y[2], y[3]); *sp = pk; }
;         }
;         __builtin_amdgcn_sched_barrier(0);
;       }
	v_pk_mul_f32 v[54:55], v[44:45], v[54:55] op_sel_hi:[0,1]
	v_pk_mul_f32 v[42:43], v[44:45], v[42:43] op_sel_hi:[0,1]
	v_lshlrev_b32_e32 v58, 16, v41
	v_and_b32_e32 v59, 0xffff0000, v41
	v_pk_fma_f32 v[46:47], v[46:47], v[54:55], v[50:51]
	v_pk_fma_f32 v[42:43], v[48:49], v[42:43], v[52:53]
	v_pk_add_f32 v[46:47], v[46:47], v[58:59]
	v_pk_add_f32 v[42:43], v[42:43], v[60:61]
	v_cvt_pk_bf16_f32 v44, v46, v47
	v_cvt_pk_bf16_f32 v45, v42, v43
	ds_write_b64 v19, v[44:45] offset:16752
	v_add_u32_e32 v46, 0x25500, v27
	v_add_u32_e32 v41, 0x25100, v27
	ds_read_b64 v[50:51], v19 offset:128
	ds_read_b128 v[42:45], v41
	ds_read_b128 v[46:49], v46
	ds_read_b32 v52, v29
	ds_read_b32 v54, v30
	ds_read_b64 v[56:57], v19 offset:16768
	s_waitcnt lgkmcnt(5)
	v_lshlrev_b32_e32 v58, 16, v50
	v_and_b32_e32 v59, 0xffff0000, v50
	v_lshlrev_b32_e32 v50, 16, v51
	v_and_b32_e32 v51, 0xffff0000, v51
	v_lshlrev_b32_e32 v62, 16, v40
	v_and_b32_e32 v63, 0xffff0000, v40
	s_waitcnt lgkmcnt(2)
	v_pk_add_f32 v[40:41], v[58:59], v[52:53] op_sel_hi:[1,0] neg_lo:[0,1] neg_hi:[0,1]
	v_pk_add_f32 v[50:51], v[50:51], v[52:53] op_sel_hi:[1,0] neg_lo:[0,1] neg_hi:[0,1]
	s_waitcnt lgkmcnt(1)
	v_pk_mul_f32 v[40:41], v[54:55], v[40:41] op_sel_hi:[0,1]
	v_pk_mul_f32 v[50:51], v[54:55], v[50:51] op_sel_hi:[0,1]
	v_lshlrev_b32_e32 v60, 16, v38
	v_and_b32_e32 v61, 0xffff0000, v38
	v_pk_fma_f32 v[40:41], v[42:43], v[40:41], v[46:47]
	v_pk_fma_f32 v[50:51], v[44:45], v[50:51], v[48:49]
	v_pk_add_f32 v[40:41], v[40:41], v[60:61]
	v_pk_add_f32 v[50:51], v[50:51], v[62:63]
	v_cvt_pk_bf16_f32 v40, v40, v41
	v_cvt_pk_bf16_f32 v41, v50, v51
	ds_write_b64 v19, v[40:41] offset:128
	ds_read_b32 v38, v31
	ds_read_b32 v40, v33
	s_waitcnt lgkmcnt(3)
	v_lshlrev_b32_e32 v50, 16, v56
	v_and_b32_e32 v51, 0xffff0000, v56
	v_lshlrev_b32_e32 v52, 16, v57
	v_and_b32_e32 v53, 0xffff0000, v57
	v_lshlrev_b32_e32 v56, 16, v39
	v_and_b32_e32 v57, 0xffff0000, v39
	s_waitcnt lgkmcnt(1)
	v_pk_add_f32 v[50:51], v[50:51], v[38:39] op_sel_hi:[1,0] neg_lo:[0,1] neg_hi:[0,1]
	v_pk_add_f32 v[38:39], v[52:53], v[38:39] op_sel_hi:[1,0] neg_lo:[0,1] neg_hi:[0,1]
	s_waitcnt lgkmcnt(0)
	v_pk_mul_f32 v[50:51], v[40:41], v[50:51] op_sel_hi:[0,1]
	v_pk_mul_f32 v[38:39], v[40:41], v[38:39] op_sel_hi:[0,1]
	v_lshlrev_b32_e32 v54, 16, v37
	v_and_b32_e32 v55, 0xffff0000, v37
	v_pk_fma_f32 v[42:43], v[42:43], v[50:51], v[46:47]
	v_pk_fma_f32 v[38:39], v[44:45], v[38:39], v[48:49]
	v_pk_add_f32 v[42:43], v[42:43], v[54:55]
	v_pk_add_f32 v[38:39], v[38:39], v[56:57]
	v_cvt_pk_bf16_f32 v40, v42, v43
	v_cvt_pk_bf16_f32 v41, v38, v39
	ds_write_b64 v19, v[40:41] offset:16768
	v_add_u32_e32 v42, 0x25520, v27
	v_add_u32_e32 v37, 0x25120, v27
	ds_read_b64 v[46:47], v19 offset:144
	ds_read_b128 v[38:41], v37
	ds_read_b128 v[42:45], v42
	ds_read_b32 v48, v29
	ds_read_b32 v50, v30
	ds_read_b64 v[52:53], v19 offset:16784
	s_waitcnt lgkmcnt(5)
	v_lshlrev_b32_e32 v54, 16, v46
	v_and_b32_e32 v55, 0xffff0000, v46
	v_lshlrev_b32_e32 v46, 16, v47
	v_and_b32_e32 v47, 0xffff0000, v47
	v_lshlrev_b32_e32 v58, 16, v36
	v_and_b32_e32 v59, 0xffff0000, v36
	s_waitcnt lgkmcnt(2)
	v_pk_add_f32 v[36:37], v[54:55], v[48:49] op_sel_hi:[1,0] neg_lo:[0,1] neg_hi:[0,1]
	v_pk_add_f32 v[46:47], v[46:47], v[48:49] op_sel_hi:[1,0] neg_lo:[0,1] neg_hi:[0,1]
	s_waitcnt lgkmcnt(1)
	v_pk_mul_f32 v[36:37], v[50:51], v[36:37] op_sel_hi:[0,1]
	v_pk_mul_f32 v[46:47], v[50:51], v[46:47] op_sel_hi:[0,1]
	v_lshlrev_b32_e32 v56, 16, v34
	v_and_b32_e32 v57, 0xffff0000, v34
	v_pk_fma_f32 v[36:37], v[38:39], v[36:37], v[42:43]
	v_pk_fma_f32 v[46:47], v[40:41], v[46:47], v[44:45]
	v_pk_add_f32 v[36:37], v[36:37], v[56:57]
	v_pk_add_f32 v[46:47], v[46:47], v[58:59]
	v_cvt_pk_bf16_f32 v36, v36, v37
	v_cvt_pk_bf16_f32 v37, v46, v47
	ds_write_b64 v19, v[36:37] offset:144
	ds_read_b32 v34, v31
	ds_read_b32 v36, v33
	s_waitcnt lgkmcnt(3)
	v_lshlrev_b32_e32 v46, 16, v52
	v_and_b32_e32 v47, 0xffff0000, v52
	v_lshlrev_b32_e32 v48, 16, v53
	v_and_b32_e32 v49, 0xffff0000, v53
	v_lshlrev_b32_e32 v52, 16, v35
	v_and_b32_e32 v53, 0xffff0000, v35
	s_waitcnt lgkmcnt(1)
	v_pk_add_f32 v[46:47], v[46:47], v[34:35] op_sel_hi:[1,0] neg_lo:[0,1] neg_hi:[0,1]
	v_pk_add_f32 v[34:35], v[48:49], v[34:35] op_sel_hi:[1,0] neg_lo:[0,1] neg_hi:[0,1]
	s_waitcnt lgkmcnt(0)
	v_pk_mul_f32 v[46:47], v[36:37], v[46:47] op_sel_hi:[0,1]
	v_pk_mul_f32 v[34:35], v[36:37], v[34:35] op_sel_hi:[0,1]
	v_lshlrev_b32_e32 v50, 16, v32
	v_and_b32_e32 v51, 0xffff0000, v32
	v_pk_fma_f32 v[38:39], v[38:39], v[46:47], v[42:43]
	v_pk_fma_f32 v[34:35], v[40:41], v[34:35], v[44:45]
	v_pk_add_f32 v[38:39], v[38:39], v[50:51]
	v_pk_add_f32 v[34:35], v[34:35], v[52:53]
	v_cvt_pk_bf16_f32 v36, v38, v39
	v_cvt_pk_bf16_f32 v37, v34, v35
	ds_write_b64 v19, v[36:37] offset:16784
	v_add_u32_e32 v32, 0x25140, v27
	v_add_u32_e32 v38, 0x25540, v27
	ds_read_b64 v[42:43], v19 offset:160
	ds_read_b128 v[34:37], v32
	ds_read_b128 v[38:41], v38
	ds_read_b32 v32, v29
	ds_read_b32 v44, v30
	ds_read_b64 v[46:47], v19 offset:16800
	s_waitcnt lgkmcnt(5)
	v_lshlrev_b32_e32 v48, 16, v42
	v_and_b32_e32 v49, 0xffff0000, v42
	v_lshlrev_b32_e32 v42, 16, v43
	v_and_b32_e32 v43, 0xffff0000, v43
	s_waitcnt lgkmcnt(2)
	v_pk_add_f32 v[48:49], v[48:49], v[32:33] op_sel_hi:[1,0] neg_lo:[0,1] neg_hi:[0,1]
	v_pk_add_f32 v[42:43], v[42:43], v[32:33] op_sel_hi:[1,0] neg_lo:[0,1] neg_hi:[0,1]
	s_waitcnt lgkmcnt(1)
; DI unsigned pack2(float a, float b) { f32x2_t v = {a, b}; bf16x2_t r = __builtin_convertvector(v, bf16x2_t); return __builtin_bit_cast(unsigned, r); }
; DI float bflo(unsigned u) { return __uint_as_float(u << 16); }
; DI float bfhi(unsigned u) { return __uint_as_float(u & 0xffff0000u); }
; template <bool LAST>
; DI void phase_gate(const Params& P, int layer, unsigned char* smem, int L, int G) {
;     ...
; #pragma unroll
;     for (int i = 0; i < 4; ++i)
; #pragma unroll
;       for (int q4 = 0; q4 < 4; ++q4) {
;         const int fl = wm2 * 128 + i * 32 + 8 * q4 + 4 * h2;
;         const int f0 = nt * 256 + fl;
;         const f32x4 gv = *(const f32x4*)(vecL + 512 + fl), bv = *(const f32x4*)(vecL + 768 + fl);
;         const float ga[4] = {gv.x, gv.y, gv.z, gv.w}, ba[4] = {bv.x, bv.y, bv.z, bv.w};
; #pragma unroll
;         for (int j = 0; j < 2; ++j) {
;           const int lrow = wn2 * 64 + j * 32 + r2;
;           const float mu = rowA[lrow], rstd = rowB[lrow];
;           uint2* sp = (uint2*)(stg + lrow * STG + fl);
;           const uint2 sv = *sp;
;           const float sa[4] = {bflo(sv.x), bfhi(sv.x), bflo(sv.y), bfhi(sv.y)};
;           float y[4];
;           const float gg[4] = {bflo(gq[i][j][2 * q4]), bfhi(gq[i][j][2 * q4]), bflo(gq[i][j][2 * q4 + 1]), bfhi(gq[i][j][2 * q4 + 1])};
; #pragma unroll
;           for (int e = 0; e < 4; ++e) y[e] = (sa[e] - mu) * rstd * ga[e] + ba[e] + gg[e];
;           if (LAST) { f32x4 o = {y[0], y[1], y[2], y[3]}; *(f32x4*)(P.out + (size_t)(mt * 256 + lrow) * 1024 + f0) = o; }
;           else { uint2 pk; pk.x = pack2(y[0], y[1]); pk.y = pack2(y[2], y[3]); *sp = pk; }
;         }
;         __builtin_amdgcn_sched_barrier(0);
;       }
	v_pk_mul_f32 v[48:49], v[44:45], v[48:49] op_sel_hi:[0,1]
	v_pk_mul_f32 v[42:43], v[44:45], v[42:43] op_sel_hi:[0,1]
	v_lshlrev_b32_e32 v50, 16, v24
	v_and_b32_e32 v51, 0xffff0000, v24
	v_lshlrev_b32_e32 v52, 16, v26
	v_and_b32_e32 v53, 0xffff0000, v26
	v_pk_fma_f32 v[48:49], v[34:35], v[48:49], v[38:39]
	v_pk_fma_f32 v[42:43], v[36:37], v[42:43], v[40:41]
	v_pk_add_f32 v[48:49], v[48:49], v[50:51]
	v_pk_add_f32 v[42:43], v[42:43], v[52:53]
	v_cvt_pk_bf16_f32 v44, v48, v49
	v_cvt_pk_bf16_f32 v45, v42, v43
	ds_write_b64 v19, v[44:45] offset:160
	ds_read_b32 v24, v31
	ds_read_b32 v26, v33
	s_waitcnt lgkmcnt(3)
	v_lshlrev_b32_e32 v42, 16, v46
	v_and_b32_e32 v43, 0xffff0000, v46
	v_lshlrev_b32_e32 v44, 16, v47
	v_and_b32_e32 v45, 0xffff0000, v47
	v_lshlrev_b32_e32 v48, 16, v25
	v_and_b32_e32 v49, 0xffff0000, v25
	s_waitcnt lgkmcnt(1)
	v_pk_add_f32 v[42:43], v[42:43], v[24:25] op_sel_hi:[1,0] neg_lo:[0,1] neg_hi:[0,1]
	v_pk_add_f32 v[24:25], v[44:45], v[24:25] op_sel_hi:[1,0] neg_lo:[0,1] neg_hi:[0,1]
	s_waitcnt lgkmcnt(0)
	v_pk_mul_f32 v[42:43], v[26:27], v[42:43] op_sel_hi:[0,1]
	v_pk_mul_f32 v[24:25], v[26:27], v[24:25] op_sel_hi:[0,1]
	v_lshlrev_b32_e32 v46, 16, v23
	v_and_b32_e32 v47, 0xffff0000, v23
	v_pk_fma_f32 v[34:35], v[34:35], v[42:43], v[38:39]
	v_pk_fma_f32 v[24:25], v[36:37], v[24:25], v[40:41]
	v_pk_add_f32 v[34:35], v[34:35], v[46:47]
	v_pk_add_f32 v[24:25], v[24:25], v[48:49]
	v_cvt_pk_bf16_f32 v34, v34, v35
	v_cvt_pk_bf16_f32 v35, v24, v25
	ds_write_b64 v19, v[34:35] offset:16800
	v_add_u32_e32 v26, 0x25560, v27
	v_add_u32_e32 v23, 0x25160, v27
	ds_read_b64 v[24:25], v19 offset:176
	ds_read_b128 v[34:37], v23
	ds_read_b128 v[38:41], v26
	ds_read_b32 v26, v29
	ds_read_b32 v32, v30
	ds_read_b64 v[42:43], v19 offset:16816
	s_waitcnt lgkmcnt(5)
	v_lshlrev_b32_e32 v44, 16, v24
	v_and_b32_e32 v45, 0xffff0000, v24
	v_lshlrev_b32_e32 v24, 16, v25
	v_and_b32_e32 v25, 0xffff0000, v25
	v_lshlrev_b32_e32 v48, 16, v22
	v_and_b32_e32 v49, 0xffff0000, v22
	s_waitcnt lgkmcnt(2)
	v_pk_add_f32 v[22:23], v[44:45], v[26:27] op_sel_hi:[1,0] neg_lo:[0,1] neg_hi:[0,1]
	v_pk_add_f32 v[24:25], v[24:25], v[26:27] op_sel_hi:[1,0] neg_lo:[0,1] neg_hi:[0,1]
	s_waitcnt lgkmcnt(1)
	v_pk_mul_f32 v[22:23], v[32:33], v[22:23] op_sel_hi:[0,1]
	v_pk_mul_f32 v[24:25], v[32:33], v[24:25] op_sel_hi:[0,1]
	v_lshlrev_b32_e32 v46, 16, v20
	v_and_b32_e32 v47, 0xffff0000, v20
	v_pk_fma_f32 v[22:23], v[34:35], v[22:23], v[38:39]
	v_pk_fma_f32 v[24:25], v[36:37], v[24:25], v[40:41]
	v_pk_add_f32 v[22:23], v[22:23], v[46:47]
	v_pk_add_f32 v[24:25], v[24:25], v[48:49]
	v_cvt_pk_bf16_f32 v22, v22, v23
	v_cvt_pk_bf16_f32 v23, v24, v25
	ds_write_b64 v19, v[22:23] offset:176
	ds_read_b32 v20, v31
	ds_read_b32 v22, v33
	s_waitcnt lgkmcnt(3)
	v_lshlrev_b32_e32 v24, 16, v42
	v_and_b32_e32 v25, 0xffff0000, v42
	v_lshlrev_b32_e32 v42, 16, v43
	v_and_b32_e32 v43, 0xffff0000, v43
	v_lshlrev_b32_e32 v46, 16, v21
	v_and_b32_e32 v47, 0xffff0000, v21
	s_waitcnt lgkmcnt(1)
	v_pk_add_f32 v[24:25], v[24:25], v[20:21] op_sel_hi:[1,0] neg_lo:[0,1] neg_hi:[0,1]
	v_pk_add_f32 v[20:21], v[42:43], v[20:21] op_sel_hi:[1,0] neg_lo:[0,1] neg_hi:[0,1]
	s_waitcnt lgkmcnt(0)
	v_pk_mul_f32 v[24:25], v[22:23], v[24:25] op_sel_hi:[0,1]
	v_pk_mul_f32 v[20:21], v[22:23], v[20:21] op_sel_hi:[0,1]
	v_lshlrev_b32_e32 v44, 16, v18
	v_and_b32_e32 v45, 0xffff0000, v18
	v_pk_fma_f32 v[24:25], v[34:35], v[24:25], v[38:39]
	v_pk_fma_f32 v[20:21], v[36:37], v[20:21], v[40:41]
	v_pk_add_f32 v[24:25], v[24:25], v[44:45]
	v_pk_add_f32 v[20:21], v[20:21], v[46:47]
	v_cvt_pk_bf16_f32 v22, v24, v25
	v_cvt_pk_bf16_f32 v23, v20, v21
	ds_write_b64 v19, v[22:23] offset:16816
	v_add_u32_e32 v18, 0x25180, v27
	v_add_u32_e32 v26, 0x25580, v27
	ds_read_b64 v[24:25], v19 offset:192
	ds_read_b128 v[20:23], v18
	ds_read_b128 v[34:37], v26
	ds_read_b32 v18, v29
	ds_read_b32 v26, v30
	ds_read_b64 v[38:39], v19 offset:16832
	s_waitcnt lgkmcnt(5)
	v_lshlrev_b32_e32 v40, 16, v24
	v_and_b32_e32 v41, 0xffff0000, v24
	v_lshlrev_b32_e32 v24, 16, v25
	v_and_b32_e32 v25, 0xffff0000, v25
	s_waitcnt lgkmcnt(2)
	v_pk_add_f32 v[40:41], v[40:41], v[18:19] op_sel_hi:[1,0] neg_lo:[0,1] neg_hi:[0,1]
	v_pk_add_f32 v[24:25], v[24:25], v[18:19] op_sel_hi:[1,0] neg_lo:[0,1] neg_hi:[0,1]
	s_waitcnt lgkmcnt(1)
	v_pk_mul_f32 v[40:41], v[26:27], v[40:41] op_sel_hi:[0,1]
	v_pk_mul_f32 v[24:25], v[26:27], v[24:25] op_sel_hi:[0,1]
	v_lshlrev_b32_e32 v42, 16, v15
	v_and_b32_e32 v43, 0xffff0000, v15
	v_lshlrev_b32_e32 v44, 16, v17
	v_and_b32_e32 v45, 0xffff0000, v17
	v_pk_fma_f32 v[40:41], v[20:21], v[40:41], v[34:35]
	v_pk_fma_f32 v[24:25], v[22:23], v[24:25], v[36:37]
	v_pk_add_f32 v[40:41], v[40:41], v[42:43]
	v_pk_add_f32 v[24:25], v[24:25], v[44:45]
	v_cvt_pk_bf16_f32 v40, v40, v41
	v_cvt_pk_bf16_f32 v41, v24, v25
	ds_write_b64 v19, v[40:41] offset:192
	ds_read_b32 v18, v31
	ds_read_b32 v24, v33
	s_waitcnt lgkmcnt(3)
	v_lshlrev_b32_e32 v40, 16, v38
	v_and_b32_e32 v41, 0xffff0000, v38
	v_lshlrev_b32_e32 v42, 16, v14
	v_and_b32_e32 v43, 0xffff0000, v14
	v_lshlrev_b32_e32 v14, 16, v16
	v_and_b32_e32 v15, 0xffff0000, v16
	s_waitcnt lgkmcnt(1)
	v_pk_add_f32 v[16:17], v[40:41], v[18:19] op_sel_hi:[1,0] neg_lo:[0,1] neg_hi:[0,1]
	v_lshlrev_b32_e32 v38, 16, v39
	v_and_b32_e32 v39, 0xffff0000, v39
	s_waitcnt lgkmcnt(0)
; DI unsigned pack2(float a, float b) { f32x2_t v = {a, b}; bf16x2_t r = __builtin_convertvector(v, bf16x2_t); return __builtin_bit_cast(unsigned, r); }
; DI float bflo(unsigned u) { return __uint_as_float(u << 16); }
; DI float bfhi(unsigned u) { return __uint_as_float(u & 0xffff0000u); }
; template <bool LAST>
; DI void phase_gate(const Params& P, int layer, unsigned char* smem, int L, int G) {
;     ...
; #pragma unroll
;     for (int i = 0; i < 4; ++i)
; #pragma unroll
;       for (int q4 = 0; q4 < 4; ++q4) {
;         const int fl = wm2 * 128 + i * 32 + 8 * q4 + 4 * h2;
;         const int f0 = nt * 256 + fl;
;         const f32x4 gv = *(const f32x4*)(vecL + 512 + fl), bv = *(const f32x4*)(vecL + 768 + fl);
;         const float ga[4] = {gv.x, gv.y, gv.z, gv.w}, ba[4] = {bv.x, bv.y, bv.z, bv.w};
; #pragma unroll
;         for (int j = 0; j < 2; ++j) {
;           const int lrow = wn2 * 64 + j * 32 + r2;
;           const float mu = rowA[lrow], rstd = rowB[lrow];
;           uint2* sp = (uint2*)(stg + lrow * STG + fl);
;           const uint2 sv = *sp;
;           const float sa[4] = {bflo(sv.x), bfhi(sv.x), bflo(sv.y), bfhi(sv.y)};
;           float y[4];
;           const float gg[4] = {bflo(gq[i][j][2 * q4]), bfhi(gq[i][j][2 * q4]), bflo(gq[i][j][2 * q4 + 1]), bfhi(gq[i][j][2 * q4 + 1])};
; #pragma unroll
;           for (int e = 0; e < 4; ++e) y[e] = (sa[e] - mu) * rstd * ga[e] + ba[e] + gg[e];
;           if (LAST) { f32x4 o = {y[0], y[1], y[2], y[3]}; *(f32x4*)(P.out + (size_t)(mt * 256 + lrow) * 1024 + f0) = o; }
;           else { uint2 pk; pk.x = pack2(y[0], y[1]); pk.y = pack2(y[2], y[3]); *sp = pk; }
;         }
;         __builtin_amdgcn_sched_barrier(0);
;       }
;     __syncthreads();
;     if (!LAST) stage_store_tile(stg, xb + (size_t)mt * 256 * 1024 + nt * 256);
	v_pk_mul_f32 v[16:17], v[24:25], v[16:17] op_sel_hi:[0,1]
	v_pk_fma_f32 v[16:17], v[20:21], v[16:17], v[34:35]
	v_pk_add_f32 v[20:21], v[38:39], v[18:19] op_sel_hi:[1,0] neg_lo:[0,1] neg_hi:[0,1]
	v_pk_add_f32 v[16:17], v[16:17], v[42:43]
	v_pk_mul_f32 v[20:21], v[24:25], v[20:21] op_sel_hi:[0,1]
	v_pk_fma_f32 v[20:21], v[22:23], v[20:21], v[36:37]
	v_cvt_pk_bf16_f32 v16, v16, v17
	v_pk_add_f32 v[14:15], v[20:21], v[14:15]
	s_nop 0
	v_cvt_pk_bf16_f32 v17, v14, v15
	ds_write_b64 v19, v[16:17] offset:16832
	v_add_u32_e32 v14, 0x251a0, v27
	v_add_u32_e32 v18, 0x255a0, v27
	ds_read_b64 v[24:25], v19 offset:208
	ds_read_b128 v[14:17], v14
	ds_read_b128 v[20:23], v18
	ds_read_b32 v18, v29
	ds_read_b32 v26, v30
	ds_read_b64 v[34:35], v19 offset:16848
	s_waitcnt lgkmcnt(5)
	v_lshlrev_b32_e32 v36, 16, v24
	v_and_b32_e32 v37, 0xffff0000, v24
	v_lshlrev_b32_e32 v24, 16, v25
	v_and_b32_e32 v25, 0xffff0000, v25
	s_waitcnt lgkmcnt(2)
	v_pk_add_f32 v[36:37], v[36:37], v[18:19] op_sel_hi:[1,0] neg_lo:[0,1] neg_hi:[0,1]
	v_pk_add_f32 v[24:25], v[24:25], v[18:19] op_sel_hi:[1,0] neg_lo:[0,1] neg_hi:[0,1]
	s_waitcnt lgkmcnt(1)
	v_pk_mul_f32 v[36:37], v[26:27], v[36:37] op_sel_hi:[0,1]
	v_pk_mul_f32 v[24:25], v[26:27], v[24:25] op_sel_hi:[0,1]
	v_lshlrev_b32_e32 v38, 16, v11
	v_and_b32_e32 v39, 0xffff0000, v11
	v_lshlrev_b32_e32 v40, 16, v13
	v_and_b32_e32 v41, 0xffff0000, v13
	v_pk_fma_f32 v[36:37], v[14:15], v[36:37], v[20:21]
	v_pk_fma_f32 v[24:25], v[16:17], v[24:25], v[22:23]
	v_pk_add_f32 v[36:37], v[36:37], v[38:39]
	v_pk_add_f32 v[24:25], v[24:25], v[40:41]
	v_cvt_pk_bf16_f32 v36, v36, v37
	v_cvt_pk_bf16_f32 v37, v24, v25
	ds_write_b64 v19, v[36:37] offset:208
	ds_read_b32 v18, v31
	ds_read_b32 v24, v33
	s_waitcnt lgkmcnt(3)
	v_lshlrev_b32_e32 v36, 16, v34
	v_and_b32_e32 v37, 0xffff0000, v34
	v_lshlrev_b32_e32 v38, 16, v10
	v_and_b32_e32 v39, 0xffff0000, v10
	v_lshlrev_b32_e32 v10, 16, v12
	v_and_b32_e32 v11, 0xffff0000, v12
	s_waitcnt lgkmcnt(1)
	v_pk_add_f32 v[12:13], v[36:37], v[18:19] op_sel_hi:[1,0] neg_lo:[0,1] neg_hi:[0,1]
	v_lshlrev_b32_e32 v34, 16, v35
	v_and_b32_e32 v35, 0xffff0000, v35
	s_waitcnt lgkmcnt(0)
	v_pk_mul_f32 v[12:13], v[24:25], v[12:13] op_sel_hi:[0,1]
	v_pk_fma_f32 v[12:13], v[14:15], v[12:13], v[20:21]
	v_pk_add_f32 v[14:15], v[34:35], v[18:19] op_sel_hi:[1,0] neg_lo:[0,1] neg_hi:[0,1]
	v_pk_add_f32 v[12:13], v[12:13], v[38:39]
	v_pk_mul_f32 v[14:15], v[24:25], v[14:15] op_sel_hi:[0,1]
	v_pk_fma_f32 v[14:15], v[16:17], v[14:15], v[22:23]
	v_cvt_pk_bf16_f32 v12, v12, v13
	v_pk_add_f32 v[10:11], v[14:15], v[10:11]
	s_nop 0
	v_cvt_pk_bf16_f32 v13, v10, v11
	ds_write_b64 v19, v[12:13] offset:16848
	v_add_u32_e32 v10, 0x251c0, v27
	v_add_u32_e32 v14, 0x255c0, v27
	ds_read_b64 v[20:21], v19 offset:224
	ds_read_b128 v[10:13], v10
	ds_read_b128 v[14:17], v14
	ds_read_b32 v18, v29
	ds_read_b32 v22, v30
	ds_read_b64 v[24:25], v19 offset:16864
	s_waitcnt lgkmcnt(5)
	v_lshlrev_b32_e32 v34, 16, v20
	v_and_b32_e32 v35, 0xffff0000, v20
	v_lshlrev_b32_e32 v20, 16, v21
	v_and_b32_e32 v21, 0xffff0000, v21
	s_waitcnt lgkmcnt(2)
	v_pk_add_f32 v[34:35], v[34:35], v[18:19] op_sel_hi:[1,0] neg_lo:[0,1] neg_hi:[0,1]
	v_pk_add_f32 v[20:21], v[20:21], v[18:19] op_sel_hi:[1,0] neg_lo:[0,1] neg_hi:[0,1]
	s_waitcnt lgkmcnt(1)
	v_pk_mul_f32 v[34:35], v[22:23], v[34:35] op_sel_hi:[0,1]
	v_pk_mul_f32 v[20:21], v[22:23], v[20:21] op_sel_hi:[0,1]
	v_lshlrev_b32_e32 v36, 16, v7
	v_and_b32_e32 v37, 0xffff0000, v7
	v_lshlrev_b32_e32 v38, 16, v9
	v_and_b32_e32 v39, 0xffff0000, v9
	v_pk_fma_f32 v[34:35], v[10:11], v[34:35], v[14:15]
	v_pk_fma_f32 v[20:21], v[12:13], v[20:21], v[16:17]
	v_pk_add_f32 v[34:35], v[34:35], v[36:37]
	v_pk_add_f32 v[20:21], v[20:21], v[38:39]
	v_cvt_pk_bf16_f32 v22, v34, v35
	v_cvt_pk_bf16_f32 v23, v20, v21
	ds_write_b64 v19, v[22:23] offset:224
	ds_read_b32 v18, v31
	ds_read_b32 v20, v33
	s_waitcnt lgkmcnt(3)
	v_lshlrev_b32_e32 v22, 16, v24
	v_and_b32_e32 v23, 0xffff0000, v24
	v_lshlrev_b32_e32 v34, 16, v6
	v_and_b32_e32 v35, 0xffff0000, v6
	v_lshlrev_b32_e32 v6, 16, v8
	v_and_b32_e32 v7, 0xffff0000, v8
	s_waitcnt lgkmcnt(1)
	v_pk_add_f32 v[8:9], v[22:23], v[18:19] op_sel_hi:[1,0] neg_lo:[0,1] neg_hi:[0,1]
	v_lshlrev_b32_e32 v24, 16, v25
	v_and_b32_e32 v25, 0xffff0000, v25
	s_waitcnt lgkmcnt(0)
	v_pk_mul_f32 v[8:9], v[20:21], v[8:9] op_sel_hi:[0,1]
	v_pk_fma_f32 v[8:9], v[10:11], v[8:9], v[14:15]
	v_pk_add_f32 v[10:11], v[24:25], v[18:19] op_sel_hi:[1,0] neg_lo:[0,1] neg_hi:[0,1]
	v_pk_add_f32 v[8:9], v[8:9], v[34:35]
	v_pk_mul_f32 v[10:11], v[20:21], v[10:11] op_sel_hi:[0,1]
	v_pk_fma_f32 v[10:11], v[12:13], v[10:11], v[16:17]
	v_cvt_pk_bf16_f32 v8, v8, v9
	v_pk_add_f32 v[6:7], v[10:11], v[6:7]
	s_nop 0
	v_cvt_pk_bf16_f32 v9, v6, v7
	ds_write_b64 v19, v[8:9] offset:16864
	ds_read_b128 v[6:9], v28 offset:480
	ds_read_b64 v[14:15], v19 offset:240
	ds_read_b32 v16, v29
	ds_read_b32 v18, v30
	v_add_u32_e32 v10, 0x255e0, v27
	ds_read_b128 v[10:13], v10
	s_waitcnt lgkmcnt(3)
	v_lshlrev_b32_e32 v20, 16, v14
	v_and_b32_e32 v21, 0xffff0000, v14
	v_lshlrev_b32_e32 v14, 16, v15
	v_and_b32_e32 v15, 0xffff0000, v15
	s_waitcnt lgkmcnt(2)
	v_pk_add_f32 v[20:21], v[20:21], v[16:17] op_sel_hi:[1,0] neg_lo:[0,1] neg_hi:[0,1]
	v_pk_add_f32 v[14:15], v[14:15], v[16:17] op_sel_hi:[1,0] neg_lo:[0,1] neg_hi:[0,1]
	s_waitcnt lgkmcnt(1)
	v_pk_mul_f32 v[20:21], v[18:19], v[20:21] op_sel_hi:[0,1]
	v_pk_mul_f32 v[14:15], v[18:19], v[14:15] op_sel_hi:[0,1]
	v_lshlrev_b32_e32 v22, 16, v4
	v_and_b32_e32 v23, 0xffff0000, v4
	v_lshlrev_b32_e32 v4, 16, v5
	v_and_b32_e32 v5, 0xffff0000, v5
	s_waitcnt lgkmcnt(0)
	v_pk_fma_f32 v[20:21], v[6:7], v[20:21], v[10:11]
	v_pk_fma_f32 v[14:15], v[8:9], v[14:15], v[12:13]
	v_pk_add_f32 v[20:21], v[20:21], v[22:23]
	v_pk_add_f32 v[4:5], v[14:15], v[4:5]
	v_cvt_pk_bf16_f32 v14, v20, v21
	v_cvt_pk_bf16_f32 v15, v4, v5
	ds_write_b64 v19, v[14:15] offset:240
	ds_read_b32 v4, v33
	ds_read_b64 v[14:15], v19 offset:16880
	ds_read_b32 v16, v31
	v_lshlrev_b32_e32 v22, 16, v2
	v_and_b32_e32 v23, 0xffff0000, v2
	v_lshlrev_b32_e32 v2, 16, v3
	s_waitcnt lgkmcnt(1)
	v_lshlrev_b32_e32 v20, 16, v14
	v_and_b32_e32 v21, 0xffff0000, v14
	s_waitcnt lgkmcnt(0)
	v_pk_add_f32 v[20:21], v[20:21], v[16:17] op_sel_hi:[1,0] neg_lo:[0,1] neg_hi:[0,1]
	v_lshlrev_b32_e32 v14, 16, v15
	v_and_b32_e32 v15, 0xffff0000, v15
	v_pk_mul_f32 v[20:21], v[4:5], v[20:21] op_sel_hi:[0,1]
	v_pk_fma_f32 v[6:7], v[6:7], v[20:21], v[10:11]
	v_pk_add_f32 v[10:11], v[14:15], v[16:17] op_sel_hi:[1,0] neg_lo:[0,1] neg_hi:[0,1]
	v_and_b32_e32 v3, 0xffff0000, v3
	v_pk_mul_f32 v[4:5], v[4:5], v[10:11] op_sel_hi:[0,1]
	v_pk_fma_f32 v[4:5], v[8:9], v[4:5], v[12:13]
	v_pk_add_f32 v[6:7], v[6:7], v[22:23]
	v_pk_add_f32 v[2:3], v[4:5], v[2:3]
	v_cvt_pk_bf16_f32 v4, v6, v7
	v_cvt_pk_bf16_f32 v5, v2, v3
	ds_write_b64 v19, v[4:5] offset:16880
	s_add_u32 s18, s80, s18
	s_addc_u32 s19, s81, s19
	v_lshl_add_u64 v[8:9], s[18:19], 0, v[0:1]
	v_mov_b32_e32 v0, v192
	s_waitcnt lgkmcnt(0)
	s_barrier
; DI int otid() { int t = threadIdx.x; asm volatile("" : "+v"(t)); return t; }
; DI void stg16_nt(void* p, u32x4 v) { __builtin_nontemporal_store(v, (u32x4*)p); }
; DI void stage_store_tile(const bf16_t* stg, bf16_t* tilebase) {
;   const int tid = otid();
;   const int r0 = tid >> 5, c = tid & 31;
;   const unsigned o0 = (unsigned)(r0 * 1024 + c * 8);
; #pragma unroll
;   for (int it = 0; it < 16; ++it) stg16_nt(tilebase + (o0 + (unsigned)(it * 16 * 1024)), stage_read16(stg, r0 + 16 * it, c));
; }
; template <bool LAST>
; DI void phase_gate(const Params& P, int layer, unsigned char* smem, int L, int G) {
;     ...
;     __syncthreads();
;     if (!LAST) stage_store_tile(stg, xb + (size_t)mt * 256 * 1024 + nt * 256);
;     __syncthreads();
	s_add_i32 s25, s25, s74
	v_ashrrev_i32_e32 v4, 5, v0
	v_and_b32_e32 v0, 31, v0
	v_mul_lo_u32 v1, v4, s34
	v_lshl_add_u32 v12, v0, 4, v1
	v_lshlrev_b32_e32 v5, 3, v0
	ds_read2_b64 v[0:3], v12 offset1:1
	v_lshl_or_b32 v160, v4, 10, v5
	v_add_u32_e32 v4, 0x2080, v12
	ds_read2_b64 v[4:7], v4 offset1:1
	v_lshl_add_u64 v[10:11], v[160:161], 1, v[8:9]
	s_waitcnt lgkmcnt(1)
	global_store_dwordx4 v[10:11], v[0:3], off nt
	s_add_i32 s22, s22, s69
	s_add_i32 s23, s23, s24
	v_add_u32_e32 v0, 0x4000, v160
	v_mov_b32_e32 v1, v161
	v_lshl_add_u64 v[0:1], v[0:1], 1, v[8:9]
	s_waitcnt lgkmcnt(0)
	global_store_dwordx4 v[0:1], v[4:7], off nt
	v_add_u32_e32 v0, 0x4100, v12
	ds_read2_b64 v[0:3], v0 offset1:1
	v_add_u32_e32 v4, 0x8000, v160
	v_mov_b32_e32 v5, v161
	v_lshl_add_u64 v[10:11], v[4:5], 1, v[8:9]
	v_add_u32_e32 v4, 0x6180, v12
	ds_read2_b64 v[4:7], v4 offset1:1
	s_waitcnt lgkmcnt(1)
	global_store_dwordx4 v[10:11], v[0:3], off nt
	s_add_i32 s18, s70, s25
	s_cmpk_lt_i32 s18, 0x400
	v_add_u32_e32 v0, 0xc000, v160
	v_mov_b32_e32 v1, v161
	v_lshl_add_u64 v[0:1], v[0:1], 1, v[8:9]
	s_waitcnt lgkmcnt(0)
	global_store_dwordx4 v[0:1], v[4:7], off nt
	v_add_u32_e32 v0, 0x8200, v12
	ds_read2_b64 v[0:3], v0 offset1:1
	v_add_u32_e32 v4, 0x10000, v160
	v_mov_b32_e32 v5, v161
	v_lshl_add_u64 v[10:11], v[4:5], 1, v[8:9]
	v_add_u32_e32 v4, 0xa280, v12
	ds_read2_b64 v[4:7], v4 offset1:1
	s_waitcnt lgkmcnt(1)
	global_store_dwordx4 v[10:11], v[0:3], off nt
	s_nop 1
	v_add_u32_e32 v0, 0x14000, v160
	v_mov_b32_e32 v1, v161
	v_lshl_add_u64 v[0:1], v[0:1], 1, v[8:9]
	s_waitcnt lgkmcnt(0)
	global_store_dwordx4 v[0:1], v[4:7], off nt
	v_add_u32_e32 v0, 0xc300, v12
	ds_read2_b64 v[0:3], v0 offset1:1
	v_add_u32_e32 v4, 0x18000, v160
	v_mov_b32_e32 v5, v161
	v_lshl_add_u64 v[10:11], v[4:5], 1, v[8:9]
	v_add_u32_e32 v4, 0xe380, v12
	ds_read2_b64 v[4:7], v4 offset1:1
	s_waitcnt lgkmcnt(1)
	global_store_dwordx4 v[10:11], v[0:3], off nt
	s_nop 1
	v_add_u32_e32 v0, 0x1c000, v160
	v_mov_b32_e32 v1, v161
	v_lshl_add_u64 v[0:1], v[0:1], 1, v[8:9]
	s_waitcnt lgkmcnt(0)
	global_store_dwordx4 v[0:1], v[4:7], off nt
	v_add_u32_e32 v0, 0x10400, v12
	ds_read2_b64 v[0:3], v0 offset1:1
	v_add_u32_e32 v4, 0x20000, v160
	v_mov_b32_e32 v5, v161
	v_lshl_add_u64 v[10:11], v[4:5], 1, v[8:9]
	v_add_u32_e32 v4, 0x12480, v12
	ds_read2_b64 v[4:7], v4 offset1:1
	s_waitcnt lgkmcnt(1)
	global_store_dwordx4 v[10:11], v[0:3], off nt
	s_nop 1
	v_add_u32_e32 v0, 0x24000, v160
	v_mov_b32_e32 v1, v161
	v_lshl_add_u64 v[0:1], v[0:1], 1, v[8:9]
	s_waitcnt lgkmcnt(0)
	global_store_dwordx4 v[0:1], v[4:7], off nt
	v_add_u32_e32 v0, 0x14500, v12
	ds_read2_b64 v[0:3], v0 offset1:1
	v_add_u32_e32 v4, 0x28000, v160
	v_mov_b32_e32 v5, v161
	v_lshl_add_u64 v[10:11], v[4:5], 1, v[8:9]
	v_add_u32_e32 v4, 0x16580, v12
	ds_read2_b64 v[4:7], v4 offset1:1
	s_waitcnt lgkmcnt(1)
	global_store_dwordx4 v[10:11], v[0:3], off nt
	s_nop 1
	v_add_u32_e32 v0, 0x2c000, v160
	v_mov_b32_e32 v1, v161
	v_lshl_add_u64 v[0:1], v[0:1], 1, v[8:9]
	s_waitcnt lgkmcnt(0)
	global_store_dwordx4 v[0:1], v[4:7], off nt
	v_add_u32_e32 v0, 0x18600, v12
	ds_read2_b64 v[0:3], v0 offset1:1
	v_add_u32_e32 v4, 0x30000, v160
	v_mov_b32_e32 v5, v161
	v_lshl_add_u64 v[10:11], v[4:5], 1, v[8:9]
	v_add_u32_e32 v4, 0x1a680, v12
	ds_read2_b64 v[4:7], v4 offset1:1
	s_waitcnt lgkmcnt(1)
	global_store_dwordx4 v[10:11], v[0:3], off nt
	v_add_u32_e32 v10, 0x38000, v160
	v_mov_b32_e32 v11, v161
	v_add_u32_e32 v0, 0x34000, v160
	v_mov_b32_e32 v1, v161
	v_lshl_add_u64 v[0:1], v[0:1], 1, v[8:9]
	s_waitcnt lgkmcnt(0)
	global_store_dwordx4 v[0:1], v[4:7], off nt
	v_add_u32_e32 v0, 0x1c700, v12
	ds_read2_b64 v[0:3], v0 offset1:1
	v_add_u32_e32 v4, 0x1e780, v12
	ds_read2_b64 v[4:7], v4 offset1:1
	v_lshl_add_u64 v[10:11], v[10:11], 1, v[8:9]
	v_add_u32_e32 v160, 0x3c000, v160
	s_waitcnt lgkmcnt(1)
	global_store_dwordx4 v[10:11], v[0:3], off nt
	s_nop 1
	v_lshl_add_u64 v[0:1], v[160:161], 1, v[8:9]
	s_waitcnt lgkmcnt(0)
	global_store_dwordx4 v[0:1], v[4:7], off nt
	s_barrier
	s_cbranch_scc0 .LBB0_1507

; DI unsigned pack2(float a, float b) { f32x2_t v = {a, b}; bf16x2_t r = __builtin_convertvector(v, bf16x2_t); return __builtin_bit_cast(unsigned, r); }
; DI float sigmoidf_(float x) { return __builtin_amdgcn_rcpf(1.f + __expf(-x)); }
; template <bool NT>
; DI void stage_load_tile(bf16_t* stg, const bf16_t* tilebase) {
;     ...
; #pragma unroll
;     for (int it = 8 * hf; it < 8 * hf + 8; ++it) {
;       const u32x4* gp = (const u32x4*)(tilebase + (o0 + (unsigned)(it * 16 * 1024)));
;       stage_write16(stg, r0 + 16 * it, c, NT ? __builtin_nontemporal_load(gp) : *gp);
; template <bool LAST>
; DI void phase_gate(const Params& P, int layer, unsigned char* smem, int L, int G) {
;     ...
; #pragma unroll
;     for (int i = 0; i < 4; ++i)
; #pragma unroll
;       for (int q4 = 0; q4 < 4; ++q4) {
;         const int fl = wm * 128 + i * 32 + 8 * q4 + 4 * h;
;         const f32x4 c1v = *(const f32x4*)(vecL + fl), c2v = *(const f32x4*)(vecL + 256 + fl);
;         const float c1a[4] = {c1v.x, c1v.y, c1v.z, c1v.w}, c2a[4] = {c2v.x, c2v.y, c2v.z, c2v.w};
; #pragma unroll
;         for (int j = 0; j < 2; ++j) {
;           const int lrow = wn * 64 + j * 32 + r;
;           const float mu = rowA[lrow], rstd = rowB[lrow];
;           float sg4[4];
; #pragma unroll
;           for (int e = 0; e < 4; ++e) sg4[e] = sigmoidf_(rstd * (accu[i][j][4 * q4 + e] - mu * c1a[e]) + c2a[e]);
;           gq[i][j][2 * q4] = pack2(sg4[0], sg4[1]); gq[i][j][2 * q4 + 1] = pack2(sg4[2], sg4[3]);
;         }
;         __builtin_amdgcn_sched_barrier(0);
;       }
.LBB0_1801:
	s_ashr_i32 s19, s18, 31
	s_lshl_b64 s[18:19], s[18:19], 19
	s_add_u32 s20, s66, s18
	s_addc_u32 s21, s67, s19
	v_and_b32_e32 v188, 31, v192
	v_ashrrev_i32_e32 v189, 5, v192
	v_lshlrev_b32_e32 v188, 3, v188
	v_lshl_or_b32 v188, v189, 10, v188
	v_add_u32_e32 v188, v188, v162
	v_lshlrev_b32_e32 v188, 1, v188
	global_load_dwordx4 v[180:183], v188, s[20:21] nt
	s_add_u32 s100, s20, 0x8000
	s_addc_u32 s101, s21, 0
	global_load_dwordx4 v[184:187], v188, s[100:101] nt
	s_add_u32 s100, s20, 0x10000
	s_addc_u32 s101, s21, 0
	global_load_dwordx4 v[194:197], v188, s[100:101] nt
	s_add_u32 s100, s20, 0x18000
	s_addc_u32 s101, s21, 0
	global_load_dwordx4 v[198:201], v188, s[100:101] nt
	s_add_u32 s100, s20, 0x20000
	s_addc_u32 s101, s21, 0
	global_load_dwordx4 v[202:205], v188, s[100:101] nt
	s_add_u32 s100, s20, 0x28000
	s_addc_u32 s101, s21, 0
	global_load_dwordx4 v[206:209], v188, s[100:101] nt
	s_add_u32 s100, s20, 0x30000
	s_addc_u32 s101, s21, 0
	global_load_dwordx4 v[210:213], v188, s[100:101] nt
	s_add_u32 s100, s20, 0x38000
	s_addc_u32 s101, s21, 0
	global_load_dwordx4 v[214:217], v188, s[100:101] nt
	s_add_u32 s100, s20, 0x40000
	s_addc_u32 s101, s21, 0
	global_load_dwordx4 v[218:221], v188, s[100:101] nt
	s_add_u32 s100, s20, 0x48000
	s_addc_u32 s101, s21, 0
	global_load_dwordx4 v[222:225], v188, s[100:101] nt
	s_add_u32 s100, s20, 0x50000
	s_addc_u32 s101, s21, 0
	global_load_dwordx4 v[226:229], v188, s[100:101] nt
	s_add_u32 s100, s20, 0x58000
	s_addc_u32 s101, s21, 0
	global_load_dwordx4 v[230:233], v188, s[100:101] nt
	s_add_u32 s100, s20, 0x60000
	s_addc_u32 s101, s21, 0
	global_load_dwordx4 v[234:237], v188, s[100:101] nt
	s_add_u32 s100, s20, 0x68000
	s_addc_u32 s101, s21, 0
	global_load_dwordx4 v[238:241], v188, s[100:101] nt
	s_add_u32 s100, s20, 0x70000
	s_addc_u32 s101, s21, 0
	global_load_dwordx4 v[242:245], v188, s[100:101] nt
	s_add_u32 s100, s20, 0x78000
	s_addc_u32 s101, s21, 0
	global_load_dwordx4 v[248:251], v188, s[100:101] nt
	v_lshrrev_b32_e32 v160, 1, v163
	v_lshrrev_b32_e32 v163, 3, v163
	v_and_b32_e32 v163, 4, v163
	v_and_or_b32 v160, v160, s33, v163
	v_lshlrev_b32_e32 v160, 2, v160
	v_add_u32_e32 v163, 0x24800, v160
	v_add_u32_e32 v164, 0x24c00, v160
	v_and_b32_e32 v167, 0x37c, v168
	ds_read_b128 v[170:173], v163
	ds_read_b128 v[174:177], v164
	v_or_b32_e32 v164, 0x24000, v167
	v_or_b32_e32 v166, 0x24080, v167
	v_or_b32_e32 v165, 0x24400, v167
	ds_read_b32 v168, v164
	ds_read_b32 v169, v165
	v_or_b32_e32 v167, 0x24480, v167
	ds_read_b32 v178, v166
	ds_read_b32 v179, v167
	s_waitcnt lgkmcnt(3)
	v_fma_f32 v112, -v170, v168, v112
	v_fma_f32 v113, -v171, v168, v113
	s_waitcnt lgkmcnt(1)
	v_fma_f32 v98, -v172, v178, v98
	v_fma_f32 v114, -v172, v168, v114
	v_fma_f32 v115, -v173, v168, v115
	v_fma_f32 v96, -v170, v178, v96
	v_fma_f32 v97, -v171, v178, v97
	s_waitcnt lgkmcnt(0)
	v_fma_f32 v98, v179, v98, v176
	v_fma_f32 v99, -v173, v178, v99
	v_fma_f32 v112, v169, v112, v174
	v_fma_f32 v113, v169, v113, v175
	v_fma_f32 v114, v169, v114, v176
	v_fma_f32 v115, v169, v115, v177
	v_fma_f32 v96, v179, v96, v174
	v_fma_f32 v97, v179, v97, v175
	v_mul_f32_e32 v98, 0xbfb8aa3b, v98
	v_fmac_f32_e32 v177, v179, v99
	v_mul_f32_e32 v112, 0xbfb8aa3b, v112
	v_mul_f32_e32 v113, 0xbfb8aa3b, v113
	v_mul_f32_e32 v114, 0xbfb8aa3b, v114
	v_mul_f32_e32 v115, 0xbfb8aa3b, v115
	v_mul_f32_e32 v96, 0xbfb8aa3b, v96
	v_mul_f32_e32 v97, 0xbfb8aa3b, v97
	v_exp_f32_e32 v98, v98
	v_mul_f32_e32 v99, 0xbfb8aa3b, v177
	v_exp_f32_e32 v112, v112
	v_exp_f32_e32 v113, v113
	v_exp_f32_e32 v114, v114
	v_exp_f32_e32 v115, v115
	v_exp_f32_e32 v96, v96
	v_exp_f32_e32 v97, v97
	v_exp_f32_e32 v99, v99
	v_add_f32_e32 v98, 1.0, v98
	v_add_f32_e32 v112, 1.0, v112
	v_add_f32_e32 v113, 1.0, v113
	v_add_f32_e32 v114, 1.0, v114
	v_add_f32_e32 v115, 1.0, v115
	v_add_f32_e32 v96, 1.0, v96
	v_add_f32_e32 v97, 1.0, v97
	v_rcp_f32_e32 v168, v98
	v_add_f32_e32 v98, 1.0, v99
	v_rcp_f32_e32 v112, v112
	v_rcp_f32_e32 v113, v113
	v_rcp_f32_e32 v114, v114
	v_rcp_f32_e32 v115, v115
	v_rcp_f32_e32 v96, v96
	v_rcp_f32_e32 v97, v97
	v_rcp_f32_e32 v169, v98
	v_cvt_pk_bf16_f32 v99, v112, v113
	v_cvt_pk_bf16_f32 v98, v114, v115
	v_cvt_pk_bf16_f32 v97, v96, v97
	v_cvt_pk_bf16_f32 v96, v168, v169
	v_add_u32_e32 v112, 0x24820, v160
	v_add_u32_e32 v168, 0x24c20, v160
	ds_read_b128 v[112:115], v112
	ds_read_b128 v[168:171], v168
	ds_read_b32 v172, v164
	ds_read_b32 v173, v165
	ds_read_b32 v174, v166
	ds_read_b32 v175, v167
	s_waitcnt lgkmcnt(3)
	v_fma_f32 v116, -v112, v172, v116
	v_fma_f32 v117, -v113, v172, v117
	s_waitcnt lgkmcnt(1)
	v_fma_f32 v102, -v114, v174, v102
	v_fma_f32 v118, -v114, v172, v118
	v_fma_f32 v119, -v115, v172, v119
	v_fma_f32 v100, -v112, v174, v100
	v_fma_f32 v101, -v113, v174, v101
	s_waitcnt lgkmcnt(0)
	v_fma_f32 v102, v175, v102, v170
	v_fma_f32 v103, -v115, v174, v103
	v_fma_f32 v116, v173, v116, v168
	v_fma_f32 v117, v173, v117, v169
	v_fma_f32 v118, v173, v118, v170
	v_fma_f32 v119, v173, v119, v171
	v_fma_f32 v100, v175, v100, v168
	v_fma_f32 v101, v175, v101, v169
	v_mul_f32_e32 v102, 0xbfb8aa3b, v102
	v_fmac_f32_e32 v171, v175, v103
	v_mul_f32_e32 v116, 0xbfb8aa3b, v116
	v_mul_f32_e32 v117, 0xbfb8aa3b, v117
	v_mul_f32_e32 v118, 0xbfb8aa3b, v118
	v_mul_f32_e32 v119, 0xbfb8aa3b, v119
	v_mul_f32_e32 v100, 0xbfb8aa3b, v100
	v_mul_f32_e32 v101, 0xbfb8aa3b, v101
	v_exp_f32_e32 v102, v102
	v_mul_f32_e32 v103, 0xbfb8aa3b, v171
	v_exp_f32_e32 v116, v116
	v_exp_f32_e32 v117, v117
	v_exp_f32_e32 v118, v118
	v_exp_f32_e32 v119, v119
	v_exp_f32_e32 v100, v100
	v_exp_f32_e32 v101, v101
	v_exp_f32_e32 v103, v103
	v_add_f32_e32 v102, 1.0, v102
	v_add_f32_e32 v116, 1.0, v116
	v_add_f32_e32 v117, 1.0, v117
	v_add_f32_e32 v118, 1.0, v118
	v_add_f32_e32 v119, 1.0, v119
	v_add_f32_e32 v100, 1.0, v100
	v_add_f32_e32 v101, 1.0, v101
	v_rcp_f32_e32 v113, v102
	v_add_f32_e32 v102, 1.0, v103
	v_rcp_f32_e32 v116, v116
	v_rcp_f32_e32 v117, v117
	v_rcp_f32_e32 v118, v118
	v_rcp_f32_e32 v112, v119
	v_rcp_f32_e32 v100, v100
	v_rcp_f32_e32 v101, v101
	v_rcp_f32_e32 v114, v102
	v_cvt_pk_bf16_f32 v103, v116, v117
	v_cvt_pk_bf16_f32 v102, v118, v112
	v_cvt_pk_bf16_f32 v101, v100, v101
	v_cvt_pk_bf16_f32 v100, v113, v114
	v_add_u32_e32 v112, 0x24840, v160
	v_add_u32_e32 v116, 0x24c40, v160
	ds_read_b128 v[112:115], v112
	ds_read_b128 v[116:119], v116
	ds_read_b32 v168, v164
	ds_read_b32 v169, v165
	ds_read_b32 v170, v166
	ds_read_b32 v171, v167
	s_waitcnt lgkmcnt(3)
; DI unsigned pack2(float a, float b) { f32x2_t v = {a, b}; bf16x2_t r = __builtin_convertvector(v, bf16x2_t); return __builtin_bit_cast(unsigned, r); }
; DI float sigmoidf_(float x) { return __builtin_amdgcn_rcpf(1.f + __expf(-x)); }
; template <bool LAST>
; DI void phase_gate(const Params& P, int layer, unsigned char* smem, int L, int G) {
;     ...
; #pragma unroll
;     for (int i = 0; i < 4; ++i)
; #pragma unroll
;       for (int q4 = 0; q4 < 4; ++q4) {
;         const int fl = wm * 128 + i * 32 + 8 * q4 + 4 * h;
;         const f32x4 c1v = *(const f32x4*)(vecL + fl), c2v = *(const f32x4*)(vecL + 256 + fl);
;         const float c1a[4] = {c1v.x, c1v.y, c1v.z, c1v.w}, c2a[4] = {c2v.x, c2v.y, c2v.z, c2v.w};
; #pragma unroll
;         for (int j = 0; j < 2; ++j) {
;           const int lrow = wn * 64 + j * 32 + r;
;           const float mu = rowA[lrow], rstd = rowB[lrow];
;           float sg4[4];
; #pragma unroll
;           for (int e = 0; e < 4; ++e) sg4[e] = sigmoidf_(rstd * (accu[i][j][4 * q4 + e] - mu * c1a[e]) + c2a[e]);
;           gq[i][j][2 * q4] = pack2(sg4[0], sg4[1]); gq[i][j][2 * q4 + 1] = pack2(sg4[2], sg4[3]);
;         }
;         __builtin_amdgcn_sched_barrier(0);
;       }
	v_fma_f32 v120, -v112, v168, v120
	v_fma_f32 v121, -v113, v168, v121
	s_waitcnt lgkmcnt(1)
	v_fma_f32 v106, -v114, v170, v106
	v_fma_f32 v122, -v114, v168, v122
	v_fma_f32 v123, -v115, v168, v123
	v_fma_f32 v104, -v112, v170, v104
	v_fma_f32 v105, -v113, v170, v105
	s_waitcnt lgkmcnt(0)
	v_fma_f32 v106, v171, v106, v118
	v_fma_f32 v107, -v115, v170, v107
	v_fma_f32 v120, v169, v120, v116
	v_fma_f32 v121, v169, v121, v117
	v_fma_f32 v122, v169, v122, v118
	v_fma_f32 v123, v169, v123, v119
	v_fma_f32 v104, v171, v104, v116
	v_fma_f32 v105, v171, v105, v117
	v_mul_f32_e32 v106, 0xbfb8aa3b, v106
	v_fmac_f32_e32 v119, v171, v107
	v_mul_f32_e32 v120, 0xbfb8aa3b, v120
	v_mul_f32_e32 v121, 0xbfb8aa3b, v121
	v_mul_f32_e32 v122, 0xbfb8aa3b, v122
	v_mul_f32_e32 v123, 0xbfb8aa3b, v123
	v_mul_f32_e32 v104, 0xbfb8aa3b, v104
	v_mul_f32_e32 v105, 0xbfb8aa3b, v105
	v_exp_f32_e32 v106, v106
	v_mul_f32_e32 v107, 0xbfb8aa3b, v119
	v_exp_f32_e32 v120, v120
	v_exp_f32_e32 v121, v121
	v_exp_f32_e32 v122, v122
	v_exp_f32_e32 v123, v123
	v_exp_f32_e32 v104, v104
	v_exp_f32_e32 v105, v105
	v_exp_f32_e32 v107, v107
	v_add_f32_e32 v106, 1.0, v106
	v_add_f32_e32 v120, 1.0, v120
	v_add_f32_e32 v121, 1.0, v121
	v_add_f32_e32 v122, 1.0, v122
	v_add_f32_e32 v123, 1.0, v123
	v_add_f32_e32 v104, 1.0, v104
	v_add_f32_e32 v105, 1.0, v105
	v_rcp_f32_e32 v113, v106
	v_add_f32_e32 v106, 1.0, v107
	v_rcp_f32_e32 v120, v120
	v_rcp_f32_e32 v121, v121
	v_rcp_f32_e32 v122, v122
	v_rcp_f32_e32 v112, v123
	v_rcp_f32_e32 v104, v104
	v_rcp_f32_e32 v105, v105
	v_rcp_f32_e32 v114, v106
	v_cvt_pk_bf16_f32 v107, v120, v121
	v_cvt_pk_bf16_f32 v106, v122, v112
	v_cvt_pk_bf16_f32 v105, v104, v105
	v_cvt_pk_bf16_f32 v104, v113, v114
	v_add_u32_e32 v112, 0x24860, v160
	v_add_u32_e32 v116, 0x24c60, v160
	ds_read_b128 v[112:115], v112
	ds_read_b128 v[116:119], v116
	ds_read_b32 v120, v164
	ds_read_b32 v121, v165
	ds_read_b32 v122, v166
	ds_read_b32 v123, v167
	s_waitcnt lgkmcnt(3)
	v_fma_f32 v125, -v113, v120, v125
	v_fma_f32 v124, -v112, v120, v124
	s_waitcnt lgkmcnt(1)
	v_fma_f32 v110, -v114, v122, v110
	v_fma_f32 v125, v121, v125, v117
	v_fma_f32 v126, -v114, v120, v126
	v_fma_f32 v120, -v115, v120, v127
	v_fma_f32 v108, -v112, v122, v108
	v_fma_f32 v109, -v113, v122, v109
	s_waitcnt lgkmcnt(0)
	v_fma_f32 v110, v123, v110, v118
	v_fma_f32 v111, -v115, v122, v111
	v_fma_f32 v124, v121, v124, v116
	v_mul_f32_e32 v125, 0xbfb8aa3b, v125
	v_fma_f32 v126, v121, v126, v118
	v_fma_f32 v120, v121, v120, v119
	v_fma_f32 v108, v123, v108, v116
	v_fma_f32 v109, v123, v109, v117
	v_mul_f32_e32 v110, 0xbfb8aa3b, v110
	v_fmac_f32_e32 v119, v123, v111
	v_mul_f32_e32 v124, 0xbfb8aa3b, v124
	v_exp_f32_e32 v125, v125
	v_mul_f32_e32 v126, 0xbfb8aa3b, v126
	v_mul_f32_e32 v120, 0xbfb8aa3b, v120
	v_mul_f32_e32 v108, 0xbfb8aa3b, v108
	v_mul_f32_e32 v109, 0xbfb8aa3b, v109
	v_exp_f32_e32 v110, v110
	v_mul_f32_e32 v111, 0xbfb8aa3b, v119
	v_exp_f32_e32 v124, v124
	v_exp_f32_e32 v126, v126
	v_exp_f32_e32 v120, v120
	v_exp_f32_e32 v108, v108
	v_exp_f32_e32 v109, v109
	v_exp_f32_e32 v111, v111
	v_add_f32_e32 v125, 1.0, v125
	v_add_f32_e32 v110, 1.0, v110
	v_add_f32_e32 v124, 1.0, v124
	v_rcp_f32_e32 v121, v125
	v_add_f32_e32 v125, 1.0, v126
	v_add_f32_e32 v120, 1.0, v120
	v_add_f32_e32 v108, 1.0, v108
	v_add_f32_e32 v109, 1.0, v109
	v_rcp_f32_e32 v113, v110
	v_add_f32_e32 v110, 1.0, v111
	v_rcp_f32_e32 v124, v124
	v_rcp_f32_e32 v125, v125
	v_rcp_f32_e32 v112, v120
	v_rcp_f32_e32 v108, v108
	v_rcp_f32_e32 v109, v109
	v_rcp_f32_e32 v114, v110
	v_cvt_pk_bf16_f32 v111, v124, v121
	v_cvt_pk_bf16_f32 v110, v125, v112
	v_cvt_pk_bf16_f32 v109, v108, v109
	v_cvt_pk_bf16_f32 v108, v113, v114
	v_add_u32_e32 v112, 0x24880, v160
	v_add_u32_e32 v116, 0x24c80, v160
	ds_read_b128 v[112:115], v112
	ds_read_b128 v[116:119], v116
	ds_read_b32 v120, v164
	ds_read_b32 v121, v165
	ds_read_b32 v122, v166
	ds_read_b32 v123, v167
	s_waitcnt lgkmcnt(3)
	v_fma_f32 v80, -v112, v120, v80
	v_fma_f32 v81, -v113, v120, v81
	s_waitcnt lgkmcnt(1)
	v_fma_f32 v66, -v114, v122, v66
	v_fma_f32 v82, -v114, v120, v82
	v_fma_f32 v83, -v115, v120, v83
	v_fma_f32 v64, -v112, v122, v64
	v_fma_f32 v65, -v113, v122, v65
	s_waitcnt lgkmcnt(0)
	v_fma_f32 v66, v123, v66, v118
	v_fma_f32 v67, -v115, v122, v67
	v_fma_f32 v80, v121, v80, v116
	v_fma_f32 v81, v121, v81, v117
	v_fma_f32 v82, v121, v82, v118
	v_fma_f32 v83, v121, v83, v119
	v_fma_f32 v64, v123, v64, v116
	v_fma_f32 v65, v123, v65, v117
	v_mul_f32_e32 v66, 0xbfb8aa3b, v66
	v_fmac_f32_e32 v119, v123, v67
	v_mul_f32_e32 v80, 0xbfb8aa3b, v80
	v_mul_f32_e32 v81, 0xbfb8aa3b, v81
	v_mul_f32_e32 v82, 0xbfb8aa3b, v82
	v_mul_f32_e32 v83, 0xbfb8aa3b, v83
	v_mul_f32_e32 v64, 0xbfb8aa3b, v64
	v_mul_f32_e32 v65, 0xbfb8aa3b, v65
	v_exp_f32_e32 v66, v66
	v_mul_f32_e32 v67, 0xbfb8aa3b, v119
	v_exp_f32_e32 v80, v80
	v_exp_f32_e32 v81, v81
	v_exp_f32_e32 v82, v82
	v_exp_f32_e32 v83, v83
	v_exp_f32_e32 v64, v64
	v_exp_f32_e32 v65, v65
	v_exp_f32_e32 v67, v67
	v_add_f32_e32 v66, 1.0, v66
	v_add_f32_e32 v80, 1.0, v80
	v_add_f32_e32 v81, 1.0, v81
	v_add_f32_e32 v82, 1.0, v82
	v_add_f32_e32 v83, 1.0, v83
	v_add_f32_e32 v64, 1.0, v64
	v_add_f32_e32 v65, 1.0, v65
	v_rcp_f32_e32 v112, v66
	v_add_f32_e32 v66, 1.0, v67
	v_rcp_f32_e32 v80, v80
	v_rcp_f32_e32 v81, v81
	v_rcp_f32_e32 v82, v82
	v_rcp_f32_e32 v83, v83
	v_rcp_f32_e32 v64, v64
	v_rcp_f32_e32 v65, v65
	v_rcp_f32_e32 v113, v66
	v_cvt_pk_bf16_f32 v67, v80, v81
	v_cvt_pk_bf16_f32 v66, v82, v83
	v_cvt_pk_bf16_f32 v65, v64, v65
	v_cvt_pk_bf16_f32 v64, v112, v113
	v_add_u32_e32 v80, 0x248a0, v160
	v_add_u32_e32 v112, 0x24ca0, v160
	ds_read_b128 v[80:83], v80
	ds_read_b128 v[112:115], v112
	ds_read_b32 v116, v164
	ds_read_b32 v117, v165
	ds_read_b32 v118, v166
	ds_read_b32 v119, v167
	s_waitcnt lgkmcnt(3)
; DI unsigned pack2(float a, float b) { f32x2_t v = {a, b}; bf16x2_t r = __builtin_convertvector(v, bf16x2_t); return __builtin_bit_cast(unsigned, r); }
; DI float sigmoidf_(float x) { return __builtin_amdgcn_rcpf(1.f + __expf(-x)); }
; template <bool LAST>
; DI void phase_gate(const Params& P, int layer, unsigned char* smem, int L, int G) {
;     ...
; #pragma unroll
;     for (int i = 0; i < 4; ++i)
; #pragma unroll
;       for (int q4 = 0; q4 < 4; ++q4) {
;         const int fl = wm * 128 + i * 32 + 8 * q4 + 4 * h;
;         const f32x4 c1v = *(const f32x4*)(vecL + fl), c2v = *(const f32x4*)(vecL + 256 + fl);
;         const float c1a[4] = {c1v.x, c1v.y, c1v.z, c1v.w}, c2a[4] = {c2v.x, c2v.y, c2v.z, c2v.w};
; #pragma unroll
;         for (int j = 0; j < 2; ++j) {
;           const int lrow = wn * 64 + j * 32 + r;
;           const float mu = rowA[lrow], rstd = rowB[lrow];
;           float sg4[4];
; #pragma unroll
;           for (int e = 0; e < 4; ++e) sg4[e] = sigmoidf_(rstd * (accu[i][j][4 * q4 + e] - mu * c1a[e]) + c2a[e]);
;           gq[i][j][2 * q4] = pack2(sg4[0], sg4[1]); gq[i][j][2 * q4 + 1] = pack2(sg4[2], sg4[3]);
;         }
;         __builtin_amdgcn_sched_barrier(0);
;       }
	v_fma_f32 v84, -v80, v116, v84
	v_fma_f32 v85, -v81, v116, v85
	s_waitcnt lgkmcnt(1)
	v_fma_f32 v70, -v82, v118, v70
	v_fma_f32 v86, -v82, v116, v86
	v_fma_f32 v87, -v83, v116, v87
	v_fma_f32 v68, -v80, v118, v68
	v_fma_f32 v69, -v81, v118, v69
	s_waitcnt lgkmcnt(0)
	v_fma_f32 v70, v119, v70, v114
	v_fma_f32 v71, -v83, v118, v71
	v_fma_f32 v84, v117, v84, v112
	v_fma_f32 v85, v117, v85, v113
	v_fma_f32 v86, v117, v86, v114
	v_fma_f32 v87, v117, v87, v115
	v_fma_f32 v68, v119, v68, v112
	v_fma_f32 v69, v119, v69, v113
	v_mul_f32_e32 v70, 0xbfb8aa3b, v70
	v_fmac_f32_e32 v115, v119, v71
	v_mul_f32_e32 v84, 0xbfb8aa3b, v84
	v_mul_f32_e32 v85, 0xbfb8aa3b, v85
	v_mul_f32_e32 v86, 0xbfb8aa3b, v86
	v_mul_f32_e32 v87, 0xbfb8aa3b, v87
	v_mul_f32_e32 v68, 0xbfb8aa3b, v68
	v_mul_f32_e32 v69, 0xbfb8aa3b, v69
	v_exp_f32_e32 v70, v70
	v_mul_f32_e32 v71, 0xbfb8aa3b, v115
	v_exp_f32_e32 v84, v84
	v_exp_f32_e32 v85, v85
	v_exp_f32_e32 v86, v86
	v_exp_f32_e32 v87, v87
	v_exp_f32_e32 v68, v68
	v_exp_f32_e32 v69, v69
	v_exp_f32_e32 v71, v71
	v_add_f32_e32 v70, 1.0, v70
	v_add_f32_e32 v84, 1.0, v84
	v_add_f32_e32 v85, 1.0, v85
	v_add_f32_e32 v86, 1.0, v86
	v_add_f32_e32 v87, 1.0, v87
	v_add_f32_e32 v68, 1.0, v68
	v_add_f32_e32 v69, 1.0, v69
	v_rcp_f32_e32 v81, v70
	v_add_f32_e32 v70, 1.0, v71
	v_rcp_f32_e32 v84, v84
	v_rcp_f32_e32 v85, v85
	v_rcp_f32_e32 v86, v86
	v_rcp_f32_e32 v80, v87
	v_rcp_f32_e32 v68, v68
	v_rcp_f32_e32 v69, v69
	v_rcp_f32_e32 v82, v70
	v_cvt_pk_bf16_f32 v71, v84, v85
	v_cvt_pk_bf16_f32 v70, v86, v80
	v_cvt_pk_bf16_f32 v69, v68, v69
	v_cvt_pk_bf16_f32 v68, v81, v82
	v_add_u32_e32 v80, 0x248c0, v160
	v_add_u32_e32 v84, 0x24cc0, v160
	ds_read_b128 v[80:83], v80
	ds_read_b128 v[84:87], v84
	ds_read_b32 v112, v164
	ds_read_b32 v113, v165
	ds_read_b32 v114, v166
	ds_read_b32 v115, v167
	s_waitcnt lgkmcnt(3)
	v_fma_f32 v88, -v80, v112, v88
	v_fma_f32 v89, -v81, v112, v89
	s_waitcnt lgkmcnt(1)
	v_fma_f32 v74, -v82, v114, v74
	v_fma_f32 v90, -v82, v112, v90
	v_fma_f32 v91, -v83, v112, v91
	v_fma_f32 v72, -v80, v114, v72
	v_fma_f32 v73, -v81, v114, v73
	s_waitcnt lgkmcnt(0)
	v_fma_f32 v74, v115, v74, v86
	v_fma_f32 v75, -v83, v114, v75
	v_fma_f32 v88, v113, v88, v84
	v_fma_f32 v89, v113, v89, v85
	v_fma_f32 v90, v113, v90, v86
	v_fma_f32 v91, v113, v91, v87
	v_fma_f32 v72, v115, v72, v84
	v_fma_f32 v73, v115, v73, v85
	v_mul_f32_e32 v74, 0xbfb8aa3b, v74
	v_fmac_f32_e32 v87, v115, v75
	v_mul_f32_e32 v88, 0xbfb8aa3b, v88
	v_mul_f32_e32 v89, 0xbfb8aa3b, v89
	v_mul_f32_e32 v90, 0xbfb8aa3b, v90
	v_mul_f32_e32 v91, 0xbfb8aa3b, v91
	v_mul_f32_e32 v72, 0xbfb8aa3b, v72
	v_mul_f32_e32 v73, 0xbfb8aa3b, v73
	v_exp_f32_e32 v74, v74
	v_mul_f32_e32 v75, 0xbfb8aa3b, v87
	v_exp_f32_e32 v88, v88
	v_exp_f32_e32 v89, v89
	v_exp_f32_e32 v90, v90
	v_exp_f32_e32 v91, v91
	v_exp_f32_e32 v72, v72
	v_exp_f32_e32 v73, v73
	v_exp_f32_e32 v75, v75
	v_add_f32_e32 v74, 1.0, v74
	v_add_f32_e32 v88, 1.0, v88
	v_add_f32_e32 v89, 1.0, v89
	v_add_f32_e32 v90, 1.0, v90
	v_add_f32_e32 v91, 1.0, v91
	v_add_f32_e32 v72, 1.0, v72
	v_add_f32_e32 v73, 1.0, v73
	v_rcp_f32_e32 v81, v74
	v_add_f32_e32 v74, 1.0, v75
	v_rcp_f32_e32 v88, v88
	v_rcp_f32_e32 v89, v89
	v_rcp_f32_e32 v90, v90
	v_rcp_f32_e32 v80, v91
	v_rcp_f32_e32 v72, v72
	v_rcp_f32_e32 v73, v73
	v_rcp_f32_e32 v82, v74
	v_cvt_pk_bf16_f32 v75, v88, v89
	v_cvt_pk_bf16_f32 v74, v90, v80
	v_cvt_pk_bf16_f32 v73, v72, v73
	v_cvt_pk_bf16_f32 v72, v81, v82
	v_add_u32_e32 v80, 0x248e0, v160
	v_add_u32_e32 v84, 0x24ce0, v160
	ds_read_b128 v[80:83], v80
	ds_read_b128 v[84:87], v84
	ds_read_b32 v88, v164
	ds_read_b32 v89, v165
	ds_read_b32 v90, v166
	ds_read_b32 v91, v167
	s_waitcnt lgkmcnt(3)
	v_fma_f32 v93, -v81, v88, v93
	v_fma_f32 v92, -v80, v88, v92
	s_waitcnt lgkmcnt(1)
	v_fma_f32 v78, -v82, v90, v78
	v_fma_f32 v93, v89, v93, v85
	v_fma_f32 v94, -v82, v88, v94
	v_fma_f32 v88, -v83, v88, v95
	v_fma_f32 v76, -v80, v90, v76
	v_fma_f32 v77, -v81, v90, v77
	s_waitcnt lgkmcnt(0)
	v_fma_f32 v78, v91, v78, v86
	v_fma_f32 v79, -v83, v90, v79
	v_fma_f32 v92, v89, v92, v84
	v_mul_f32_e32 v93, 0xbfb8aa3b, v93
	v_fma_f32 v94, v89, v94, v86
	v_fma_f32 v88, v89, v88, v87
	v_fma_f32 v76, v91, v76, v84
	v_fma_f32 v77, v91, v77, v85
	v_mul_f32_e32 v78, 0xbfb8aa3b, v78
	v_fmac_f32_e32 v87, v91, v79
	v_mul_f32_e32 v92, 0xbfb8aa3b, v92
	v_exp_f32_e32 v93, v93
	v_mul_f32_e32 v94, 0xbfb8aa3b, v94
	v_mul_f32_e32 v88, 0xbfb8aa3b, v88
	v_mul_f32_e32 v76, 0xbfb8aa3b, v76
	v_mul_f32_e32 v77, 0xbfb8aa3b, v77
	v_exp_f32_e32 v78, v78
	v_mul_f32_e32 v79, 0xbfb8aa3b, v87
	v_exp_f32_e32 v92, v92
	v_exp_f32_e32 v94, v94
	v_exp_f32_e32 v88, v88
	v_exp_f32_e32 v76, v76
	v_exp_f32_e32 v77, v77
	v_exp_f32_e32 v79, v79
	v_add_f32_e32 v93, 1.0, v93
	v_add_f32_e32 v78, 1.0, v78
	v_add_f32_e32 v92, 1.0, v92
	v_rcp_f32_e32 v89, v93
	v_add_f32_e32 v93, 1.0, v94
	v_add_f32_e32 v88, 1.0, v88
	v_add_f32_e32 v76, 1.0, v76
	v_add_f32_e32 v77, 1.0, v77
	v_rcp_f32_e32 v81, v78
	v_add_f32_e32 v78, 1.0, v79
	v_rcp_f32_e32 v92, v92
	v_rcp_f32_e32 v93, v93
	v_rcp_f32_e32 v80, v88
	v_rcp_f32_e32 v76, v76
	v_rcp_f32_e32 v77, v77
	v_rcp_f32_e32 v82, v78
	v_cvt_pk_bf16_f32 v79, v92, v89
	v_cvt_pk_bf16_f32 v78, v93, v80
	v_cvt_pk_bf16_f32 v77, v76, v77
	v_cvt_pk_bf16_f32 v76, v81, v82
	v_add_u32_e32 v80, 0x24900, v160
	v_add_u32_e32 v84, 0x24d00, v160
	ds_read_b128 v[80:83], v80
	ds_read_b128 v[84:87], v84
	ds_read_b32 v88, v164
	ds_read_b32 v89, v165
	ds_read_b32 v90, v166
	ds_read_b32 v91, v167
	s_waitcnt lgkmcnt(3)
	v_fma_f32 v48, -v80, v88, v48
	v_fma_f32 v49, -v81, v88, v49
	s_waitcnt lgkmcnt(1)
	v_fma_f32 v34, -v82, v90, v34
	v_fma_f32 v50, -v82, v88, v50
	v_fma_f32 v51, -v83, v88, v51
	v_fma_f32 v32, -v80, v90, v32
	v_fma_f32 v33, -v81, v90, v33
	s_waitcnt lgkmcnt(0)
; DI unsigned pack2(float a, float b) { f32x2_t v = {a, b}; bf16x2_t r = __builtin_convertvector(v, bf16x2_t); return __builtin_bit_cast(unsigned, r); }
; DI float sigmoidf_(float x) { return __builtin_amdgcn_rcpf(1.f + __expf(-x)); }
; template <bool LAST>
; DI void phase_gate(const Params& P, int layer, unsigned char* smem, int L, int G) {
;     ...
; #pragma unroll
;     for (int i = 0; i < 4; ++i)
; #pragma unroll
;       for (int q4 = 0; q4 < 4; ++q4) {
;         const int fl = wm * 128 + i * 32 + 8 * q4 + 4 * h;
;         const f32x4 c1v = *(const f32x4*)(vecL + fl), c2v = *(const f32x4*)(vecL + 256 + fl);
;         const float c1a[4] = {c1v.x, c1v.y, c1v.z, c1v.w}, c2a[4] = {c2v.x, c2v.y, c2v.z, c2v.w};
; #pragma unroll
;         for (int j = 0; j < 2; ++j) {
;           const int lrow = wn * 64 + j * 32 + r;
;           const float mu = rowA[lrow], rstd = rowB[lrow];
;           float sg4[4];
; #pragma unroll
;           for (int e = 0; e < 4; ++e) sg4[e] = sigmoidf_(rstd * (accu[i][j][4 * q4 + e] - mu * c1a[e]) + c2a[e]);
;           gq[i][j][2 * q4] = pack2(sg4[0], sg4[1]); gq[i][j][2 * q4 + 1] = pack2(sg4[2], sg4[3]);
;         }
;         __builtin_amdgcn_sched_barrier(0);
;       }
	v_fma_f32 v34, v91, v34, v86
	v_fma_f32 v35, -v83, v90, v35
	v_fma_f32 v48, v89, v48, v84
	v_fma_f32 v49, v89, v49, v85
	v_fma_f32 v50, v89, v50, v86
	v_fma_f32 v51, v89, v51, v87
	v_fma_f32 v32, v91, v32, v84
	v_fma_f32 v33, v91, v33, v85
	v_mul_f32_e32 v34, 0xbfb8aa3b, v34
	v_fmac_f32_e32 v87, v91, v35
	v_mul_f32_e32 v48, 0xbfb8aa3b, v48
	v_mul_f32_e32 v49, 0xbfb8aa3b, v49
	v_mul_f32_e32 v50, 0xbfb8aa3b, v50
	v_mul_f32_e32 v51, 0xbfb8aa3b, v51
	v_mul_f32_e32 v32, 0xbfb8aa3b, v32
	v_mul_f32_e32 v33, 0xbfb8aa3b, v33
	v_exp_f32_e32 v34, v34
	v_mul_f32_e32 v35, 0xbfb8aa3b, v87
	v_exp_f32_e32 v48, v48
	v_exp_f32_e32 v49, v49
	v_exp_f32_e32 v50, v50
	v_exp_f32_e32 v51, v51
	v_exp_f32_e32 v32, v32
	v_exp_f32_e32 v33, v33
	v_exp_f32_e32 v35, v35
	v_add_f32_e32 v34, 1.0, v34
	v_add_f32_e32 v48, 1.0, v48
	v_add_f32_e32 v49, 1.0, v49
	v_add_f32_e32 v50, 1.0, v50
	v_add_f32_e32 v51, 1.0, v51
	v_add_f32_e32 v32, 1.0, v32
	v_add_f32_e32 v33, 1.0, v33
	v_rcp_f32_e32 v80, v34
	v_add_f32_e32 v34, 1.0, v35
	v_rcp_f32_e32 v48, v48
	v_rcp_f32_e32 v49, v49
	v_rcp_f32_e32 v50, v50
	v_rcp_f32_e32 v51, v51
	v_rcp_f32_e32 v32, v32
	v_rcp_f32_e32 v33, v33
	v_rcp_f32_e32 v81, v34
	v_cvt_pk_bf16_f32 v35, v48, v49
	v_cvt_pk_bf16_f32 v34, v50, v51
	v_cvt_pk_bf16_f32 v33, v32, v33
	v_cvt_pk_bf16_f32 v32, v80, v81
	v_add_u32_e32 v48, 0x24920, v160
	v_add_u32_e32 v80, 0x24d20, v160
	ds_read_b128 v[48:51], v48
	ds_read_b128 v[80:83], v80
	ds_read_b32 v84, v164
	ds_read_b32 v85, v165
	ds_read_b32 v86, v166
	ds_read_b32 v87, v167
	s_waitcnt lgkmcnt(3)
	v_fma_f32 v53, -v49, v84, v53
	v_fma_f32 v52, -v48, v84, v52
	s_waitcnt lgkmcnt(1)
	v_fma_f32 v36, -v48, v86, v36
	s_waitcnt lgkmcnt(0)
	v_fma_f32 v36, v87, v36, v80
	v_fma_f32 v37, -v49, v86, v37
	v_mul_f32_e32 v36, 0xbfb8aa3b, v36
	v_fma_f32 v37, v87, v37, v81
	v_exp_f32_e32 v36, v36
	v_mul_f32_e32 v37, 0xbfb8aa3b, v37
	v_exp_f32_e32 v37, v37
	v_fma_f32 v54, -v50, v84, v54
	v_add_f32_e32 v36, 1.0, v36
	v_rcp_f32_e32 v49, v36
	v_add_f32_e32 v36, 1.0, v37
	v_fma_f32 v37, -v50, v86, v38
	v_fma_f32 v55, -v51, v84, v55
	v_fma_f32 v37, v87, v37, v82
	v_fma_f32 v38, -v51, v86, v39
	v_fma_f32 v52, v85, v52, v80
	v_fma_f32 v53, v85, v53, v81
	v_fma_f32 v54, v85, v54, v82
	v_fma_f32 v55, v85, v55, v83
	v_mul_f32_e32 v37, 0xbfb8aa3b, v37
	v_fmac_f32_e32 v83, v87, v38
	v_mul_f32_e32 v52, 0xbfb8aa3b, v52
	v_mul_f32_e32 v53, 0xbfb8aa3b, v53
	v_mul_f32_e32 v54, 0xbfb8aa3b, v54
	v_mul_f32_e32 v55, 0xbfb8aa3b, v55
	v_exp_f32_e32 v37, v37
	v_mul_f32_e32 v38, 0xbfb8aa3b, v83
	v_exp_f32_e32 v52, v52
	v_exp_f32_e32 v53, v53
	v_exp_f32_e32 v54, v54
	v_exp_f32_e32 v55, v55
	v_exp_f32_e32 v38, v38
	v_rcp_f32_e32 v39, v36
	v_add_f32_e32 v36, 1.0, v37
	v_add_f32_e32 v52, 1.0, v52
	v_add_f32_e32 v53, 1.0, v53
	v_add_f32_e32 v54, 1.0, v54
	v_add_f32_e32 v55, 1.0, v55
	v_rcp_f32_e32 v37, v36
	v_add_f32_e32 v36, 1.0, v38
	v_rcp_f32_e32 v52, v52
	v_rcp_f32_e32 v53, v53
	v_rcp_f32_e32 v54, v54
	v_rcp_f32_e32 v48, v55
	v_rcp_f32_e32 v50, v36
	v_cvt_pk_bf16_f32 v80, v52, v53
	v_cvt_pk_bf16_f32 v38, v49, v39
	v_cvt_pk_bf16_f32 v36, v54, v48
	v_cvt_pk_bf16_f32 v37, v37, v50
	v_add_u32_e32 v39, 0x24940, v160
	v_add_u32_e32 v52, 0x24d40, v160
	ds_read_b128 v[48:51], v39
	ds_read_b128 v[52:55], v52
	ds_read_b32 v39, v164
	ds_read_b32 v81, v165
	ds_read_b32 v82, v166
	ds_read_b32 v83, v167
	s_waitcnt lgkmcnt(3)
	v_fma_f32 v56, -v48, v39, v56
	v_fma_f32 v57, -v49, v39, v57
	v_fma_f32 v58, -v50, v39, v58
	v_fma_f32 v39, -v51, v39, v59
	s_waitcnt lgkmcnt(1)
	v_fma_f32 v40, -v48, v82, v40
	v_fma_f32 v41, -v49, v82, v41
	v_fma_f32 v42, -v50, v82, v42
	v_fma_f32 v43, -v51, v82, v43
	v_fma_f32 v56, v81, v56, v52
	v_fma_f32 v57, v81, v57, v53
	v_fma_f32 v58, v81, v58, v54
	v_fma_f32 v39, v81, v39, v55
	s_waitcnt lgkmcnt(0)
	v_fma_f32 v40, v83, v40, v52
	v_fma_f32 v41, v83, v41, v53
	v_fma_f32 v42, v83, v42, v54
	v_fmac_f32_e32 v55, v83, v43
	v_mul_f32_e32 v56, 0xbfb8aa3b, v56
	v_mul_f32_e32 v57, 0xbfb8aa3b, v57
	v_mul_f32_e32 v58, 0xbfb8aa3b, v58
	v_mul_f32_e32 v39, 0xbfb8aa3b, v39
	v_mul_f32_e32 v40, 0xbfb8aa3b, v40
	v_mul_f32_e32 v41, 0xbfb8aa3b, v41
	v_mul_f32_e32 v42, 0xbfb8aa3b, v42
	v_mul_f32_e32 v43, 0xbfb8aa3b, v55
	v_exp_f32_e32 v56, v56
	v_exp_f32_e32 v57, v57
	v_exp_f32_e32 v58, v58
	v_exp_f32_e32 v39, v39
	v_exp_f32_e32 v40, v40
	v_exp_f32_e32 v41, v41
	v_exp_f32_e32 v42, v42
	v_exp_f32_e32 v43, v43
	v_add_f32_e32 v56, 1.0, v56
	v_add_f32_e32 v57, 1.0, v57
	v_add_f32_e32 v58, 1.0, v58
	v_add_f32_e32 v39, 1.0, v39
	v_add_f32_e32 v40, 1.0, v40
	v_add_f32_e32 v41, 1.0, v41
	v_add_f32_e32 v42, 1.0, v42
	v_add_f32_e32 v43, 1.0, v43
	v_rcp_f32_e32 v56, v56
	v_rcp_f32_e32 v57, v57
	v_rcp_f32_e32 v58, v58
	v_rcp_f32_e32 v39, v39
	v_rcp_f32_e32 v40, v40
	v_rcp_f32_e32 v41, v41
	v_rcp_f32_e32 v42, v42
	v_rcp_f32_e32 v43, v43
	v_cvt_pk_bf16_f32 v87, v56, v57
	v_cvt_pk_bf16_f32 v83, v58, v39
	v_cvt_pk_bf16_f32 v82, v40, v41
	v_cvt_pk_bf16_f32 v81, v42, v43
	v_add_u32_e32 v39, 0x24960, v160
	v_add_u32_e32 v48, 0x24d60, v160
	ds_read_b128 v[40:43], v39
	ds_read_b128 v[48:51], v48
	ds_read_b32 v39, v164
	ds_read_b32 v52, v165
	ds_read_b32 v53, v166
	ds_read_b32 v54, v167
	s_waitcnt lgkmcnt(3)
	v_fma_f32 v56, -v41, v39, v61
	v_fma_f32 v55, -v40, v39, v60
	s_waitcnt lgkmcnt(2)
	v_fma_f32 v56, v52, v56, v49
	v_fma_f32 v57, -v42, v39, v62
	v_fma_f32 v39, -v43, v39, v63
	s_waitcnt lgkmcnt(1)
	v_fma_f32 v40, -v40, v53, v44
	v_fma_f32 v41, -v41, v53, v45
	v_fma_f32 v42, -v42, v53, v46
	v_fma_f32 v43, -v43, v53, v47
	v_fma_f32 v55, v52, v55, v48
	v_mul_f32_e32 v56, 0xbfb8aa3b, v56
	v_fma_f32 v57, v52, v57, v50
	v_fma_f32 v39, v52, v39, v51
	s_waitcnt lgkmcnt(0)
; DI unsigned pack2(float a, float b) { f32x2_t v = {a, b}; bf16x2_t r = __builtin_convertvector(v, bf16x2_t); return __builtin_bit_cast(unsigned, r); }
; DI float sigmoidf_(float x) { return __builtin_amdgcn_rcpf(1.f + __expf(-x)); }
; template <bool LAST>
; DI void phase_gate(const Params& P, int layer, unsigned char* smem, int L, int G) {
;     ...
; #pragma unroll
;     for (int i = 0; i < 4; ++i)
; #pragma unroll
;       for (int q4 = 0; q4 < 4; ++q4) {
;         const int fl = wm * 128 + i * 32 + 8 * q4 + 4 * h;
;         const f32x4 c1v = *(const f32x4*)(vecL + fl), c2v = *(const f32x4*)(vecL + 256 + fl);
;         const float c1a[4] = {c1v.x, c1v.y, c1v.z, c1v.w}, c2a[4] = {c2v.x, c2v.y, c2v.z, c2v.w};
; #pragma unroll
;         for (int j = 0; j < 2; ++j) {
;           const int lrow = wn * 64 + j * 32 + r;
;           const float mu = rowA[lrow], rstd = rowB[lrow];
;           float sg4[4];
; #pragma unroll
;           for (int e = 0; e < 4; ++e) sg4[e] = sigmoidf_(rstd * (accu[i][j][4 * q4 + e] - mu * c1a[e]) + c2a[e]);
;           gq[i][j][2 * q4] = pack2(sg4[0], sg4[1]); gq[i][j][2 * q4 + 1] = pack2(sg4[2], sg4[3]);
;         }
;         __builtin_amdgcn_sched_barrier(0);
;       }
	v_fma_f32 v40, v54, v40, v48
	v_fma_f32 v41, v54, v41, v49
	v_fma_f32 v42, v54, v42, v50
	v_fmac_f32_e32 v51, v54, v43
	v_mul_f32_e32 v55, 0xbfb8aa3b, v55
	v_exp_f32_e32 v56, v56
	v_mul_f32_e32 v57, 0xbfb8aa3b, v57
	v_mul_f32_e32 v39, 0xbfb8aa3b, v39
	v_mul_f32_e32 v40, 0xbfb8aa3b, v40
	v_mul_f32_e32 v41, 0xbfb8aa3b, v41
	v_mul_f32_e32 v42, 0xbfb8aa3b, v42
	v_mul_f32_e32 v43, 0xbfb8aa3b, v51
	v_exp_f32_e32 v55, v55
	v_exp_f32_e32 v57, v57
	v_exp_f32_e32 v39, v39
	v_exp_f32_e32 v40, v40
	v_exp_f32_e32 v41, v41
	v_exp_f32_e32 v42, v42
	v_exp_f32_e32 v43, v43
	v_add_f32_e32 v56, 1.0, v56
	v_add_f32_e32 v55, 1.0, v55
	v_rcp_f32_e32 v52, v56
	v_add_f32_e32 v56, 1.0, v57
	v_add_f32_e32 v39, 1.0, v39
	v_add_f32_e32 v40, 1.0, v40
	v_add_f32_e32 v41, 1.0, v41
	v_add_f32_e32 v42, 1.0, v42
	v_add_f32_e32 v43, 1.0, v43
	v_rcp_f32_e32 v55, v55
	v_rcp_f32_e32 v56, v56
	v_rcp_f32_e32 v39, v39
	v_rcp_f32_e32 v40, v40
	v_rcp_f32_e32 v41, v41
	v_rcp_f32_e32 v42, v42
	v_rcp_f32_e32 v43, v43
	v_cvt_pk_bf16_f32 v93, v55, v52
	v_cvt_pk_bf16_f32 v90, v56, v39
	v_cvt_pk_bf16_f32 v89, v40, v41
	v_cvt_pk_bf16_f32 v88, v42, v43
	v_add_u32_e32 v39, 0x24980, v160
	v_add_u32_e32 v44, 0x24d80, v160
	ds_read_b128 v[40:43], v39
	ds_read_b128 v[44:47], v44
	ds_read_b32 v39, v164
	ds_read_b32 v48, v165
	ds_read_b32 v49, v166
	ds_read_b32 v50, v167
	s_waitcnt lgkmcnt(3)
	v_fma_f32 v16, -v40, v39, v16
	v_fma_f32 v17, -v41, v39, v17
	v_fma_f32 v18, -v42, v39, v18
	v_fma_f32 v19, -v43, v39, v19
	s_waitcnt lgkmcnt(1)
	v_fma_f32 v0, -v40, v49, v0
	v_fma_f32 v1, -v41, v49, v1
	v_fma_f32 v2, -v42, v49, v2
	v_fma_f32 v3, -v43, v49, v3
	v_fma_f32 v16, v48, v16, v44
	v_fma_f32 v17, v48, v17, v45
	v_fma_f32 v18, v48, v18, v46
	v_fma_f32 v19, v48, v19, v47
	s_waitcnt lgkmcnt(0)
	v_fma_f32 v0, v50, v0, v44
	v_fma_f32 v1, v50, v1, v45
	v_fma_f32 v2, v50, v2, v46
	v_fmac_f32_e32 v47, v50, v3
	v_mul_f32_e32 v16, 0xbfb8aa3b, v16
	v_mul_f32_e32 v17, 0xbfb8aa3b, v17
	v_mul_f32_e32 v18, 0xbfb8aa3b, v18
	v_mul_f32_e32 v19, 0xbfb8aa3b, v19
	v_mul_f32_e32 v0, 0xbfb8aa3b, v0
	v_mul_f32_e32 v1, 0xbfb8aa3b, v1
	v_mul_f32_e32 v2, 0xbfb8aa3b, v2
	v_mul_f32_e32 v3, 0xbfb8aa3b, v47
	v_exp_f32_e32 v16, v16
	v_exp_f32_e32 v17, v17
	v_exp_f32_e32 v18, v18
	v_exp_f32_e32 v19, v19
	v_exp_f32_e32 v0, v0
	v_exp_f32_e32 v1, v1
	v_exp_f32_e32 v2, v2
	v_exp_f32_e32 v3, v3
	v_add_f32_e32 v16, 1.0, v16
	v_add_f32_e32 v17, 1.0, v17
	v_add_f32_e32 v18, 1.0, v18
	v_add_f32_e32 v19, 1.0, v19
	v_add_f32_e32 v0, 1.0, v0
	v_add_f32_e32 v1, 1.0, v1
	v_add_f32_e32 v2, 1.0, v2
	v_add_f32_e32 v3, 1.0, v3
	v_rcp_f32_e32 v16, v16
	v_rcp_f32_e32 v17, v17
	v_rcp_f32_e32 v18, v18
	v_rcp_f32_e32 v19, v19
	v_rcp_f32_e32 v0, v0
	v_rcp_f32_e32 v1, v1
	v_rcp_f32_e32 v2, v2
	v_rcp_f32_e32 v3, v3
	v_cvt_pk_bf16_f32 v17, v16, v17
	v_cvt_pk_bf16_f32 v19, v18, v19
	v_cvt_pk_bf16_f32 v16, v0, v1
	v_cvt_pk_bf16_f32 v18, v2, v3
	v_add_u32_e32 v0, 0x249a0, v160
	v_add_u32_e32 v39, 0x24da0, v160
	ds_read_b128 v[0:3], v0
	ds_read_b128 v[40:43], v39
	ds_read_b32 v39, v164
	ds_read_b32 v44, v165
	ds_read_b32 v45, v166
	ds_read_b32 v46, v167
	s_waitcnt lgkmcnt(3)
	v_fma_f32 v20, -v0, v39, v20
	v_fma_f32 v21, -v1, v39, v21
	v_fma_f32 v22, -v2, v39, v22
	v_fma_f32 v23, -v3, v39, v23
	s_waitcnt lgkmcnt(1)
	v_fma_f32 v0, -v0, v45, v4
	v_fma_f32 v1, -v1, v45, v5
	v_fma_f32 v2, -v2, v45, v6
	v_fma_f32 v3, -v3, v45, v7
	v_fma_f32 v20, v44, v20, v40
	v_fma_f32 v21, v44, v21, v41
	v_fma_f32 v22, v44, v22, v42
	v_fma_f32 v23, v44, v23, v43
	s_waitcnt lgkmcnt(0)
	v_fma_f32 v0, v46, v0, v40
	v_fma_f32 v1, v46, v1, v41
	v_fma_f32 v2, v46, v2, v42
	v_fmac_f32_e32 v43, v46, v3
	v_mul_f32_e32 v20, 0xbfb8aa3b, v20
	v_mul_f32_e32 v21, 0xbfb8aa3b, v21
	v_mul_f32_e32 v22, 0xbfb8aa3b, v22
	v_mul_f32_e32 v23, 0xbfb8aa3b, v23
	v_mul_f32_e32 v0, 0xbfb8aa3b, v0
	v_mul_f32_e32 v1, 0xbfb8aa3b, v1
	v_mul_f32_e32 v2, 0xbfb8aa3b, v2
	v_mul_f32_e32 v3, 0xbfb8aa3b, v43
	v_exp_f32_e32 v20, v20
	v_exp_f32_e32 v21, v21
	v_exp_f32_e32 v22, v22
	v_exp_f32_e32 v23, v23
	v_exp_f32_e32 v0, v0
	v_exp_f32_e32 v1, v1
	v_exp_f32_e32 v2, v2
	v_exp_f32_e32 v3, v3
	v_add_f32_e32 v20, 1.0, v20
	v_add_f32_e32 v21, 1.0, v21
	v_add_f32_e32 v22, 1.0, v22
	v_add_f32_e32 v23, 1.0, v23
	v_add_f32_e32 v0, 1.0, v0
	v_add_f32_e32 v1, 1.0, v1
	v_add_f32_e32 v2, 1.0, v2
	v_add_f32_e32 v3, 1.0, v3
	v_rcp_f32_e32 v20, v20
	v_rcp_f32_e32 v21, v21
	v_rcp_f32_e32 v22, v22
	v_rcp_f32_e32 v4, v23
	v_rcp_f32_e32 v0, v0
	v_rcp_f32_e32 v1, v1
	v_rcp_f32_e32 v2, v2
	v_rcp_f32_e32 v3, v3
	v_cvt_pk_bf16_f32 v7, v20, v21
	v_cvt_pk_bf16_f32 v6, v22, v4
	v_cvt_pk_bf16_f32 v5, v0, v1
	v_cvt_pk_bf16_f32 v4, v2, v3
	v_add_u32_e32 v0, 0x249c0, v160
	v_add_u32_e32 v20, 0x24dc0, v160
	ds_read_b128 v[0:3], v0
	ds_read_b128 v[20:23], v20
	ds_read_b32 v39, v164
	ds_read_b32 v40, v165
	ds_read_b32 v41, v166
	ds_read_b32 v42, v167
	s_waitcnt lgkmcnt(3)
	v_fma_f32 v24, -v0, v39, v24
	v_fma_f32 v25, -v1, v39, v25
	v_fma_f32 v26, -v2, v39, v26
	v_fma_f32 v27, -v3, v39, v27
	s_waitcnt lgkmcnt(1)
	v_fma_f32 v0, -v0, v41, v8
	v_fma_f32 v1, -v1, v41, v9
	v_fma_f32 v2, -v2, v41, v10
	v_fma_f32 v3, -v3, v41, v11
	v_fma_f32 v24, v40, v24, v20
	v_fma_f32 v25, v40, v25, v21
	v_fma_f32 v26, v40, v26, v22
	v_fma_f32 v27, v40, v27, v23
	s_waitcnt lgkmcnt(0)
; DI unsigned pack2(float a, float b) { f32x2_t v = {a, b}; bf16x2_t r = __builtin_convertvector(v, bf16x2_t); return __builtin_bit_cast(unsigned, r); }
; DI float sigmoidf_(float x) { return __builtin_amdgcn_rcpf(1.f + __expf(-x)); }
; DI int otid() { int t = threadIdx.x; asm volatile("" : "+v"(t)); return t; }
; template <bool NT>
; DI void stage_load_tile(bf16_t* stg, const bf16_t* tilebase) {
;   const int tid = otid();
;   const int r0 = tid >> 5, c = tid & 31;
;   const unsigned o0 = (unsigned)(r0 * 1024 + c * 8);
;   __builtin_amdgcn_sched_barrier(0);
; #pragma unroll
;   for (int hf = 0; hf < 2; ++hf) {
; #pragma unroll
;     for (int it = 8 * hf; it < 8 * hf + 8; ++it) {
;       const u32x4* gp = (const u32x4*)(tilebase + (o0 + (unsigned)(it * 16 * 1024)));
;       stage_write16(stg, r0 + 16 * it, c, NT ? __builtin_nontemporal_load(gp) : *gp);
;     }
;     __builtin_amdgcn_sched_barrier(0);
;   }
; template <bool LAST>
; DI void phase_gate(const Params& P, int layer, unsigned char* smem, int L, int G) {
;     ...
;           for (int e = 0; e < 4; ++e) sg4[e] = sigmoidf_(rstd * (accu[i][j][4 * q4 + e] - mu * c1a[e]) + c2a[e]);
;           gq[i][j][2 * q4] = pack2(sg4[0], sg4[1]); gq[i][j][2 * q4 + 1] = pack2(sg4[2], sg4[3]);
;         }
;         __builtin_amdgcn_sched_barrier(0);
;       }
;     stage_load_tile<true>(stg, PPb + (size_t)mt * 256 * 1024 + nt * 256);
	v_fma_f32 v0, v42, v0, v20
	v_fma_f32 v1, v42, v1, v21
	v_fma_f32 v2, v42, v2, v22
	v_fmac_f32_e32 v23, v42, v3
	v_mul_f32_e32 v24, 0xbfb8aa3b, v24
	v_mul_f32_e32 v25, 0xbfb8aa3b, v25
	v_mul_f32_e32 v26, 0xbfb8aa3b, v26
	v_mul_f32_e32 v27, 0xbfb8aa3b, v27
	v_mul_f32_e32 v0, 0xbfb8aa3b, v0
	v_mul_f32_e32 v1, 0xbfb8aa3b, v1
	v_mul_f32_e32 v2, 0xbfb8aa3b, v2
	v_mul_f32_e32 v3, 0xbfb8aa3b, v23
	v_exp_f32_e32 v24, v24
	v_exp_f32_e32 v25, v25
	v_exp_f32_e32 v26, v26
	v_exp_f32_e32 v27, v27
	v_exp_f32_e32 v0, v0
	v_exp_f32_e32 v1, v1
	v_exp_f32_e32 v2, v2
	v_exp_f32_e32 v3, v3
	v_add_f32_e32 v24, 1.0, v24
	v_add_f32_e32 v25, 1.0, v25
	v_add_f32_e32 v26, 1.0, v26
	v_add_f32_e32 v27, 1.0, v27
	v_add_f32_e32 v0, 1.0, v0
	v_add_f32_e32 v1, 1.0, v1
	v_add_f32_e32 v2, 1.0, v2
	v_add_f32_e32 v3, 1.0, v3
	v_rcp_f32_e32 v24, v24
	v_rcp_f32_e32 v25, v25
	v_rcp_f32_e32 v26, v26
	v_rcp_f32_e32 v8, v27
	v_rcp_f32_e32 v0, v0
	v_rcp_f32_e32 v1, v1
	v_rcp_f32_e32 v2, v2
	v_rcp_f32_e32 v3, v3
	v_cvt_pk_bf16_f32 v9, v24, v25
	v_cvt_pk_bf16_f32 v11, v26, v8
	v_cvt_pk_bf16_f32 v8, v0, v1
	v_cvt_pk_bf16_f32 v10, v2, v3
	v_add_u32_e32 v20, 0x24de0, v160
	ds_read_b128 v[0:3], v163 offset:480
	ds_read_b32 v24, v164
	ds_read_b128 v[20:23], v20
	ds_read_b32 v25, v165
	ds_read_b32 v26, v166
	s_waitcnt lgkmcnt(3)
	v_fma_f32 v27, -v0, v24, v28
	ds_read_b32 v28, v167
	v_fma_f32 v29, -v1, v24, v29
	s_waitcnt lgkmcnt(2)
	v_fma_f32 v29, v25, v29, v21
	v_fma_f32 v30, -v2, v24, v30
	v_fma_f32 v24, -v3, v24, v31
	s_waitcnt lgkmcnt(1)
	v_fma_f32 v0, -v0, v26, v12
	v_fma_f32 v1, -v1, v26, v13
	v_fma_f32 v2, -v2, v26, v14
	v_fma_f32 v3, -v3, v26, v15
	v_fma_f32 v27, v25, v27, v20
	v_mul_f32_e32 v29, 0xbfb8aa3b, v29
	v_fma_f32 v30, v25, v30, v22
	v_fma_f32 v24, v25, v24, v23
	s_waitcnt lgkmcnt(0)
	v_fma_f32 v0, v28, v0, v20
	v_fma_f32 v1, v28, v1, v21
	v_fma_f32 v2, v28, v2, v22
	v_fmac_f32_e32 v23, v28, v3
	v_mul_f32_e32 v27, 0xbfb8aa3b, v27
	v_exp_f32_e32 v29, v29
	v_mul_f32_e32 v30, 0xbfb8aa3b, v30
	v_mul_f32_e32 v24, 0xbfb8aa3b, v24
	v_mul_f32_e32 v0, 0xbfb8aa3b, v0
	v_mul_f32_e32 v1, 0xbfb8aa3b, v1
	v_mul_f32_e32 v2, 0xbfb8aa3b, v2
	v_mul_f32_e32 v3, 0xbfb8aa3b, v23
	v_exp_f32_e32 v27, v27
	v_exp_f32_e32 v30, v30
	v_exp_f32_e32 v24, v24
	v_exp_f32_e32 v0, v0
	v_exp_f32_e32 v1, v1
	v_exp_f32_e32 v2, v2
	v_exp_f32_e32 v3, v3
	v_add_f32_e32 v29, 1.0, v29
	v_add_f32_e32 v27, 1.0, v27
	v_rcp_f32_e32 v25, v29
	v_add_f32_e32 v29, 1.0, v30
	v_add_f32_e32 v24, 1.0, v24
	v_add_f32_e32 v0, 1.0, v0
	v_add_f32_e32 v1, 1.0, v1
	v_add_f32_e32 v2, 1.0, v2
	v_add_f32_e32 v3, 1.0, v3
	v_rcp_f32_e32 v27, v27
	v_rcp_f32_e32 v29, v29
	v_rcp_f32_e32 v12, v24
	v_rcp_f32_e32 v0, v0
	v_rcp_f32_e32 v1, v1
	v_rcp_f32_e32 v2, v2
	v_rcp_f32_e32 v3, v3
	v_cvt_pk_bf16_f32 v31, v27, v25
	v_cvt_pk_bf16_f32 v30, v29, v12
	v_cvt_pk_bf16_f32 v29, v0, v1
	v_cvt_pk_bf16_f32 v24, v2, v3
	v_mov_b32_e32 v163, v161
	v_lshlrev_b64 v[0:1], 1, v[162:163]
	v_and_b32_e32 v28, 31, v192
	v_ashrrev_i32_e32 v25, 5, v192
	v_mul_lo_u32 v25, v25, s34
	v_lshl_add_u32 v25, v28, 4, v25
	v_add_u32_e32 v26, 0x2080, v25
	v_add_u32_e32 v27, 0x4100, v25
	v_add_u32_e32 v28, 0x6180, v25
	v_add_u32_e32 v39, 0x8200, v25
	v_add_u32_e32 v84, 0xa280, v25
	v_add_u32_e32 v85, 0xc300, v25
	v_add_u32_e32 v86, 0xe380, v25
	s_waitcnt vmcnt(15)
	ds_write2_b64 v25, v[180:181], v[182:183] offset1:1
	s_waitcnt vmcnt(14)
	ds_write2_b64 v26, v[184:185], v[186:187] offset1:1
	s_waitcnt vmcnt(13)
	ds_write2_b64 v27, v[194:195], v[196:197] offset1:1
	s_waitcnt vmcnt(12)
	ds_write2_b64 v28, v[198:199], v[200:201] offset1:1
	s_waitcnt vmcnt(11)
	ds_write2_b64 v39, v[202:203], v[204:205] offset1:1
	s_waitcnt vmcnt(10)
	ds_write2_b64 v84, v[206:207], v[208:209] offset1:1
	s_waitcnt vmcnt(9)
	ds_write2_b64 v85, v[210:211], v[212:213] offset1:1
	s_waitcnt vmcnt(8)
	ds_write2_b64 v86, v[214:215], v[216:217] offset1:1
	v_add_u32_e32 v2, 0x10400, v25
	v_add_u32_e32 v3, 0x12480, v25
	v_add_u32_e32 v26, 0x14500, v25
	v_add_u32_e32 v27, 0x16580, v25
	v_add_u32_e32 v28, 0x18600, v25
	v_add_u32_e32 v39, 0x1a680, v25
	v_add_u32_e32 v84, 0x1c700, v25
	v_add_u32_e32 v25, 0x1e780, v25
	s_waitcnt vmcnt(7)
	ds_write2_b64 v2, v[218:219], v[220:221] offset1:1
	s_waitcnt vmcnt(6)
	ds_write2_b64 v3, v[222:223], v[224:225] offset1:1
	s_waitcnt vmcnt(5)
	ds_write2_b64 v26, v[226:227], v[228:229] offset1:1
	s_waitcnt vmcnt(4)
	ds_write2_b64 v27, v[230:231], v[232:233] offset1:1
	s_waitcnt vmcnt(3)
	ds_write2_b64 v28, v[234:235], v[236:237] offset1:1
	s_waitcnt vmcnt(2)
	ds_write2_b64 v39, v[238:239], v[240:241] offset1:1
	s_waitcnt vmcnt(1)
	ds_write2_b64 v84, v[242:243], v[244:245] offset1:1
	s_waitcnt vmcnt(0)
	ds_write2_b64 v25, v[248:249], v[250:251] offset1:1
	v_mov_b32_e32 v2, v192
	s_waitcnt lgkmcnt(0)
	s_barrier
; DI unsigned pack2(float a, float b) { f32x2_t v = {a, b}; bf16x2_t r = __builtin_convertvector(v, bf16x2_t); return __builtin_bit_cast(unsigned, r); }
; DI float bflo(unsigned u) { return __uint_as_float(u << 16); }
; DI float bfhi(unsigned u) { return __uint_as_float(u & 0xffff0000u); }
; template <bool LAST>
; DI void phase_gate(const Params& P, int layer, unsigned char* smem, int L, int G) {
;     ...
; #pragma unroll
;       for (int i = 0; i < 4; ++i)
; #pragma unroll
;         for (int q4 = 0; q4 < 4; ++q4) {
; #pragma unroll
;           for (int j = 0; j < 2; ++j) {
;             const uint2 pv = *(const uint2*)(stg + (wn1 * 64 + j * 32 + r1) * STG + wm1 * 128 + i * 32 + 8 * q4 + 4 * h1);
;             const unsigned g0 = gq[i][j][2 * q4], g1 = gq[i][j][2 * q4 + 1];
;             gq[i][j][2 * q4] = pack2(bflo(g0) * bflo(pv.x), bfhi(g0) * bfhi(pv.x));
;             gq[i][j][2 * q4 + 1] = pack2(bflo(g1) * bflo(pv.y), bfhi(g1) * bfhi(pv.y));
;           }
;           __builtin_amdgcn_sched_barrier(0);
;         }
	v_and_b32_e32 v13, 0xffff0000, v99
	v_lshrrev_b32_e32 v12, 2, v2
	v_and_b32_e32 v12, 8, v12
	v_and_b32_e32 v3, 0xdf, v2
	v_and_or_b32 v2, v2, s31, v12
	v_mad_u32_u24 v112, v3, s34, v2
	ds_read_b64 v[2:3], v112
	ds_read_b64 v[14:15], v112 offset:16640
	v_lshlrev_b32_e32 v12, 16, v99
	s_waitcnt lgkmcnt(1)
	v_lshlrev_b32_e32 v20, 16, v2
	v_and_b32_e32 v21, 0xffff0000, v2
	v_pk_mul_f32 v[12:13], v[12:13], v[20:21]
	v_lshlrev_b32_e32 v2, 16, v3
	v_cvt_pk_bf16_f32 v99, v12, v13
	v_lshlrev_b32_e32 v12, 16, v98
	v_and_b32_e32 v13, 0xffff0000, v98
	v_and_b32_e32 v3, 0xffff0000, v3
	v_pk_mul_f32 v[2:3], v[12:13], v[2:3]
	s_waitcnt lgkmcnt(0)
	v_lshlrev_b32_e32 v12, 16, v14
	v_cvt_pk_bf16_f32 v98, v2, v3
	v_lshlrev_b32_e32 v2, 16, v97
	v_and_b32_e32 v3, 0xffff0000, v97
	v_and_b32_e32 v13, 0xffff0000, v14
	v_pk_mul_f32 v[2:3], v[2:3], v[12:13]
	v_lshlrev_b32_e32 v12, 16, v15
	v_cvt_pk_bf16_f32 v94, v2, v3
	v_lshlrev_b32_e32 v2, 16, v96
	v_and_b32_e32 v3, 0xffff0000, v96
	v_and_b32_e32 v13, 0xffff0000, v15
	v_pk_mul_f32 v[2:3], v[2:3], v[12:13]
	s_nop 0
	v_cvt_pk_bf16_f32 v95, v2, v3
	ds_read_b64 v[2:3], v112 offset:16
	ds_read_b64 v[14:15], v112 offset:16656
	v_lshlrev_b32_e32 v12, 16, v103
	v_and_b32_e32 v13, 0xffff0000, v103
	s_waitcnt lgkmcnt(1)
	v_lshlrev_b32_e32 v20, 16, v2
	v_and_b32_e32 v21, 0xffff0000, v2
	v_pk_mul_f32 v[12:13], v[12:13], v[20:21]
	v_lshlrev_b32_e32 v20, 16, v3
	v_cvt_pk_bf16_f32 v2, v12, v13
	v_lshlrev_b32_e32 v12, 16, v102
	v_and_b32_e32 v13, 0xffff0000, v102
	v_and_b32_e32 v21, 0xffff0000, v3
	v_pk_mul_f32 v[12:13], v[12:13], v[20:21]
	s_waitcnt lgkmcnt(0)
	v_lshlrev_b32_e32 v20, 16, v14
	v_cvt_pk_bf16_f32 v3, v12, v13
	v_lshlrev_b32_e32 v12, 16, v101
	v_and_b32_e32 v13, 0xffff0000, v101
	v_and_b32_e32 v21, 0xffff0000, v14
	v_pk_mul_f32 v[12:13], v[12:13], v[20:21]
	v_lshlrev_b32_e32 v14, 16, v15
	v_cvt_pk_bf16_f32 v91, v12, v13
	v_lshlrev_b32_e32 v12, 16, v100
	v_and_b32_e32 v13, 0xffff0000, v100
	v_and_b32_e32 v15, 0xffff0000, v15
	v_pk_mul_f32 v[12:13], v[12:13], v[14:15]
	s_nop 0
	v_cvt_pk_bf16_f32 v92, v12, v13
	ds_read_b64 v[12:13], v112 offset:32
	ds_read_b64 v[20:21], v112 offset:16672
	v_lshlrev_b32_e32 v14, 16, v107
	v_and_b32_e32 v15, 0xffff0000, v107
	s_waitcnt lgkmcnt(1)
	v_lshlrev_b32_e32 v22, 16, v12
	v_and_b32_e32 v23, 0xffff0000, v12
	v_pk_mul_f32 v[14:15], v[14:15], v[22:23]
	v_lshlrev_b32_e32 v12, 16, v13
	v_cvt_pk_bf16_f32 v84, v14, v15
	v_lshlrev_b32_e32 v14, 16, v106
	v_and_b32_e32 v15, 0xffff0000, v106
	v_and_b32_e32 v13, 0xffff0000, v13
	v_pk_mul_f32 v[12:13], v[14:15], v[12:13]
	s_waitcnt lgkmcnt(0)
	v_lshlrev_b32_e32 v14, 16, v20
	v_cvt_pk_bf16_f32 v86, v12, v13
	v_lshlrev_b32_e32 v12, 16, v105
	v_and_b32_e32 v13, 0xffff0000, v105
	v_and_b32_e32 v15, 0xffff0000, v20
	v_pk_mul_f32 v[12:13], v[12:13], v[14:15]
	v_lshlrev_b32_e32 v14, 16, v21
	v_cvt_pk_bf16_f32 v63, v12, v13
	v_lshlrev_b32_e32 v12, 16, v104
	v_and_b32_e32 v13, 0xffff0000, v104
	v_and_b32_e32 v15, 0xffff0000, v21
	v_pk_mul_f32 v[12:13], v[12:13], v[14:15]
	s_nop 0
	v_cvt_pk_bf16_f32 v85, v12, v13
	ds_read_b64 v[12:13], v112 offset:48
	ds_read_b64 v[20:21], v112 offset:16688
	v_lshlrev_b32_e32 v14, 16, v111
	v_and_b32_e32 v15, 0xffff0000, v111
	s_waitcnt lgkmcnt(1)
	v_lshlrev_b32_e32 v22, 16, v12
	v_and_b32_e32 v23, 0xffff0000, v12
	v_pk_mul_f32 v[14:15], v[14:15], v[22:23]
	v_lshlrev_b32_e32 v12, 16, v13
	v_cvt_pk_bf16_f32 v60, v14, v15
	v_lshlrev_b32_e32 v14, 16, v110
	v_and_b32_e32 v15, 0xffff0000, v110
	v_and_b32_e32 v13, 0xffff0000, v13
	v_pk_mul_f32 v[12:13], v[14:15], v[12:13]
	s_waitcnt lgkmcnt(0)
	v_lshlrev_b32_e32 v14, 16, v20
	v_cvt_pk_bf16_f32 v62, v12, v13
	v_lshlrev_b32_e32 v12, 16, v109
	v_and_b32_e32 v13, 0xffff0000, v109
	v_and_b32_e32 v15, 0xffff0000, v20
	v_pk_mul_f32 v[12:13], v[12:13], v[14:15]
	v_lshlrev_b32_e32 v14, 16, v21
	v_cvt_pk_bf16_f32 v59, v12, v13
	v_lshlrev_b32_e32 v12, 16, v108
	v_and_b32_e32 v13, 0xffff0000, v108
	v_and_b32_e32 v15, 0xffff0000, v21
	v_pk_mul_f32 v[12:13], v[12:13], v[14:15]
	s_nop 0
	v_cvt_pk_bf16_f32 v61, v12, v13
	ds_read_b64 v[12:13], v112 offset:64
	ds_read_b64 v[20:21], v112 offset:16704
	v_lshlrev_b32_e32 v14, 16, v67
	v_and_b32_e32 v15, 0xffff0000, v67
	s_waitcnt lgkmcnt(1)
	v_lshlrev_b32_e32 v22, 16, v12
	v_and_b32_e32 v23, 0xffff0000, v12
	v_pk_mul_f32 v[14:15], v[14:15], v[22:23]
	v_lshlrev_b32_e32 v12, 16, v13
	v_cvt_pk_bf16_f32 v56, v14, v15
	v_lshlrev_b32_e32 v14, 16, v66
	v_and_b32_e32 v15, 0xffff0000, v66
	v_and_b32_e32 v13, 0xffff0000, v13
	v_pk_mul_f32 v[12:13], v[14:15], v[12:13]
	s_waitcnt lgkmcnt(0)
	v_lshlrev_b32_e32 v14, 16, v20
	v_cvt_pk_bf16_f32 v58, v12, v13
	v_lshlrev_b32_e32 v12, 16, v65
	v_and_b32_e32 v13, 0xffff0000, v65
	v_and_b32_e32 v15, 0xffff0000, v20
	v_pk_mul_f32 v[12:13], v[12:13], v[14:15]
	v_lshlrev_b32_e32 v14, 16, v21
	v_cvt_pk_bf16_f32 v55, v12, v13
	v_lshlrev_b32_e32 v12, 16, v64
	v_and_b32_e32 v13, 0xffff0000, v64
	v_and_b32_e32 v15, 0xffff0000, v21
	v_pk_mul_f32 v[12:13], v[12:13], v[14:15]
	s_nop 0
	v_cvt_pk_bf16_f32 v57, v12, v13
	ds_read_b64 v[12:13], v112 offset:80
	ds_read_b64 v[20:21], v112 offset:16720
	v_lshlrev_b32_e32 v14, 16, v71
	v_and_b32_e32 v15, 0xffff0000, v71
	s_waitcnt lgkmcnt(1)
	v_lshlrev_b32_e32 v22, 16, v12
	v_and_b32_e32 v23, 0xffff0000, v12
	v_pk_mul_f32 v[14:15], v[14:15], v[22:23]
	v_lshlrev_b32_e32 v12, 16, v13
	v_cvt_pk_bf16_f32 v52, v14, v15
	v_lshlrev_b32_e32 v14, 16, v70
	v_and_b32_e32 v15, 0xffff0000, v70
	v_and_b32_e32 v13, 0xffff0000, v13
	v_pk_mul_f32 v[12:13], v[14:15], v[12:13]
	s_waitcnt lgkmcnt(0)
; DI unsigned pack2(float a, float b) { f32x2_t v = {a, b}; bf16x2_t r = __builtin_convertvector(v, bf16x2_t); return __builtin_bit_cast(unsigned, r); }
; DI float bflo(unsigned u) { return __uint_as_float(u << 16); }
; DI float bfhi(unsigned u) { return __uint_as_float(u & 0xffff0000u); }
; template <bool LAST>
; DI void phase_gate(const Params& P, int layer, unsigned char* smem, int L, int G) {
;     ...
; #pragma unroll
;       for (int i = 0; i < 4; ++i)
; #pragma unroll
;         for (int q4 = 0; q4 < 4; ++q4) {
; #pragma unroll
;           for (int j = 0; j < 2; ++j) {
;             const uint2 pv = *(const uint2*)(stg + (wn1 * 64 + j * 32 + r1) * STG + wm1 * 128 + i * 32 + 8 * q4 + 4 * h1);
;             const unsigned g0 = gq[i][j][2 * q4], g1 = gq[i][j][2 * q4 + 1];
;             gq[i][j][2 * q4] = pack2(bflo(g0) * bflo(pv.x), bfhi(g0) * bfhi(pv.x));
;             gq[i][j][2 * q4 + 1] = pack2(bflo(g1) * bflo(pv.y), bfhi(g1) * bfhi(pv.y));
;           }
;           __builtin_amdgcn_sched_barrier(0);
;         }
	v_lshlrev_b32_e32 v14, 16, v20
	v_cvt_pk_bf16_f32 v54, v12, v13
	v_lshlrev_b32_e32 v12, 16, v69
	v_and_b32_e32 v13, 0xffff0000, v69
	v_and_b32_e32 v15, 0xffff0000, v20
	v_pk_mul_f32 v[12:13], v[12:13], v[14:15]
	v_lshlrev_b32_e32 v14, 16, v21
	v_cvt_pk_bf16_f32 v51, v12, v13
	v_lshlrev_b32_e32 v12, 16, v68
	v_and_b32_e32 v13, 0xffff0000, v68
	v_and_b32_e32 v15, 0xffff0000, v21
	v_pk_mul_f32 v[12:13], v[12:13], v[14:15]
	s_nop 0
	v_cvt_pk_bf16_f32 v53, v12, v13
	ds_read_b64 v[12:13], v112 offset:96
	ds_read_b64 v[20:21], v112 offset:16736
	v_lshlrev_b32_e32 v14, 16, v75
	v_and_b32_e32 v15, 0xffff0000, v75
	s_waitcnt lgkmcnt(1)
	v_lshlrev_b32_e32 v22, 16, v12
	v_and_b32_e32 v23, 0xffff0000, v12
	v_pk_mul_f32 v[14:15], v[14:15], v[22:23]
	v_lshlrev_b32_e32 v12, 16, v13
	v_cvt_pk_bf16_f32 v48, v14, v15
	v_lshlrev_b32_e32 v14, 16, v74
	v_and_b32_e32 v15, 0xffff0000, v74
	v_and_b32_e32 v13, 0xffff0000, v13
	v_pk_mul_f32 v[12:13], v[14:15], v[12:13]
	s_waitcnt lgkmcnt(0)
	v_lshlrev_b32_e32 v14, 16, v20
	v_cvt_pk_bf16_f32 v50, v12, v13
	v_lshlrev_b32_e32 v12, 16, v73
	v_and_b32_e32 v13, 0xffff0000, v73
	v_and_b32_e32 v15, 0xffff0000, v20
	v_pk_mul_f32 v[12:13], v[12:13], v[14:15]
	v_lshlrev_b32_e32 v14, 16, v21
	v_cvt_pk_bf16_f32 v47, v12, v13
	v_lshlrev_b32_e32 v12, 16, v72
	v_and_b32_e32 v13, 0xffff0000, v72
	v_and_b32_e32 v15, 0xffff0000, v21
	v_pk_mul_f32 v[12:13], v[12:13], v[14:15]
	s_nop 0
	v_cvt_pk_bf16_f32 v49, v12, v13
	ds_read_b64 v[12:13], v112 offset:112
	ds_read_b64 v[20:21], v112 offset:16752
	v_lshlrev_b32_e32 v14, 16, v79
	v_and_b32_e32 v15, 0xffff0000, v79
	s_waitcnt lgkmcnt(1)
	v_lshlrev_b32_e32 v22, 16, v12
	v_and_b32_e32 v23, 0xffff0000, v12
	v_pk_mul_f32 v[14:15], v[14:15], v[22:23]
	v_lshlrev_b32_e32 v12, 16, v13
	v_cvt_pk_bf16_f32 v44, v14, v15
	v_lshlrev_b32_e32 v14, 16, v78
	v_and_b32_e32 v15, 0xffff0000, v78
	v_and_b32_e32 v13, 0xffff0000, v13
	v_pk_mul_f32 v[12:13], v[14:15], v[12:13]
	s_waitcnt lgkmcnt(0)
	v_lshlrev_b32_e32 v14, 16, v20
	v_cvt_pk_bf16_f32 v46, v12, v13
	v_lshlrev_b32_e32 v12, 16, v77
	v_and_b32_e32 v13, 0xffff0000, v77
	v_and_b32_e32 v15, 0xffff0000, v20
	v_pk_mul_f32 v[12:13], v[12:13], v[14:15]
	v_lshlrev_b32_e32 v14, 16, v21
	v_cvt_pk_bf16_f32 v43, v12, v13
	v_lshlrev_b32_e32 v12, 16, v76
	v_and_b32_e32 v13, 0xffff0000, v76
	v_and_b32_e32 v15, 0xffff0000, v21
	v_pk_mul_f32 v[12:13], v[12:13], v[14:15]
	s_nop 0
	v_cvt_pk_bf16_f32 v45, v12, v13
	ds_read_b64 v[12:13], v112 offset:128
	ds_read_b64 v[20:21], v112 offset:16768
	v_lshlrev_b32_e32 v14, 16, v35
	v_and_b32_e32 v15, 0xffff0000, v35
	s_waitcnt lgkmcnt(1)
	v_lshlrev_b32_e32 v22, 16, v12
	v_and_b32_e32 v23, 0xffff0000, v12
	v_pk_mul_f32 v[14:15], v[14:15], v[22:23]
	v_lshlrev_b32_e32 v12, 16, v13
	v_cvt_pk_bf16_f32 v40, v14, v15
	v_lshlrev_b32_e32 v14, 16, v34
	v_and_b32_e32 v15, 0xffff0000, v34
	v_and_b32_e32 v13, 0xffff0000, v13
	v_pk_mul_f32 v[12:13], v[14:15], v[12:13]
	s_waitcnt lgkmcnt(0)
	v_lshlrev_b32_e32 v14, 16, v20
	v_cvt_pk_bf16_f32 v42, v12, v13
	v_lshlrev_b32_e32 v12, 16, v33
	v_and_b32_e32 v13, 0xffff0000, v33
	v_and_b32_e32 v15, 0xffff0000, v20
	v_pk_mul_f32 v[12:13], v[12:13], v[14:15]
	v_lshlrev_b32_e32 v14, 16, v21
	v_cvt_pk_bf16_f32 v39, v12, v13
	v_lshlrev_b32_e32 v12, 16, v32
	v_and_b32_e32 v13, 0xffff0000, v32
	v_and_b32_e32 v15, 0xffff0000, v21
	v_pk_mul_f32 v[12:13], v[12:13], v[14:15]
	s_nop 0
	v_cvt_pk_bf16_f32 v41, v12, v13
	ds_read_b64 v[12:13], v112 offset:144
	ds_read_b64 v[20:21], v112 offset:16784
	v_lshlrev_b32_e32 v14, 16, v80
	v_and_b32_e32 v15, 0xffff0000, v80
	s_waitcnt lgkmcnt(1)
	v_lshlrev_b32_e32 v22, 16, v12
	v_and_b32_e32 v23, 0xffff0000, v12
	v_pk_mul_f32 v[14:15], v[14:15], v[22:23]
	v_lshlrev_b32_e32 v12, 16, v13
	v_cvt_pk_bf16_f32 v34, v14, v15
	v_lshlrev_b32_e32 v14, 16, v36
	v_and_b32_e32 v15, 0xffff0000, v36
	v_and_b32_e32 v13, 0xffff0000, v13
	v_pk_mul_f32 v[12:13], v[14:15], v[12:13]
	s_waitcnt lgkmcnt(0)
	v_lshlrev_b32_e32 v14, 16, v20
	v_cvt_pk_bf16_f32 v36, v12, v13
	v_lshlrev_b32_e32 v12, 16, v38
	v_and_b32_e32 v13, 0xffff0000, v38
	v_and_b32_e32 v15, 0xffff0000, v20
	v_pk_mul_f32 v[12:13], v[12:13], v[14:15]
	v_lshlrev_b32_e32 v14, 16, v21
	v_cvt_pk_bf16_f32 v33, v12, v13
	v_lshlrev_b32_e32 v12, 16, v37
	v_and_b32_e32 v13, 0xffff0000, v37
	v_and_b32_e32 v15, 0xffff0000, v21
	v_pk_mul_f32 v[12:13], v[12:13], v[14:15]
	s_nop 0
	v_cvt_pk_bf16_f32 v35, v12, v13
	ds_read_b64 v[12:13], v112 offset:160
	ds_read_b64 v[20:21], v112 offset:16800
	v_lshlrev_b32_e32 v14, 16, v87
	v_and_b32_e32 v15, 0xffff0000, v87
	s_waitcnt lgkmcnt(1)
	v_lshlrev_b32_e32 v22, 16, v12
	v_and_b32_e32 v23, 0xffff0000, v12
	v_pk_mul_f32 v[14:15], v[14:15], v[22:23]
	v_lshlrev_b32_e32 v12, 16, v13
	v_cvt_pk_bf16_f32 v26, v14, v15
	v_lshlrev_b32_e32 v14, 16, v83
	v_and_b32_e32 v15, 0xffff0000, v83
	v_and_b32_e32 v13, 0xffff0000, v13
	v_pk_mul_f32 v[12:13], v[14:15], v[12:13]
	s_waitcnt lgkmcnt(0)
	v_lshlrev_b32_e32 v14, 16, v20
	v_cvt_pk_bf16_f32 v28, v12, v13
	v_lshlrev_b32_e32 v12, 16, v82
	v_and_b32_e32 v13, 0xffff0000, v82
	v_and_b32_e32 v15, 0xffff0000, v20
	v_pk_mul_f32 v[12:13], v[12:13], v[14:15]
	v_lshlrev_b32_e32 v14, 16, v21
	v_cvt_pk_bf16_f32 v25, v12, v13
	v_lshlrev_b32_e32 v12, 16, v81
	v_and_b32_e32 v13, 0xffff0000, v81
	v_and_b32_e32 v15, 0xffff0000, v21
	v_pk_mul_f32 v[12:13], v[12:13], v[14:15]
	s_nop 0
	v_cvt_pk_bf16_f32 v27, v12, v13
	ds_read_b64 v[12:13], v112 offset:176
	ds_read_b64 v[64:65], v112 offset:16816
	v_lshlrev_b32_e32 v14, 16, v93
	v_and_b32_e32 v15, 0xffff0000, v93
	s_waitcnt lgkmcnt(1)
; DI unsigned pack2(float a, float b) { f32x2_t v = {a, b}; bf16x2_t r = __builtin_convertvector(v, bf16x2_t); return __builtin_bit_cast(unsigned, r); }
; DI float bflo(unsigned u) { return __uint_as_float(u << 16); }
; DI float bfhi(unsigned u) { return __uint_as_float(u & 0xffff0000u); }
; template <bool LAST>
; DI void phase_gate(const Params& P, int layer, unsigned char* smem, int L, int G) {
;     ...
; #pragma unroll
;       for (int i = 0; i < 4; ++i)
; #pragma unroll
;         for (int q4 = 0; q4 < 4; ++q4) {
; #pragma unroll
;           for (int j = 0; j < 2; ++j) {
;             const uint2 pv = *(const uint2*)(stg + (wn1 * 64 + j * 32 + r1) * STG + wm1 * 128 + i * 32 + 8 * q4 + 4 * h1);
;             const unsigned g0 = gq[i][j][2 * q4], g1 = gq[i][j][2 * q4 + 1];
;             gq[i][j][2 * q4] = pack2(bflo(g0) * bflo(pv.x), bfhi(g0) * bfhi(pv.x));
;             gq[i][j][2 * q4 + 1] = pack2(bflo(g1) * bflo(pv.y), bfhi(g1) * bfhi(pv.y));
;           }
;           __builtin_amdgcn_sched_barrier(0);
;         }
	v_lshlrev_b32_e32 v20, 16, v12
	v_and_b32_e32 v21, 0xffff0000, v12
	v_pk_mul_f32 v[14:15], v[14:15], v[20:21]
	v_lshlrev_b32_e32 v12, 16, v13
	v_cvt_pk_bf16_f32 v21, v14, v15
	v_lshlrev_b32_e32 v14, 16, v90
	v_and_b32_e32 v15, 0xffff0000, v90
	v_and_b32_e32 v13, 0xffff0000, v13
	v_pk_mul_f32 v[12:13], v[14:15], v[12:13]
	s_waitcnt lgkmcnt(0)
	v_lshlrev_b32_e32 v14, 16, v64
	v_cvt_pk_bf16_f32 v23, v12, v13
	v_lshlrev_b32_e32 v12, 16, v89
	v_and_b32_e32 v13, 0xffff0000, v89
	v_and_b32_e32 v15, 0xffff0000, v64
	v_pk_mul_f32 v[12:13], v[12:13], v[14:15]
	v_lshlrev_b32_e32 v14, 16, v65
	v_cvt_pk_bf16_f32 v20, v12, v13
	v_lshlrev_b32_e32 v12, 16, v88
	v_and_b32_e32 v13, 0xffff0000, v88
	v_and_b32_e32 v15, 0xffff0000, v65
	v_pk_mul_f32 v[12:13], v[12:13], v[14:15]
	s_nop 0
	v_cvt_pk_bf16_f32 v22, v12, v13
	ds_read_b64 v[12:13], v112 offset:192
	ds_read_b64 v[64:65], v112 offset:16832
	v_lshlrev_b32_e32 v14, 16, v17
	v_and_b32_e32 v15, 0xffff0000, v17
	s_waitcnt lgkmcnt(1)
	v_lshlrev_b32_e32 v66, 16, v12
	v_and_b32_e32 v67, 0xffff0000, v12
	v_pk_mul_f32 v[14:15], v[14:15], v[66:67]
	v_lshlrev_b32_e32 v12, 16, v13
	v_cvt_pk_bf16_f32 v17, v14, v15
	v_lshlrev_b32_e32 v14, 16, v19
	v_and_b32_e32 v15, 0xffff0000, v19
	v_and_b32_e32 v13, 0xffff0000, v13
	v_pk_mul_f32 v[12:13], v[14:15], v[12:13]
	s_waitcnt lgkmcnt(0)
	v_lshlrev_b32_e32 v14, 16, v64
	v_cvt_pk_bf16_f32 v19, v12, v13
	v_lshlrev_b32_e32 v12, 16, v16
	v_and_b32_e32 v13, 0xffff0000, v16
	v_and_b32_e32 v15, 0xffff0000, v64
	v_pk_mul_f32 v[12:13], v[12:13], v[14:15]
	v_lshlrev_b32_e32 v14, 16, v65
	v_cvt_pk_bf16_f32 v16, v12, v13
	v_lshlrev_b32_e32 v12, 16, v18
	v_and_b32_e32 v13, 0xffff0000, v18
	v_and_b32_e32 v15, 0xffff0000, v65
	v_pk_mul_f32 v[12:13], v[12:13], v[14:15]
	s_nop 0
	v_cvt_pk_bf16_f32 v18, v12, v13
	ds_read_b64 v[14:15], v112 offset:208
	ds_read_b64 v[64:65], v112 offset:16848
	v_lshlrev_b32_e32 v12, 16, v7
	v_and_b32_e32 v13, 0xffff0000, v7
	s_waitcnt lgkmcnt(1)
	v_lshlrev_b32_e32 v66, 16, v14
	v_and_b32_e32 v67, 0xffff0000, v14
	v_pk_mul_f32 v[12:13], v[12:13], v[66:67]
	v_lshlrev_b32_e32 v66, 16, v6
	v_lshlrev_b32_e32 v14, 16, v15
	v_and_b32_e32 v67, 0xffff0000, v6
	v_and_b32_e32 v15, 0xffff0000, v15
	v_pk_mul_f32 v[6:7], v[66:67], v[14:15]
	s_waitcnt lgkmcnt(0)
	v_lshlrev_b32_e32 v66, 16, v64
	v_cvt_pk_bf16_f32 v15, v6, v7
	v_lshlrev_b32_e32 v6, 16, v5
	v_and_b32_e32 v7, 0xffff0000, v5
	v_and_b32_e32 v67, 0xffff0000, v64
	v_pk_mul_f32 v[6:7], v[6:7], v[66:67]
	v_cvt_pk_bf16_f32 v13, v12, v13
	v_cvt_pk_bf16_f32 v12, v6, v7
	v_lshlrev_b32_e32 v6, 16, v4
	v_lshlrev_b32_e32 v64, 16, v65
	v_and_b32_e32 v7, 0xffff0000, v4
	v_and_b32_e32 v65, 0xffff0000, v65
	v_pk_mul_f32 v[4:5], v[6:7], v[64:65]
	s_nop 0
	v_cvt_pk_bf16_f32 v14, v4, v5
	ds_read_b64 v[4:5], v112 offset:224
	ds_read_b64 v[64:65], v112 offset:16864
	v_lshlrev_b32_e32 v6, 16, v9
	v_and_b32_e32 v7, 0xffff0000, v9
	s_waitcnt lgkmcnt(1)
	v_lshlrev_b32_e32 v66, 16, v4
	v_and_b32_e32 v67, 0xffff0000, v4
	v_pk_mul_f32 v[6:7], v[6:7], v[66:67]
	v_lshlrev_b32_e32 v4, 16, v5
	v_cvt_pk_bf16_f32 v9, v6, v7
	v_lshlrev_b32_e32 v6, 16, v11
	v_and_b32_e32 v7, 0xffff0000, v11
	v_and_b32_e32 v5, 0xffff0000, v5
	v_pk_mul_f32 v[4:5], v[6:7], v[4:5]
	s_waitcnt lgkmcnt(0)
	v_lshlrev_b32_e32 v6, 16, v64
	v_cvt_pk_bf16_f32 v11, v4, v5
	v_lshlrev_b32_e32 v4, 16, v8
	v_and_b32_e32 v5, 0xffff0000, v8
	v_and_b32_e32 v7, 0xffff0000, v64
	v_pk_mul_f32 v[4:5], v[4:5], v[6:7]
	v_lshlrev_b32_e32 v6, 16, v65
	v_cvt_pk_bf16_f32 v8, v4, v5
	v_lshlrev_b32_e32 v4, 16, v10
	v_and_b32_e32 v5, 0xffff0000, v10
	v_and_b32_e32 v7, 0xffff0000, v65
	v_pk_mul_f32 v[4:5], v[4:5], v[6:7]
	s_nop 0
	v_cvt_pk_bf16_f32 v10, v4, v5
	ds_read_b64 v[4:5], v112 offset:240
	ds_read_b64 v[64:65], v112 offset:16880
	v_lshlrev_b32_e32 v6, 16, v31
	v_and_b32_e32 v7, 0xffff0000, v31
	s_waitcnt lgkmcnt(1)
	v_lshlrev_b32_e32 v66, 16, v4
	v_and_b32_e32 v67, 0xffff0000, v4
	v_pk_mul_f32 v[6:7], v[6:7], v[66:67]
	v_lshlrev_b32_e32 v66, 16, v30
	v_lshlrev_b32_e32 v4, 16, v5
	v_and_b32_e32 v67, 0xffff0000, v30
	v_and_b32_e32 v5, 0xffff0000, v5
	v_pk_mul_f32 v[4:5], v[66:67], v[4:5]
	v_cvt_pk_bf16_f32 v6, v6, v7
	v_cvt_pk_bf16_f32 v7, v4, v5
	v_lshlrev_b32_e32 v4, 16, v29
	s_waitcnt lgkmcnt(0)
	v_lshlrev_b32_e32 v30, 16, v64
	v_and_b32_e32 v5, 0xffff0000, v29
	v_and_b32_e32 v31, 0xffff0000, v64
	v_pk_mul_f32 v[4:5], v[4:5], v[30:31]
	v_lshlrev_b32_e32 v30, 16, v24
	v_lshlrev_b32_e32 v64, 16, v65
	v_and_b32_e32 v31, 0xffff0000, v24
	v_and_b32_e32 v65, 0xffff0000, v65
	v_pk_mul_f32 v[30:31], v[30:31], v[64:65]
	v_cvt_pk_bf16_f32 v4, v4, v5
	v_cvt_pk_bf16_f32 v5, v30, v31
	v_mov_b32_e32 v24, v192
	s_barrier
; DI int otid() { int t = threadIdx.x; asm volatile("" : "+v"(t)); return t; }
; template <bool NT>
; DI void stage_load_tile(bf16_t* stg, const bf16_t* tilebase) {
;   const int tid = otid();
;   const int r0 = tid >> 5, c = tid & 31;
;   const unsigned o0 = (unsigned)(r0 * 1024 + c * 8);
;   __builtin_amdgcn_sched_barrier(0);
; #pragma unroll
;   for (int hf = 0; hf < 2; ++hf) {
; #pragma unroll
;     for (int it = 8 * hf; it < 8 * hf + 8; ++it) {
;       const u32x4* gp = (const u32x4*)(tilebase + (o0 + (unsigned)(it * 16 * 1024)));
;       stage_write16(stg, r0 + 16 * it, c, NT ? __builtin_nontemporal_load(gp) : *gp);
;     }
;     __builtin_amdgcn_sched_barrier(0);
;   }
; }
; template <bool LAST>
; DI void phase_gate(const Params& P, int layer, unsigned char* smem, int L, int G) {
;     ...
;     __syncthreads();
;     stage_load_tile<false>(stg, Sb + (size_t)mt * 256 * 1024 + nt * 256);
;     __syncthreads();
	s_add_u32 s18, s76, s18
	v_ashrrev_i32_e32 v29, 5, v24
	v_and_b32_e32 v24, 31, v24
	s_addc_u32 s19, s77, s19
	v_lshlrev_b32_e32 v30, 3, v24
	v_lshl_add_u64 v[0:1], s[18:19], 0, v[0:1]
	v_lshl_or_b32 v160, v29, 10, v30
	v_add_u32_e32 v64, 0x4000, v160
	v_mov_b32_e32 v65, v161
	v_lshl_add_u64 v[30:31], v[160:161], 1, v[0:1]
	v_lshl_add_u64 v[68:69], v[64:65], 1, v[0:1]
	global_load_dwordx4 v[64:67], v[30:31], off
	s_nop 0
	global_load_dwordx4 v[68:71], v[68:69], off
	v_add_u32_e32 v30, 0x8000, v160
	v_mov_b32_e32 v31, v161
	v_lshl_add_u64 v[30:31], v[30:31], 1, v[0:1]
	v_add_u32_e32 v72, 0xc000, v160
	v_mov_b32_e32 v73, v161
	v_lshl_add_u64 v[80:81], v[72:73], 1, v[0:1]
	global_load_dwordx4 v[72:75], v[30:31], off
	global_load_dwordx4 v[76:79], v[80:81], off
	v_add_u32_e32 v30, 0x10000, v160
	v_mov_b32_e32 v31, v161
	v_lshl_add_u64 v[30:31], v[30:31], 1, v[0:1]
	v_add_u32_e32 v80, 0x14000, v160
	v_mov_b32_e32 v81, v161
	v_lshl_add_u64 v[88:89], v[80:81], 1, v[0:1]
	global_load_dwordx4 v[80:83], v[30:31], off
	global_load_dwordx4 v[100:103], v[88:89], off
	v_add_u32_e32 v30, 0x18000, v160
	v_mov_b32_e32 v31, v161
	v_lshl_add_u64 v[30:31], v[30:31], 1, v[0:1]
	v_add_u32_e32 v88, 0x1c000, v160
	v_mov_b32_e32 v89, v161
	v_lshl_add_u64 v[88:89], v[88:89], 1, v[0:1]
	global_load_dwordx4 v[104:107], v[30:31], off
	global_load_dwordx4 v[108:111], v[88:89], off
	v_add_u32_e32 v252, 0x20000, v160
	v_mov_b32_e32 v253, v161
	v_add_u32_e32 v218, 0x24000, v160
	v_mov_b32_e32 v219, v161
	v_lshl_add_u64 v[252:253], v[252:253], 1, v[0:1]
	v_lshl_add_u64 v[222:223], v[218:219], 1, v[0:1]
	global_load_dwordx4 v[218:221], v[252:253], off
	s_nop 0
	global_load_dwordx4 v[222:225], v[222:223], off
	v_add_u32_e32 v252, 0x28000, v160
	v_mov_b32_e32 v253, v161
	v_lshl_add_u64 v[252:253], v[252:253], 1, v[0:1]
	v_add_u32_e32 v226, 0x2c000, v160
	v_mov_b32_e32 v227, v161
	v_lshl_add_u64 v[234:235], v[226:227], 1, v[0:1]
	global_load_dwordx4 v[226:229], v[252:253], off
	global_load_dwordx4 v[230:233], v[234:235], off
	v_add_u32_e32 v252, 0x30000, v160
	v_mov_b32_e32 v253, v161
	v_lshl_add_u64 v[252:253], v[252:253], 1, v[0:1]
	v_add_u32_e32 v234, 0x34000, v160
	v_mov_b32_e32 v235, v161
	v_lshl_add_u64 v[254:255], v[234:235], 1, v[0:1]
	global_load_dwordx4 v[234:237], v[252:253], off
	global_load_dwordx4 v[238:241], v[254:255], off
	v_add_u32_e32 v252, 0x38000, v160
	v_mov_b32_e32 v253, v161
	v_lshl_add_u64 v[252:253], v[252:253], 1, v[0:1]
	v_add_u32_e32 v160, 0x3c000, v160
	v_lshl_add_u64 v[190:191], v[160:161], 1, v[0:1]
	global_load_dwordx4 v[242:245], v[252:253], off
	global_load_dwordx4 v[248:251], v[190:191], off
	v_mul_lo_u32 v29, v29, s34
	v_lshl_add_u32 v24, v24, 4, v29
	v_add_u32_e32 v29, 0x2080, v24
	v_add_u32_e32 v30, 0x4100, v24
	v_add_u32_e32 v31, 0x6180, v24
	v_add_u32_e32 v32, 0x8200, v24
	v_add_u32_e32 v37, 0xa280, v24
	v_add_u32_e32 v38, 0xc300, v24
	v_add_u32_e32 v87, 0xe380, v24
	s_waitcnt vmcnt(15)
	ds_write2_b64 v24, v[64:65], v[66:67] offset1:1
	s_waitcnt vmcnt(14)
	ds_write2_b64 v29, v[68:69], v[70:71] offset1:1
	s_waitcnt vmcnt(13)
	ds_write2_b64 v30, v[72:73], v[74:75] offset1:1
	s_waitcnt vmcnt(12)
	ds_write2_b64 v31, v[76:77], v[78:79] offset1:1
	s_waitcnt vmcnt(11)
	ds_write2_b64 v32, v[80:81], v[82:83] offset1:1
	s_waitcnt vmcnt(10)
	ds_write2_b64 v37, v[100:101], v[102:103] offset1:1
	s_waitcnt vmcnt(9)
	ds_write2_b64 v38, v[104:105], v[106:107] offset1:1
	s_waitcnt vmcnt(8)
	ds_write2_b64 v87, v[108:109], v[110:111] offset1:1
	v_add_u32_e32 v0, 0x10400, v24
	v_add_u32_e32 v1, 0x12480, v24
	v_add_u32_e32 v29, 0x14500, v24
	v_add_u32_e32 v30, 0x16580, v24
	v_add_u32_e32 v31, 0x18600, v24
	v_add_u32_e32 v32, 0x1a680, v24
	v_add_u32_e32 v37, 0x1c700, v24
	v_add_u32_e32 v24, 0x1e780, v24
	s_waitcnt vmcnt(7)
	ds_write2_b64 v0, v[218:219], v[220:221] offset1:1
	s_waitcnt vmcnt(6)
	ds_write2_b64 v1, v[222:223], v[224:225] offset1:1
	s_waitcnt vmcnt(5)
	ds_write2_b64 v29, v[226:227], v[228:229] offset1:1
	s_waitcnt vmcnt(4)
	ds_write2_b64 v30, v[230:231], v[232:233] offset1:1
	s_waitcnt vmcnt(3)
	ds_write2_b64 v31, v[234:235], v[236:237] offset1:1
	s_waitcnt vmcnt(2)
	ds_write2_b64 v32, v[238:239], v[240:241] offset1:1
	s_waitcnt vmcnt(1)
	ds_write2_b64 v37, v[242:243], v[244:245] offset1:1
	s_waitcnt vmcnt(0)
	ds_write2_b64 v24, v[248:249], v[250:251] offset1:1
	v_mov_b32_e32 v1, v192
	s_waitcnt lgkmcnt(0)
	s_barrier
; DI unsigned pack2(float a, float b) { f32x2_t v = {a, b}; bf16x2_t r = __builtin_convertvector(v, bf16x2_t); return __builtin_bit_cast(unsigned, r); }
; DI float bflo(unsigned u) { return __uint_as_float(u << 16); }
; DI float bfhi(unsigned u) { return __uint_as_float(u & 0xffff0000u); }
; template <bool LAST>
; DI void phase_gate(const Params& P, int layer, unsigned char* smem, int L, int G) {
;     ...
; #pragma unroll
;     for (int i = 0; i < 4; ++i)
; #pragma unroll
;       for (int q4 = 0; q4 < 4; ++q4) {
;         const int fl = wm2 * 128 + i * 32 + 8 * q4 + 4 * h2;
;         const int f0 = nt * 256 + fl;
;         const f32x4 gv = *(const f32x4*)(vecL + 512 + fl), bv = *(const f32x4*)(vecL + 768 + fl);
;         const float ga[4] = {gv.x, gv.y, gv.z, gv.w}, ba[4] = {bv.x, bv.y, bv.z, bv.w};
; #pragma unroll
;         for (int j = 0; j < 2; ++j) {
;           const int lrow = wn2 * 64 + j * 32 + r2;
;           const float mu = rowA[lrow], rstd = rowB[lrow];
;           uint2* sp = (uint2*)(stg + lrow * STG + fl);
;           const uint2 sv = *sp;
;           const float sa[4] = {bflo(sv.x), bfhi(sv.x), bflo(sv.y), bfhi(sv.y)};
;           float y[4];
;           const float gg[4] = {bflo(gq[i][j][2 * q4]), bfhi(gq[i][j][2 * q4]), bflo(gq[i][j][2 * q4 + 1]), bfhi(gq[i][j][2 * q4 + 1])};
; #pragma unroll
;           for (int e = 0; e < 4; ++e) y[e] = (sa[e] - mu) * rstd * ga[e] + ba[e] + gg[e];
;           if (LAST) { f32x4 o = {y[0], y[1], y[2], y[3]}; *(f32x4*)(P.out + (size_t)(mt * 256 + lrow) * 1024 + f0) = o; }
;           else { uint2 pk; pk.x = pack2(y[0], y[1]); pk.y = pack2(y[2], y[3]); *sp = pk; }
;         }
;         __builtin_amdgcn_sched_barrier(0);
;       }
	v_lshlrev_b32_e32 v74, 16, v98
	v_lshrrev_b32_e32 v24, 3, v1
	v_ashrrev_i32_e32 v0, 1, v1
	v_and_b32_e32 v24, 4, v24
	v_and_or_b32 v0, v0, s35, v24
	v_lshlrev_b32_e32 v29, 2, v0
	v_and_b32_e32 v1, 0xdf, v1
	v_add_u32_e32 v30, 0x25000, v29
	v_add_u32_e32 v24, 0x25400, v29
	ds_read_b128 v[64:67], v30
	ds_read_b128 v[68:71], v24
	v_mul_u32_u24_e32 v24, 0x208, v1
	v_lshl_add_u32 v24, v0, 1, v24
	ds_read_b64 v[72:73], v24
	v_lshlrev_b32_e32 v32, 2, v1
	v_or_b32_e32 v31, 0x24000, v32
	v_or_b32_e32 v32, 0x24400, v32
	ds_read_b32 v37, v31
	ds_read_b32 v38, v32
	ds_read_b64 v[78:79], v24 offset:16640
	s_waitcnt lgkmcnt(3)
	v_lshlrev_b32_e32 v80, 16, v73
	v_and_b32_e32 v81, 0xffff0000, v73
	s_waitcnt lgkmcnt(2)
	v_sub_f32_e32 v81, v81, v37
	v_sub_f32_e32 v80, v80, v37
	s_waitcnt lgkmcnt(1)
	v_pk_mul_f32 v[80:81], v[38:39], v[80:81] op_sel_hi:[0,1]
	v_and_b32_e32 v75, 0xffff0000, v98
	v_pk_fma_f32 v[80:81], v[66:67], v[80:81], v[70:71]
	v_lshlrev_b32_e32 v82, 16, v72
	v_and_b32_e32 v83, 0xffff0000, v72
	v_pk_add_f32 v[74:75], v[80:81], v[74:75]
	v_or_b32_e32 v80, s36, v1
	v_add_u32_e32 v76, v0, v162
	v_sub_f32_e32 v83, v83, v37
	v_sub_f32_e32 v82, v82, v37
	v_ashrrev_i32_e32 v81, 31, v80
	v_ashrrev_i32_e32 v77, 31, v76
	v_pk_mul_f32 v[82:83], v[38:39], v[82:83] op_sel_hi:[0,1]
	v_lshlrev_b64 v[80:81], 12, v[80:81]
	v_lshlrev_b32_e32 v72, 16, v99
	v_and_b32_e32 v73, 0xffff0000, v99
	v_pk_fma_f32 v[82:83], v[64:65], v[82:83], v[68:69]
	v_lshl_add_u64 v[80:81], s[94:95], 0, v[80:81]
	v_lshlrev_b64 v[76:77], 2, v[76:77]
	v_or_b32_e32 v1, 32, v1
	v_pk_add_f32 v[72:73], v[82:83], v[72:73]
	v_lshl_add_u64 v[82:83], v[80:81], 0, v[76:77]
	v_lshlrev_b32_e32 v38, 2, v1
	global_store_dwordx4 v[82:83], v[72:75], off
	v_or_b32_e32 v37, 0x24000, v38
	v_or_b32_e32 v38, 0x24400, v38
	ds_read_b32 v73, v37
	ds_read_b32 v72, v38
	s_waitcnt lgkmcnt(2)
	v_lshlrev_b32_e32 v87, 16, v78
	v_and_b32_e32 v88, 0xffff0000, v78
	v_lshlrev_b32_e32 v82, 16, v79
	s_waitcnt lgkmcnt(1)
	v_sub_f32_e32 v89, v88, v73
	v_sub_f32_e32 v88, v87, v73
	v_and_b32_e32 v83, 0xffff0000, v79
	s_waitcnt lgkmcnt(0)
	v_pk_mul_f32 v[88:89], v[72:73], v[88:89] op_sel_hi:[0,1]
	v_sub_f32_e32 v83, v83, v73
	v_sub_f32_e32 v82, v82, v73
	v_pk_fma_f32 v[64:65], v[64:65], v[88:89], v[68:69]
	v_or_b32_e32 v68, s36, v1
	v_pk_mul_f32 v[72:73], v[72:73], v[82:83] op_sel_hi:[0,1]
	v_ashrrev_i32_e32 v69, 31, v68
	v_lshlrev_b32_e32 v78, 16, v95
	v_and_b32_e32 v79, 0xffff0000, v95
	v_pk_fma_f32 v[66:67], v[66:67], v[72:73], v[70:71]
	v_lshlrev_b64 v[68:69], 12, v[68:69]
	v_lshlrev_b32_e32 v74, 16, v94
	v_and_b32_e32 v75, 0xffff0000, v94
	v_pk_add_f32 v[66:67], v[66:67], v[78:79]
	v_lshl_add_u64 v[78:79], s[94:95], 0, v[68:69]
	v_pk_add_f32 v[64:65], v[64:65], v[74:75]
	v_lshl_add_u64 v[68:69], v[78:79], 0, v[76:77]
	global_store_dwordx4 v[68:69], v[64:67], off
	v_add_u32_e32 v1, 0x25020, v29
	ds_read_b128 v[64:67], v1
	v_add_u32_e32 v1, 0x25420, v29
	ds_read_b64 v[72:73], v24 offset:16
	ds_read_b128 v[68:71], v1
	ds_read_b32 v1, v31
	ds_read_b32 v74, v32
	ds_read_b64 v[76:77], v24 offset:16656
	s_waitcnt lgkmcnt(4)
	v_lshlrev_b32_e32 v75, 16, v72
	v_and_b32_e32 v87, 0xffff0000, v72
	v_lshlrev_b32_e32 v82, 16, v73
	v_and_b32_e32 v83, 0xffff0000, v73
	s_waitcnt lgkmcnt(2)
	v_sub_f32_e32 v83, v83, v1
	v_sub_f32_e32 v82, v82, v1
	v_sub_f32_e32 v89, v87, v1
	v_sub_f32_e32 v88, v75, v1
	s_waitcnt lgkmcnt(1)
	v_pk_mul_f32 v[88:89], v[74:75], v[88:89] op_sel_hi:[0,1]
	v_pk_mul_f32 v[74:75], v[74:75], v[82:83] op_sel_hi:[0,1]
	ds_read_b32 v83, v37
	ds_read_b32 v82, v38
	v_ashrrev_i32_e32 v163, 31, v162
	v_ashrrev_i32_e32 v1, 31, v0
	v_lshl_add_u64 v[0:1], v[0:1], 0, v[162:163]
	v_lshlrev_b32_e32 v72, 16, v2
	v_and_b32_e32 v73, 0xffff0000, v2
	v_lshlrev_b32_e32 v2, 16, v3
	v_and_b32_e32 v3, 0xffff0000, v3
	v_pk_fma_f32 v[74:75], v[66:67], v[74:75], v[70:71]
	v_lshlrev_b64 v[0:1], 2, v[0:1]
	v_pk_add_f32 v[74:75], v[74:75], v[2:3]
	v_lshl_add_u64 v[2:3], v[80:81], 0, v[0:1]
	s_waitcnt lgkmcnt(2)
	v_lshlrev_b32_e32 v80, 16, v76
	v_and_b32_e32 v81, 0xffff0000, v76
	v_lshlrev_b32_e32 v76, 16, v77
	v_and_b32_e32 v77, 0xffff0000, v77
	v_pk_fma_f32 v[88:89], v[64:65], v[88:89], v[68:69]
	s_waitcnt lgkmcnt(1)
	v_sub_f32_e32 v77, v77, v83
	v_sub_f32_e32 v76, v76, v83
	v_sub_f32_e32 v81, v81, v83
	v_sub_f32_e32 v80, v80, v83
	v_pk_add_f32 v[72:73], v[88:89], v[72:73]
	s_waitcnt lgkmcnt(0)
	v_pk_mul_f32 v[80:81], v[82:83], v[80:81] op_sel_hi:[0,1]
	v_pk_mul_f32 v[76:77], v[82:83], v[76:77] op_sel_hi:[0,1]
	global_store_dwordx4 v[2:3], v[72:75], off offset:32
	v_pk_fma_f32 v[66:67], v[66:67], v[76:77], v[70:71]
	v_pk_fma_f32 v[64:65], v[64:65], v[80:81], v[68:69]
	v_lshlrev_b32_e32 v72, 16, v91
	v_and_b32_e32 v73, 0xffff0000, v91
	v_lshlrev_b32_e32 v74, 16, v92
	v_and_b32_e32 v75, 0xffff0000, v92
	v_pk_add_f32 v[66:67], v[66:67], v[74:75]
	v_pk_add_f32 v[64:65], v[64:65], v[72:73]
	v_lshl_add_u64 v[0:1], v[78:79], 0, v[0:1]
	global_store_dwordx4 v[0:1], v[64:67], off offset:32
	s_nop 1
	v_add_u32_e32 v64, 0x25040, v29
	v_add_u32_e32 v68, 0x25440, v29
	ds_read_b128 v[64:67], v64
	ds_read_b64 v[72:73], v24 offset:32
	ds_read_b128 v[68:71], v68
	ds_read_b32 v75, v31
	ds_read_b32 v74, v32
	ds_read_b64 v[76:77], v24 offset:16672
	s_waitcnt lgkmcnt(4)
	v_lshlrev_b32_e32 v82, 16, v72
	v_and_b32_e32 v83, 0xffff0000, v72
	v_lshlrev_b32_e32 v80, 16, v73
	v_and_b32_e32 v81, 0xffff0000, v73
	s_waitcnt lgkmcnt(2)
	v_sub_f32_e32 v81, v81, v75
	v_sub_f32_e32 v80, v80, v75
	v_sub_f32_e32 v83, v83, v75
	v_sub_f32_e32 v82, v82, v75
	s_waitcnt lgkmcnt(1)
; DI unsigned pack2(float a, float b) { f32x2_t v = {a, b}; bf16x2_t r = __builtin_convertvector(v, bf16x2_t); return __builtin_bit_cast(unsigned, r); }
; DI float bflo(unsigned u) { return __uint_as_float(u << 16); }
; DI float bfhi(unsigned u) { return __uint_as_float(u & 0xffff0000u); }
; template <bool LAST>
; DI void phase_gate(const Params& P, int layer, unsigned char* smem, int L, int G) {
;     ...
; #pragma unroll
;     for (int i = 0; i < 4; ++i)
; #pragma unroll
;       for (int q4 = 0; q4 < 4; ++q4) {
;         const int fl = wm2 * 128 + i * 32 + 8 * q4 + 4 * h2;
;         const int f0 = nt * 256 + fl;
;         const f32x4 gv = *(const f32x4*)(vecL + 512 + fl), bv = *(const f32x4*)(vecL + 768 + fl);
;         const float ga[4] = {gv.x, gv.y, gv.z, gv.w}, ba[4] = {bv.x, bv.y, bv.z, bv.w};
; #pragma unroll
;         for (int j = 0; j < 2; ++j) {
;           const int lrow = wn2 * 64 + j * 32 + r2;
;           const float mu = rowA[lrow], rstd = rowB[lrow];
;           uint2* sp = (uint2*)(stg + lrow * STG + fl);
;           const uint2 sv = *sp;
;           const float sa[4] = {bflo(sv.x), bfhi(sv.x), bflo(sv.y), bfhi(sv.y)};
;           float y[4];
;           const float gg[4] = {bflo(gq[i][j][2 * q4]), bfhi(gq[i][j][2 * q4]), bflo(gq[i][j][2 * q4 + 1]), bfhi(gq[i][j][2 * q4 + 1])};
; #pragma unroll
;           for (int e = 0; e < 4; ++e) y[e] = (sa[e] - mu) * rstd * ga[e] + ba[e] + gg[e];
;           if (LAST) { f32x4 o = {y[0], y[1], y[2], y[3]}; *(f32x4*)(P.out + (size_t)(mt * 256 + lrow) * 1024 + f0) = o; }
;           else { uint2 pk; pk.x = pack2(y[0], y[1]); pk.y = pack2(y[2], y[3]); *sp = pk; }
;         }
;         __builtin_amdgcn_sched_barrier(0);
;       }
	v_pk_mul_f32 v[82:83], v[74:75], v[82:83] op_sel_hi:[0,1]
	v_pk_mul_f32 v[74:75], v[74:75], v[80:81] op_sel_hi:[0,1]
	ds_read_b32 v81, v37
	ds_read_b32 v80, v38
	v_lshlrev_b32_e32 v78, 16, v86
	v_and_b32_e32 v79, 0xffff0000, v86
	v_pk_fma_f32 v[74:75], v[66:67], v[74:75], v[70:71]
	v_lshlrev_b32_e32 v72, 16, v84
	v_pk_add_f32 v[74:75], v[74:75], v[78:79]
	s_waitcnt lgkmcnt(2)
	v_lshlrev_b32_e32 v78, 16, v76
	v_and_b32_e32 v79, 0xffff0000, v76
	v_lshlrev_b32_e32 v76, 16, v77
	v_and_b32_e32 v77, 0xffff0000, v77
	v_and_b32_e32 v73, 0xffff0000, v84
	v_pk_fma_f32 v[82:83], v[64:65], v[82:83], v[68:69]
	s_waitcnt lgkmcnt(1)
	v_sub_f32_e32 v77, v77, v81
	v_sub_f32_e32 v76, v76, v81
	v_sub_f32_e32 v79, v79, v81
	v_sub_f32_e32 v78, v78, v81
	v_pk_add_f32 v[72:73], v[82:83], v[72:73]
	s_waitcnt lgkmcnt(0)
	v_pk_mul_f32 v[78:79], v[80:81], v[78:79] op_sel_hi:[0,1]
	v_pk_mul_f32 v[76:77], v[80:81], v[76:77] op_sel_hi:[0,1]
	global_store_dwordx4 v[2:3], v[72:75], off offset:64
	v_pk_fma_f32 v[66:67], v[66:67], v[76:77], v[70:71]
	v_pk_fma_f32 v[64:65], v[64:65], v[78:79], v[68:69]
	v_lshlrev_b32_e32 v72, 16, v63
	v_and_b32_e32 v73, 0xffff0000, v63
	v_lshlrev_b32_e32 v74, 16, v85
	v_and_b32_e32 v75, 0xffff0000, v85
	v_pk_add_f32 v[66:67], v[66:67], v[74:75]
	v_pk_add_f32 v[64:65], v[64:65], v[72:73]
	global_store_dwordx4 v[0:1], v[64:67], off offset:64
	v_add_u32_e32 v63, 0x25060, v29
	ds_read_b128 v[64:67], v63
	v_add_u32_e32 v63, 0x25460, v29
	ds_read_b64 v[72:73], v24 offset:48
	ds_read_b128 v[68:71], v63
	ds_read_b32 v75, v31
	ds_read_b32 v74, v32
	ds_read_b64 v[76:77], v24 offset:16688
	s_waitcnt lgkmcnt(4)
	v_lshlrev_b32_e32 v80, 16, v72
	v_and_b32_e32 v81, 0xffff0000, v72
	v_lshlrev_b32_e32 v82, 16, v73
	v_and_b32_e32 v63, 0xffff0000, v73
	v_lshlrev_b32_e32 v78, 16, v62
	v_and_b32_e32 v79, 0xffff0000, v62
	s_waitcnt lgkmcnt(2)
	v_sub_f32_e32 v63, v63, v75
	v_sub_f32_e32 v62, v82, v75
	v_sub_f32_e32 v81, v81, v75
	v_sub_f32_e32 v80, v80, v75
	v_lshlrev_b32_e32 v72, 16, v60
	v_and_b32_e32 v73, 0xffff0000, v60
	s_waitcnt lgkmcnt(1)
	v_pk_mul_f32 v[80:81], v[74:75], v[80:81] op_sel_hi:[0,1]
	v_pk_mul_f32 v[62:63], v[74:75], v[62:63] op_sel_hi:[0,1]
	ds_read_b32 v82, v37
	ds_read_b32 v60, v38
	v_pk_fma_f32 v[62:63], v[66:67], v[62:63], v[70:71]
	v_pk_fma_f32 v[80:81], v[64:65], v[80:81], v[68:69]
	v_pk_add_f32 v[74:75], v[62:63], v[78:79]
	v_pk_add_f32 v[72:73], v[80:81], v[72:73]
	global_store_dwordx4 v[2:3], v[72:75], off offset:96
	s_waitcnt lgkmcnt(2)
	v_lshlrev_b32_e32 v78, 16, v76
	v_and_b32_e32 v76, 0xffff0000, v76
	v_lshlrev_b32_e32 v74, 16, v77
	v_and_b32_e32 v75, 0xffff0000, v77
	s_waitcnt lgkmcnt(1)
	v_sub_f32_e32 v75, v75, v82
	v_sub_f32_e32 v74, v74, v82
	v_sub_f32_e32 v77, v76, v82
	v_sub_f32_e32 v76, v78, v82
	v_lshlrev_b32_e32 v62, 16, v61
	v_and_b32_e32 v63, 0xffff0000, v61
	s_waitcnt lgkmcnt(0)
	v_pk_mul_f32 v[76:77], v[60:61], v[76:77] op_sel_hi:[0,1]
	v_pk_mul_f32 v[60:61], v[60:61], v[74:75] op_sel_hi:[0,1]
	v_lshlrev_b32_e32 v72, 16, v59
	v_and_b32_e32 v73, 0xffff0000, v59
	v_pk_fma_f32 v[60:61], v[66:67], v[60:61], v[70:71]
	v_pk_fma_f32 v[64:65], v[64:65], v[76:77], v[68:69]
	v_pk_add_f32 v[62:63], v[60:61], v[62:63]
	v_pk_add_f32 v[60:61], v[64:65], v[72:73]
	global_store_dwordx4 v[0:1], v[60:63], off offset:96
	v_add_u32_e32 v59, 0x25080, v29
	ds_read_b128 v[60:63], v59
	v_add_u32_e32 v59, 0x25480, v29
	ds_read_b64 v[68:69], v24 offset:64
	ds_read_b128 v[64:67], v59
	ds_read_b32 v71, v31
	ds_read_b32 v70, v32
	ds_read_b64 v[72:73], v24 offset:16704
	s_waitcnt lgkmcnt(4)
	v_lshlrev_b32_e32 v76, 16, v68
	v_and_b32_e32 v77, 0xffff0000, v68
	v_lshlrev_b32_e32 v78, 16, v69
	v_and_b32_e32 v59, 0xffff0000, v69
	v_lshlrev_b32_e32 v74, 16, v58
	v_and_b32_e32 v75, 0xffff0000, v58
	s_waitcnt lgkmcnt(2)
	v_sub_f32_e32 v59, v59, v71
	v_sub_f32_e32 v58, v78, v71
	v_sub_f32_e32 v77, v77, v71
	v_sub_f32_e32 v76, v76, v71
	v_lshlrev_b32_e32 v68, 16, v56
	v_and_b32_e32 v69, 0xffff0000, v56
	s_waitcnt lgkmcnt(1)
	v_pk_mul_f32 v[76:77], v[70:71], v[76:77] op_sel_hi:[0,1]
	v_pk_mul_f32 v[58:59], v[70:71], v[58:59] op_sel_hi:[0,1]
	ds_read_b32 v78, v37
	ds_read_b32 v56, v38
	v_pk_fma_f32 v[58:59], v[62:63], v[58:59], v[66:67]
	v_pk_fma_f32 v[76:77], v[60:61], v[76:77], v[64:65]
	v_pk_add_f32 v[70:71], v[58:59], v[74:75]
	v_pk_add_f32 v[68:69], v[76:77], v[68:69]
	global_store_dwordx4 v[2:3], v[68:71], off offset:128
	s_waitcnt lgkmcnt(2)
	v_lshlrev_b32_e32 v74, 16, v72
	v_and_b32_e32 v72, 0xffff0000, v72
	v_lshlrev_b32_e32 v70, 16, v73
	v_and_b32_e32 v71, 0xffff0000, v73
	s_waitcnt lgkmcnt(1)
	v_sub_f32_e32 v71, v71, v78
	v_sub_f32_e32 v70, v70, v78
	v_sub_f32_e32 v73, v72, v78
	v_sub_f32_e32 v72, v74, v78
	v_lshlrev_b32_e32 v58, 16, v57
	v_and_b32_e32 v59, 0xffff0000, v57
	s_waitcnt lgkmcnt(0)
	v_pk_mul_f32 v[72:73], v[56:57], v[72:73] op_sel_hi:[0,1]
	v_pk_mul_f32 v[56:57], v[56:57], v[70:71] op_sel_hi:[0,1]
	v_lshlrev_b32_e32 v68, 16, v55
	v_and_b32_e32 v69, 0xffff0000, v55
	v_pk_fma_f32 v[56:57], v[62:63], v[56:57], v[66:67]
	v_pk_fma_f32 v[60:61], v[60:61], v[72:73], v[64:65]
	v_pk_add_f32 v[58:59], v[56:57], v[58:59]
	v_pk_add_f32 v[56:57], v[60:61], v[68:69]
	global_store_dwordx4 v[0:1], v[56:59], off offset:128
	v_add_u32_e32 v55, 0x250a0, v29
	ds_read_b128 v[56:59], v55
	v_add_u32_e32 v55, 0x254a0, v29
	ds_read_b64 v[64:65], v24 offset:80
	ds_read_b128 v[60:63], v55
	ds_read_b32 v67, v31
	ds_read_b32 v66, v32
	ds_read_b64 v[68:69], v24 offset:16720
	s_waitcnt lgkmcnt(4)
	v_lshlrev_b32_e32 v72, 16, v64
	v_and_b32_e32 v73, 0xffff0000, v64
	v_lshlrev_b32_e32 v74, 16, v65
	v_and_b32_e32 v55, 0xffff0000, v65
	v_lshlrev_b32_e32 v70, 16, v54
	v_and_b32_e32 v71, 0xffff0000, v54
	s_waitcnt lgkmcnt(2)
; DI unsigned pack2(float a, float b) { f32x2_t v = {a, b}; bf16x2_t r = __builtin_convertvector(v, bf16x2_t); return __builtin_bit_cast(unsigned, r); }
; DI float bflo(unsigned u) { return __uint_as_float(u << 16); }
; DI float bfhi(unsigned u) { return __uint_as_float(u & 0xffff0000u); }
; template <bool LAST>
; DI void phase_gate(const Params& P, int layer, unsigned char* smem, int L, int G) {
;     ...
; #pragma unroll
;     for (int i = 0; i < 4; ++i)
; #pragma unroll
;       for (int q4 = 0; q4 < 4; ++q4) {
;         const int fl = wm2 * 128 + i * 32 + 8 * q4 + 4 * h2;
;         const int f0 = nt * 256 + fl;
;         const f32x4 gv = *(const f32x4*)(vecL + 512 + fl), bv = *(const f32x4*)(vecL + 768 + fl);
;         const float ga[4] = {gv.x, gv.y, gv.z, gv.w}, ba[4] = {bv.x, bv.y, bv.z, bv.w};
; #pragma unroll
;         for (int j = 0; j < 2; ++j) {
;           const int lrow = wn2 * 64 + j * 32 + r2;
;           const float mu = rowA[lrow], rstd = rowB[lrow];
;           uint2* sp = (uint2*)(stg + lrow * STG + fl);
;           const uint2 sv = *sp;
;           const float sa[4] = {bflo(sv.x), bfhi(sv.x), bflo(sv.y), bfhi(sv.y)};
;           float y[4];
;           const float gg[4] = {bflo(gq[i][j][2 * q4]), bfhi(gq[i][j][2 * q4]), bflo(gq[i][j][2 * q4 + 1]), bfhi(gq[i][j][2 * q4 + 1])};
; #pragma unroll
;           for (int e = 0; e < 4; ++e) y[e] = (sa[e] - mu) * rstd * ga[e] + ba[e] + gg[e];
;           if (LAST) { f32x4 o = {y[0], y[1], y[2], y[3]}; *(f32x4*)(P.out + (size_t)(mt * 256 + lrow) * 1024 + f0) = o; }
;           else { uint2 pk; pk.x = pack2(y[0], y[1]); pk.y = pack2(y[2], y[3]); *sp = pk; }
;         }
;         __builtin_amdgcn_sched_barrier(0);
;       }
	v_sub_f32_e32 v55, v55, v67
	v_sub_f32_e32 v54, v74, v67
	v_sub_f32_e32 v73, v73, v67
	v_sub_f32_e32 v72, v72, v67
	v_lshlrev_b32_e32 v64, 16, v52
	v_and_b32_e32 v65, 0xffff0000, v52
	s_waitcnt lgkmcnt(1)
	v_pk_mul_f32 v[72:73], v[66:67], v[72:73] op_sel_hi:[0,1]
	v_pk_mul_f32 v[54:55], v[66:67], v[54:55] op_sel_hi:[0,1]
	ds_read_b32 v74, v37
	ds_read_b32 v52, v38
	v_pk_fma_f32 v[54:55], v[58:59], v[54:55], v[62:63]
	v_pk_fma_f32 v[72:73], v[56:57], v[72:73], v[60:61]
	v_pk_add_f32 v[66:67], v[54:55], v[70:71]
	v_pk_add_f32 v[64:65], v[72:73], v[64:65]
	global_store_dwordx4 v[2:3], v[64:67], off offset:160
	s_waitcnt lgkmcnt(2)
	v_lshlrev_b32_e32 v70, 16, v68
	v_and_b32_e32 v68, 0xffff0000, v68
	v_lshlrev_b32_e32 v66, 16, v69
	v_and_b32_e32 v67, 0xffff0000, v69
	s_waitcnt lgkmcnt(1)
	v_sub_f32_e32 v67, v67, v74
	v_sub_f32_e32 v66, v66, v74
	v_sub_f32_e32 v69, v68, v74
	v_sub_f32_e32 v68, v70, v74
	v_lshlrev_b32_e32 v54, 16, v53
	v_and_b32_e32 v55, 0xffff0000, v53
	s_waitcnt lgkmcnt(0)
	v_pk_mul_f32 v[68:69], v[52:53], v[68:69] op_sel_hi:[0,1]
	v_pk_mul_f32 v[52:53], v[52:53], v[66:67] op_sel_hi:[0,1]
	v_lshlrev_b32_e32 v64, 16, v51
	v_and_b32_e32 v65, 0xffff0000, v51
	v_pk_fma_f32 v[52:53], v[58:59], v[52:53], v[62:63]
	v_pk_fma_f32 v[56:57], v[56:57], v[68:69], v[60:61]
	v_pk_add_f32 v[54:55], v[52:53], v[54:55]
	v_pk_add_f32 v[52:53], v[56:57], v[64:65]
	global_store_dwordx4 v[0:1], v[52:55], off offset:160
	v_add_u32_e32 v51, 0x250c0, v29
	ds_read_b128 v[52:55], v51
	v_add_u32_e32 v51, 0x254c0, v29
	ds_read_b64 v[60:61], v24 offset:96
	ds_read_b128 v[56:59], v51
	ds_read_b32 v63, v31
	ds_read_b32 v62, v32
	ds_read_b64 v[64:65], v24 offset:16736
	s_waitcnt lgkmcnt(4)
	v_lshlrev_b32_e32 v68, 16, v60
	v_and_b32_e32 v69, 0xffff0000, v60
	v_lshlrev_b32_e32 v70, 16, v61
	v_and_b32_e32 v51, 0xffff0000, v61
	v_lshlrev_b32_e32 v66, 16, v50
	v_and_b32_e32 v67, 0xffff0000, v50
	s_waitcnt lgkmcnt(2)
	v_sub_f32_e32 v51, v51, v63
	v_sub_f32_e32 v50, v70, v63
	v_sub_f32_e32 v69, v69, v63
	v_sub_f32_e32 v68, v68, v63
	v_lshlrev_b32_e32 v60, 16, v48
	v_and_b32_e32 v61, 0xffff0000, v48
	s_waitcnt lgkmcnt(1)
	v_pk_mul_f32 v[68:69], v[62:63], v[68:69] op_sel_hi:[0,1]
	v_pk_mul_f32 v[50:51], v[62:63], v[50:51] op_sel_hi:[0,1]
	ds_read_b32 v70, v37
	ds_read_b32 v48, v38
	v_pk_fma_f32 v[50:51], v[54:55], v[50:51], v[58:59]
	v_pk_fma_f32 v[68:69], v[52:53], v[68:69], v[56:57]
	v_pk_add_f32 v[62:63], v[50:51], v[66:67]
	v_pk_add_f32 v[60:61], v[68:69], v[60:61]
	global_store_dwordx4 v[2:3], v[60:63], off offset:192
	s_waitcnt lgkmcnt(2)
	v_lshlrev_b32_e32 v66, 16, v64
	v_and_b32_e32 v64, 0xffff0000, v64
	v_lshlrev_b32_e32 v62, 16, v65
	v_and_b32_e32 v63, 0xffff0000, v65
	s_waitcnt lgkmcnt(1)
	v_sub_f32_e32 v63, v63, v70
	v_sub_f32_e32 v62, v62, v70
	v_sub_f32_e32 v65, v64, v70
	v_sub_f32_e32 v64, v66, v70
	v_lshlrev_b32_e32 v50, 16, v49
	v_and_b32_e32 v51, 0xffff0000, v49
	s_waitcnt lgkmcnt(0)
	v_pk_mul_f32 v[64:65], v[48:49], v[64:65] op_sel_hi:[0,1]
	v_pk_mul_f32 v[48:49], v[48:49], v[62:63] op_sel_hi:[0,1]
	v_lshlrev_b32_e32 v60, 16, v47
	v_and_b32_e32 v61, 0xffff0000, v47
	v_pk_fma_f32 v[48:49], v[54:55], v[48:49], v[58:59]
	v_pk_fma_f32 v[52:53], v[52:53], v[64:65], v[56:57]
	v_pk_add_f32 v[50:51], v[48:49], v[50:51]
	v_pk_add_f32 v[48:49], v[52:53], v[60:61]
	global_store_dwordx4 v[0:1], v[48:51], off offset:192
	v_add_u32_e32 v47, 0x250e0, v29
	ds_read_b128 v[48:51], v47
	v_add_u32_e32 v47, 0x254e0, v29
	ds_read_b64 v[56:57], v24 offset:112
	ds_read_b128 v[52:55], v47
	ds_read_b32 v59, v31
	ds_read_b32 v58, v32
	ds_read_b64 v[60:61], v24 offset:16752
	s_waitcnt lgkmcnt(4)
	v_lshlrev_b32_e32 v64, 16, v56
	v_and_b32_e32 v65, 0xffff0000, v56
	v_lshlrev_b32_e32 v66, 16, v57
	v_and_b32_e32 v47, 0xffff0000, v57
	v_lshlrev_b32_e32 v62, 16, v46
	v_and_b32_e32 v63, 0xffff0000, v46
	s_waitcnt lgkmcnt(2)
	v_sub_f32_e32 v47, v47, v59
	v_sub_f32_e32 v46, v66, v59
	v_sub_f32_e32 v65, v65, v59
	v_sub_f32_e32 v64, v64, v59
	v_lshlrev_b32_e32 v56, 16, v44
	v_and_b32_e32 v57, 0xffff0000, v44
	s_waitcnt lgkmcnt(1)
	v_pk_mul_f32 v[64:65], v[58:59], v[64:65] op_sel_hi:[0,1]
	v_pk_mul_f32 v[46:47], v[58:59], v[46:47] op_sel_hi:[0,1]
	ds_read_b32 v66, v37
	ds_read_b32 v44, v38
	v_pk_fma_f32 v[46:47], v[50:51], v[46:47], v[54:55]
	v_pk_fma_f32 v[64:65], v[48:49], v[64:65], v[52:53]
	v_pk_add_f32 v[58:59], v[46:47], v[62:63]
	v_pk_add_f32 v[56:57], v[64:65], v[56:57]
	global_store_dwordx4 v[2:3], v[56:59], off offset:224
	s_waitcnt lgkmcnt(2)
	v_lshlrev_b32_e32 v62, 16, v60
	v_and_b32_e32 v60, 0xffff0000, v60
	v_lshlrev_b32_e32 v58, 16, v61
	v_and_b32_e32 v59, 0xffff0000, v61
	s_waitcnt lgkmcnt(1)
	v_sub_f32_e32 v59, v59, v66
	v_sub_f32_e32 v58, v58, v66
	v_sub_f32_e32 v61, v60, v66
	v_sub_f32_e32 v60, v62, v66
	v_lshlrev_b32_e32 v46, 16, v45
	v_and_b32_e32 v47, 0xffff0000, v45
	s_waitcnt lgkmcnt(0)
	v_pk_mul_f32 v[60:61], v[44:45], v[60:61] op_sel_hi:[0,1]
	v_pk_mul_f32 v[44:45], v[44:45], v[58:59] op_sel_hi:[0,1]
	v_lshlrev_b32_e32 v56, 16, v43
	v_and_b32_e32 v57, 0xffff0000, v43
	v_pk_fma_f32 v[44:45], v[50:51], v[44:45], v[54:55]
	v_pk_fma_f32 v[48:49], v[48:49], v[60:61], v[52:53]
	v_pk_add_f32 v[46:47], v[44:45], v[46:47]
	v_pk_add_f32 v[44:45], v[48:49], v[56:57]
	global_store_dwordx4 v[0:1], v[44:47], off offset:224
	v_add_u32_e32 v43, 0x25100, v29
	ds_read_b128 v[44:47], v43
	v_add_u32_e32 v43, 0x25500, v29
	ds_read_b64 v[52:53], v24 offset:128
	ds_read_b128 v[48:51], v43
	ds_read_b32 v55, v31
	ds_read_b32 v54, v32
	ds_read_b64 v[56:57], v24 offset:16768
	s_waitcnt lgkmcnt(4)
; DI unsigned pack2(float a, float b) { f32x2_t v = {a, b}; bf16x2_t r = __builtin_convertvector(v, bf16x2_t); return __builtin_bit_cast(unsigned, r); }
; DI float bflo(unsigned u) { return __uint_as_float(u << 16); }
; DI float bfhi(unsigned u) { return __uint_as_float(u & 0xffff0000u); }
; template <bool LAST>
; DI void phase_gate(const Params& P, int layer, unsigned char* smem, int L, int G) {
;     ...
; #pragma unroll
;     for (int i = 0; i < 4; ++i)
; #pragma unroll
;       for (int q4 = 0; q4 < 4; ++q4) {
;         const int fl = wm2 * 128 + i * 32 + 8 * q4 + 4 * h2;
;         const int f0 = nt * 256 + fl;
;         const f32x4 gv = *(const f32x4*)(vecL + 512 + fl), bv = *(const f32x4*)(vecL + 768 + fl);
;         const float ga[4] = {gv.x, gv.y, gv.z, gv.w}, ba[4] = {bv.x, bv.y, bv.z, bv.w};
; #pragma unroll
;         for (int j = 0; j < 2; ++j) {
;           const int lrow = wn2 * 64 + j * 32 + r2;
;           const float mu = rowA[lrow], rstd = rowB[lrow];
;           uint2* sp = (uint2*)(stg + lrow * STG + fl);
;           const uint2 sv = *sp;
;           const float sa[4] = {bflo(sv.x), bfhi(sv.x), bflo(sv.y), bfhi(sv.y)};
;           float y[4];
;           const float gg[4] = {bflo(gq[i][j][2 * q4]), bfhi(gq[i][j][2 * q4]), bflo(gq[i][j][2 * q4 + 1]), bfhi(gq[i][j][2 * q4 + 1])};
; #pragma unroll
;           for (int e = 0; e < 4; ++e) y[e] = (sa[e] - mu) * rstd * ga[e] + ba[e] + gg[e];
;           if (LAST) { f32x4 o = {y[0], y[1], y[2], y[3]}; *(f32x4*)(P.out + (size_t)(mt * 256 + lrow) * 1024 + f0) = o; }
;           else { uint2 pk; pk.x = pack2(y[0], y[1]); pk.y = pack2(y[2], y[3]); *sp = pk; }
;         }
;         __builtin_amdgcn_sched_barrier(0);
;       }
	v_lshlrev_b32_e32 v60, 16, v52
	v_and_b32_e32 v61, 0xffff0000, v52
	v_lshlrev_b32_e32 v62, 16, v53
	v_and_b32_e32 v43, 0xffff0000, v53
	v_lshlrev_b32_e32 v58, 16, v42
	v_and_b32_e32 v59, 0xffff0000, v42
	s_waitcnt lgkmcnt(2)
	v_sub_f32_e32 v43, v43, v55
	v_sub_f32_e32 v42, v62, v55
	v_sub_f32_e32 v61, v61, v55
	v_sub_f32_e32 v60, v60, v55
	v_lshlrev_b32_e32 v52, 16, v40
	v_and_b32_e32 v53, 0xffff0000, v40
	s_waitcnt lgkmcnt(1)
	v_pk_mul_f32 v[60:61], v[54:55], v[60:61] op_sel_hi:[0,1]
	v_pk_mul_f32 v[42:43], v[54:55], v[42:43] op_sel_hi:[0,1]
	ds_read_b32 v62, v37
	ds_read_b32 v40, v38
	v_pk_fma_f32 v[42:43], v[46:47], v[42:43], v[50:51]
	v_pk_fma_f32 v[60:61], v[44:45], v[60:61], v[48:49]
	v_pk_add_f32 v[54:55], v[42:43], v[58:59]
	v_pk_add_f32 v[52:53], v[60:61], v[52:53]
	global_store_dwordx4 v[2:3], v[52:55], off offset:256
	s_waitcnt lgkmcnt(2)
	v_lshlrev_b32_e32 v58, 16, v56
	v_and_b32_e32 v56, 0xffff0000, v56
	v_lshlrev_b32_e32 v54, 16, v57
	v_and_b32_e32 v55, 0xffff0000, v57
	s_waitcnt lgkmcnt(1)
	v_sub_f32_e32 v55, v55, v62
	v_sub_f32_e32 v54, v54, v62
	v_sub_f32_e32 v57, v56, v62
	v_sub_f32_e32 v56, v58, v62
	v_lshlrev_b32_e32 v42, 16, v41
	v_and_b32_e32 v43, 0xffff0000, v41
	s_waitcnt lgkmcnt(0)
	v_pk_mul_f32 v[56:57], v[40:41], v[56:57] op_sel_hi:[0,1]
	v_pk_mul_f32 v[40:41], v[40:41], v[54:55] op_sel_hi:[0,1]
	v_lshlrev_b32_e32 v52, 16, v39
	v_and_b32_e32 v53, 0xffff0000, v39
	v_pk_fma_f32 v[40:41], v[46:47], v[40:41], v[50:51]
	v_pk_fma_f32 v[44:45], v[44:45], v[56:57], v[48:49]
	v_pk_add_f32 v[42:43], v[40:41], v[42:43]
	v_pk_add_f32 v[40:41], v[44:45], v[52:53]
	global_store_dwordx4 v[0:1], v[40:43], off offset:256
	v_add_u32_e32 v39, 0x25120, v29
	ds_read_b128 v[40:43], v39
	v_add_u32_e32 v39, 0x25520, v29
	ds_read_b64 v[48:49], v24 offset:144
	ds_read_b128 v[44:47], v39
	ds_read_b32 v39, v31
	ds_read_b32 v50, v32
	ds_read_b64 v[52:53], v24 offset:16784
	s_waitcnt lgkmcnt(4)
	v_lshlrev_b32_e32 v51, 16, v48
	v_and_b32_e32 v58, 0xffff0000, v48
	v_lshlrev_b32_e32 v56, 16, v49
	v_and_b32_e32 v57, 0xffff0000, v49
	v_lshlrev_b32_e32 v48, 16, v34
	v_and_b32_e32 v49, 0xffff0000, v34
	v_lshlrev_b32_e32 v54, 16, v36
	v_and_b32_e32 v55, 0xffff0000, v36
	s_waitcnt lgkmcnt(2)
	v_sub_f32_e32 v57, v57, v39
	v_sub_f32_e32 v56, v56, v39
	v_sub_f32_e32 v59, v58, v39
	v_sub_f32_e32 v58, v51, v39
	ds_read_b32 v36, v37
	ds_read_b32 v34, v38
	s_waitcnt lgkmcnt(3)
	v_pk_mul_f32 v[58:59], v[50:51], v[58:59] op_sel_hi:[0,1]
	v_pk_mul_f32 v[50:51], v[50:51], v[56:57] op_sel_hi:[0,1]
	v_pk_fma_f32 v[50:51], v[42:43], v[50:51], v[46:47]
	v_pk_fma_f32 v[56:57], v[40:41], v[58:59], v[44:45]
	v_pk_add_f32 v[50:51], v[50:51], v[54:55]
	s_waitcnt lgkmcnt(2)
	v_lshlrev_b32_e32 v39, 16, v52
	v_and_b32_e32 v54, 0xffff0000, v52
	v_lshlrev_b32_e32 v52, 16, v53
	v_and_b32_e32 v53, 0xffff0000, v53
	v_pk_add_f32 v[48:49], v[56:57], v[48:49]
	s_waitcnt lgkmcnt(1)
	v_sub_f32_e32 v53, v53, v36
	v_sub_f32_e32 v52, v52, v36
	v_sub_f32_e32 v55, v54, v36
	v_sub_f32_e32 v54, v39, v36
	global_store_dwordx4 v[2:3], v[48:51], off offset:288
	s_waitcnt lgkmcnt(0)
	v_pk_mul_f32 v[54:55], v[34:35], v[54:55] op_sel_hi:[0,1]
	v_pk_fma_f32 v[40:41], v[40:41], v[54:55], v[44:45]
	v_lshlrev_b32_e32 v50, 16, v35
	v_and_b32_e32 v51, 0xffff0000, v35
	v_pk_mul_f32 v[34:35], v[34:35], v[52:53] op_sel_hi:[0,1]
	v_lshlrev_b32_e32 v48, 16, v33
	v_and_b32_e32 v49, 0xffff0000, v33
	v_pk_fma_f32 v[34:35], v[42:43], v[34:35], v[46:47]
	v_pk_add_f32 v[40:41], v[40:41], v[48:49]
	v_pk_add_f32 v[42:43], v[34:35], v[50:51]
	global_store_dwordx4 v[0:1], v[40:43], off offset:288
	v_add_u32_e32 v33, 0x25140, v29
	ds_read_b128 v[40:43], v33
	v_add_u32_e32 v33, 0x25540, v29
	ds_read_b64 v[34:35], v24 offset:160
	ds_read_b128 v[44:47], v33
	ds_read_b32 v33, v31
	ds_read_b32 v36, v32
	ds_read_b64 v[52:53], v24 offset:16800
	s_waitcnt lgkmcnt(4)
	v_lshlrev_b32_e32 v39, 16, v34
	v_and_b32_e32 v54, 0xffff0000, v34
	v_lshlrev_b32_e32 v50, 16, v35
	v_and_b32_e32 v51, 0xffff0000, v35
	s_waitcnt lgkmcnt(2)
	v_sub_f32_e32 v51, v51, v33
	v_sub_f32_e32 v50, v50, v33
	v_sub_f32_e32 v55, v54, v33
	v_sub_f32_e32 v54, v39, v33
	v_lshlrev_b32_e32 v34, 16, v26
	v_and_b32_e32 v35, 0xffff0000, v26
	v_lshlrev_b32_e32 v48, 16, v28
	v_and_b32_e32 v49, 0xffff0000, v28
	s_waitcnt lgkmcnt(1)
	v_pk_mul_f32 v[54:55], v[36:37], v[54:55] op_sel_hi:[0,1]
	v_pk_mul_f32 v[50:51], v[36:37], v[50:51] op_sel_hi:[0,1]
	ds_read_b32 v28, v37
	ds_read_b32 v26, v38
	v_pk_fma_f32 v[50:51], v[42:43], v[50:51], v[46:47]
	v_pk_fma_f32 v[54:55], v[40:41], v[54:55], v[44:45]
	v_pk_add_f32 v[50:51], v[50:51], v[48:49]
	v_pk_add_f32 v[48:49], v[54:55], v[34:35]
	global_store_dwordx4 v[2:3], v[48:51], off offset:320
	s_waitcnt lgkmcnt(2)
	v_lshlrev_b32_e32 v33, 16, v52
	v_and_b32_e32 v36, 0xffff0000, v52
	v_lshlrev_b32_e32 v39, 16, v53
	v_and_b32_e32 v50, 0xffff0000, v53
	s_waitcnt lgkmcnt(1)
	v_sub_f32_e32 v51, v50, v28
	v_sub_f32_e32 v50, v39, v28
	v_sub_f32_e32 v53, v36, v28
	v_sub_f32_e32 v52, v33, v28
	v_lshlrev_b32_e32 v48, 16, v27
	v_and_b32_e32 v49, 0xffff0000, v27
	s_waitcnt lgkmcnt(0)
	v_pk_mul_f32 v[52:53], v[26:27], v[52:53] op_sel_hi:[0,1]
	v_pk_mul_f32 v[26:27], v[26:27], v[50:51] op_sel_hi:[0,1]
	v_lshlrev_b32_e32 v34, 16, v25
	v_and_b32_e32 v35, 0xffff0000, v25
	v_pk_fma_f32 v[26:27], v[42:43], v[26:27], v[46:47]
	v_pk_fma_f32 v[40:41], v[40:41], v[52:53], v[44:45]
	v_pk_add_f32 v[42:43], v[26:27], v[48:49]
	v_pk_add_f32 v[40:41], v[40:41], v[34:35]
	global_store_dwordx4 v[0:1], v[40:43], off offset:320
	v_add_u32_e32 v25, 0x25160, v29
	ds_read_b128 v[40:43], v25
	v_add_u32_e32 v25, 0x25560, v29
	ds_read_b64 v[26:27], v24 offset:176
	ds_read_b128 v[44:47], v25
	ds_read_b32 v25, v31
	ds_read_b32 v28, v32
	ds_read_b64 v[34:35], v24 offset:16816
	s_waitcnt lgkmcnt(4)
; DI unsigned pack2(float a, float b) { f32x2_t v = {a, b}; bf16x2_t r = __builtin_convertvector(v, bf16x2_t); return __builtin_bit_cast(unsigned, r); }
; DI float bflo(unsigned u) { return __uint_as_float(u << 16); }
; DI float bfhi(unsigned u) { return __uint_as_float(u & 0xffff0000u); }
; template <bool LAST>
; DI void phase_gate(const Params& P, int layer, unsigned char* smem, int L, int G) {
;     ...
; #pragma unroll
;     for (int i = 0; i < 4; ++i)
; #pragma unroll
;       for (int q4 = 0; q4 < 4; ++q4) {
;         const int fl = wm2 * 128 + i * 32 + 8 * q4 + 4 * h2;
;         const int f0 = nt * 256 + fl;
;         const f32x4 gv = *(const f32x4*)(vecL + 512 + fl), bv = *(const f32x4*)(vecL + 768 + fl);
;         const float ga[4] = {gv.x, gv.y, gv.z, gv.w}, ba[4] = {bv.x, bv.y, bv.z, bv.w};
; #pragma unroll
;         for (int j = 0; j < 2; ++j) {
;           const int lrow = wn2 * 64 + j * 32 + r2;
;           const float mu = rowA[lrow], rstd = rowB[lrow];
;           uint2* sp = (uint2*)(stg + lrow * STG + fl);
;           const uint2 sv = *sp;
;           const float sa[4] = {bflo(sv.x), bfhi(sv.x), bflo(sv.y), bfhi(sv.y)};
;           float y[4];
;           const float gg[4] = {bflo(gq[i][j][2 * q4]), bfhi(gq[i][j][2 * q4]), bflo(gq[i][j][2 * q4 + 1]), bfhi(gq[i][j][2 * q4 + 1])};
; #pragma unroll
;           for (int e = 0; e < 4; ++e) y[e] = (sa[e] - mu) * rstd * ga[e] + ba[e] + gg[e];
;           if (LAST) { f32x4 o = {y[0], y[1], y[2], y[3]}; *(f32x4*)(P.out + (size_t)(mt * 256 + lrow) * 1024 + f0) = o; }
;           else { uint2 pk; pk.x = pack2(y[0], y[1]); pk.y = pack2(y[2], y[3]); *sp = pk; }
;         }
;         __builtin_amdgcn_sched_barrier(0);
;       }
	v_lshlrev_b32_e32 v33, 16, v26
	v_and_b32_e32 v36, 0xffff0000, v26
	v_lshlrev_b32_e32 v39, 16, v27
	v_and_b32_e32 v50, 0xffff0000, v27
	s_waitcnt lgkmcnt(2)
	v_sub_f32_e32 v51, v50, v25
	v_sub_f32_e32 v50, v39, v25
	v_sub_f32_e32 v53, v36, v25
	v_sub_f32_e32 v52, v33, v25
	s_waitcnt lgkmcnt(1)
	v_pk_mul_f32 v[52:53], v[28:29], v[52:53] op_sel_hi:[0,1]
	v_pk_mul_f32 v[50:51], v[28:29], v[50:51] op_sel_hi:[0,1]
	ds_read_b32 v25, v37
	ds_read_b32 v28, v38
	v_lshlrev_b32_e32 v26, 16, v21
	v_and_b32_e32 v27, 0xffff0000, v21
	v_lshlrev_b32_e32 v48, 16, v23
	v_and_b32_e32 v49, 0xffff0000, v23
	v_pk_fma_f32 v[50:51], v[42:43], v[50:51], v[46:47]
	v_pk_fma_f32 v[52:53], v[40:41], v[52:53], v[44:45]
	s_waitcnt lgkmcnt(2)
	v_lshlrev_b32_e32 v33, 16, v34
	v_and_b32_e32 v34, 0xffff0000, v34
	v_lshlrev_b32_e32 v36, 16, v35
	v_and_b32_e32 v23, 0xffff0000, v35
	v_pk_add_f32 v[50:51], v[50:51], v[48:49]
	v_pk_add_f32 v[48:49], v[52:53], v[26:27]
	v_lshlrev_b32_e32 v26, 16, v20
	v_and_b32_e32 v27, 0xffff0000, v20
	v_lshlrev_b32_e32 v20, 16, v22
	v_and_b32_e32 v21, 0xffff0000, v22
	s_waitcnt lgkmcnt(1)
	v_sub_f32_e32 v23, v23, v25
	v_sub_f32_e32 v22, v36, v25
	v_sub_f32_e32 v35, v34, v25
	v_sub_f32_e32 v34, v33, v25
	s_waitcnt lgkmcnt(0)
	v_pk_mul_f32 v[34:35], v[28:29], v[34:35] op_sel_hi:[0,1]
	v_pk_mul_f32 v[22:23], v[28:29], v[22:23] op_sel_hi:[0,1]
	v_pk_fma_f32 v[22:23], v[42:43], v[22:23], v[46:47]
	v_pk_fma_f32 v[34:35], v[40:41], v[34:35], v[44:45]
	v_pk_add_f32 v[22:23], v[22:23], v[20:21]
	v_pk_add_f32 v[20:21], v[34:35], v[26:27]
	global_store_dwordx4 v[2:3], v[48:51], off offset:352
	global_store_dwordx4 v[0:1], v[20:23], off offset:352
	s_nop 1
	v_add_u32_e32 v20, 0x25180, v29
	v_add_u32_e32 v25, 0x25580, v29
	ds_read_b128 v[20:23], v20
	ds_read_b64 v[26:27], v24 offset:192
	ds_read_b128 v[40:43], v25
	ds_read_b32 v25, v31
	ds_read_b32 v28, v32
	ds_read_b64 v[34:35], v24 offset:16832
	s_waitcnt lgkmcnt(4)
	v_lshlrev_b32_e32 v33, 16, v26
	v_and_b32_e32 v36, 0xffff0000, v26
	v_lshlrev_b32_e32 v39, 16, v27
	v_and_b32_e32 v46, 0xffff0000, v27
	s_waitcnt lgkmcnt(2)
	v_sub_f32_e32 v47, v46, v25
	v_sub_f32_e32 v46, v39, v25
	v_sub_f32_e32 v49, v36, v25
	v_sub_f32_e32 v48, v33, v25
	s_waitcnt lgkmcnt(1)
	v_pk_mul_f32 v[48:49], v[28:29], v[48:49] op_sel_hi:[0,1]
	v_pk_mul_f32 v[46:47], v[28:29], v[46:47] op_sel_hi:[0,1]
	ds_read_b32 v25, v37
	ds_read_b32 v28, v38
	v_lshlrev_b32_e32 v26, 16, v17
	v_and_b32_e32 v27, 0xffff0000, v17
	v_lshlrev_b32_e32 v44, 16, v19
	v_and_b32_e32 v45, 0xffff0000, v19
	v_pk_fma_f32 v[46:47], v[22:23], v[46:47], v[42:43]
	v_pk_fma_f32 v[48:49], v[20:21], v[48:49], v[40:41]
	s_waitcnt lgkmcnt(2)
	v_lshlrev_b32_e32 v33, 16, v34
	v_and_b32_e32 v34, 0xffff0000, v34
	v_lshlrev_b32_e32 v36, 16, v35
	v_and_b32_e32 v19, 0xffff0000, v35
	v_pk_add_f32 v[46:47], v[46:47], v[44:45]
	v_pk_add_f32 v[44:45], v[48:49], v[26:27]
	v_lshlrev_b32_e32 v26, 16, v16
	v_and_b32_e32 v27, 0xffff0000, v16
	v_lshlrev_b32_e32 v16, 16, v18
	v_and_b32_e32 v17, 0xffff0000, v18
	s_waitcnt lgkmcnt(1)
	v_sub_f32_e32 v19, v19, v25
	v_sub_f32_e32 v18, v36, v25
	v_sub_f32_e32 v35, v34, v25
	v_sub_f32_e32 v34, v33, v25
	s_waitcnt lgkmcnt(0)
	v_pk_mul_f32 v[34:35], v[28:29], v[34:35] op_sel_hi:[0,1]
	v_pk_mul_f32 v[18:19], v[28:29], v[18:19] op_sel_hi:[0,1]
	v_pk_fma_f32 v[18:19], v[22:23], v[18:19], v[42:43]
	v_pk_fma_f32 v[20:21], v[20:21], v[34:35], v[40:41]
	v_pk_add_f32 v[18:19], v[18:19], v[16:17]
	v_pk_add_f32 v[16:17], v[20:21], v[26:27]
	global_store_dwordx4 v[2:3], v[44:47], off offset:384
	global_store_dwordx4 v[0:1], v[16:19], off offset:384
	s_nop 1
	v_add_u32_e32 v16, 0x251a0, v29
	v_add_u32_e32 v20, 0x255a0, v29
	ds_read_b128 v[16:19], v16
	ds_read_b64 v[26:27], v24 offset:208
	ds_read_b128 v[20:23], v20
	ds_read_b32 v25, v31
	ds_read_b32 v28, v32
	ds_read_b64 v[34:35], v24 offset:16848
	s_waitcnt lgkmcnt(4)
	v_lshlrev_b32_e32 v33, 16, v26
	v_and_b32_e32 v36, 0xffff0000, v26
	v_lshlrev_b32_e32 v39, 16, v27
	v_and_b32_e32 v42, 0xffff0000, v27
	s_waitcnt lgkmcnt(2)
	v_sub_f32_e32 v43, v42, v25
	v_sub_f32_e32 v42, v39, v25
	v_sub_f32_e32 v45, v36, v25
	v_sub_f32_e32 v44, v33, v25
	s_waitcnt lgkmcnt(1)
	v_pk_mul_f32 v[44:45], v[28:29], v[44:45] op_sel_hi:[0,1]
	v_pk_mul_f32 v[42:43], v[28:29], v[42:43] op_sel_hi:[0,1]
	ds_read_b32 v25, v37
	ds_read_b32 v28, v38
	v_lshlrev_b32_e32 v26, 16, v13
	v_and_b32_e32 v27, 0xffff0000, v13
	v_lshlrev_b32_e32 v40, 16, v15
	v_and_b32_e32 v41, 0xffff0000, v15
	v_pk_fma_f32 v[42:43], v[18:19], v[42:43], v[22:23]
	v_pk_fma_f32 v[44:45], v[16:17], v[44:45], v[20:21]
	s_waitcnt lgkmcnt(2)
; DI unsigned pack2(float a, float b) { f32x2_t v = {a, b}; bf16x2_t r = __builtin_convertvector(v, bf16x2_t); return __builtin_bit_cast(unsigned, r); }
; DI float bflo(unsigned u) { return __uint_as_float(u << 16); }
; DI float bfhi(unsigned u) { return __uint_as_float(u & 0xffff0000u); }
; template <bool LAST>
; DI void phase_gate(const Params& P, int layer, unsigned char* smem, int L, int G) {
;     ...
; #pragma unroll
;     for (int i = 0; i < 4; ++i)
; #pragma unroll
;       for (int q4 = 0; q4 < 4; ++q4) {
;         const int fl = wm2 * 128 + i * 32 + 8 * q4 + 4 * h2;
;         const int f0 = nt * 256 + fl;
;         const f32x4 gv = *(const f32x4*)(vecL + 512 + fl), bv = *(const f32x4*)(vecL + 768 + fl);
;         const float ga[4] = {gv.x, gv.y, gv.z, gv.w}, ba[4] = {bv.x, bv.y, bv.z, bv.w};
; #pragma unroll
;         for (int j = 0; j < 2; ++j) {
;           const int lrow = wn2 * 64 + j * 32 + r2;
;           const float mu = rowA[lrow], rstd = rowB[lrow];
;           uint2* sp = (uint2*)(stg + lrow * STG + fl);
;           const uint2 sv = *sp;
;           const float sa[4] = {bflo(sv.x), bfhi(sv.x), bflo(sv.y), bfhi(sv.y)};
;           float y[4];
;           const float gg[4] = {bflo(gq[i][j][2 * q4]), bfhi(gq[i][j][2 * q4]), bflo(gq[i][j][2 * q4 + 1]), bfhi(gq[i][j][2 * q4 + 1])};
; #pragma unroll
;           for (int e = 0; e < 4; ++e) y[e] = (sa[e] - mu) * rstd * ga[e] + ba[e] + gg[e];
;           if (LAST) { f32x4 o = {y[0], y[1], y[2], y[3]}; *(f32x4*)(P.out + (size_t)(mt * 256 + lrow) * 1024 + f0) = o; }
;           else { uint2 pk; pk.x = pack2(y[0], y[1]); pk.y = pack2(y[2], y[3]); *sp = pk; }
;         }
;         __builtin_amdgcn_sched_barrier(0);
;       }
;     __syncthreads();
;     if (!LAST) stage_store_tile(stg, xb + (size_t)mt * 256 * 1024 + nt * 256);
;     __syncthreads();
	v_lshlrev_b32_e32 v33, 16, v34
	v_and_b32_e32 v34, 0xffff0000, v34
	v_lshlrev_b32_e32 v36, 16, v35
	v_and_b32_e32 v15, 0xffff0000, v35
	v_pk_add_f32 v[42:43], v[42:43], v[40:41]
	v_pk_add_f32 v[40:41], v[44:45], v[26:27]
	v_lshlrev_b32_e32 v26, 16, v12
	v_and_b32_e32 v27, 0xffff0000, v12
	v_lshlrev_b32_e32 v12, 16, v14
	v_and_b32_e32 v13, 0xffff0000, v14
	s_waitcnt lgkmcnt(1)
	v_sub_f32_e32 v15, v15, v25
	v_sub_f32_e32 v14, v36, v25
	v_sub_f32_e32 v35, v34, v25
	v_sub_f32_e32 v34, v33, v25
	s_waitcnt lgkmcnt(0)
	v_pk_mul_f32 v[34:35], v[28:29], v[34:35] op_sel_hi:[0,1]
	v_pk_mul_f32 v[14:15], v[28:29], v[14:15] op_sel_hi:[0,1]
	v_pk_fma_f32 v[14:15], v[18:19], v[14:15], v[22:23]
	v_pk_fma_f32 v[16:17], v[16:17], v[34:35], v[20:21]
	v_pk_add_f32 v[14:15], v[14:15], v[12:13]
	v_pk_add_f32 v[12:13], v[16:17], v[26:27]
	global_store_dwordx4 v[2:3], v[40:43], off offset:416
	global_store_dwordx4 v[0:1], v[12:15], off offset:416
	s_nop 1
	v_add_u32_e32 v12, 0x251c0, v29
	v_add_u32_e32 v16, 0x255c0, v29
	ds_read_b128 v[12:15], v12
	ds_read_b64 v[20:21], v24 offset:224
	ds_read_b128 v[16:19], v16
	ds_read_b32 v23, v31
	ds_read_b32 v22, v32
	ds_read_b64 v[26:27], v24 offset:16864
	s_waitcnt lgkmcnt(4)
	v_lshlrev_b32_e32 v25, 16, v20
	v_and_b32_e32 v28, 0xffff0000, v20
	v_lshlrev_b32_e32 v33, 16, v21
	v_and_b32_e32 v36, 0xffff0000, v21
	s_waitcnt lgkmcnt(2)
	v_sub_f32_e32 v41, v36, v23
	v_sub_f32_e32 v40, v33, v23
	v_sub_f32_e32 v43, v28, v23
	v_sub_f32_e32 v42, v25, v23
	s_waitcnt lgkmcnt(1)
	v_pk_mul_f32 v[42:43], v[22:23], v[42:43] op_sel_hi:[0,1]
	v_pk_mul_f32 v[22:23], v[22:23], v[40:41] op_sel_hi:[0,1]
	ds_read_b32 v25, v37
	ds_read_b32 v28, v38
	v_lshlrev_b32_e32 v20, 16, v9
	v_and_b32_e32 v21, 0xffff0000, v9
	v_lshlrev_b32_e32 v34, 16, v11
	v_and_b32_e32 v35, 0xffff0000, v11
	v_pk_fma_f32 v[22:23], v[14:15], v[22:23], v[18:19]
	v_pk_fma_f32 v[40:41], v[12:13], v[42:43], v[16:17]
	v_pk_add_f32 v[22:23], v[22:23], v[34:35]
	v_pk_add_f32 v[20:21], v[40:41], v[20:21]
	global_store_dwordx4 v[2:3], v[20:23], off offset:448
	s_waitcnt lgkmcnt(2)
	v_and_b32_e32 v11, 0xffff0000, v27
	v_and_b32_e32 v9, 0xffff0000, v10
	v_lshlrev_b32_e32 v22, 16, v26
	v_and_b32_e32 v23, 0xffff0000, v26
	v_lshlrev_b32_e32 v26, 16, v27
	v_lshlrev_b32_e32 v20, 16, v8
	v_and_b32_e32 v21, 0xffff0000, v8
	v_lshlrev_b32_e32 v8, 16, v10
	s_waitcnt lgkmcnt(1)
	v_sub_f32_e32 v11, v11, v25
	v_sub_f32_e32 v10, v26, v25
	v_sub_f32_e32 v23, v23, v25
	v_sub_f32_e32 v22, v22, v25
	s_waitcnt lgkmcnt(0)
	v_pk_mul_f32 v[22:23], v[28:29], v[22:23] op_sel_hi:[0,1]
	v_pk_mul_f32 v[10:11], v[28:29], v[10:11] op_sel_hi:[0,1]
	v_pk_fma_f32 v[10:11], v[14:15], v[10:11], v[18:19]
	v_pk_fma_f32 v[12:13], v[12:13], v[22:23], v[16:17]
	v_pk_add_f32 v[10:11], v[10:11], v[8:9]
	v_pk_add_f32 v[8:9], v[12:13], v[20:21]
	global_store_dwordx4 v[0:1], v[8:11], off offset:448
	ds_read_b128 v[8:11], v30 offset:480
	ds_read_b64 v[16:17], v24 offset:240
	ds_read_b32 v19, v31
	ds_read_b32 v18, v32
	v_add_u32_e32 v12, 0x255e0, v29
	ds_read_b128 v[12:15], v12
	s_waitcnt lgkmcnt(3)
	v_lshlrev_b32_e32 v22, 16, v16
	v_and_b32_e32 v23, 0xffff0000, v16
	v_lshlrev_b32_e32 v20, 16, v17
	v_and_b32_e32 v21, 0xffff0000, v17
	s_waitcnt lgkmcnt(2)
	v_sub_f32_e32 v21, v21, v19
	v_sub_f32_e32 v20, v20, v19
	v_sub_f32_e32 v23, v23, v19
	v_sub_f32_e32 v22, v22, v19
	s_waitcnt lgkmcnt(1)
	v_pk_mul_f32 v[22:23], v[18:19], v[22:23] op_sel_hi:[0,1]
	v_pk_mul_f32 v[18:19], v[18:19], v[20:21] op_sel_hi:[0,1]
	ds_read_b32 v20, v38
	ds_read_b32 v21, v37
	ds_read_b64 v[24:25], v24 offset:16880
	v_lshlrev_b32_e32 v16, 16, v6
	v_and_b32_e32 v17, 0xffff0000, v6
	v_lshlrev_b32_e32 v6, 16, v7
	v_and_b32_e32 v7, 0xffff0000, v7
	s_waitcnt lgkmcnt(3)
	v_pk_fma_f32 v[18:19], v[10:11], v[18:19], v[14:15]
	v_pk_fma_f32 v[22:23], v[8:9], v[22:23], v[12:13]
	v_pk_add_f32 v[18:19], v[18:19], v[6:7]
	v_pk_add_f32 v[16:17], v[22:23], v[16:17]
	global_store_dwordx4 v[2:3], v[16:19], off offset:480
	s_waitcnt lgkmcnt(0)
	v_lshlrev_b32_e32 v6, 16, v25
	v_and_b32_e32 v7, 0xffff0000, v25
	v_lshlrev_b32_e32 v16, 16, v24
	v_and_b32_e32 v17, 0xffff0000, v24
	v_sub_f32_e32 v7, v7, v21
	v_sub_f32_e32 v6, v6, v21
	v_sub_f32_e32 v17, v17, v21
	v_sub_f32_e32 v16, v16, v21
	v_pk_mul_f32 v[16:17], v[20:21], v[16:17] op_sel_hi:[0,1]
	v_pk_mul_f32 v[6:7], v[20:21], v[6:7] op_sel_hi:[0,1]
	v_lshlrev_b32_e32 v2, 16, v4
	v_and_b32_e32 v3, 0xffff0000, v4
	v_lshlrev_b32_e32 v4, 16, v5
	v_and_b32_e32 v5, 0xffff0000, v5
	v_pk_fma_f32 v[6:7], v[10:11], v[6:7], v[14:15]
	v_pk_fma_f32 v[8:9], v[8:9], v[16:17], v[12:13]
	v_pk_add_f32 v[4:5], v[6:7], v[4:5]
	v_pk_add_f32 v[2:3], v[8:9], v[2:3]
	global_store_dwordx4 v[0:1], v[2:5], off offset:480
	s_add_i32 s25, s25, s74
	s_add_i32 s22, s22, s69
	s_add_i32 s23, s23, s24
	s_add_i32 s18, s70, s25
	s_cmpk_lt_i32 s18, 0x400
	s_barrier
	s_barrier
	s_cbranch_scc0 .LBB0_1810
